# attention: 4-deep K LDS ring (static LDS +24 KiB) with K fragments prefetched across the step barrier, exps split between QK and PV segments; out-proj and gate GEMM epilogues rewritten with hoisted lo
# speedup vs baseline: 1.1095x; 1.0380x over previous
.LBB0_417:
	s_ashr_i32 s40, s77, 8
	s_ashr_i32 s41, s40, 31
	s_and_b32 s49, s77, 7
	s_lshl_b32 s1, s77, 5
	s_and_b32 s34, s1, 0x1f00
	s_lshl_b32 s2, s40, 3
	s_or_b32 s2, s2, s49
	s_mul_i32 s3, s2, 0x300000
	s_mul_i32 s1, s34, 0x180
	s_add_u32 s12, s68, s3
	s_addc_u32 s13, s69, 0
	s_add_u32 s12, s12, s1
	s_addc_u32 s13, s13, 0
	s_add_u32 s42, s70, s3
	s_addc_u32 s43, s71, 0
	s_lshl_b32 s1, s40, 25
	s_lshl_b32 s3, s49, 9
	s_add_i32 s1, s1, s3
	s_add_i32 s1, s1, 0x24000100
	s_add_u32 s46, s38, s1
	s_addc_u32 s47, s39, 0
	s_lshr_b32 s15, s85, 6
	s_lshl_b32 s52, s15, 5
	s_lshl_b32 s1, s15, 8
	s_add_i32 s44, s1, 0x1e000
	s_mul_i32 s60, s15, 0xc00
	s_lshl_b32 s61, s15, 11
	v_mbcnt_lo_u32_b32 v176, -1, 0
	v_mbcnt_hi_u32_b32 v200, -1, v176
	v_and_b32_e32 v196, 31, v200
	v_lshrrev_b32_e32 v198, 5, v200
	v_or_b32_e32 v187, s52, v196
	v_mul_u32_u24_e32 v187, 0x180, v187
	v_lshl_add_u32 v187, v198, 4, v187
	global_load_dwordx4 v[96:99], v187, s[12:13] offset:0
	global_load_dwordx4 v[100:103], v187, s[12:13] offset:32
	global_load_dwordx4 v[104:107], v187, s[12:13] offset:64
	global_load_dwordx4 v[108:111], v187, s[12:13] offset:96
	global_load_dwordx4 v[112:115], v187, s[12:13] offset:128
	global_load_dwordx4 v[116:119], v187, s[12:13] offset:160
	global_load_dwordx4 v[120:123], v187, s[12:13] offset:192
	global_load_dwordx4 v[124:127], v187, s[12:13] offset:224
	global_load_dwordx4 v[128:131], v187, s[12:13] offset:256
	global_load_dwordx4 v[132:135], v187, s[12:13] offset:288
	global_load_dwordx4 v[136:139], v187, s[12:13] offset:320
	global_load_dwordx4 v[140:143], v187, s[12:13] offset:352
	s_mul_i32 s1, s15, 3
	s_add_i32 s1, s1, 0
	s_lshl_b32 s1, s1, 6
	v_add_u32_e32 v247, s1, v200
	v_mul_u32_u24_e32 v248, 0xaab, v247
	v_lshrrev_b32_e32 v248, 16, v248
	v_mul_u32_u24_e32 v249, 24, v248
	v_sub_u32_e32 v247, v247, v249
	v_bfe_u32 v249, v248, 1, 3
	v_xor_b32_e32 v247, v247, v249
	v_mul_u32_u24_e32 v248, 0x180, v248
	v_lshl_add_u32 v182, v247, 4, v248
	s_mul_i32 s1, s15, 3
	s_add_i32 s1, s1, 1
	s_lshl_b32 s1, s1, 6
	v_add_u32_e32 v247, s1, v200
	v_mul_u32_u24_e32 v248, 0xaab, v247
	v_lshrrev_b32_e32 v248, 16, v248
	v_mul_u32_u24_e32 v249, 24, v248
	v_sub_u32_e32 v247, v247, v249
	v_bfe_u32 v249, v248, 1, 3
	v_xor_b32_e32 v247, v247, v249
	v_mul_u32_u24_e32 v248, 0x180, v248
	v_lshl_add_u32 v183, v247, 4, v248
	s_mul_i32 s1, s15, 3
	s_add_i32 s1, s1, 2
	s_lshl_b32 s1, s1, 6
	v_add_u32_e32 v247, s1, v200
	v_mul_u32_u24_e32 v248, 0xaab, v247
	v_lshrrev_b32_e32 v248, 16, v248
	v_mul_u32_u24_e32 v249, 24, v248
	v_sub_u32_e32 v247, v247, v249
	v_bfe_u32 v249, v248, 1, 3
	v_xor_b32_e32 v247, v247, v249
	v_mul_u32_u24_e32 v248, 0x180, v248
	v_lshl_add_u32 v184, v247, 4, v248
	s_lshl_b32 s1, s15, 1
	s_add_i32 s1, s1, 0
	s_lshl_b32 s1, s1, 6
	v_add_u32_e32 v247, s1, v200
	v_lshrrev_b32_e32 v248, 7, v247
	v_lshlrev_b32_e32 v248, 3, v248
	v_bfe_u32 v249, v247, 2, 3
	v_or_b32_e32 v248, v248, v249
	v_bfe_u32 v249, v247, 5, 2
	v_and_b32_e32 v247, 3, v247
	v_lshlrev_b32_e32 v247, 4, v247
	v_lshl_add_u32 v247, v249, 6, v247
	v_lshl_add_u32 v185, v248, 12, v247
	s_lshl_b32 s1, s15, 1
	s_add_i32 s1, s1, 1
	s_lshl_b32 s1, s1, 6
	v_add_u32_e32 v247, s1, v200
	v_lshrrev_b32_e32 v248, 7, v247
	v_lshlrev_b32_e32 v248, 3, v248
	v_bfe_u32 v249, v247, 2, 3
	v_or_b32_e32 v248, v248, v249
	v_bfe_u32 v249, v247, 5, 2
	v_and_b32_e32 v247, 3, v247
	v_lshlrev_b32_e32 v247, 4, v247
	v_lshl_add_u32 v247, v249, 6, v247
	v_lshl_add_u32 v186, v248, 12, v247
	v_bfe_u32 v247, v196, 1, 3
	v_mul_u32_u24_e32 v248, 0x180, v196
	v_add_u32_e32 v248, 0xc000, v248
	v_or_b32_e32 v249, 0, v198
	v_xor_b32_e32 v249, v249, v247
	v_lshl_add_u32 v240, v249, 4, v248
	v_or_b32_e32 v249, 2, v198
	v_xor_b32_e32 v249, v249, v247
	v_lshl_add_u32 v241, v249, 4, v248
	v_or_b32_e32 v249, 4, v198
	v_xor_b32_e32 v249, v249, v247
	v_lshl_add_u32 v242, v249, 4, v248
	v_or_b32_e32 v249, 6, v198
	v_xor_b32_e32 v249, v249, v247
	v_lshl_add_u32 v243, v249, 4, v248
	v_and_b32_e32 v247, 3, v200
	v_lshlrev_b32_e32 v244, 3, v247
	v_bfe_u32 v247, v200, 2, 2
	v_lshl_or_b32 v244, v247, 6, v244
	v_bfe_u32 v247, v200, 4, 1
	v_lshl_or_b32 v244, v247, 5, v244
	v_lshl_or_b32 v244, v198, 8, v244
	v_mov_b32_e32 v0, 0
	v_mov_b32_e32 v1, 0
	v_mov_b32_e32 v2, 0
	v_mov_b32_e32 v3, 0
	v_mov_b32_e32 v4, 0
	v_mov_b32_e32 v5, 0
	v_mov_b32_e32 v6, 0
	v_mov_b32_e32 v7, 0
	v_mov_b32_e32 v8, 0
	v_mov_b32_e32 v9, 0
	v_mov_b32_e32 v10, 0
	v_mov_b32_e32 v11, 0
	v_mov_b32_e32 v12, 0
	v_mov_b32_e32 v13, 0
	v_mov_b32_e32 v14, 0
	v_mov_b32_e32 v15, 0
	v_mov_b32_e32 v16, 0
	v_mov_b32_e32 v17, 0
	v_mov_b32_e32 v18, 0
	v_mov_b32_e32 v19, 0
	v_mov_b32_e32 v20, 0
	v_mov_b32_e32 v21, 0
	v_mov_b32_e32 v22, 0
	v_mov_b32_e32 v23, 0
	v_mov_b32_e32 v24, 0
	v_mov_b32_e32 v25, 0
	v_mov_b32_e32 v26, 0
	v_mov_b32_e32 v27, 0
	v_mov_b32_e32 v28, 0
	v_mov_b32_e32 v29, 0
	v_mov_b32_e32 v30, 0
	v_mov_b32_e32 v31, 0
	v_mov_b32_e32 v32, 0
	v_mov_b32_e32 v33, 0
	v_mov_b32_e32 v34, 0
	v_mov_b32_e32 v35, 0
	v_mov_b32_e32 v36, 0
	v_mov_b32_e32 v37, 0
	v_mov_b32_e32 v38, 0
	v_mov_b32_e32 v39, 0
	v_mov_b32_e32 v40, 0
	v_mov_b32_e32 v41, 0
	v_mov_b32_e32 v42, 0
	v_mov_b32_e32 v43, 0
	v_mov_b32_e32 v44, 0
	v_mov_b32_e32 v45, 0
	v_mov_b32_e32 v46, 0
	v_mov_b32_e32 v47, 0
	v_mov_b32_e32 v48, 0
	v_mov_b32_e32 v49, 0
	v_mov_b32_e32 v50, 0
	v_mov_b32_e32 v51, 0
	v_mov_b32_e32 v52, 0
	v_mov_b32_e32 v53, 0
	v_mov_b32_e32 v54, 0
	v_mov_b32_e32 v55, 0
	v_mov_b32_e32 v56, 0
	v_mov_b32_e32 v57, 0
	v_mov_b32_e32 v58, 0
	v_mov_b32_e32 v59, 0
	v_mov_b32_e32 v60, 0
	v_mov_b32_e32 v61, 0
	v_mov_b32_e32 v62, 0
	v_mov_b32_e32 v63, 0
	v_mov_b32_e32 v245, 0
	v_mov_b32_e32 v246, 0
	s_add_i32 m0, s60, 0xc000
	s_nop 0
	global_load_lds_dwordx4 v182, s[42:43]
	s_add_i32 m0, s60, 0xc400
	s_nop 0
	global_load_lds_dwordx4 v183, s[42:43]
	s_add_i32 m0, s60, 0xc800
	s_nop 0
	global_load_lds_dwordx4 v184, s[42:43]
	s_add_u32 s42, s42, 0x6000
	s_addc_u32 s43, s43, 0
	s_add_i32 m0, s60, 0x12000
	s_nop 0
	global_load_lds_dwordx4 v182, s[42:43]
	s_add_i32 m0, s60, 0x12400
	s_nop 0
	global_load_lds_dwordx4 v183, s[42:43]
	s_add_i32 m0, s60, 0x12800
	s_nop 0
	global_load_lds_dwordx4 v184, s[42:43]
	s_add_u32 s42, s42, 0x6000
	s_addc_u32 s43, s43, 0
	s_add_i32 m0, s60, 0x18000
	s_nop 0
	global_load_lds_dwordx4 v182, s[42:43]
	s_add_i32 m0, s60, 0x18400
	s_nop 0
	global_load_lds_dwordx4 v183, s[42:43]
	s_add_i32 m0, s60, 0x18800
	s_nop 0
	global_load_lds_dwordx4 v184, s[42:43]
	s_add_u32 s42, s42, 0x6000
	s_addc_u32 s43, s43, 0
	s_add_i32 m0, s61, 0x0
	s_nop 0
	global_load_lds_dwordx4 v185, s[46:47]
	s_add_i32 m0, s61, 0x400
	s_nop 0
	global_load_lds_dwordx4 v186, s[46:47]
	s_add_u32 s46, s46, 0x40000
	s_addc_u32 s47, s47, 0
	s_waitcnt vmcnt(5)
	s_barrier
	ds_read_b128 v[144:147], v240 offset:0
	ds_read_b128 v[148:151], v240 offset:12288
	ds_read_b128 v[152:155], v241 offset:0
	ds_read_b128 v[156:159], v241 offset:12288
	ds_read_b128 v[160:163], v242 offset:0
	ds_read_b128 v[164:167], v242 offset:12288
	ds_read_b128 v[168:171], v243 offset:0
	s_waitcnt lgkmcnt(6)
	v_mfma_f32_32x32x16_bf16 v[208:223], v[144:147], v[96:99], 0
	s_add_i32 m0, s60, 0x21010
	s_nop 0
	global_load_lds_dwordx4 v182, s[42:43]
	ds_read_b128 v[172:175], v243 offset:12288
	s_waitcnt lgkmcnt(6)
	v_mfma_f32_32x32x16_bf16 v[224:239], v[148:151], v[96:99], 0
	s_add_i32 m0, s60, 0x21410
	s_nop 0
	global_load_lds_dwordx4 v183, s[42:43]
	ds_read_b128 v[144:147], v240 offset:128
	s_waitcnt lgkmcnt(6)
	v_mfma_f32_32x32x16_bf16 v[208:223], v[152:155], v[100:103], v[208:223]
	s_add_i32 m0, s60, 0x21810
	s_nop 0
	global_load_lds_dwordx4 v184, s[42:43]
	ds_read_b128 v[148:151], v240 offset:12416
	s_waitcnt lgkmcnt(6)
	v_mfma_f32_32x32x16_bf16 v[224:239], v[156:159], v[100:103], v[224:239]
	s_add_i32 m0, s61, 0x4000
	s_nop 0
	global_load_lds_dwordx4 v185, s[46:47]
	ds_read_b128 v[152:155], v241 offset:128
	s_waitcnt lgkmcnt(6)
	v_mfma_f32_32x32x16_bf16 v[208:223], v[160:163], v[104:107], v[208:223]
	s_add_i32 m0, s61, 0x4400
	s_nop 0
	global_load_lds_dwordx4 v186, s[46:47]
	ds_read_b128 v[156:159], v241 offset:12416
	s_waitcnt lgkmcnt(6)
	v_mfma_f32_32x32x16_bf16 v[224:239], v[164:167], v[104:107], v[224:239]
	s_add_u32 s42, s42, 0x6000
	s_addc_u32 s43, s43, 0
	ds_read_b128 v[160:163], v242 offset:128
	s_waitcnt lgkmcnt(6)
	v_mfma_f32_32x32x16_bf16 v[208:223], v[168:171], v[108:111], v[208:223]
	s_add_u32 s46, s46, 0x40000
	s_addc_u32 s47, s47, 0
	ds_read_b128 v[164:167], v242 offset:12416
	s_waitcnt lgkmcnt(6)
	v_mfma_f32_32x32x16_bf16 v[224:239], v[172:175], v[108:111], v[224:239]
	ds_read_b128 v[168:171], v243 offset:128
	s_waitcnt lgkmcnt(6)
	v_mfma_f32_32x32x16_bf16 v[208:223], v[144:147], v[112:115], v[208:223]
	ds_read_b128 v[172:175], v243 offset:12416
	s_waitcnt lgkmcnt(6)
	v_mfma_f32_32x32x16_bf16 v[224:239], v[148:151], v[112:115], v[224:239]
	ds_read_b128 v[144:147], v240 offset:256
	s_waitcnt lgkmcnt(6)
	v_mfma_f32_32x32x16_bf16 v[208:223], v[152:155], v[116:119], v[208:223]
	ds_read_b128 v[148:151], v240 offset:12544
	s_waitcnt lgkmcnt(6)
	v_mfma_f32_32x32x16_bf16 v[224:239], v[156:159], v[116:119], v[224:239]
	ds_read_b128 v[152:155], v241 offset:256
	s_waitcnt lgkmcnt(6)
	v_mfma_f32_32x32x16_bf16 v[208:223], v[160:163], v[120:123], v[208:223]
	ds_read_b128 v[156:159], v241 offset:12544
	s_waitcnt lgkmcnt(6)
	v_mfma_f32_32x32x16_bf16 v[224:239], v[164:167], v[120:123], v[224:239]
	ds_read_b128 v[160:163], v242 offset:256
	s_waitcnt lgkmcnt(6)
	v_mfma_f32_32x32x16_bf16 v[208:223], v[168:171], v[124:127], v[208:223]
	ds_read_b128 v[164:167], v242 offset:12544
	s_waitcnt lgkmcnt(6)
	v_mfma_f32_32x32x16_bf16 v[224:239], v[172:175], v[124:127], v[224:239]
	ds_read_b128 v[168:171], v243 offset:256
	s_waitcnt lgkmcnt(6)
	v_mfma_f32_32x32x16_bf16 v[208:223], v[144:147], v[128:131], v[208:223]
	ds_read_b128 v[172:175], v243 offset:12544
	s_waitcnt lgkmcnt(6)
	v_mfma_f32_32x32x16_bf16 v[224:239], v[148:151], v[128:131], v[224:239]
	v_add_u32_e32 v240, 0x6000, v240
	s_waitcnt lgkmcnt(5)
	v_mfma_f32_32x32x16_bf16 v[208:223], v[152:155], v[132:135], v[208:223]
	v_add_u32_e32 v241, 0x6000, v241
	s_waitcnt lgkmcnt(4)
	v_mfma_f32_32x32x16_bf16 v[224:239], v[156:159], v[132:135], v[224:239]
	v_add_u32_e32 v242, 0x6000, v242
	s_waitcnt lgkmcnt(3)
	v_mfma_f32_32x32x16_bf16 v[208:223], v[160:163], v[136:139], v[208:223]
	v_add_u32_e32 v243, 0x6000, v243
	s_waitcnt lgkmcnt(2)
	v_mfma_f32_32x32x16_bf16 v[224:239], v[164:167], v[136:139], v[224:239]
	s_waitcnt lgkmcnt(1)
	v_mfma_f32_32x32x16_bf16 v[208:223], v[168:171], v[140:143], v[208:223]
	s_waitcnt lgkmcnt(0)
	v_mfma_f32_32x32x16_bf16 v[224:239], v[172:175], v[140:143], v[224:239]
	s_nop 7
	s_nop 7
	v_exp_f32_e32 v208, v208
	v_exp_f32_e32 v209, v209
	v_exp_f32_e32 v210, v210
	v_exp_f32_e32 v211, v211
	v_exp_f32_e32 v212, v212
	v_exp_f32_e32 v213, v213
	v_exp_f32_e32 v214, v214
	v_exp_f32_e32 v215, v215
	v_exp_f32_e32 v216, v216
	v_exp_f32_e32 v217, v217
	v_exp_f32_e32 v218, v218
	v_exp_f32_e32 v219, v219
	v_exp_f32_e32 v220, v220
	v_exp_f32_e32 v221, v221
	v_exp_f32_e32 v222, v222
	v_exp_f32_e32 v223, v223
	s_mov_b32 s78, 10
	s_waitcnt vmcnt(5)
	s_barrier
	ds_read_b128 v[144:147], v240 offset:0
	ds_read_b128 v[148:151], v240 offset:12288
	ds_read_b128 v[152:155], v241 offset:0
	ds_read_b128 v[156:159], v241 offset:12288
	ds_read_b128 v[160:163], v242 offset:0
	ds_read_b128 v[164:167], v242 offset:12288
	v_exp_f32_e32 v224, v224
	v_add_f32_e32 v245, v208, v245
	v_exp_f32_e32 v225, v225
	v_add_f32_e32 v246, v209, v246
	v_exp_f32_e32 v226, v226
	v_add_f32_e32 v245, v210, v245
	v_exp_f32_e32 v227, v227
	v_add_f32_e32 v246, v211, v246
	ds_read_b128 v[168:171], v243 offset:0
	s_waitcnt lgkmcnt(6)
	v_mfma_f32_32x32x16_bf16 v[64:79], v[144:147], v[96:99], 0
	v_exp_f32_e32 v228, v228
	v_add_f32_e32 v245, v212, v245
	v_exp_f32_e32 v229, v229
	ds_read_b128 v[172:175], v243 offset:12288
	s_waitcnt lgkmcnt(6)
	v_mfma_f32_32x32x16_bf16 v[80:95], v[148:151], v[96:99], 0
	v_add_f32_e32 v246, v213, v246
	v_exp_f32_e32 v230, v230
	v_add_f32_e32 v245, v214, v245
	ds_read_b128 v[144:147], v240 offset:128
	s_waitcnt lgkmcnt(6)
	v_mfma_f32_32x32x16_bf16 v[64:79], v[152:155], v[100:103], v[64:79]
	v_exp_f32_e32 v231, v231
	s_add_i32 m0, s60, 0xc000
	s_nop 0
	global_load_lds_dwordx4 v182, s[42:43]
	v_add_f32_e32 v246, v215, v246
	ds_read_b128 v[148:151], v240 offset:12416
	s_waitcnt lgkmcnt(6)
	v_mfma_f32_32x32x16_bf16 v[80:95], v[156:159], v[100:103], v[80:95]
	v_exp_f32_e32 v232, v232
	v_add_f32_e32 v245, v216, v245
	v_exp_f32_e32 v233, v233
	ds_read_b128 v[152:155], v241 offset:128
	s_waitcnt lgkmcnt(6)
	v_mfma_f32_32x32x16_bf16 v[64:79], v[160:163], v[104:107], v[64:79]
	v_add_f32_e32 v246, v217, v246
	v_exp_f32_e32 v234, v234
	v_add_f32_e32 v245, v218, v245
	ds_read_b128 v[156:159], v241 offset:12416
	s_waitcnt lgkmcnt(6)
	v_mfma_f32_32x32x16_bf16 v[80:95], v[164:167], v[104:107], v[80:95]
	s_add_i32 m0, s60, 0xc400
	s_nop 0
	global_load_lds_dwordx4 v183, s[42:43]
	v_exp_f32_e32 v235, v235
	v_add_f32_e32 v246, v219, v246
	ds_read_b128 v[160:163], v242 offset:128
	s_waitcnt lgkmcnt(6)
	v_mfma_f32_32x32x16_bf16 v[64:79], v[168:171], v[108:111], v[64:79]
	v_exp_f32_e32 v236, v236
	v_add_f32_e32 v245, v220, v245
	v_exp_f32_e32 v237, v237
	ds_read_b128 v[164:167], v242 offset:12416
	s_waitcnt lgkmcnt(6)
	v_mfma_f32_32x32x16_bf16 v[80:95], v[172:175], v[108:111], v[80:95]
	v_add_f32_e32 v246, v221, v246
	v_exp_f32_e32 v238, v238
	s_add_i32 m0, s60, 0xc800
	s_nop 0
	global_load_lds_dwordx4 v184, s[42:43]
	ds_read_b128 v[168:171], v243 offset:128
	s_waitcnt lgkmcnt(6)
	v_mfma_f32_32x32x16_bf16 v[64:79], v[144:147], v[112:115], v[64:79]
	v_add_f32_e32 v245, v222, v245
	v_exp_f32_e32 v239, v239
	v_add_f32_e32 v246, v223, v246
	ds_read_b128 v[172:175], v243 offset:12416
	s_waitcnt lgkmcnt(6)
	v_mfma_f32_32x32x16_bf16 v[80:95], v[148:151], v[112:115], v[80:95]
	v_add_f32_e32 v245, v224, v245
	v_add_f32_e32 v246, v225, v246
	v_add_f32_e32 v245, v226, v245
	ds_read_b128 v[144:147], v240 offset:256
	s_waitcnt lgkmcnt(6)
	v_mfma_f32_32x32x16_bf16 v[64:79], v[152:155], v[116:119], v[64:79]
	v_add_f32_e32 v246, v227, v246
	s_add_i32 m0, s61, 0x8000
	s_nop 0
	global_load_lds_dwordx4 v185, s[46:47]
	v_add_f32_e32 v245, v228, v245
	ds_read_b128 v[148:151], v240 offset:12544
	s_waitcnt lgkmcnt(6)
	v_mfma_f32_32x32x16_bf16 v[80:95], v[156:159], v[116:119], v[80:95]
	v_add_f32_e32 v246, v229, v246
	v_add_f32_e32 v245, v230, v245
	v_add_f32_e32 v246, v231, v246
	ds_read_b128 v[152:155], v241 offset:256
	s_waitcnt lgkmcnt(6)
	v_mfma_f32_32x32x16_bf16 v[64:79], v[160:163], v[120:123], v[64:79]
	v_add_f32_e32 v245, v232, v245
	v_add_f32_e32 v246, v233, v246
	v_add_f32_e32 v245, v234, v245
	ds_read_b128 v[156:159], v241 offset:12544
	s_waitcnt lgkmcnt(6)
	v_mfma_f32_32x32x16_bf16 v[80:95], v[164:167], v[120:123], v[80:95]
	s_add_i32 m0, s61, 0x8400
	s_nop 0
	global_load_lds_dwordx4 v186, s[46:47]
	v_add_f32_e32 v246, v235, v246
	v_add_f32_e32 v245, v236, v245
	ds_read_b128 v[160:163], v242 offset:256
	s_waitcnt lgkmcnt(6)
	v_mfma_f32_32x32x16_bf16 v[64:79], v[168:171], v[124:127], v[64:79]
	v_add_f32_e32 v246, v237, v246
	v_add_f32_e32 v245, v238, v245
	v_add_f32_e32 v246, v239, v246
	ds_read_b128 v[164:167], v242 offset:12544
	s_waitcnt lgkmcnt(6)
	v_mfma_f32_32x32x16_bf16 v[80:95], v[172:175], v[124:127], v[80:95]
	v_cvt_pk_bf16_f32 v208, v208, v209
	v_cvt_pk_bf16_f32 v209, v210, v211
	ds_read_b128 v[168:171], v243 offset:256
	s_waitcnt lgkmcnt(6)
	v_mfma_f32_32x32x16_bf16 v[64:79], v[144:147], v[128:131], v[64:79]
	s_add_u32 s42, s42, 0x6000
	s_addc_u32 s43, s43, 0
	v_cvt_pk_bf16_f32 v210, v212, v213
	ds_read_b128 v[172:175], v243 offset:12544
	s_waitcnt lgkmcnt(6)
	v_mfma_f32_32x32x16_bf16 v[80:95], v[148:151], v[128:131], v[80:95]
	v_cvt_pk_bf16_f32 v211, v214, v215
	v_cvt_pk_bf16_f32 v212, v216, v217
	v_add_u32_e32 v240, 0x6000, v240
	ds_read_b64_tr_b16 v[144:145], v244 offset:0
	ds_read_b64_tr_b16 v[146:147], v244 offset:2048
	s_waitcnt lgkmcnt(7)
	v_mfma_f32_32x32x16_bf16 v[64:79], v[152:155], v[132:135], v[64:79]
	v_cvt_pk_bf16_f32 v213, v218, v219
	v_cvt_pk_bf16_f32 v214, v220, v221
	v_add_u32_e32 v241, 0x6000, v241
	ds_read_b64_tr_b16 v[148:149], v244 offset:4096
	ds_read_b64_tr_b16 v[150:151], v244 offset:6144
	s_waitcnt lgkmcnt(8)
	v_mfma_f32_32x32x16_bf16 v[80:95], v[156:159], v[132:135], v[80:95]
	v_cvt_pk_bf16_f32 v215, v222, v223
	v_cvt_pk_bf16_f32 v224, v224, v225
	v_add_u32_e32 v242, 0x6000, v242
	ds_read_b64_tr_b16 v[152:153], v244 offset:8192
	ds_read_b64_tr_b16 v[154:155], v244 offset:10240
	s_waitcnt lgkmcnt(9)
	v_mfma_f32_32x32x16_bf16 v[64:79], v[160:163], v[136:139], v[64:79]
	s_add_u32 s46, s46, 0x40000
	s_addc_u32 s47, s47, 0
	v_cvt_pk_bf16_f32 v225, v226, v227
	v_add_u32_e32 v243, 0x6000, v243
	ds_read_b64_tr_b16 v[156:157], v244 offset:12288
	ds_read_b64_tr_b16 v[158:159], v244 offset:14336
	s_waitcnt lgkmcnt(10)
	v_mfma_f32_32x32x16_bf16 v[80:95], v[164:167], v[136:139], v[80:95]
	v_cvt_pk_bf16_f32 v226, v228, v229
	v_cvt_pk_bf16_f32 v227, v230, v231
	ds_read_b64_tr_b16 v[160:161], v244 offset:512
	ds_read_b64_tr_b16 v[162:163], v244 offset:2560
	s_waitcnt lgkmcnt(11)
	v_mfma_f32_32x32x16_bf16 v[64:79], v[168:171], v[140:143], v[64:79]
	v_cvt_pk_bf16_f32 v228, v232, v233
	v_cvt_pk_bf16_f32 v229, v234, v235
	ds_read_b64_tr_b16 v[164:165], v244 offset:4608
	ds_read_b64_tr_b16 v[166:167], v244 offset:6656
	s_waitcnt lgkmcnt(12)
	v_mfma_f32_32x32x16_bf16 v[80:95], v[172:175], v[140:143], v[80:95]
	v_cvt_pk_bf16_f32 v230, v236, v237
	v_cvt_pk_bf16_f32 v231, v238, v239
	s_waitcnt lgkmcnt(10)
	v_mfma_f32_32x32x16_bf16 v[48:63], v[208:211], v[144:147], v[48:63]
	s_waitcnt lgkmcnt(8)
	v_mfma_f32_32x32x16_bf16 v[48:63], v[212:215], v[148:151], v[48:63]
	ds_read_b64_tr_b16 v[168:169], v244 offset:8704
	ds_read_b64_tr_b16 v[170:171], v244 offset:10752
	s_waitcnt lgkmcnt(8)
	v_mfma_f32_32x32x16_bf16 v[48:63], v[224:227], v[152:155], v[48:63]
	v_exp_f32_e32 v64, v64
	v_exp_f32_e32 v65, v65
	ds_read_b64_tr_b16 v[172:173], v244 offset:12800
	ds_read_b64_tr_b16 v[174:175], v244 offset:14848
	s_waitcnt lgkmcnt(8)
	v_mfma_f32_32x32x16_bf16 v[48:63], v[228:231], v[156:159], v[48:63]
	v_exp_f32_e32 v66, v66
	v_exp_f32_e32 v67, v67
	ds_read_b64_tr_b16 v[144:145], v244 offset:1024
	ds_read_b64_tr_b16 v[146:147], v244 offset:3072
	s_waitcnt lgkmcnt(8)
	v_mfma_f32_32x32x16_bf16 v[32:47], v[208:211], v[160:163], v[32:47]
	v_exp_f32_e32 v68, v68
	ds_read_b64_tr_b16 v[148:149], v244 offset:5120
	ds_read_b64_tr_b16 v[150:151], v244 offset:7168
	s_waitcnt lgkmcnt(8)
	v_mfma_f32_32x32x16_bf16 v[32:47], v[212:215], v[164:167], v[32:47]
	v_exp_f32_e32 v69, v69
	ds_read_b64_tr_b16 v[152:153], v244 offset:9216
	ds_read_b64_tr_b16 v[154:155], v244 offset:11264
	s_waitcnt lgkmcnt(8)
	v_mfma_f32_32x32x16_bf16 v[32:47], v[224:227], v[168:171], v[32:47]
	v_exp_f32_e32 v70, v70
	ds_read_b64_tr_b16 v[156:157], v244 offset:13312
	ds_read_b64_tr_b16 v[158:159], v244 offset:15360
	s_waitcnt lgkmcnt(8)
	v_mfma_f32_32x32x16_bf16 v[32:47], v[228:231], v[172:175], v[32:47]
	v_exp_f32_e32 v71, v71
	ds_read_b64_tr_b16 v[160:161], v244 offset:1536
	ds_read_b64_tr_b16 v[162:163], v244 offset:3584
	s_waitcnt lgkmcnt(8)
	v_mfma_f32_32x32x16_bf16 v[16:31], v[208:211], v[144:147], v[16:31]
	v_exp_f32_e32 v72, v72
	ds_read_b64_tr_b16 v[164:165], v244 offset:5632
	ds_read_b64_tr_b16 v[166:167], v244 offset:7680
	s_waitcnt lgkmcnt(8)
	v_mfma_f32_32x32x16_bf16 v[16:31], v[212:215], v[148:151], v[16:31]
	v_exp_f32_e32 v73, v73
	ds_read_b64_tr_b16 v[168:169], v244 offset:9728
	ds_read_b64_tr_b16 v[170:171], v244 offset:11776
	ds_read_b64_tr_b16 v[172:173], v244 offset:13824
	ds_read_b64_tr_b16 v[174:175], v244 offset:15872
	ds_read_b128 v[144:147], v240 offset:0
	s_waitcnt lgkmcnt(11)
	v_mfma_f32_32x32x16_bf16 v[16:31], v[224:227], v[152:155], v[16:31]
	v_exp_f32_e32 v74, v74
	v_add_u32_e32 v244, 0x4000, v244
	ds_read_b128 v[148:151], v240 offset:12288
	s_waitcnt lgkmcnt(10)
	v_mfma_f32_32x32x16_bf16 v[16:31], v[228:231], v[156:159], v[16:31]
	v_exp_f32_e32 v75, v75
	ds_read_b128 v[152:155], v241 offset:0
	s_waitcnt lgkmcnt(9)
	v_mfma_f32_32x32x16_bf16 v[0:15], v[208:211], v[160:163], v[0:15]
	v_exp_f32_e32 v76, v76
	ds_read_b128 v[156:159], v241 offset:12288
	s_waitcnt lgkmcnt(8)
	v_mfma_f32_32x32x16_bf16 v[0:15], v[212:215], v[164:167], v[0:15]
	v_exp_f32_e32 v77, v77
	ds_read_b128 v[160:163], v242 offset:0
	s_waitcnt lgkmcnt(7)
	v_mfma_f32_32x32x16_bf16 v[0:15], v[224:227], v[168:171], v[0:15]
	v_exp_f32_e32 v78, v78
	ds_read_b128 v[164:167], v242 offset:12288
	s_waitcnt lgkmcnt(6)
	v_mfma_f32_32x32x16_bf16 v[0:15], v[228:231], v[172:175], v[0:15]
	v_exp_f32_e32 v79, v79
.Lattn_loop:
	s_waitcnt vmcnt(5)
	s_barrier
	ds_read_b128 v[168:171], v243 offset:0
	s_waitcnt lgkmcnt(6)
	v_mfma_f32_32x32x16_bf16 v[208:223], v[144:147], v[96:99], 0
	v_exp_f32_e32 v80, v80
	v_add_f32_e32 v245, v64, v245
	v_exp_f32_e32 v81, v81
	ds_read_b128 v[172:175], v243 offset:12288
	s_waitcnt lgkmcnt(6)
	v_mfma_f32_32x32x16_bf16 v[224:239], v[148:151], v[96:99], 0
	v_add_f32_e32 v246, v65, v246
	v_exp_f32_e32 v82, v82
	v_add_f32_e32 v245, v66, v245
	ds_read_b128 v[144:147], v240 offset:128
	s_waitcnt lgkmcnt(6)
	v_mfma_f32_32x32x16_bf16 v[208:223], v[152:155], v[100:103], v[208:223]
	v_exp_f32_e32 v83, v83
	v_add_f32_e32 v246, v67, v246
	s_add_i32 m0, s60, 0x12000
	s_nop 0
	global_load_lds_dwordx4 v182, s[42:43]
	ds_read_b128 v[148:151], v240 offset:12416
	s_waitcnt lgkmcnt(6)
	v_mfma_f32_32x32x16_bf16 v[224:239], v[156:159], v[100:103], v[224:239]
	v_exp_f32_e32 v84, v84
	v_add_f32_e32 v245, v68, v245
	v_exp_f32_e32 v85, v85
	ds_read_b128 v[152:155], v241 offset:128
	s_waitcnt lgkmcnt(6)
	v_mfma_f32_32x32x16_bf16 v[208:223], v[160:163], v[104:107], v[208:223]
	v_add_f32_e32 v246, v69, v246
	v_exp_f32_e32 v86, v86
	v_add_f32_e32 v245, v70, v245
	ds_read_b128 v[156:159], v241 offset:12416
	s_waitcnt lgkmcnt(6)
	v_mfma_f32_32x32x16_bf16 v[224:239], v[164:167], v[104:107], v[224:239]
	v_exp_f32_e32 v87, v87
	v_add_f32_e32 v246, v71, v246
	s_add_i32 m0, s60, 0x12400
	s_nop 0
	global_load_lds_dwordx4 v183, s[42:43]
	ds_read_b128 v[160:163], v242 offset:128
	s_waitcnt lgkmcnt(6)
	v_mfma_f32_32x32x16_bf16 v[208:223], v[168:171], v[108:111], v[208:223]
	v_exp_f32_e32 v88, v88
	v_add_f32_e32 v245, v72, v245
	v_exp_f32_e32 v89, v89
	ds_read_b128 v[164:167], v242 offset:12416
	s_waitcnt lgkmcnt(6)
	v_mfma_f32_32x32x16_bf16 v[224:239], v[172:175], v[108:111], v[224:239]
	v_add_f32_e32 v246, v73, v246
	v_exp_f32_e32 v90, v90
	v_add_f32_e32 v245, v74, v245
	ds_read_b128 v[168:171], v243 offset:128
	s_waitcnt lgkmcnt(6)
	v_mfma_f32_32x32x16_bf16 v[208:223], v[144:147], v[112:115], v[208:223]
	v_exp_f32_e32 v91, v91
	v_add_f32_e32 v246, v75, v246
	s_add_i32 m0, s60, 0x12800
	s_nop 0
	global_load_lds_dwordx4 v184, s[42:43]
	ds_read_b128 v[172:175], v243 offset:12416
	s_waitcnt lgkmcnt(6)
	v_mfma_f32_32x32x16_bf16 v[224:239], v[148:151], v[112:115], v[224:239]
	v_exp_f32_e32 v92, v92
	v_add_f32_e32 v245, v76, v245
	v_exp_f32_e32 v93, v93
	ds_read_b128 v[144:147], v240 offset:256
	s_waitcnt lgkmcnt(6)
	v_mfma_f32_32x32x16_bf16 v[208:223], v[152:155], v[116:119], v[208:223]
	v_add_f32_e32 v246, v77, v246
	v_exp_f32_e32 v94, v94
	v_add_f32_e32 v245, v78, v245
	ds_read_b128 v[148:151], v240 offset:12544
	s_waitcnt lgkmcnt(6)
	v_mfma_f32_32x32x16_bf16 v[224:239], v[156:159], v[116:119], v[224:239]
	v_exp_f32_e32 v95, v95
	v_add_f32_e32 v246, v79, v246
	s_add_i32 m0, s61, 0x0
	s_nop 0
	global_load_lds_dwordx4 v185, s[46:47]
	ds_read_b128 v[152:155], v241 offset:256
	s_waitcnt lgkmcnt(6)
	v_mfma_f32_32x32x16_bf16 v[208:223], v[160:163], v[120:123], v[208:223]
	v_add_f32_e32 v245, v80, v245
	v_add_f32_e32 v246, v81, v246
	v_add_f32_e32 v245, v82, v245
	ds_read_b128 v[156:159], v241 offset:12544
	s_waitcnt lgkmcnt(6)
	v_mfma_f32_32x32x16_bf16 v[224:239], v[164:167], v[120:123], v[224:239]
	v_add_f32_e32 v246, v83, v246
	v_add_f32_e32 v245, v84, v245
	v_add_f32_e32 v246, v85, v246
	ds_read_b128 v[160:163], v242 offset:256
	s_waitcnt lgkmcnt(6)
	v_mfma_f32_32x32x16_bf16 v[208:223], v[168:171], v[124:127], v[208:223]
	v_add_f32_e32 v245, v86, v245
	v_add_f32_e32 v246, v87, v246
	s_add_i32 m0, s61, 0x400
	s_nop 0
	global_load_lds_dwordx4 v186, s[46:47]
	ds_read_b128 v[164:167], v242 offset:12544
	s_waitcnt lgkmcnt(6)
	v_mfma_f32_32x32x16_bf16 v[224:239], v[172:175], v[124:127], v[224:239]
	v_add_f32_e32 v245, v88, v245
	v_add_f32_e32 v246, v89, v246
	v_add_f32_e32 v245, v90, v245
	ds_read_b128 v[168:171], v243 offset:256
	s_waitcnt lgkmcnt(6)
	v_mfma_f32_32x32x16_bf16 v[208:223], v[144:147], v[128:131], v[208:223]
	v_add_f32_e32 v246, v91, v246
	v_add_f32_e32 v245, v92, v245
	v_add_f32_e32 v246, v93, v246
	ds_read_b128 v[172:175], v243 offset:12544
	s_waitcnt lgkmcnt(6)
	v_mfma_f32_32x32x16_bf16 v[224:239], v[148:151], v[128:131], v[224:239]
	v_add_f32_e32 v245, v94, v245
	v_add_f32_e32 v246, v95, v246
	s_add_u32 s42, s42, 0x6000
	s_addc_u32 s43, s43, 0
	v_add_u32_e32 v240, 0x9010, v240
	ds_read_b64_tr_b16 v[144:145], v244 offset:0
	ds_read_b64_tr_b16 v[146:147], v244 offset:2048
	s_waitcnt lgkmcnt(7)
	v_mfma_f32_32x32x16_bf16 v[208:223], v[152:155], v[132:135], v[208:223]
	v_cvt_pk_bf16_f32 v64, v64, v65
	v_cvt_pk_bf16_f32 v65, v66, v67
	v_cvt_pk_bf16_f32 v66, v68, v69
	v_add_u32_e32 v241, 0x9010, v241
	ds_read_b64_tr_b16 v[148:149], v244 offset:4096
	ds_read_b64_tr_b16 v[150:151], v244 offset:6144
	s_waitcnt lgkmcnt(8)
	v_mfma_f32_32x32x16_bf16 v[224:239], v[156:159], v[132:135], v[224:239]
	v_cvt_pk_bf16_f32 v67, v70, v71
	v_cvt_pk_bf16_f32 v68, v72, v73
	v_cvt_pk_bf16_f32 v69, v74, v75
	v_add_u32_e32 v242, 0x9010, v242
	ds_read_b64_tr_b16 v[152:153], v244 offset:8192
	ds_read_b64_tr_b16 v[154:155], v244 offset:10240
	s_waitcnt lgkmcnt(9)
	v_mfma_f32_32x32x16_bf16 v[208:223], v[160:163], v[136:139], v[208:223]
	v_cvt_pk_bf16_f32 v70, v76, v77
	v_cvt_pk_bf16_f32 v71, v78, v79
	s_add_u32 s46, s46, 0x40000
	s_addc_u32 s47, s47, 0
	v_add_u32_e32 v243, 0x9010, v243
	ds_read_b64_tr_b16 v[156:157], v244 offset:12288
	ds_read_b64_tr_b16 v[158:159], v244 offset:14336
	s_waitcnt lgkmcnt(10)
	v_mfma_f32_32x32x16_bf16 v[224:239], v[164:167], v[136:139], v[224:239]
	v_cvt_pk_bf16_f32 v80, v80, v81
	v_cvt_pk_bf16_f32 v81, v82, v83
	v_cvt_pk_bf16_f32 v82, v84, v85
	ds_read_b64_tr_b16 v[160:161], v244 offset:512
	ds_read_b64_tr_b16 v[162:163], v244 offset:2560
	s_waitcnt lgkmcnt(11)
	v_mfma_f32_32x32x16_bf16 v[208:223], v[168:171], v[140:143], v[208:223]
	v_cvt_pk_bf16_f32 v83, v86, v87
	v_cvt_pk_bf16_f32 v84, v88, v89
	v_cvt_pk_bf16_f32 v85, v90, v91
	ds_read_b64_tr_b16 v[164:165], v244 offset:4608
	ds_read_b64_tr_b16 v[166:167], v244 offset:6656
	s_waitcnt lgkmcnt(12)
	v_mfma_f32_32x32x16_bf16 v[224:239], v[172:175], v[140:143], v[224:239]
	v_cvt_pk_bf16_f32 v86, v92, v93
	v_cvt_pk_bf16_f32 v87, v94, v95
	s_waitcnt lgkmcnt(10)
	v_mfma_f32_32x32x16_bf16 v[48:63], v[64:67], v[144:147], v[48:63]
	s_waitcnt lgkmcnt(8)
	v_mfma_f32_32x32x16_bf16 v[48:63], v[68:71], v[148:151], v[48:63]
	ds_read_b64_tr_b16 v[168:169], v244 offset:8704
	ds_read_b64_tr_b16 v[170:171], v244 offset:10752
	s_waitcnt lgkmcnt(8)
	v_mfma_f32_32x32x16_bf16 v[48:63], v[80:83], v[152:155], v[48:63]
	v_exp_f32_e32 v208, v208
	v_exp_f32_e32 v209, v209
	ds_read_b64_tr_b16 v[172:173], v244 offset:12800
	ds_read_b64_tr_b16 v[174:175], v244 offset:14848
	s_waitcnt lgkmcnt(8)
	v_mfma_f32_32x32x16_bf16 v[48:63], v[84:87], v[156:159], v[48:63]
	v_exp_f32_e32 v210, v210
	v_exp_f32_e32 v211, v211
	ds_read_b64_tr_b16 v[144:145], v244 offset:1024
	ds_read_b64_tr_b16 v[146:147], v244 offset:3072
	s_waitcnt lgkmcnt(8)
	v_mfma_f32_32x32x16_bf16 v[32:47], v[64:67], v[160:163], v[32:47]
	v_exp_f32_e32 v212, v212
	ds_read_b64_tr_b16 v[148:149], v244 offset:5120
	ds_read_b64_tr_b16 v[150:151], v244 offset:7168
	s_waitcnt lgkmcnt(8)
	v_mfma_f32_32x32x16_bf16 v[32:47], v[68:71], v[164:167], v[32:47]
	v_exp_f32_e32 v213, v213
	ds_read_b64_tr_b16 v[152:153], v244 offset:9216
	ds_read_b64_tr_b16 v[154:155], v244 offset:11264
	s_waitcnt lgkmcnt(8)
	v_mfma_f32_32x32x16_bf16 v[32:47], v[80:83], v[168:171], v[32:47]
	v_exp_f32_e32 v214, v214
	ds_read_b64_tr_b16 v[156:157], v244 offset:13312
	ds_read_b64_tr_b16 v[158:159], v244 offset:15360
	s_waitcnt lgkmcnt(8)
	v_mfma_f32_32x32x16_bf16 v[32:47], v[84:87], v[172:175], v[32:47]
	v_exp_f32_e32 v215, v215
	ds_read_b64_tr_b16 v[160:161], v244 offset:1536
	ds_read_b64_tr_b16 v[162:163], v244 offset:3584
	s_waitcnt lgkmcnt(8)
	v_mfma_f32_32x32x16_bf16 v[16:31], v[64:67], v[144:147], v[16:31]
	v_exp_f32_e32 v216, v216
	ds_read_b64_tr_b16 v[164:165], v244 offset:5632
	ds_read_b64_tr_b16 v[166:167], v244 offset:7680
	s_waitcnt lgkmcnt(8)
	v_mfma_f32_32x32x16_bf16 v[16:31], v[68:71], v[148:151], v[16:31]
	v_exp_f32_e32 v217, v217
	ds_read_b64_tr_b16 v[168:169], v244 offset:9728
	ds_read_b64_tr_b16 v[170:171], v244 offset:11776
	ds_read_b64_tr_b16 v[172:173], v244 offset:13824
	ds_read_b64_tr_b16 v[174:175], v244 offset:15872
	ds_read_b128 v[144:147], v240 offset:0
	s_waitcnt lgkmcnt(11)
	v_mfma_f32_32x32x16_bf16 v[16:31], v[80:83], v[152:155], v[16:31]
	v_exp_f32_e32 v218, v218
	v_add_u32_e32 v244, 0x4000, v244
	ds_read_b128 v[148:151], v240 offset:12288
	s_waitcnt lgkmcnt(10)
	v_mfma_f32_32x32x16_bf16 v[16:31], v[84:87], v[156:159], v[16:31]
	v_exp_f32_e32 v219, v219
	ds_read_b128 v[152:155], v241 offset:0
	s_waitcnt lgkmcnt(9)
	v_mfma_f32_32x32x16_bf16 v[0:15], v[64:67], v[160:163], v[0:15]
	v_exp_f32_e32 v220, v220
	ds_read_b128 v[156:159], v241 offset:12288
	s_waitcnt lgkmcnt(8)
	v_mfma_f32_32x32x16_bf16 v[0:15], v[68:71], v[164:167], v[0:15]
	v_exp_f32_e32 v221, v221
	ds_read_b128 v[160:163], v242 offset:0
	s_waitcnt lgkmcnt(7)
	v_mfma_f32_32x32x16_bf16 v[0:15], v[80:83], v[168:171], v[0:15]
	v_exp_f32_e32 v222, v222
	ds_read_b128 v[164:167], v242 offset:12288
	s_waitcnt lgkmcnt(6)
	v_mfma_f32_32x32x16_bf16 v[0:15], v[84:87], v[172:175], v[0:15]
	v_exp_f32_e32 v223, v223
	s_waitcnt vmcnt(5)
	s_barrier
	ds_read_b128 v[168:171], v243 offset:0
	s_waitcnt lgkmcnt(6)
	v_mfma_f32_32x32x16_bf16 v[64:79], v[144:147], v[96:99], 0
	v_exp_f32_e32 v224, v224
	v_add_f32_e32 v245, v208, v245
	v_exp_f32_e32 v225, v225
	ds_read_b128 v[172:175], v243 offset:12288
	s_waitcnt lgkmcnt(6)
	v_mfma_f32_32x32x16_bf16 v[80:95], v[148:151], v[96:99], 0
	v_add_f32_e32 v246, v209, v246
	v_exp_f32_e32 v226, v226
	v_add_f32_e32 v245, v210, v245
	ds_read_b128 v[144:147], v240 offset:128
	s_waitcnt lgkmcnt(6)
	v_mfma_f32_32x32x16_bf16 v[64:79], v[152:155], v[100:103], v[64:79]
	v_exp_f32_e32 v227, v227
	v_add_f32_e32 v246, v211, v246
	s_add_i32 m0, s60, 0x18000
	s_nop 0
	global_load_lds_dwordx4 v182, s[42:43]
	ds_read_b128 v[148:151], v240 offset:12416
	s_waitcnt lgkmcnt(6)
	v_mfma_f32_32x32x16_bf16 v[80:95], v[156:159], v[100:103], v[80:95]
	v_exp_f32_e32 v228, v228
	v_add_f32_e32 v245, v212, v245
	v_exp_f32_e32 v229, v229
	ds_read_b128 v[152:155], v241 offset:128
	s_waitcnt lgkmcnt(6)
	v_mfma_f32_32x32x16_bf16 v[64:79], v[160:163], v[104:107], v[64:79]
	v_add_f32_e32 v246, v213, v246
	v_exp_f32_e32 v230, v230
	v_add_f32_e32 v245, v214, v245
	ds_read_b128 v[156:159], v241 offset:12416
	s_waitcnt lgkmcnt(6)
	v_mfma_f32_32x32x16_bf16 v[80:95], v[164:167], v[104:107], v[80:95]
	v_exp_f32_e32 v231, v231
	v_add_f32_e32 v246, v215, v246
	s_add_i32 m0, s60, 0x18400
	s_nop 0
	global_load_lds_dwordx4 v183, s[42:43]
	ds_read_b128 v[160:163], v242 offset:128
	s_waitcnt lgkmcnt(6)
	v_mfma_f32_32x32x16_bf16 v[64:79], v[168:171], v[108:111], v[64:79]
	v_exp_f32_e32 v232, v232
	v_add_f32_e32 v245, v216, v245
	v_exp_f32_e32 v233, v233
	ds_read_b128 v[164:167], v242 offset:12416
	s_waitcnt lgkmcnt(6)
	v_mfma_f32_32x32x16_bf16 v[80:95], v[172:175], v[108:111], v[80:95]
	v_add_f32_e32 v246, v217, v246
	v_exp_f32_e32 v234, v234
	v_add_f32_e32 v245, v218, v245
	ds_read_b128 v[168:171], v243 offset:128
	s_waitcnt lgkmcnt(6)
	v_mfma_f32_32x32x16_bf16 v[64:79], v[144:147], v[112:115], v[64:79]
	v_exp_f32_e32 v235, v235
	v_add_f32_e32 v246, v219, v246
	s_add_i32 m0, s60, 0x18800
	s_nop 0
	global_load_lds_dwordx4 v184, s[42:43]
	ds_read_b128 v[172:175], v243 offset:12416
	s_waitcnt lgkmcnt(6)
	v_mfma_f32_32x32x16_bf16 v[80:95], v[148:151], v[112:115], v[80:95]
	v_exp_f32_e32 v236, v236
	v_add_f32_e32 v245, v220, v245
	v_exp_f32_e32 v237, v237
	ds_read_b128 v[144:147], v240 offset:256
	s_waitcnt lgkmcnt(6)
	v_mfma_f32_32x32x16_bf16 v[64:79], v[152:155], v[116:119], v[64:79]
	v_add_f32_e32 v246, v221, v246
	v_exp_f32_e32 v238, v238
	v_add_f32_e32 v245, v222, v245
	ds_read_b128 v[148:151], v240 offset:12544
	s_waitcnt lgkmcnt(6)
	v_mfma_f32_32x32x16_bf16 v[80:95], v[156:159], v[116:119], v[80:95]
	v_exp_f32_e32 v239, v239
	v_add_f32_e32 v246, v223, v246
	s_add_i32 m0, s61, 0x4000
	s_nop 0
	global_load_lds_dwordx4 v185, s[46:47]
	ds_read_b128 v[152:155], v241 offset:256
	s_waitcnt lgkmcnt(6)
	v_mfma_f32_32x32x16_bf16 v[64:79], v[160:163], v[120:123], v[64:79]
	v_add_f32_e32 v245, v224, v245
	v_add_f32_e32 v246, v225, v246
	v_add_f32_e32 v245, v226, v245
	ds_read_b128 v[156:159], v241 offset:12544
	s_waitcnt lgkmcnt(6)
	v_mfma_f32_32x32x16_bf16 v[80:95], v[164:167], v[120:123], v[80:95]
	v_add_f32_e32 v246, v227, v246
	v_add_f32_e32 v245, v228, v245
	v_add_f32_e32 v246, v229, v246
	ds_read_b128 v[160:163], v242 offset:256
	s_waitcnt lgkmcnt(6)
	v_mfma_f32_32x32x16_bf16 v[64:79], v[168:171], v[124:127], v[64:79]
	v_add_f32_e32 v245, v230, v245
	v_add_f32_e32 v246, v231, v246
	s_add_i32 m0, s61, 0x4400
	s_nop 0
	global_load_lds_dwordx4 v186, s[46:47]
	ds_read_b128 v[164:167], v242 offset:12544
	s_waitcnt lgkmcnt(6)
	v_mfma_f32_32x32x16_bf16 v[80:95], v[172:175], v[124:127], v[80:95]
	v_add_f32_e32 v245, v232, v245
	v_add_f32_e32 v246, v233, v246
	v_add_f32_e32 v245, v234, v245
	ds_read_b128 v[168:171], v243 offset:256
	s_waitcnt lgkmcnt(6)
	v_mfma_f32_32x32x16_bf16 v[64:79], v[144:147], v[128:131], v[64:79]
	v_add_f32_e32 v246, v235, v246
	v_add_f32_e32 v245, v236, v245
	v_add_f32_e32 v246, v237, v246
	ds_read_b128 v[172:175], v243 offset:12544
	s_waitcnt lgkmcnt(6)
	v_mfma_f32_32x32x16_bf16 v[80:95], v[148:151], v[128:131], v[80:95]
	v_add_f32_e32 v245, v238, v245
	v_add_f32_e32 v246, v239, v246
	s_add_u32 s42, s42, 0x6000
	s_addc_u32 s43, s43, 0
	v_add_u32_e32 v240, 0xfffeaff0, v240
	ds_read_b64_tr_b16 v[144:145], v244 offset:0
	ds_read_b64_tr_b16 v[146:147], v244 offset:2048
	s_waitcnt lgkmcnt(7)
	v_mfma_f32_32x32x16_bf16 v[64:79], v[152:155], v[132:135], v[64:79]
	v_cvt_pk_bf16_f32 v208, v208, v209
	v_cvt_pk_bf16_f32 v209, v210, v211
	v_cvt_pk_bf16_f32 v210, v212, v213
	v_add_u32_e32 v241, 0xfffeaff0, v241
	ds_read_b64_tr_b16 v[148:149], v244 offset:4096
	ds_read_b64_tr_b16 v[150:151], v244 offset:6144
	s_waitcnt lgkmcnt(8)
	v_mfma_f32_32x32x16_bf16 v[80:95], v[156:159], v[132:135], v[80:95]
	v_cvt_pk_bf16_f32 v211, v214, v215
	v_cvt_pk_bf16_f32 v212, v216, v217
	v_cvt_pk_bf16_f32 v213, v218, v219
	v_add_u32_e32 v242, 0xfffeaff0, v242
	ds_read_b64_tr_b16 v[152:153], v244 offset:8192
	ds_read_b64_tr_b16 v[154:155], v244 offset:10240
	s_waitcnt lgkmcnt(9)
	v_mfma_f32_32x32x16_bf16 v[64:79], v[160:163], v[136:139], v[64:79]
	v_cvt_pk_bf16_f32 v214, v220, v221
	v_cvt_pk_bf16_f32 v215, v222, v223
	s_add_u32 s46, s46, 0x40000
	s_addc_u32 s47, s47, 0
	v_add_u32_e32 v243, 0xfffeaff0, v243
	ds_read_b64_tr_b16 v[156:157], v244 offset:12288
	ds_read_b64_tr_b16 v[158:159], v244 offset:14336
	s_waitcnt lgkmcnt(10)
	v_mfma_f32_32x32x16_bf16 v[80:95], v[164:167], v[136:139], v[80:95]
	v_cvt_pk_bf16_f32 v224, v224, v225
	v_cvt_pk_bf16_f32 v225, v226, v227
	v_cvt_pk_bf16_f32 v226, v228, v229
	ds_read_b64_tr_b16 v[160:161], v244 offset:512
	ds_read_b64_tr_b16 v[162:163], v244 offset:2560
	s_waitcnt lgkmcnt(11)
	v_mfma_f32_32x32x16_bf16 v[64:79], v[168:171], v[140:143], v[64:79]
	v_cvt_pk_bf16_f32 v227, v230, v231
	v_cvt_pk_bf16_f32 v228, v232, v233
	v_cvt_pk_bf16_f32 v229, v234, v235
	ds_read_b64_tr_b16 v[164:165], v244 offset:4608
	ds_read_b64_tr_b16 v[166:167], v244 offset:6656
	s_waitcnt lgkmcnt(12)
	v_mfma_f32_32x32x16_bf16 v[80:95], v[172:175], v[140:143], v[80:95]
	v_cvt_pk_bf16_f32 v230, v236, v237
	v_cvt_pk_bf16_f32 v231, v238, v239
	s_waitcnt lgkmcnt(10)
	v_mfma_f32_32x32x16_bf16 v[48:63], v[208:211], v[144:147], v[48:63]
	s_waitcnt lgkmcnt(8)
	v_mfma_f32_32x32x16_bf16 v[48:63], v[212:215], v[148:151], v[48:63]
	ds_read_b64_tr_b16 v[168:169], v244 offset:8704
	ds_read_b64_tr_b16 v[170:171], v244 offset:10752
	s_waitcnt lgkmcnt(8)
	v_mfma_f32_32x32x16_bf16 v[48:63], v[224:227], v[152:155], v[48:63]
	v_exp_f32_e32 v64, v64
	v_exp_f32_e32 v65, v65
	ds_read_b64_tr_b16 v[172:173], v244 offset:12800
	ds_read_b64_tr_b16 v[174:175], v244 offset:14848
	s_waitcnt lgkmcnt(8)
	v_mfma_f32_32x32x16_bf16 v[48:63], v[228:231], v[156:159], v[48:63]
	v_exp_f32_e32 v66, v66
	v_exp_f32_e32 v67, v67
	ds_read_b64_tr_b16 v[144:145], v244 offset:1024
	ds_read_b64_tr_b16 v[146:147], v244 offset:3072
	s_waitcnt lgkmcnt(8)
	v_mfma_f32_32x32x16_bf16 v[32:47], v[208:211], v[160:163], v[32:47]
	v_exp_f32_e32 v68, v68
	ds_read_b64_tr_b16 v[148:149], v244 offset:5120
	ds_read_b64_tr_b16 v[150:151], v244 offset:7168
	s_waitcnt lgkmcnt(8)
	v_mfma_f32_32x32x16_bf16 v[32:47], v[212:215], v[164:167], v[32:47]
	v_exp_f32_e32 v69, v69
	ds_read_b64_tr_b16 v[152:153], v244 offset:9216
	ds_read_b64_tr_b16 v[154:155], v244 offset:11264
	s_waitcnt lgkmcnt(8)
	v_mfma_f32_32x32x16_bf16 v[32:47], v[224:227], v[168:171], v[32:47]
	v_exp_f32_e32 v70, v70
	ds_read_b64_tr_b16 v[156:157], v244 offset:13312
	ds_read_b64_tr_b16 v[158:159], v244 offset:15360
	s_waitcnt lgkmcnt(8)
	v_mfma_f32_32x32x16_bf16 v[32:47], v[228:231], v[172:175], v[32:47]
	v_exp_f32_e32 v71, v71
	ds_read_b64_tr_b16 v[160:161], v244 offset:1536
	ds_read_b64_tr_b16 v[162:163], v244 offset:3584
	s_waitcnt lgkmcnt(8)
	v_mfma_f32_32x32x16_bf16 v[16:31], v[208:211], v[144:147], v[16:31]
	v_exp_f32_e32 v72, v72
	ds_read_b64_tr_b16 v[164:165], v244 offset:5632
	ds_read_b64_tr_b16 v[166:167], v244 offset:7680
	s_waitcnt lgkmcnt(8)
	v_mfma_f32_32x32x16_bf16 v[16:31], v[212:215], v[148:151], v[16:31]
	v_exp_f32_e32 v73, v73
	ds_read_b64_tr_b16 v[168:169], v244 offset:9728
	ds_read_b64_tr_b16 v[170:171], v244 offset:11776
	ds_read_b64_tr_b16 v[172:173], v244 offset:13824
	ds_read_b64_tr_b16 v[174:175], v244 offset:15872
	ds_read_b128 v[144:147], v240 offset:0
	s_waitcnt lgkmcnt(11)
	v_mfma_f32_32x32x16_bf16 v[16:31], v[224:227], v[152:155], v[16:31]
	v_exp_f32_e32 v74, v74
	v_add_u32_e32 v244, 0xffff8000, v244
	ds_read_b128 v[148:151], v240 offset:12288
	s_waitcnt lgkmcnt(10)
	v_mfma_f32_32x32x16_bf16 v[16:31], v[228:231], v[156:159], v[16:31]
	v_exp_f32_e32 v75, v75
	ds_read_b128 v[152:155], v241 offset:0
	s_waitcnt lgkmcnt(9)
	v_mfma_f32_32x32x16_bf16 v[0:15], v[208:211], v[160:163], v[0:15]
	v_exp_f32_e32 v76, v76
	ds_read_b128 v[156:159], v241 offset:12288
	s_waitcnt lgkmcnt(8)
	v_mfma_f32_32x32x16_bf16 v[0:15], v[212:215], v[164:167], v[0:15]
	v_exp_f32_e32 v77, v77
	ds_read_b128 v[160:163], v242 offset:0
	s_waitcnt lgkmcnt(7)
	v_mfma_f32_32x32x16_bf16 v[0:15], v[224:227], v[168:171], v[0:15]
	v_exp_f32_e32 v78, v78
	ds_read_b128 v[164:167], v242 offset:12288
	s_waitcnt lgkmcnt(6)
	v_mfma_f32_32x32x16_bf16 v[0:15], v[228:231], v[172:175], v[0:15]
	v_exp_f32_e32 v79, v79
	s_waitcnt vmcnt(5)
	s_barrier
	ds_read_b128 v[168:171], v243 offset:0
	s_waitcnt lgkmcnt(6)
	v_mfma_f32_32x32x16_bf16 v[208:223], v[144:147], v[96:99], 0
	v_exp_f32_e32 v80, v80
	v_add_f32_e32 v245, v64, v245
	v_exp_f32_e32 v81, v81
	ds_read_b128 v[172:175], v243 offset:12288
	s_waitcnt lgkmcnt(6)
	v_mfma_f32_32x32x16_bf16 v[224:239], v[148:151], v[96:99], 0
	v_add_f32_e32 v246, v65, v246
	v_exp_f32_e32 v82, v82
	v_add_f32_e32 v245, v66, v245
	ds_read_b128 v[144:147], v240 offset:128
	s_waitcnt lgkmcnt(6)
	v_mfma_f32_32x32x16_bf16 v[208:223], v[152:155], v[100:103], v[208:223]
	v_exp_f32_e32 v83, v83
	v_add_f32_e32 v246, v67, v246
	s_add_i32 m0, s60, 0x21010
	s_nop 0
	global_load_lds_dwordx4 v182, s[42:43]
	ds_read_b128 v[148:151], v240 offset:12416
	s_waitcnt lgkmcnt(6)
	v_mfma_f32_32x32x16_bf16 v[224:239], v[156:159], v[100:103], v[224:239]
	v_exp_f32_e32 v84, v84
	v_add_f32_e32 v245, v68, v245
	v_exp_f32_e32 v85, v85
	ds_read_b128 v[152:155], v241 offset:128
	s_waitcnt lgkmcnt(6)
	v_mfma_f32_32x32x16_bf16 v[208:223], v[160:163], v[104:107], v[208:223]
	v_add_f32_e32 v246, v69, v246
	v_exp_f32_e32 v86, v86
	v_add_f32_e32 v245, v70, v245
	ds_read_b128 v[156:159], v241 offset:12416
	s_waitcnt lgkmcnt(6)
	v_mfma_f32_32x32x16_bf16 v[224:239], v[164:167], v[104:107], v[224:239]
	v_exp_f32_e32 v87, v87
	v_add_f32_e32 v246, v71, v246
	s_add_i32 m0, s60, 0x21410
	s_nop 0
	global_load_lds_dwordx4 v183, s[42:43]
	ds_read_b128 v[160:163], v242 offset:128
	s_waitcnt lgkmcnt(6)
	v_mfma_f32_32x32x16_bf16 v[208:223], v[168:171], v[108:111], v[208:223]
	v_exp_f32_e32 v88, v88
	v_add_f32_e32 v245, v72, v245
	v_exp_f32_e32 v89, v89
	ds_read_b128 v[164:167], v242 offset:12416
	s_waitcnt lgkmcnt(6)
	v_mfma_f32_32x32x16_bf16 v[224:239], v[172:175], v[108:111], v[224:239]
	v_add_f32_e32 v246, v73, v246
	v_exp_f32_e32 v90, v90
	v_add_f32_e32 v245, v74, v245
	ds_read_b128 v[168:171], v243 offset:128
	s_waitcnt lgkmcnt(6)
	v_mfma_f32_32x32x16_bf16 v[208:223], v[144:147], v[112:115], v[208:223]
	v_exp_f32_e32 v91, v91
	v_add_f32_e32 v246, v75, v246
	s_add_i32 m0, s60, 0x21810
	s_nop 0
	global_load_lds_dwordx4 v184, s[42:43]
	ds_read_b128 v[172:175], v243 offset:12416
	s_waitcnt lgkmcnt(6)
	v_mfma_f32_32x32x16_bf16 v[224:239], v[148:151], v[112:115], v[224:239]
	v_exp_f32_e32 v92, v92
	v_add_f32_e32 v245, v76, v245
	v_exp_f32_e32 v93, v93
	ds_read_b128 v[144:147], v240 offset:256
	s_waitcnt lgkmcnt(6)
	v_mfma_f32_32x32x16_bf16 v[208:223], v[152:155], v[116:119], v[208:223]
	v_add_f32_e32 v246, v77, v246
	v_exp_f32_e32 v94, v94
	v_add_f32_e32 v245, v78, v245
	ds_read_b128 v[148:151], v240 offset:12544
	s_waitcnt lgkmcnt(6)
	v_mfma_f32_32x32x16_bf16 v[224:239], v[156:159], v[116:119], v[224:239]
	v_exp_f32_e32 v95, v95
	v_add_f32_e32 v246, v79, v246
	s_add_i32 m0, s61, 0x8000
	s_nop 0
	global_load_lds_dwordx4 v185, s[46:47]
	ds_read_b128 v[152:155], v241 offset:256
	s_waitcnt lgkmcnt(6)
	v_mfma_f32_32x32x16_bf16 v[208:223], v[160:163], v[120:123], v[208:223]
	v_add_f32_e32 v245, v80, v245
	v_add_f32_e32 v246, v81, v246
	v_add_f32_e32 v245, v82, v245
	ds_read_b128 v[156:159], v241 offset:12544
	s_waitcnt lgkmcnt(6)
	v_mfma_f32_32x32x16_bf16 v[224:239], v[164:167], v[120:123], v[224:239]
	v_add_f32_e32 v246, v83, v246
	v_add_f32_e32 v245, v84, v245
	v_add_f32_e32 v246, v85, v246
	ds_read_b128 v[160:163], v242 offset:256
	s_waitcnt lgkmcnt(6)
	v_mfma_f32_32x32x16_bf16 v[208:223], v[168:171], v[124:127], v[208:223]
	v_add_f32_e32 v245, v86, v245
	v_add_f32_e32 v246, v87, v246
	s_add_i32 m0, s61, 0x8400
	s_nop 0
	global_load_lds_dwordx4 v186, s[46:47]
	ds_read_b128 v[164:167], v242 offset:12544
	s_waitcnt lgkmcnt(6)
	v_mfma_f32_32x32x16_bf16 v[224:239], v[172:175], v[124:127], v[224:239]
	v_add_f32_e32 v245, v88, v245
	v_add_f32_e32 v246, v89, v246
	v_add_f32_e32 v245, v90, v245
	ds_read_b128 v[168:171], v243 offset:256
	s_waitcnt lgkmcnt(6)
	v_mfma_f32_32x32x16_bf16 v[208:223], v[144:147], v[128:131], v[208:223]
	v_add_f32_e32 v246, v91, v246
	v_add_f32_e32 v245, v92, v245
	v_add_f32_e32 v246, v93, v246
	ds_read_b128 v[172:175], v243 offset:12544
	s_waitcnt lgkmcnt(6)
	v_mfma_f32_32x32x16_bf16 v[224:239], v[148:151], v[128:131], v[224:239]
	v_add_f32_e32 v245, v94, v245
	v_add_f32_e32 v246, v95, v246
	s_add_u32 s42, s42, 0x6000
	s_addc_u32 s43, s43, 0
	v_add_u32_e32 v240, 0x6000, v240
	ds_read_b64_tr_b16 v[144:145], v244 offset:0
	ds_read_b64_tr_b16 v[146:147], v244 offset:2048
	s_waitcnt lgkmcnt(7)
	v_mfma_f32_32x32x16_bf16 v[208:223], v[152:155], v[132:135], v[208:223]
	v_cvt_pk_bf16_f32 v64, v64, v65
	v_cvt_pk_bf16_f32 v65, v66, v67
	v_cvt_pk_bf16_f32 v66, v68, v69
	v_add_u32_e32 v241, 0x6000, v241
	ds_read_b64_tr_b16 v[148:149], v244 offset:4096
	ds_read_b64_tr_b16 v[150:151], v244 offset:6144
	s_waitcnt lgkmcnt(8)
	v_mfma_f32_32x32x16_bf16 v[224:239], v[156:159], v[132:135], v[224:239]
	v_cvt_pk_bf16_f32 v67, v70, v71
	v_cvt_pk_bf16_f32 v68, v72, v73
	v_cvt_pk_bf16_f32 v69, v74, v75
	v_add_u32_e32 v242, 0x6000, v242
	ds_read_b64_tr_b16 v[152:153], v244 offset:8192
	ds_read_b64_tr_b16 v[154:155], v244 offset:10240
	s_waitcnt lgkmcnt(9)
	v_mfma_f32_32x32x16_bf16 v[208:223], v[160:163], v[136:139], v[208:223]
	v_cvt_pk_bf16_f32 v70, v76, v77
	v_cvt_pk_bf16_f32 v71, v78, v79
	s_add_u32 s46, s46, 0x40000
	s_addc_u32 s47, s47, 0
	v_add_u32_e32 v243, 0x6000, v243
	ds_read_b64_tr_b16 v[156:157], v244 offset:12288
	ds_read_b64_tr_b16 v[158:159], v244 offset:14336
	s_waitcnt lgkmcnt(10)
	v_mfma_f32_32x32x16_bf16 v[224:239], v[164:167], v[136:139], v[224:239]
	v_cvt_pk_bf16_f32 v80, v80, v81
	v_cvt_pk_bf16_f32 v81, v82, v83
	v_cvt_pk_bf16_f32 v82, v84, v85
	ds_read_b64_tr_b16 v[160:161], v244 offset:512
	ds_read_b64_tr_b16 v[162:163], v244 offset:2560
	s_waitcnt lgkmcnt(11)
	v_mfma_f32_32x32x16_bf16 v[208:223], v[168:171], v[140:143], v[208:223]
	v_cvt_pk_bf16_f32 v83, v86, v87
	v_cvt_pk_bf16_f32 v84, v88, v89
	v_cvt_pk_bf16_f32 v85, v90, v91
	ds_read_b64_tr_b16 v[164:165], v244 offset:4608
	ds_read_b64_tr_b16 v[166:167], v244 offset:6656
	s_waitcnt lgkmcnt(12)
	v_mfma_f32_32x32x16_bf16 v[224:239], v[172:175], v[140:143], v[224:239]
	v_cvt_pk_bf16_f32 v86, v92, v93
	v_cvt_pk_bf16_f32 v87, v94, v95
	s_waitcnt lgkmcnt(10)
	v_mfma_f32_32x32x16_bf16 v[48:63], v[64:67], v[144:147], v[48:63]
	s_waitcnt lgkmcnt(8)
	v_mfma_f32_32x32x16_bf16 v[48:63], v[68:71], v[148:151], v[48:63]
	ds_read_b64_tr_b16 v[168:169], v244 offset:8704
	ds_read_b64_tr_b16 v[170:171], v244 offset:10752
	s_waitcnt lgkmcnt(8)
	v_mfma_f32_32x32x16_bf16 v[48:63], v[80:83], v[152:155], v[48:63]
	v_exp_f32_e32 v208, v208
	v_exp_f32_e32 v209, v209
	ds_read_b64_tr_b16 v[172:173], v244 offset:12800
	ds_read_b64_tr_b16 v[174:175], v244 offset:14848
	s_waitcnt lgkmcnt(8)
	v_mfma_f32_32x32x16_bf16 v[48:63], v[84:87], v[156:159], v[48:63]
	v_exp_f32_e32 v210, v210
	v_exp_f32_e32 v211, v211
	ds_read_b64_tr_b16 v[144:145], v244 offset:1024
	ds_read_b64_tr_b16 v[146:147], v244 offset:3072
	s_waitcnt lgkmcnt(8)
	v_mfma_f32_32x32x16_bf16 v[32:47], v[64:67], v[160:163], v[32:47]
	v_exp_f32_e32 v212, v212
	ds_read_b64_tr_b16 v[148:149], v244 offset:5120
	ds_read_b64_tr_b16 v[150:151], v244 offset:7168
	s_waitcnt lgkmcnt(8)
	v_mfma_f32_32x32x16_bf16 v[32:47], v[68:71], v[164:167], v[32:47]
	v_exp_f32_e32 v213, v213
	ds_read_b64_tr_b16 v[152:153], v244 offset:9216
	ds_read_b64_tr_b16 v[154:155], v244 offset:11264
	s_waitcnt lgkmcnt(8)
	v_mfma_f32_32x32x16_bf16 v[32:47], v[80:83], v[168:171], v[32:47]
	v_exp_f32_e32 v214, v214
	ds_read_b64_tr_b16 v[156:157], v244 offset:13312
	ds_read_b64_tr_b16 v[158:159], v244 offset:15360
	s_waitcnt lgkmcnt(8)
	v_mfma_f32_32x32x16_bf16 v[32:47], v[84:87], v[172:175], v[32:47]
	v_exp_f32_e32 v215, v215
	ds_read_b64_tr_b16 v[160:161], v244 offset:1536
	ds_read_b64_tr_b16 v[162:163], v244 offset:3584
	s_waitcnt lgkmcnt(8)
	v_mfma_f32_32x32x16_bf16 v[16:31], v[64:67], v[144:147], v[16:31]
	v_exp_f32_e32 v216, v216
	ds_read_b64_tr_b16 v[164:165], v244 offset:5632
	ds_read_b64_tr_b16 v[166:167], v244 offset:7680
	s_waitcnt lgkmcnt(8)
	v_mfma_f32_32x32x16_bf16 v[16:31], v[68:71], v[148:151], v[16:31]
	v_exp_f32_e32 v217, v217
	ds_read_b64_tr_b16 v[168:169], v244 offset:9728
	ds_read_b64_tr_b16 v[170:171], v244 offset:11776
	ds_read_b64_tr_b16 v[172:173], v244 offset:13824
	ds_read_b64_tr_b16 v[174:175], v244 offset:15872
	ds_read_b128 v[144:147], v240 offset:0
	s_waitcnt lgkmcnt(11)
	v_mfma_f32_32x32x16_bf16 v[16:31], v[80:83], v[152:155], v[16:31]
	v_exp_f32_e32 v218, v218
	v_add_u32_e32 v244, 0x4000, v244
	ds_read_b128 v[148:151], v240 offset:12288
	s_waitcnt lgkmcnt(10)
	v_mfma_f32_32x32x16_bf16 v[16:31], v[84:87], v[156:159], v[16:31]
	v_exp_f32_e32 v219, v219
	ds_read_b128 v[152:155], v241 offset:0
	s_waitcnt lgkmcnt(9)
	v_mfma_f32_32x32x16_bf16 v[0:15], v[64:67], v[160:163], v[0:15]
	v_exp_f32_e32 v220, v220
	ds_read_b128 v[156:159], v241 offset:12288
	s_waitcnt lgkmcnt(8)
	v_mfma_f32_32x32x16_bf16 v[0:15], v[68:71], v[164:167], v[0:15]
	v_exp_f32_e32 v221, v221
	ds_read_b128 v[160:163], v242 offset:0
	s_waitcnt lgkmcnt(7)
	v_mfma_f32_32x32x16_bf16 v[0:15], v[80:83], v[168:171], v[0:15]
	v_exp_f32_e32 v222, v222
	ds_read_b128 v[164:167], v242 offset:12288
	s_waitcnt lgkmcnt(6)
	v_mfma_f32_32x32x16_bf16 v[0:15], v[84:87], v[172:175], v[0:15]
	v_exp_f32_e32 v223, v223
	s_waitcnt vmcnt(5)
	s_barrier
	ds_read_b128 v[168:171], v243 offset:0
	s_waitcnt lgkmcnt(6)
	v_mfma_f32_32x32x16_bf16 v[64:79], v[144:147], v[96:99], 0
	v_exp_f32_e32 v224, v224
	v_add_f32_e32 v245, v208, v245
	v_exp_f32_e32 v225, v225
	ds_read_b128 v[172:175], v243 offset:12288
	s_waitcnt lgkmcnt(6)
	v_mfma_f32_32x32x16_bf16 v[80:95], v[148:151], v[96:99], 0
	v_add_f32_e32 v246, v209, v246
	v_exp_f32_e32 v226, v226
	v_add_f32_e32 v245, v210, v245
	ds_read_b128 v[144:147], v240 offset:128
	s_waitcnt lgkmcnt(6)
	v_mfma_f32_32x32x16_bf16 v[64:79], v[152:155], v[100:103], v[64:79]
	v_exp_f32_e32 v227, v227
	v_add_f32_e32 v246, v211, v246
	s_add_i32 m0, s60, 0xc000
	s_nop 0
	global_load_lds_dwordx4 v182, s[42:43]
	ds_read_b128 v[148:151], v240 offset:12416
	s_waitcnt lgkmcnt(6)
	v_mfma_f32_32x32x16_bf16 v[80:95], v[156:159], v[100:103], v[80:95]
	v_exp_f32_e32 v228, v228
	v_add_f32_e32 v245, v212, v245
	v_exp_f32_e32 v229, v229
	ds_read_b128 v[152:155], v241 offset:128
	s_waitcnt lgkmcnt(6)
	v_mfma_f32_32x32x16_bf16 v[64:79], v[160:163], v[104:107], v[64:79]
	v_add_f32_e32 v246, v213, v246
	v_exp_f32_e32 v230, v230
	v_add_f32_e32 v245, v214, v245
	ds_read_b128 v[156:159], v241 offset:12416
	s_waitcnt lgkmcnt(6)
	v_mfma_f32_32x32x16_bf16 v[80:95], v[164:167], v[104:107], v[80:95]
	v_exp_f32_e32 v231, v231
	v_add_f32_e32 v246, v215, v246
	s_add_i32 m0, s60, 0xc400
	s_nop 0
	global_load_lds_dwordx4 v183, s[42:43]
	ds_read_b128 v[160:163], v242 offset:128
	s_waitcnt lgkmcnt(6)
	v_mfma_f32_32x32x16_bf16 v[64:79], v[168:171], v[108:111], v[64:79]
	v_exp_f32_e32 v232, v232
	v_add_f32_e32 v245, v216, v245
	v_exp_f32_e32 v233, v233
	ds_read_b128 v[164:167], v242 offset:12416
	s_waitcnt lgkmcnt(6)
	v_mfma_f32_32x32x16_bf16 v[80:95], v[172:175], v[108:111], v[80:95]
	v_add_f32_e32 v246, v217, v246
	v_exp_f32_e32 v234, v234
	v_add_f32_e32 v245, v218, v245
	ds_read_b128 v[168:171], v243 offset:128
	s_waitcnt lgkmcnt(6)
	v_mfma_f32_32x32x16_bf16 v[64:79], v[144:147], v[112:115], v[64:79]
	v_exp_f32_e32 v235, v235
	v_add_f32_e32 v246, v219, v246
	s_add_i32 m0, s60, 0xc800
	s_nop 0
	global_load_lds_dwordx4 v184, s[42:43]
	ds_read_b128 v[172:175], v243 offset:12416
	s_waitcnt lgkmcnt(6)
	v_mfma_f32_32x32x16_bf16 v[80:95], v[148:151], v[112:115], v[80:95]
	v_exp_f32_e32 v236, v236
	v_add_f32_e32 v245, v220, v245
	v_exp_f32_e32 v237, v237
	ds_read_b128 v[144:147], v240 offset:256
	s_waitcnt lgkmcnt(6)
	v_mfma_f32_32x32x16_bf16 v[64:79], v[152:155], v[116:119], v[64:79]
	v_add_f32_e32 v246, v221, v246
	v_exp_f32_e32 v238, v238
	v_add_f32_e32 v245, v222, v245
	ds_read_b128 v[148:151], v240 offset:12544
	s_waitcnt lgkmcnt(6)
	v_mfma_f32_32x32x16_bf16 v[80:95], v[156:159], v[116:119], v[80:95]
	v_exp_f32_e32 v239, v239
	v_add_f32_e32 v246, v223, v246
	s_add_i32 m0, s61, 0x0
	s_nop 0
	global_load_lds_dwordx4 v185, s[46:47]
	ds_read_b128 v[152:155], v241 offset:256
	s_waitcnt lgkmcnt(6)
	v_mfma_f32_32x32x16_bf16 v[64:79], v[160:163], v[120:123], v[64:79]
	v_add_f32_e32 v245, v224, v245
	v_add_f32_e32 v246, v225, v246
	v_add_f32_e32 v245, v226, v245
	ds_read_b128 v[156:159], v241 offset:12544
	s_waitcnt lgkmcnt(6)
	v_mfma_f32_32x32x16_bf16 v[80:95], v[164:167], v[120:123], v[80:95]
	v_add_f32_e32 v246, v227, v246
	v_add_f32_e32 v245, v228, v245
	v_add_f32_e32 v246, v229, v246
	ds_read_b128 v[160:163], v242 offset:256
	s_waitcnt lgkmcnt(6)
	v_mfma_f32_32x32x16_bf16 v[64:79], v[168:171], v[124:127], v[64:79]
	v_add_f32_e32 v245, v230, v245
	v_add_f32_e32 v246, v231, v246
	s_add_i32 m0, s61, 0x400
	s_nop 0
	global_load_lds_dwordx4 v186, s[46:47]
	ds_read_b128 v[164:167], v242 offset:12544
	s_waitcnt lgkmcnt(6)
	v_mfma_f32_32x32x16_bf16 v[80:95], v[172:175], v[124:127], v[80:95]
	v_add_f32_e32 v245, v232, v245
	v_add_f32_e32 v246, v233, v246
	v_add_f32_e32 v245, v234, v245
	ds_read_b128 v[168:171], v243 offset:256
	s_waitcnt lgkmcnt(6)
	v_mfma_f32_32x32x16_bf16 v[64:79], v[144:147], v[128:131], v[64:79]
	v_add_f32_e32 v246, v235, v246
	v_add_f32_e32 v245, v236, v245
	v_add_f32_e32 v246, v237, v246
	ds_read_b128 v[172:175], v243 offset:12544
	s_waitcnt lgkmcnt(6)
	v_mfma_f32_32x32x16_bf16 v[80:95], v[148:151], v[128:131], v[80:95]
	v_add_f32_e32 v245, v238, v245
	v_add_f32_e32 v246, v239, v246
	s_add_u32 s42, s42, 0x6000
	s_addc_u32 s43, s43, 0
	v_add_u32_e32 v240, 0x6000, v240
	ds_read_b64_tr_b16 v[144:145], v244 offset:0
	ds_read_b64_tr_b16 v[146:147], v244 offset:2048
	s_waitcnt lgkmcnt(7)
	v_mfma_f32_32x32x16_bf16 v[64:79], v[152:155], v[132:135], v[64:79]
	v_cvt_pk_bf16_f32 v208, v208, v209
	v_cvt_pk_bf16_f32 v209, v210, v211
	v_cvt_pk_bf16_f32 v210, v212, v213
	v_add_u32_e32 v241, 0x6000, v241
	ds_read_b64_tr_b16 v[148:149], v244 offset:4096
	ds_read_b64_tr_b16 v[150:151], v244 offset:6144
	s_waitcnt lgkmcnt(8)
	v_mfma_f32_32x32x16_bf16 v[80:95], v[156:159], v[132:135], v[80:95]
	v_cvt_pk_bf16_f32 v211, v214, v215
	v_cvt_pk_bf16_f32 v212, v216, v217
	v_cvt_pk_bf16_f32 v213, v218, v219
	v_add_u32_e32 v242, 0x6000, v242
	ds_read_b64_tr_b16 v[152:153], v244 offset:8192
	ds_read_b64_tr_b16 v[154:155], v244 offset:10240
	s_waitcnt lgkmcnt(9)
	v_mfma_f32_32x32x16_bf16 v[64:79], v[160:163], v[136:139], v[64:79]
	v_cvt_pk_bf16_f32 v214, v220, v221
	v_cvt_pk_bf16_f32 v215, v222, v223
	s_add_u32 s46, s46, 0x40000
	s_addc_u32 s47, s47, 0
	v_add_u32_e32 v243, 0x6000, v243
	ds_read_b64_tr_b16 v[156:157], v244 offset:12288
	ds_read_b64_tr_b16 v[158:159], v244 offset:14336
	s_waitcnt lgkmcnt(10)
	v_mfma_f32_32x32x16_bf16 v[80:95], v[164:167], v[136:139], v[80:95]
	v_cvt_pk_bf16_f32 v224, v224, v225
	v_cvt_pk_bf16_f32 v225, v226, v227
	v_cvt_pk_bf16_f32 v226, v228, v229
	ds_read_b64_tr_b16 v[160:161], v244 offset:512
	ds_read_b64_tr_b16 v[162:163], v244 offset:2560
	s_waitcnt lgkmcnt(11)
	v_mfma_f32_32x32x16_bf16 v[64:79], v[168:171], v[140:143], v[64:79]
	v_cvt_pk_bf16_f32 v227, v230, v231
	v_cvt_pk_bf16_f32 v228, v232, v233
	v_cvt_pk_bf16_f32 v229, v234, v235
	ds_read_b64_tr_b16 v[164:165], v244 offset:4608
	ds_read_b64_tr_b16 v[166:167], v244 offset:6656
	s_waitcnt lgkmcnt(12)
	v_mfma_f32_32x32x16_bf16 v[80:95], v[172:175], v[140:143], v[80:95]
	v_cvt_pk_bf16_f32 v230, v236, v237
	v_cvt_pk_bf16_f32 v231, v238, v239
	s_waitcnt lgkmcnt(10)
	v_mfma_f32_32x32x16_bf16 v[48:63], v[208:211], v[144:147], v[48:63]
	s_waitcnt lgkmcnt(8)
	v_mfma_f32_32x32x16_bf16 v[48:63], v[212:215], v[148:151], v[48:63]
	ds_read_b64_tr_b16 v[168:169], v244 offset:8704
	ds_read_b64_tr_b16 v[170:171], v244 offset:10752
	s_waitcnt lgkmcnt(8)
	v_mfma_f32_32x32x16_bf16 v[48:63], v[224:227], v[152:155], v[48:63]
	v_exp_f32_e32 v64, v64
	v_exp_f32_e32 v65, v65
	ds_read_b64_tr_b16 v[172:173], v244 offset:12800
	ds_read_b64_tr_b16 v[174:175], v244 offset:14848
	s_waitcnt lgkmcnt(8)
	v_mfma_f32_32x32x16_bf16 v[48:63], v[228:231], v[156:159], v[48:63]
	v_exp_f32_e32 v66, v66
	v_exp_f32_e32 v67, v67
	ds_read_b64_tr_b16 v[144:145], v244 offset:1024
	ds_read_b64_tr_b16 v[146:147], v244 offset:3072
	s_waitcnt lgkmcnt(8)
	v_mfma_f32_32x32x16_bf16 v[32:47], v[208:211], v[160:163], v[32:47]
	v_exp_f32_e32 v68, v68
	ds_read_b64_tr_b16 v[148:149], v244 offset:5120
	ds_read_b64_tr_b16 v[150:151], v244 offset:7168
	s_waitcnt lgkmcnt(8)
	v_mfma_f32_32x32x16_bf16 v[32:47], v[212:215], v[164:167], v[32:47]
	v_exp_f32_e32 v69, v69
	ds_read_b64_tr_b16 v[152:153], v244 offset:9216
	ds_read_b64_tr_b16 v[154:155], v244 offset:11264
	s_waitcnt lgkmcnt(8)
	v_mfma_f32_32x32x16_bf16 v[32:47], v[224:227], v[168:171], v[32:47]
	v_exp_f32_e32 v70, v70
	ds_read_b64_tr_b16 v[156:157], v244 offset:13312
	ds_read_b64_tr_b16 v[158:159], v244 offset:15360
	s_waitcnt lgkmcnt(8)
	v_mfma_f32_32x32x16_bf16 v[32:47], v[228:231], v[172:175], v[32:47]
	v_exp_f32_e32 v71, v71
	ds_read_b64_tr_b16 v[160:161], v244 offset:1536
	ds_read_b64_tr_b16 v[162:163], v244 offset:3584
	s_waitcnt lgkmcnt(8)
	v_mfma_f32_32x32x16_bf16 v[16:31], v[208:211], v[144:147], v[16:31]
	v_exp_f32_e32 v72, v72
	ds_read_b64_tr_b16 v[164:165], v244 offset:5632
	ds_read_b64_tr_b16 v[166:167], v244 offset:7680
	s_waitcnt lgkmcnt(8)
	v_mfma_f32_32x32x16_bf16 v[16:31], v[212:215], v[148:151], v[16:31]
	v_exp_f32_e32 v73, v73
	ds_read_b64_tr_b16 v[168:169], v244 offset:9728
	ds_read_b64_tr_b16 v[170:171], v244 offset:11776
	ds_read_b64_tr_b16 v[172:173], v244 offset:13824
	ds_read_b64_tr_b16 v[174:175], v244 offset:15872
	ds_read_b128 v[144:147], v240 offset:0
	s_waitcnt lgkmcnt(11)
	v_mfma_f32_32x32x16_bf16 v[16:31], v[224:227], v[152:155], v[16:31]
	v_exp_f32_e32 v74, v74
	v_add_u32_e32 v244, 0x4000, v244
	ds_read_b128 v[148:151], v240 offset:12288
	s_waitcnt lgkmcnt(10)
	v_mfma_f32_32x32x16_bf16 v[16:31], v[228:231], v[156:159], v[16:31]
	v_exp_f32_e32 v75, v75
	ds_read_b128 v[152:155], v241 offset:0
	s_waitcnt lgkmcnt(9)
	v_mfma_f32_32x32x16_bf16 v[0:15], v[208:211], v[160:163], v[0:15]
	v_exp_f32_e32 v76, v76
	ds_read_b128 v[156:159], v241 offset:12288
	s_waitcnt lgkmcnt(8)
	v_mfma_f32_32x32x16_bf16 v[0:15], v[212:215], v[164:167], v[0:15]
	v_exp_f32_e32 v77, v77
	ds_read_b128 v[160:163], v242 offset:0
	s_waitcnt lgkmcnt(7)
	v_mfma_f32_32x32x16_bf16 v[0:15], v[224:227], v[168:171], v[0:15]
	v_exp_f32_e32 v78, v78
	ds_read_b128 v[164:167], v242 offset:12288
	s_waitcnt lgkmcnt(6)
	v_mfma_f32_32x32x16_bf16 v[0:15], v[228:231], v[172:175], v[0:15]
	v_exp_f32_e32 v79, v79
	s_waitcnt vmcnt(5)
	s_barrier
	ds_read_b128 v[168:171], v243 offset:0
	s_waitcnt lgkmcnt(6)
	v_mfma_f32_32x32x16_bf16 v[208:223], v[144:147], v[96:99], 0
	v_exp_f32_e32 v80, v80
	v_add_f32_e32 v245, v64, v245
	v_exp_f32_e32 v81, v81
	ds_read_b128 v[172:175], v243 offset:12288
	s_waitcnt lgkmcnt(6)
	v_mfma_f32_32x32x16_bf16 v[224:239], v[148:151], v[96:99], 0
	v_add_f32_e32 v246, v65, v246
	v_exp_f32_e32 v82, v82
	v_add_f32_e32 v245, v66, v245
	ds_read_b128 v[144:147], v240 offset:128
	s_waitcnt lgkmcnt(6)
	v_mfma_f32_32x32x16_bf16 v[208:223], v[152:155], v[100:103], v[208:223]
	v_exp_f32_e32 v83, v83
	v_add_f32_e32 v246, v67, v246
	s_add_i32 m0, s60, 0x12000
	s_nop 0
	global_load_lds_dwordx4 v182, s[42:43]
	ds_read_b128 v[148:151], v240 offset:12416
	s_waitcnt lgkmcnt(6)
	v_mfma_f32_32x32x16_bf16 v[224:239], v[156:159], v[100:103], v[224:239]
	v_exp_f32_e32 v84, v84
	v_add_f32_e32 v245, v68, v245
	v_exp_f32_e32 v85, v85
	ds_read_b128 v[152:155], v241 offset:128
	s_waitcnt lgkmcnt(6)
	v_mfma_f32_32x32x16_bf16 v[208:223], v[160:163], v[104:107], v[208:223]
	v_add_f32_e32 v246, v69, v246
	v_exp_f32_e32 v86, v86
	v_add_f32_e32 v245, v70, v245
	ds_read_b128 v[156:159], v241 offset:12416
	s_waitcnt lgkmcnt(6)
	v_mfma_f32_32x32x16_bf16 v[224:239], v[164:167], v[104:107], v[224:239]
	v_exp_f32_e32 v87, v87
	v_add_f32_e32 v246, v71, v246
	s_add_i32 m0, s60, 0x12400
	s_nop 0
	global_load_lds_dwordx4 v183, s[42:43]
	ds_read_b128 v[160:163], v242 offset:128
	s_waitcnt lgkmcnt(6)
	v_mfma_f32_32x32x16_bf16 v[208:223], v[168:171], v[108:111], v[208:223]
	v_exp_f32_e32 v88, v88
	v_add_f32_e32 v245, v72, v245
	v_exp_f32_e32 v89, v89
	ds_read_b128 v[164:167], v242 offset:12416
	s_waitcnt lgkmcnt(6)
	v_mfma_f32_32x32x16_bf16 v[224:239], v[172:175], v[108:111], v[224:239]
	v_add_f32_e32 v246, v73, v246
	v_exp_f32_e32 v90, v90
	v_add_f32_e32 v245, v74, v245
	ds_read_b128 v[168:171], v243 offset:128
	s_waitcnt lgkmcnt(6)
	v_mfma_f32_32x32x16_bf16 v[208:223], v[144:147], v[112:115], v[208:223]
	v_exp_f32_e32 v91, v91
	v_add_f32_e32 v246, v75, v246
	s_add_i32 m0, s60, 0x12800
	s_nop 0
	global_load_lds_dwordx4 v184, s[42:43]
	ds_read_b128 v[172:175], v243 offset:12416
	s_waitcnt lgkmcnt(6)
	v_mfma_f32_32x32x16_bf16 v[224:239], v[148:151], v[112:115], v[224:239]
	v_exp_f32_e32 v92, v92
	v_add_f32_e32 v245, v76, v245
	v_exp_f32_e32 v93, v93
	ds_read_b128 v[144:147], v240 offset:256
	s_waitcnt lgkmcnt(6)
	v_mfma_f32_32x32x16_bf16 v[208:223], v[152:155], v[116:119], v[208:223]
	v_add_f32_e32 v246, v77, v246
	v_exp_f32_e32 v94, v94
	v_add_f32_e32 v245, v78, v245
	ds_read_b128 v[148:151], v240 offset:12544
	s_waitcnt lgkmcnt(6)
	v_mfma_f32_32x32x16_bf16 v[224:239], v[156:159], v[116:119], v[224:239]
	v_exp_f32_e32 v95, v95
	v_add_f32_e32 v246, v79, v246
	s_add_i32 m0, s61, 0x4000
	s_nop 0
	global_load_lds_dwordx4 v185, s[46:47]
	ds_read_b128 v[152:155], v241 offset:256
	s_waitcnt lgkmcnt(6)
	v_mfma_f32_32x32x16_bf16 v[208:223], v[160:163], v[120:123], v[208:223]
	v_add_f32_e32 v245, v80, v245
	v_add_f32_e32 v246, v81, v246
	v_add_f32_e32 v245, v82, v245
	ds_read_b128 v[156:159], v241 offset:12544
	s_waitcnt lgkmcnt(6)
	v_mfma_f32_32x32x16_bf16 v[224:239], v[164:167], v[120:123], v[224:239]
	v_add_f32_e32 v246, v83, v246
	v_add_f32_e32 v245, v84, v245
	v_add_f32_e32 v246, v85, v246
	ds_read_b128 v[160:163], v242 offset:256
	s_waitcnt lgkmcnt(6)
	v_mfma_f32_32x32x16_bf16 v[208:223], v[168:171], v[124:127], v[208:223]
	v_add_f32_e32 v245, v86, v245
	v_add_f32_e32 v246, v87, v246
	s_add_i32 m0, s61, 0x4400
	s_nop 0
	global_load_lds_dwordx4 v186, s[46:47]
	ds_read_b128 v[164:167], v242 offset:12544
	s_waitcnt lgkmcnt(6)
	v_mfma_f32_32x32x16_bf16 v[224:239], v[172:175], v[124:127], v[224:239]
	v_add_f32_e32 v245, v88, v245
	v_add_f32_e32 v246, v89, v246
	v_add_f32_e32 v245, v90, v245
	ds_read_b128 v[168:171], v243 offset:256
	s_waitcnt lgkmcnt(6)
	v_mfma_f32_32x32x16_bf16 v[208:223], v[144:147], v[128:131], v[208:223]
	v_add_f32_e32 v246, v91, v246
	v_add_f32_e32 v245, v92, v245
	v_add_f32_e32 v246, v93, v246
	ds_read_b128 v[172:175], v243 offset:12544
	s_waitcnt lgkmcnt(6)
	v_mfma_f32_32x32x16_bf16 v[224:239], v[148:151], v[128:131], v[224:239]
	v_add_f32_e32 v245, v94, v245
	v_add_f32_e32 v246, v95, v246
	s_add_u32 s42, s42, 0x6000
	s_addc_u32 s43, s43, 0
	v_add_u32_e32 v240, 0x9010, v240
	ds_read_b64_tr_b16 v[144:145], v244 offset:0
	ds_read_b64_tr_b16 v[146:147], v244 offset:2048
	s_waitcnt lgkmcnt(7)
	v_mfma_f32_32x32x16_bf16 v[208:223], v[152:155], v[132:135], v[208:223]
	v_cvt_pk_bf16_f32 v64, v64, v65
	v_cvt_pk_bf16_f32 v65, v66, v67
	v_cvt_pk_bf16_f32 v66, v68, v69
	v_add_u32_e32 v241, 0x9010, v241
	ds_read_b64_tr_b16 v[148:149], v244 offset:4096
	ds_read_b64_tr_b16 v[150:151], v244 offset:6144
	s_waitcnt lgkmcnt(8)
	v_mfma_f32_32x32x16_bf16 v[224:239], v[156:159], v[132:135], v[224:239]
	v_cvt_pk_bf16_f32 v67, v70, v71
	v_cvt_pk_bf16_f32 v68, v72, v73
	v_cvt_pk_bf16_f32 v69, v74, v75
	v_add_u32_e32 v242, 0x9010, v242
	ds_read_b64_tr_b16 v[152:153], v244 offset:8192
	ds_read_b64_tr_b16 v[154:155], v244 offset:10240
	s_waitcnt lgkmcnt(9)
	v_mfma_f32_32x32x16_bf16 v[208:223], v[160:163], v[136:139], v[208:223]
	v_cvt_pk_bf16_f32 v70, v76, v77
	v_cvt_pk_bf16_f32 v71, v78, v79
	s_add_u32 s46, s46, 0x40000
	s_addc_u32 s47, s47, 0
	v_add_u32_e32 v243, 0x9010, v243
	ds_read_b64_tr_b16 v[156:157], v244 offset:12288
	ds_read_b64_tr_b16 v[158:159], v244 offset:14336
	s_waitcnt lgkmcnt(10)
	v_mfma_f32_32x32x16_bf16 v[224:239], v[164:167], v[136:139], v[224:239]
	v_cvt_pk_bf16_f32 v80, v80, v81
	v_cvt_pk_bf16_f32 v81, v82, v83
	v_cvt_pk_bf16_f32 v82, v84, v85
	ds_read_b64_tr_b16 v[160:161], v244 offset:512
	ds_read_b64_tr_b16 v[162:163], v244 offset:2560
	s_waitcnt lgkmcnt(11)
	v_mfma_f32_32x32x16_bf16 v[208:223], v[168:171], v[140:143], v[208:223]
	v_cvt_pk_bf16_f32 v83, v86, v87
	v_cvt_pk_bf16_f32 v84, v88, v89
	v_cvt_pk_bf16_f32 v85, v90, v91
	ds_read_b64_tr_b16 v[164:165], v244 offset:4608
	ds_read_b64_tr_b16 v[166:167], v244 offset:6656
	s_waitcnt lgkmcnt(12)
	v_mfma_f32_32x32x16_bf16 v[224:239], v[172:175], v[140:143], v[224:239]
	v_cvt_pk_bf16_f32 v86, v92, v93
	v_cvt_pk_bf16_f32 v87, v94, v95
	s_waitcnt lgkmcnt(10)
	v_mfma_f32_32x32x16_bf16 v[48:63], v[64:67], v[144:147], v[48:63]
	s_waitcnt lgkmcnt(8)
	v_mfma_f32_32x32x16_bf16 v[48:63], v[68:71], v[148:151], v[48:63]
	ds_read_b64_tr_b16 v[168:169], v244 offset:8704
	ds_read_b64_tr_b16 v[170:171], v244 offset:10752
	s_waitcnt lgkmcnt(8)
	v_mfma_f32_32x32x16_bf16 v[48:63], v[80:83], v[152:155], v[48:63]
	v_exp_f32_e32 v208, v208
	v_exp_f32_e32 v209, v209
	ds_read_b64_tr_b16 v[172:173], v244 offset:12800
	ds_read_b64_tr_b16 v[174:175], v244 offset:14848
	s_waitcnt lgkmcnt(8)
	v_mfma_f32_32x32x16_bf16 v[48:63], v[84:87], v[156:159], v[48:63]
	v_exp_f32_e32 v210, v210
	v_exp_f32_e32 v211, v211
	ds_read_b64_tr_b16 v[144:145], v244 offset:1024
	ds_read_b64_tr_b16 v[146:147], v244 offset:3072
	s_waitcnt lgkmcnt(8)
	v_mfma_f32_32x32x16_bf16 v[32:47], v[64:67], v[160:163], v[32:47]
	v_exp_f32_e32 v212, v212
	ds_read_b64_tr_b16 v[148:149], v244 offset:5120
	ds_read_b64_tr_b16 v[150:151], v244 offset:7168
	s_waitcnt lgkmcnt(8)
	v_mfma_f32_32x32x16_bf16 v[32:47], v[68:71], v[164:167], v[32:47]
	v_exp_f32_e32 v213, v213
	ds_read_b64_tr_b16 v[152:153], v244 offset:9216
	ds_read_b64_tr_b16 v[154:155], v244 offset:11264
	s_waitcnt lgkmcnt(8)
	v_mfma_f32_32x32x16_bf16 v[32:47], v[80:83], v[168:171], v[32:47]
	v_exp_f32_e32 v214, v214
	ds_read_b64_tr_b16 v[156:157], v244 offset:13312
	ds_read_b64_tr_b16 v[158:159], v244 offset:15360
	s_waitcnt lgkmcnt(8)
	v_mfma_f32_32x32x16_bf16 v[32:47], v[84:87], v[172:175], v[32:47]
	v_exp_f32_e32 v215, v215
	ds_read_b64_tr_b16 v[160:161], v244 offset:1536
	ds_read_b64_tr_b16 v[162:163], v244 offset:3584
	s_waitcnt lgkmcnt(8)
	v_mfma_f32_32x32x16_bf16 v[16:31], v[64:67], v[144:147], v[16:31]
	v_exp_f32_e32 v216, v216
	ds_read_b64_tr_b16 v[164:165], v244 offset:5632
	ds_read_b64_tr_b16 v[166:167], v244 offset:7680
	s_waitcnt lgkmcnt(8)
	v_mfma_f32_32x32x16_bf16 v[16:31], v[68:71], v[148:151], v[16:31]
	v_exp_f32_e32 v217, v217
	ds_read_b64_tr_b16 v[168:169], v244 offset:9728
	ds_read_b64_tr_b16 v[170:171], v244 offset:11776
	ds_read_b64_tr_b16 v[172:173], v244 offset:13824
	ds_read_b64_tr_b16 v[174:175], v244 offset:15872
	ds_read_b128 v[144:147], v240 offset:0
	s_waitcnt lgkmcnt(11)
	v_mfma_f32_32x32x16_bf16 v[16:31], v[80:83], v[152:155], v[16:31]
	v_exp_f32_e32 v218, v218
	v_add_u32_e32 v244, 0xffff8000, v244
	ds_read_b128 v[148:151], v240 offset:12288
	s_waitcnt lgkmcnt(10)
	v_mfma_f32_32x32x16_bf16 v[16:31], v[84:87], v[156:159], v[16:31]
	v_exp_f32_e32 v219, v219
	ds_read_b128 v[152:155], v241 offset:0
	s_waitcnt lgkmcnt(9)
	v_mfma_f32_32x32x16_bf16 v[0:15], v[64:67], v[160:163], v[0:15]
	v_exp_f32_e32 v220, v220
	ds_read_b128 v[156:159], v241 offset:12288
	s_waitcnt lgkmcnt(8)
	v_mfma_f32_32x32x16_bf16 v[0:15], v[68:71], v[164:167], v[0:15]
	v_exp_f32_e32 v221, v221
	ds_read_b128 v[160:163], v242 offset:0
	s_waitcnt lgkmcnt(7)
	v_mfma_f32_32x32x16_bf16 v[0:15], v[80:83], v[168:171], v[0:15]
	v_exp_f32_e32 v222, v222
	ds_read_b128 v[164:167], v242 offset:12288
	s_waitcnt lgkmcnt(6)
	v_mfma_f32_32x32x16_bf16 v[0:15], v[84:87], v[172:175], v[0:15]
	v_exp_f32_e32 v223, v223
	s_waitcnt vmcnt(5)
	s_barrier
	ds_read_b128 v[168:171], v243 offset:0
	s_waitcnt lgkmcnt(6)
	v_mfma_f32_32x32x16_bf16 v[64:79], v[144:147], v[96:99], 0
	v_exp_f32_e32 v224, v224
	v_add_f32_e32 v245, v208, v245
	v_exp_f32_e32 v225, v225
	ds_read_b128 v[172:175], v243 offset:12288
	s_waitcnt lgkmcnt(6)
	v_mfma_f32_32x32x16_bf16 v[80:95], v[148:151], v[96:99], 0
	v_add_f32_e32 v246, v209, v246
	v_exp_f32_e32 v226, v226
	v_add_f32_e32 v245, v210, v245
	ds_read_b128 v[144:147], v240 offset:128
	s_waitcnt lgkmcnt(6)
	v_mfma_f32_32x32x16_bf16 v[64:79], v[152:155], v[100:103], v[64:79]
	v_exp_f32_e32 v227, v227
	v_add_f32_e32 v246, v211, v246
	s_add_i32 m0, s60, 0x18000
	s_nop 0
	global_load_lds_dwordx4 v182, s[42:43]
	ds_read_b128 v[148:151], v240 offset:12416
	s_waitcnt lgkmcnt(6)
	v_mfma_f32_32x32x16_bf16 v[80:95], v[156:159], v[100:103], v[80:95]
	v_exp_f32_e32 v228, v228
	v_add_f32_e32 v245, v212, v245
	v_exp_f32_e32 v229, v229
	ds_read_b128 v[152:155], v241 offset:128
	s_waitcnt lgkmcnt(6)
	v_mfma_f32_32x32x16_bf16 v[64:79], v[160:163], v[104:107], v[64:79]
	v_add_f32_e32 v246, v213, v246
	v_exp_f32_e32 v230, v230
	v_add_f32_e32 v245, v214, v245
	ds_read_b128 v[156:159], v241 offset:12416
	s_waitcnt lgkmcnt(6)
	v_mfma_f32_32x32x16_bf16 v[80:95], v[164:167], v[104:107], v[80:95]
	v_exp_f32_e32 v231, v231
	v_add_f32_e32 v246, v215, v246
	s_add_i32 m0, s60, 0x18400
	s_nop 0
	global_load_lds_dwordx4 v183, s[42:43]
	ds_read_b128 v[160:163], v242 offset:128
	s_waitcnt lgkmcnt(6)
	v_mfma_f32_32x32x16_bf16 v[64:79], v[168:171], v[108:111], v[64:79]
	v_exp_f32_e32 v232, v232
	v_add_f32_e32 v245, v216, v245
	v_exp_f32_e32 v233, v233
	ds_read_b128 v[164:167], v242 offset:12416
	s_waitcnt lgkmcnt(6)
	v_mfma_f32_32x32x16_bf16 v[80:95], v[172:175], v[108:111], v[80:95]
	v_add_f32_e32 v246, v217, v246
	v_exp_f32_e32 v234, v234
	v_add_f32_e32 v245, v218, v245
	ds_read_b128 v[168:171], v243 offset:128
	s_waitcnt lgkmcnt(6)
	v_mfma_f32_32x32x16_bf16 v[64:79], v[144:147], v[112:115], v[64:79]
	v_exp_f32_e32 v235, v235
	v_add_f32_e32 v246, v219, v246
	s_add_i32 m0, s60, 0x18800
	s_nop 0
	global_load_lds_dwordx4 v184, s[42:43]
	ds_read_b128 v[172:175], v243 offset:12416
	s_waitcnt lgkmcnt(6)
	v_mfma_f32_32x32x16_bf16 v[80:95], v[148:151], v[112:115], v[80:95]
	v_exp_f32_e32 v236, v236
	v_add_f32_e32 v245, v220, v245
	v_exp_f32_e32 v237, v237
	ds_read_b128 v[144:147], v240 offset:256
	s_waitcnt lgkmcnt(6)
	v_mfma_f32_32x32x16_bf16 v[64:79], v[152:155], v[116:119], v[64:79]
	v_add_f32_e32 v246, v221, v246
	v_exp_f32_e32 v238, v238
	v_add_f32_e32 v245, v222, v245
	ds_read_b128 v[148:151], v240 offset:12544
	s_waitcnt lgkmcnt(6)
	v_mfma_f32_32x32x16_bf16 v[80:95], v[156:159], v[116:119], v[80:95]
	v_exp_f32_e32 v239, v239
	v_add_f32_e32 v246, v223, v246
	s_add_i32 m0, s61, 0x8000
	s_nop 0
	global_load_lds_dwordx4 v185, s[46:47]
	ds_read_b128 v[152:155], v241 offset:256
	s_waitcnt lgkmcnt(6)
	v_mfma_f32_32x32x16_bf16 v[64:79], v[160:163], v[120:123], v[64:79]
	v_add_f32_e32 v245, v224, v245
	v_add_f32_e32 v246, v225, v246
	v_add_f32_e32 v245, v226, v245
	ds_read_b128 v[156:159], v241 offset:12544
	s_waitcnt lgkmcnt(6)
	v_mfma_f32_32x32x16_bf16 v[80:95], v[164:167], v[120:123], v[80:95]
	v_add_f32_e32 v246, v227, v246
	v_add_f32_e32 v245, v228, v245
	v_add_f32_e32 v246, v229, v246
	ds_read_b128 v[160:163], v242 offset:256
	s_waitcnt lgkmcnt(6)
	v_mfma_f32_32x32x16_bf16 v[64:79], v[168:171], v[124:127], v[64:79]
	v_add_f32_e32 v245, v230, v245
	v_add_f32_e32 v246, v231, v246
	s_add_i32 m0, s61, 0x8400
	s_nop 0
	global_load_lds_dwordx4 v186, s[46:47]
	ds_read_b128 v[164:167], v242 offset:12544
	s_waitcnt lgkmcnt(6)
	v_mfma_f32_32x32x16_bf16 v[80:95], v[172:175], v[124:127], v[80:95]
	v_add_f32_e32 v245, v232, v245
	v_add_f32_e32 v246, v233, v246
	v_add_f32_e32 v245, v234, v245
	ds_read_b128 v[168:171], v243 offset:256
	s_waitcnt lgkmcnt(6)
	v_mfma_f32_32x32x16_bf16 v[64:79], v[144:147], v[128:131], v[64:79]
	v_add_f32_e32 v246, v235, v246
	v_add_f32_e32 v245, v236, v245
	v_add_f32_e32 v246, v237, v246
	ds_read_b128 v[172:175], v243 offset:12544
	s_waitcnt lgkmcnt(6)
	v_mfma_f32_32x32x16_bf16 v[80:95], v[148:151], v[128:131], v[80:95]
	v_add_f32_e32 v245, v238, v245
	v_add_f32_e32 v246, v239, v246
	s_add_u32 s42, s42, 0x6000
	s_addc_u32 s43, s43, 0
	v_add_u32_e32 v240, 0xfffeaff0, v240
	ds_read_b64_tr_b16 v[144:145], v244 offset:0
	ds_read_b64_tr_b16 v[146:147], v244 offset:2048
	s_waitcnt lgkmcnt(7)
	v_mfma_f32_32x32x16_bf16 v[64:79], v[152:155], v[132:135], v[64:79]
	v_cvt_pk_bf16_f32 v208, v208, v209
	v_cvt_pk_bf16_f32 v209, v210, v211
	v_cvt_pk_bf16_f32 v210, v212, v213
	v_add_u32_e32 v241, 0xfffeaff0, v241
	ds_read_b64_tr_b16 v[148:149], v244 offset:4096
	ds_read_b64_tr_b16 v[150:151], v244 offset:6144
	s_waitcnt lgkmcnt(8)
	v_mfma_f32_32x32x16_bf16 v[80:95], v[156:159], v[132:135], v[80:95]
	v_cvt_pk_bf16_f32 v211, v214, v215
	v_cvt_pk_bf16_f32 v212, v216, v217
	v_cvt_pk_bf16_f32 v213, v218, v219
	v_add_u32_e32 v242, 0xfffeaff0, v242
	ds_read_b64_tr_b16 v[152:153], v244 offset:8192
	ds_read_b64_tr_b16 v[154:155], v244 offset:10240
	s_waitcnt lgkmcnt(9)
	v_mfma_f32_32x32x16_bf16 v[64:79], v[160:163], v[136:139], v[64:79]
	v_cvt_pk_bf16_f32 v214, v220, v221
	v_cvt_pk_bf16_f32 v215, v222, v223
	s_add_u32 s46, s46, 0x40000
	s_addc_u32 s47, s47, 0
	v_add_u32_e32 v243, 0xfffeaff0, v243
	ds_read_b64_tr_b16 v[156:157], v244 offset:12288
	ds_read_b64_tr_b16 v[158:159], v244 offset:14336
	s_waitcnt lgkmcnt(10)
	v_mfma_f32_32x32x16_bf16 v[80:95], v[164:167], v[136:139], v[80:95]
	v_cvt_pk_bf16_f32 v224, v224, v225
	v_cvt_pk_bf16_f32 v225, v226, v227
	v_cvt_pk_bf16_f32 v226, v228, v229
	ds_read_b64_tr_b16 v[160:161], v244 offset:512
	ds_read_b64_tr_b16 v[162:163], v244 offset:2560
	s_waitcnt lgkmcnt(11)
	v_mfma_f32_32x32x16_bf16 v[64:79], v[168:171], v[140:143], v[64:79]
	v_cvt_pk_bf16_f32 v227, v230, v231
	v_cvt_pk_bf16_f32 v228, v232, v233
	v_cvt_pk_bf16_f32 v229, v234, v235
	ds_read_b64_tr_b16 v[164:165], v244 offset:4608
	ds_read_b64_tr_b16 v[166:167], v244 offset:6656
	s_waitcnt lgkmcnt(12)
	v_mfma_f32_32x32x16_bf16 v[80:95], v[172:175], v[140:143], v[80:95]
	v_cvt_pk_bf16_f32 v230, v236, v237
	v_cvt_pk_bf16_f32 v231, v238, v239
	s_waitcnt lgkmcnt(10)
	v_mfma_f32_32x32x16_bf16 v[48:63], v[208:211], v[144:147], v[48:63]
	s_waitcnt lgkmcnt(8)
	v_mfma_f32_32x32x16_bf16 v[48:63], v[212:215], v[148:151], v[48:63]
	ds_read_b64_tr_b16 v[168:169], v244 offset:8704
	ds_read_b64_tr_b16 v[170:171], v244 offset:10752
	s_waitcnt lgkmcnt(8)
	v_mfma_f32_32x32x16_bf16 v[48:63], v[224:227], v[152:155], v[48:63]
	v_exp_f32_e32 v64, v64
	v_exp_f32_e32 v65, v65
	ds_read_b64_tr_b16 v[172:173], v244 offset:12800
	ds_read_b64_tr_b16 v[174:175], v244 offset:14848
	s_waitcnt lgkmcnt(8)
	v_mfma_f32_32x32x16_bf16 v[48:63], v[228:231], v[156:159], v[48:63]
	v_exp_f32_e32 v66, v66
	v_exp_f32_e32 v67, v67
	ds_read_b64_tr_b16 v[144:145], v244 offset:1024
	ds_read_b64_tr_b16 v[146:147], v244 offset:3072
	s_waitcnt lgkmcnt(8)
	v_mfma_f32_32x32x16_bf16 v[32:47], v[208:211], v[160:163], v[32:47]
	v_exp_f32_e32 v68, v68
	ds_read_b64_tr_b16 v[148:149], v244 offset:5120
	ds_read_b64_tr_b16 v[150:151], v244 offset:7168
	s_waitcnt lgkmcnt(8)
	v_mfma_f32_32x32x16_bf16 v[32:47], v[212:215], v[164:167], v[32:47]
	v_exp_f32_e32 v69, v69
	ds_read_b64_tr_b16 v[152:153], v244 offset:9216
	ds_read_b64_tr_b16 v[154:155], v244 offset:11264
	s_waitcnt lgkmcnt(8)
	v_mfma_f32_32x32x16_bf16 v[32:47], v[224:227], v[168:171], v[32:47]
	v_exp_f32_e32 v70, v70
	ds_read_b64_tr_b16 v[156:157], v244 offset:13312
	ds_read_b64_tr_b16 v[158:159], v244 offset:15360
	s_waitcnt lgkmcnt(8)
	v_mfma_f32_32x32x16_bf16 v[32:47], v[228:231], v[172:175], v[32:47]
	v_exp_f32_e32 v71, v71
	ds_read_b64_tr_b16 v[160:161], v244 offset:1536
	ds_read_b64_tr_b16 v[162:163], v244 offset:3584
	s_waitcnt lgkmcnt(8)
	v_mfma_f32_32x32x16_bf16 v[16:31], v[208:211], v[144:147], v[16:31]
	v_exp_f32_e32 v72, v72
	ds_read_b64_tr_b16 v[164:165], v244 offset:5632
	ds_read_b64_tr_b16 v[166:167], v244 offset:7680
	s_waitcnt lgkmcnt(8)
	v_mfma_f32_32x32x16_bf16 v[16:31], v[212:215], v[148:151], v[16:31]
	v_exp_f32_e32 v73, v73
	ds_read_b64_tr_b16 v[168:169], v244 offset:9728
	ds_read_b64_tr_b16 v[170:171], v244 offset:11776
	ds_read_b64_tr_b16 v[172:173], v244 offset:13824
	ds_read_b64_tr_b16 v[174:175], v244 offset:15872
	ds_read_b128 v[144:147], v240 offset:0
	s_waitcnt lgkmcnt(11)
	v_mfma_f32_32x32x16_bf16 v[16:31], v[224:227], v[152:155], v[16:31]
	v_exp_f32_e32 v74, v74
	v_add_u32_e32 v244, 0x4000, v244
	ds_read_b128 v[148:151], v240 offset:12288
	s_waitcnt lgkmcnt(10)
	v_mfma_f32_32x32x16_bf16 v[16:31], v[228:231], v[156:159], v[16:31]
	v_exp_f32_e32 v75, v75
	ds_read_b128 v[152:155], v241 offset:0
	s_waitcnt lgkmcnt(9)
	v_mfma_f32_32x32x16_bf16 v[0:15], v[208:211], v[160:163], v[0:15]
	v_exp_f32_e32 v76, v76
	ds_read_b128 v[156:159], v241 offset:12288
	s_waitcnt lgkmcnt(8)
	v_mfma_f32_32x32x16_bf16 v[0:15], v[212:215], v[164:167], v[0:15]
	v_exp_f32_e32 v77, v77
	ds_read_b128 v[160:163], v242 offset:0
	s_waitcnt lgkmcnt(7)
	v_mfma_f32_32x32x16_bf16 v[0:15], v[224:227], v[168:171], v[0:15]
	v_exp_f32_e32 v78, v78
	ds_read_b128 v[164:167], v242 offset:12288
	s_waitcnt lgkmcnt(6)
	v_mfma_f32_32x32x16_bf16 v[0:15], v[228:231], v[172:175], v[0:15]
	v_exp_f32_e32 v79, v79
	s_waitcnt vmcnt(5)
	s_barrier
	ds_read_b128 v[168:171], v243 offset:0
	s_waitcnt lgkmcnt(6)
	v_mfma_f32_32x32x16_bf16 v[208:223], v[144:147], v[96:99], 0
	v_exp_f32_e32 v80, v80
	v_add_f32_e32 v245, v64, v245
	v_exp_f32_e32 v81, v81
	ds_read_b128 v[172:175], v243 offset:12288
	s_waitcnt lgkmcnt(6)
	v_mfma_f32_32x32x16_bf16 v[224:239], v[148:151], v[96:99], 0
	v_add_f32_e32 v246, v65, v246
	v_exp_f32_e32 v82, v82
	v_add_f32_e32 v245, v66, v245
	ds_read_b128 v[144:147], v240 offset:128
	s_waitcnt lgkmcnt(6)
	v_mfma_f32_32x32x16_bf16 v[208:223], v[152:155], v[100:103], v[208:223]
	v_exp_f32_e32 v83, v83
	v_add_f32_e32 v246, v67, v246
	s_add_i32 m0, s60, 0x21010
	s_nop 0
	global_load_lds_dwordx4 v182, s[42:43]
	ds_read_b128 v[148:151], v240 offset:12416
	s_waitcnt lgkmcnt(6)
	v_mfma_f32_32x32x16_bf16 v[224:239], v[156:159], v[100:103], v[224:239]
	v_exp_f32_e32 v84, v84
	v_add_f32_e32 v245, v68, v245
	v_exp_f32_e32 v85, v85
	ds_read_b128 v[152:155], v241 offset:128
	s_waitcnt lgkmcnt(6)
	v_mfma_f32_32x32x16_bf16 v[208:223], v[160:163], v[104:107], v[208:223]
	v_add_f32_e32 v246, v69, v246
	v_exp_f32_e32 v86, v86
	v_add_f32_e32 v245, v70, v245
	ds_read_b128 v[156:159], v241 offset:12416
	s_waitcnt lgkmcnt(6)
	v_mfma_f32_32x32x16_bf16 v[224:239], v[164:167], v[104:107], v[224:239]
	v_exp_f32_e32 v87, v87
	v_add_f32_e32 v246, v71, v246
	s_add_i32 m0, s60, 0x21410
	s_nop 0
	global_load_lds_dwordx4 v183, s[42:43]
	ds_read_b128 v[160:163], v242 offset:128
	s_waitcnt lgkmcnt(6)
	v_mfma_f32_32x32x16_bf16 v[208:223], v[168:171], v[108:111], v[208:223]
	v_exp_f32_e32 v88, v88
	v_add_f32_e32 v245, v72, v245
	v_exp_f32_e32 v89, v89
	ds_read_b128 v[164:167], v242 offset:12416
	s_waitcnt lgkmcnt(6)
	v_mfma_f32_32x32x16_bf16 v[224:239], v[172:175], v[108:111], v[224:239]
	v_add_f32_e32 v246, v73, v246
	v_exp_f32_e32 v90, v90
	v_add_f32_e32 v245, v74, v245
	ds_read_b128 v[168:171], v243 offset:128
	s_waitcnt lgkmcnt(6)
	v_mfma_f32_32x32x16_bf16 v[208:223], v[144:147], v[112:115], v[208:223]
	v_exp_f32_e32 v91, v91
	v_add_f32_e32 v246, v75, v246
	s_add_i32 m0, s60, 0x21810
	s_nop 0
	global_load_lds_dwordx4 v184, s[42:43]
	ds_read_b128 v[172:175], v243 offset:12416
	s_waitcnt lgkmcnt(6)
	v_mfma_f32_32x32x16_bf16 v[224:239], v[148:151], v[112:115], v[224:239]
	v_exp_f32_e32 v92, v92
	v_add_f32_e32 v245, v76, v245
	v_exp_f32_e32 v93, v93
	ds_read_b128 v[144:147], v240 offset:256
	s_waitcnt lgkmcnt(6)
	v_mfma_f32_32x32x16_bf16 v[208:223], v[152:155], v[116:119], v[208:223]
	v_add_f32_e32 v246, v77, v246
	v_exp_f32_e32 v94, v94
	v_add_f32_e32 v245, v78, v245
	ds_read_b128 v[148:151], v240 offset:12544
	s_waitcnt lgkmcnt(6)
	v_mfma_f32_32x32x16_bf16 v[224:239], v[156:159], v[116:119], v[224:239]
	v_exp_f32_e32 v95, v95
	v_add_f32_e32 v246, v79, v246
	s_add_i32 m0, s61, 0x0
	s_nop 0
	global_load_lds_dwordx4 v185, s[46:47]
	ds_read_b128 v[152:155], v241 offset:256
	s_waitcnt lgkmcnt(6)
	v_mfma_f32_32x32x16_bf16 v[208:223], v[160:163], v[120:123], v[208:223]
	v_add_f32_e32 v245, v80, v245
	v_add_f32_e32 v246, v81, v246
	v_add_f32_e32 v245, v82, v245
	ds_read_b128 v[156:159], v241 offset:12544
	s_waitcnt lgkmcnt(6)
	v_mfma_f32_32x32x16_bf16 v[224:239], v[164:167], v[120:123], v[224:239]
	v_add_f32_e32 v246, v83, v246
	v_add_f32_e32 v245, v84, v245
	v_add_f32_e32 v246, v85, v246
	ds_read_b128 v[160:163], v242 offset:256
	s_waitcnt lgkmcnt(6)
	v_mfma_f32_32x32x16_bf16 v[208:223], v[168:171], v[124:127], v[208:223]
	v_add_f32_e32 v245, v86, v245
	v_add_f32_e32 v246, v87, v246
	s_add_i32 m0, s61, 0x400
	s_nop 0
	global_load_lds_dwordx4 v186, s[46:47]
	ds_read_b128 v[164:167], v242 offset:12544
	s_waitcnt lgkmcnt(6)
	v_mfma_f32_32x32x16_bf16 v[224:239], v[172:175], v[124:127], v[224:239]
	v_add_f32_e32 v245, v88, v245
	v_add_f32_e32 v246, v89, v246
	v_add_f32_e32 v245, v90, v245
	ds_read_b128 v[168:171], v243 offset:256
	s_waitcnt lgkmcnt(6)
	v_mfma_f32_32x32x16_bf16 v[208:223], v[144:147], v[128:131], v[208:223]
	v_add_f32_e32 v246, v91, v246
	v_add_f32_e32 v245, v92, v245
	v_add_f32_e32 v246, v93, v246
	ds_read_b128 v[172:175], v243 offset:12544
	s_waitcnt lgkmcnt(6)
	v_mfma_f32_32x32x16_bf16 v[224:239], v[148:151], v[128:131], v[224:239]
	v_add_f32_e32 v245, v94, v245
	v_add_f32_e32 v246, v95, v246
	s_add_u32 s42, s42, 0x6000
	s_addc_u32 s43, s43, 0
	v_add_u32_e32 v240, 0x6000, v240
	ds_read_b64_tr_b16 v[144:145], v244 offset:0
	ds_read_b64_tr_b16 v[146:147], v244 offset:2048
	s_waitcnt lgkmcnt(7)
	v_mfma_f32_32x32x16_bf16 v[208:223], v[152:155], v[132:135], v[208:223]
	v_cvt_pk_bf16_f32 v64, v64, v65
	v_cvt_pk_bf16_f32 v65, v66, v67
	v_cvt_pk_bf16_f32 v66, v68, v69
	v_add_u32_e32 v241, 0x6000, v241
	ds_read_b64_tr_b16 v[148:149], v244 offset:4096
	ds_read_b64_tr_b16 v[150:151], v244 offset:6144
	s_waitcnt lgkmcnt(8)
	v_mfma_f32_32x32x16_bf16 v[224:239], v[156:159], v[132:135], v[224:239]
	v_cvt_pk_bf16_f32 v67, v70, v71
	v_cvt_pk_bf16_f32 v68, v72, v73
	v_cvt_pk_bf16_f32 v69, v74, v75
	v_add_u32_e32 v242, 0x6000, v242
	ds_read_b64_tr_b16 v[152:153], v244 offset:8192
	ds_read_b64_tr_b16 v[154:155], v244 offset:10240
	s_waitcnt lgkmcnt(9)
	v_mfma_f32_32x32x16_bf16 v[208:223], v[160:163], v[136:139], v[208:223]
	v_cvt_pk_bf16_f32 v70, v76, v77
	v_cvt_pk_bf16_f32 v71, v78, v79
	s_add_u32 s46, s46, 0x40000
	s_addc_u32 s47, s47, 0
	v_add_u32_e32 v243, 0x6000, v243
	ds_read_b64_tr_b16 v[156:157], v244 offset:12288
	ds_read_b64_tr_b16 v[158:159], v244 offset:14336
	s_waitcnt lgkmcnt(10)
	v_mfma_f32_32x32x16_bf16 v[224:239], v[164:167], v[136:139], v[224:239]
	v_cvt_pk_bf16_f32 v80, v80, v81
	v_cvt_pk_bf16_f32 v81, v82, v83
	v_cvt_pk_bf16_f32 v82, v84, v85
	ds_read_b64_tr_b16 v[160:161], v244 offset:512
	ds_read_b64_tr_b16 v[162:163], v244 offset:2560
	s_waitcnt lgkmcnt(11)
	v_mfma_f32_32x32x16_bf16 v[208:223], v[168:171], v[140:143], v[208:223]
	v_cvt_pk_bf16_f32 v83, v86, v87
	v_cvt_pk_bf16_f32 v84, v88, v89
	v_cvt_pk_bf16_f32 v85, v90, v91
	ds_read_b64_tr_b16 v[164:165], v244 offset:4608
	ds_read_b64_tr_b16 v[166:167], v244 offset:6656
	s_waitcnt lgkmcnt(12)
	v_mfma_f32_32x32x16_bf16 v[224:239], v[172:175], v[140:143], v[224:239]
	v_cvt_pk_bf16_f32 v86, v92, v93
	v_cvt_pk_bf16_f32 v87, v94, v95
	s_waitcnt lgkmcnt(10)
	v_mfma_f32_32x32x16_bf16 v[48:63], v[64:67], v[144:147], v[48:63]
	s_waitcnt lgkmcnt(8)
	v_mfma_f32_32x32x16_bf16 v[48:63], v[68:71], v[148:151], v[48:63]
	ds_read_b64_tr_b16 v[168:169], v244 offset:8704
	ds_read_b64_tr_b16 v[170:171], v244 offset:10752
	s_waitcnt lgkmcnt(8)
	v_mfma_f32_32x32x16_bf16 v[48:63], v[80:83], v[152:155], v[48:63]
	v_exp_f32_e32 v208, v208
	v_exp_f32_e32 v209, v209
	ds_read_b64_tr_b16 v[172:173], v244 offset:12800
	ds_read_b64_tr_b16 v[174:175], v244 offset:14848
	s_waitcnt lgkmcnt(8)
	v_mfma_f32_32x32x16_bf16 v[48:63], v[84:87], v[156:159], v[48:63]
	v_exp_f32_e32 v210, v210
	v_exp_f32_e32 v211, v211
	ds_read_b64_tr_b16 v[144:145], v244 offset:1024
	ds_read_b64_tr_b16 v[146:147], v244 offset:3072
	s_waitcnt lgkmcnt(8)
	v_mfma_f32_32x32x16_bf16 v[32:47], v[64:67], v[160:163], v[32:47]
	v_exp_f32_e32 v212, v212
	ds_read_b64_tr_b16 v[148:149], v244 offset:5120
	ds_read_b64_tr_b16 v[150:151], v244 offset:7168
	s_waitcnt lgkmcnt(8)
	v_mfma_f32_32x32x16_bf16 v[32:47], v[68:71], v[164:167], v[32:47]
	v_exp_f32_e32 v213, v213
	ds_read_b64_tr_b16 v[152:153], v244 offset:9216
	ds_read_b64_tr_b16 v[154:155], v244 offset:11264
	s_waitcnt lgkmcnt(8)
	v_mfma_f32_32x32x16_bf16 v[32:47], v[80:83], v[168:171], v[32:47]
	v_exp_f32_e32 v214, v214
	ds_read_b64_tr_b16 v[156:157], v244 offset:13312
	ds_read_b64_tr_b16 v[158:159], v244 offset:15360
	s_waitcnt lgkmcnt(8)
	v_mfma_f32_32x32x16_bf16 v[32:47], v[84:87], v[172:175], v[32:47]
	v_exp_f32_e32 v215, v215
	ds_read_b64_tr_b16 v[160:161], v244 offset:1536
	ds_read_b64_tr_b16 v[162:163], v244 offset:3584
	s_waitcnt lgkmcnt(8)
	v_mfma_f32_32x32x16_bf16 v[16:31], v[64:67], v[144:147], v[16:31]
	v_exp_f32_e32 v216, v216
	ds_read_b64_tr_b16 v[164:165], v244 offset:5632
	ds_read_b64_tr_b16 v[166:167], v244 offset:7680
	s_waitcnt lgkmcnt(8)
	v_mfma_f32_32x32x16_bf16 v[16:31], v[68:71], v[148:151], v[16:31]
	v_exp_f32_e32 v217, v217
	ds_read_b64_tr_b16 v[168:169], v244 offset:9728
	ds_read_b64_tr_b16 v[170:171], v244 offset:11776
	ds_read_b64_tr_b16 v[172:173], v244 offset:13824
	ds_read_b64_tr_b16 v[174:175], v244 offset:15872
	ds_read_b128 v[144:147], v240 offset:0
	s_waitcnt lgkmcnt(11)
	v_mfma_f32_32x32x16_bf16 v[16:31], v[80:83], v[152:155], v[16:31]
	v_exp_f32_e32 v218, v218
	v_add_u32_e32 v244, 0x4000, v244
	ds_read_b128 v[148:151], v240 offset:12288
	s_waitcnt lgkmcnt(10)
	v_mfma_f32_32x32x16_bf16 v[16:31], v[84:87], v[156:159], v[16:31]
	v_exp_f32_e32 v219, v219
	ds_read_b128 v[152:155], v241 offset:0
	s_waitcnt lgkmcnt(9)
	v_mfma_f32_32x32x16_bf16 v[0:15], v[64:67], v[160:163], v[0:15]
	v_exp_f32_e32 v220, v220
	ds_read_b128 v[156:159], v241 offset:12288
	s_waitcnt lgkmcnt(8)
	v_mfma_f32_32x32x16_bf16 v[0:15], v[68:71], v[164:167], v[0:15]
	v_exp_f32_e32 v221, v221
	ds_read_b128 v[160:163], v242 offset:0
	s_waitcnt lgkmcnt(7)
	v_mfma_f32_32x32x16_bf16 v[0:15], v[80:83], v[168:171], v[0:15]
	v_exp_f32_e32 v222, v222
	ds_read_b128 v[164:167], v242 offset:12288
	s_waitcnt lgkmcnt(6)
	v_mfma_f32_32x32x16_bf16 v[0:15], v[84:87], v[172:175], v[0:15]
	v_exp_f32_e32 v223, v223
	s_waitcnt vmcnt(5)
	s_barrier
	ds_read_b128 v[168:171], v243 offset:0
	s_waitcnt lgkmcnt(6)
	v_mfma_f32_32x32x16_bf16 v[64:79], v[144:147], v[96:99], 0
	v_exp_f32_e32 v224, v224
	v_add_f32_e32 v245, v208, v245
	v_exp_f32_e32 v225, v225
	ds_read_b128 v[172:175], v243 offset:12288
	s_waitcnt lgkmcnt(6)
	v_mfma_f32_32x32x16_bf16 v[80:95], v[148:151], v[96:99], 0
	v_add_f32_e32 v246, v209, v246
	v_exp_f32_e32 v226, v226
	v_add_f32_e32 v245, v210, v245
	ds_read_b128 v[144:147], v240 offset:128
	s_waitcnt lgkmcnt(6)
	v_mfma_f32_32x32x16_bf16 v[64:79], v[152:155], v[100:103], v[64:79]
	v_exp_f32_e32 v227, v227
	v_add_f32_e32 v246, v211, v246
	s_add_i32 m0, s60, 0xc000
	s_nop 0
	global_load_lds_dwordx4 v182, s[42:43]
	ds_read_b128 v[148:151], v240 offset:12416
	s_waitcnt lgkmcnt(6)
	v_mfma_f32_32x32x16_bf16 v[80:95], v[156:159], v[100:103], v[80:95]
	v_exp_f32_e32 v228, v228
	v_add_f32_e32 v245, v212, v245
	v_exp_f32_e32 v229, v229
	ds_read_b128 v[152:155], v241 offset:128
	s_waitcnt lgkmcnt(6)
	v_mfma_f32_32x32x16_bf16 v[64:79], v[160:163], v[104:107], v[64:79]
	v_add_f32_e32 v246, v213, v246
	v_exp_f32_e32 v230, v230
	v_add_f32_e32 v245, v214, v245
	ds_read_b128 v[156:159], v241 offset:12416
	s_waitcnt lgkmcnt(6)
	v_mfma_f32_32x32x16_bf16 v[80:95], v[164:167], v[104:107], v[80:95]
	v_exp_f32_e32 v231, v231
	v_add_f32_e32 v246, v215, v246
	s_add_i32 m0, s60, 0xc400
	s_nop 0
	global_load_lds_dwordx4 v183, s[42:43]
	ds_read_b128 v[160:163], v242 offset:128
	s_waitcnt lgkmcnt(6)
	v_mfma_f32_32x32x16_bf16 v[64:79], v[168:171], v[108:111], v[64:79]
	v_exp_f32_e32 v232, v232
	v_add_f32_e32 v245, v216, v245
	v_exp_f32_e32 v233, v233
	ds_read_b128 v[164:167], v242 offset:12416
	s_waitcnt lgkmcnt(6)
	v_mfma_f32_32x32x16_bf16 v[80:95], v[172:175], v[108:111], v[80:95]
	v_add_f32_e32 v246, v217, v246
	v_exp_f32_e32 v234, v234
	v_add_f32_e32 v245, v218, v245
	ds_read_b128 v[168:171], v243 offset:128
	s_waitcnt lgkmcnt(6)
	v_mfma_f32_32x32x16_bf16 v[64:79], v[144:147], v[112:115], v[64:79]
	v_exp_f32_e32 v235, v235
	v_add_f32_e32 v246, v219, v246
	s_add_i32 m0, s60, 0xc800
	s_nop 0
	global_load_lds_dwordx4 v184, s[42:43]
	ds_read_b128 v[172:175], v243 offset:12416
	s_waitcnt lgkmcnt(6)
	v_mfma_f32_32x32x16_bf16 v[80:95], v[148:151], v[112:115], v[80:95]
	v_exp_f32_e32 v236, v236
	v_add_f32_e32 v245, v220, v245
	v_exp_f32_e32 v237, v237
	ds_read_b128 v[144:147], v240 offset:256
	s_waitcnt lgkmcnt(6)
	v_mfma_f32_32x32x16_bf16 v[64:79], v[152:155], v[116:119], v[64:79]
	v_add_f32_e32 v246, v221, v246
	v_exp_f32_e32 v238, v238
	v_add_f32_e32 v245, v222, v245
	ds_read_b128 v[148:151], v240 offset:12544
	s_waitcnt lgkmcnt(6)
	v_mfma_f32_32x32x16_bf16 v[80:95], v[156:159], v[116:119], v[80:95]
	v_exp_f32_e32 v239, v239
	v_add_f32_e32 v246, v223, v246
	s_add_i32 m0, s61, 0x4000
	s_nop 0
	global_load_lds_dwordx4 v185, s[46:47]
	ds_read_b128 v[152:155], v241 offset:256
	s_waitcnt lgkmcnt(6)
	v_mfma_f32_32x32x16_bf16 v[64:79], v[160:163], v[120:123], v[64:79]
	v_add_f32_e32 v245, v224, v245
	v_add_f32_e32 v246, v225, v246
	v_add_f32_e32 v245, v226, v245
	ds_read_b128 v[156:159], v241 offset:12544
	s_waitcnt lgkmcnt(6)
	v_mfma_f32_32x32x16_bf16 v[80:95], v[164:167], v[120:123], v[80:95]
	v_add_f32_e32 v246, v227, v246
	v_add_f32_e32 v245, v228, v245
	v_add_f32_e32 v246, v229, v246
	ds_read_b128 v[160:163], v242 offset:256
	s_waitcnt lgkmcnt(6)
	v_mfma_f32_32x32x16_bf16 v[64:79], v[168:171], v[124:127], v[64:79]
	v_add_f32_e32 v245, v230, v245
	v_add_f32_e32 v246, v231, v246
	s_add_i32 m0, s61, 0x4400
	s_nop 0
	global_load_lds_dwordx4 v186, s[46:47]
	ds_read_b128 v[164:167], v242 offset:12544
	s_waitcnt lgkmcnt(6)
	v_mfma_f32_32x32x16_bf16 v[80:95], v[172:175], v[124:127], v[80:95]
	v_add_f32_e32 v245, v232, v245
	v_add_f32_e32 v246, v233, v246
	v_add_f32_e32 v245, v234, v245
	ds_read_b128 v[168:171], v243 offset:256
	s_waitcnt lgkmcnt(6)
	v_mfma_f32_32x32x16_bf16 v[64:79], v[144:147], v[128:131], v[64:79]
	v_add_f32_e32 v246, v235, v246
	v_add_f32_e32 v245, v236, v245
	v_add_f32_e32 v246, v237, v246
	ds_read_b128 v[172:175], v243 offset:12544
	s_waitcnt lgkmcnt(6)
	v_mfma_f32_32x32x16_bf16 v[80:95], v[148:151], v[128:131], v[80:95]
	v_add_f32_e32 v245, v238, v245
	v_add_f32_e32 v246, v239, v246
	s_add_u32 s42, s42, 0x6000
	s_addc_u32 s43, s43, 0
	v_add_u32_e32 v240, 0x6000, v240
	ds_read_b64_tr_b16 v[144:145], v244 offset:0
	ds_read_b64_tr_b16 v[146:147], v244 offset:2048
	s_waitcnt lgkmcnt(7)
	v_mfma_f32_32x32x16_bf16 v[64:79], v[152:155], v[132:135], v[64:79]
	v_cvt_pk_bf16_f32 v208, v208, v209
	v_cvt_pk_bf16_f32 v209, v210, v211
	v_cvt_pk_bf16_f32 v210, v212, v213
	v_add_u32_e32 v241, 0x6000, v241
	ds_read_b64_tr_b16 v[148:149], v244 offset:4096
	ds_read_b64_tr_b16 v[150:151], v244 offset:6144
	s_waitcnt lgkmcnt(8)
	v_mfma_f32_32x32x16_bf16 v[80:95], v[156:159], v[132:135], v[80:95]
	v_cvt_pk_bf16_f32 v211, v214, v215
	v_cvt_pk_bf16_f32 v212, v216, v217
	v_cvt_pk_bf16_f32 v213, v218, v219
	v_add_u32_e32 v242, 0x6000, v242
	ds_read_b64_tr_b16 v[152:153], v244 offset:8192
	ds_read_b64_tr_b16 v[154:155], v244 offset:10240
	s_waitcnt lgkmcnt(9)
	v_mfma_f32_32x32x16_bf16 v[64:79], v[160:163], v[136:139], v[64:79]
	v_cvt_pk_bf16_f32 v214, v220, v221
	v_cvt_pk_bf16_f32 v215, v222, v223
	s_add_u32 s46, s46, 0x40000
	s_addc_u32 s47, s47, 0
	v_add_u32_e32 v243, 0x6000, v243
	ds_read_b64_tr_b16 v[156:157], v244 offset:12288
	ds_read_b64_tr_b16 v[158:159], v244 offset:14336
	s_waitcnt lgkmcnt(10)
	v_mfma_f32_32x32x16_bf16 v[80:95], v[164:167], v[136:139], v[80:95]
	v_cvt_pk_bf16_f32 v224, v224, v225
	v_cvt_pk_bf16_f32 v225, v226, v227
	v_cvt_pk_bf16_f32 v226, v228, v229
	ds_read_b64_tr_b16 v[160:161], v244 offset:512
	ds_read_b64_tr_b16 v[162:163], v244 offset:2560
	s_waitcnt lgkmcnt(11)
	v_mfma_f32_32x32x16_bf16 v[64:79], v[168:171], v[140:143], v[64:79]
	v_cvt_pk_bf16_f32 v227, v230, v231
	v_cvt_pk_bf16_f32 v228, v232, v233
	v_cvt_pk_bf16_f32 v229, v234, v235
	ds_read_b64_tr_b16 v[164:165], v244 offset:4608
	ds_read_b64_tr_b16 v[166:167], v244 offset:6656
	s_waitcnt lgkmcnt(12)
	v_mfma_f32_32x32x16_bf16 v[80:95], v[172:175], v[140:143], v[80:95]
	v_cvt_pk_bf16_f32 v230, v236, v237
	v_cvt_pk_bf16_f32 v231, v238, v239
	s_waitcnt lgkmcnt(10)
	v_mfma_f32_32x32x16_bf16 v[48:63], v[208:211], v[144:147], v[48:63]
	s_waitcnt lgkmcnt(8)
	v_mfma_f32_32x32x16_bf16 v[48:63], v[212:215], v[148:151], v[48:63]
	ds_read_b64_tr_b16 v[168:169], v244 offset:8704
	ds_read_b64_tr_b16 v[170:171], v244 offset:10752
	s_waitcnt lgkmcnt(8)
	v_mfma_f32_32x32x16_bf16 v[48:63], v[224:227], v[152:155], v[48:63]
	v_exp_f32_e32 v64, v64
	v_exp_f32_e32 v65, v65
	ds_read_b64_tr_b16 v[172:173], v244 offset:12800
	ds_read_b64_tr_b16 v[174:175], v244 offset:14848
	s_waitcnt lgkmcnt(8)
	v_mfma_f32_32x32x16_bf16 v[48:63], v[228:231], v[156:159], v[48:63]
	v_exp_f32_e32 v66, v66
	v_exp_f32_e32 v67, v67
	ds_read_b64_tr_b16 v[144:145], v244 offset:1024
	ds_read_b64_tr_b16 v[146:147], v244 offset:3072
	s_waitcnt lgkmcnt(8)
	v_mfma_f32_32x32x16_bf16 v[32:47], v[208:211], v[160:163], v[32:47]
	v_exp_f32_e32 v68, v68
	ds_read_b64_tr_b16 v[148:149], v244 offset:5120
	ds_read_b64_tr_b16 v[150:151], v244 offset:7168
	s_waitcnt lgkmcnt(8)
	v_mfma_f32_32x32x16_bf16 v[32:47], v[212:215], v[164:167], v[32:47]
	v_exp_f32_e32 v69, v69
	ds_read_b64_tr_b16 v[152:153], v244 offset:9216
	ds_read_b64_tr_b16 v[154:155], v244 offset:11264
	s_waitcnt lgkmcnt(8)
	v_mfma_f32_32x32x16_bf16 v[32:47], v[224:227], v[168:171], v[32:47]
	v_exp_f32_e32 v70, v70
	ds_read_b64_tr_b16 v[156:157], v244 offset:13312
	ds_read_b64_tr_b16 v[158:159], v244 offset:15360
	s_waitcnt lgkmcnt(8)
	v_mfma_f32_32x32x16_bf16 v[32:47], v[228:231], v[172:175], v[32:47]
	v_exp_f32_e32 v71, v71
	ds_read_b64_tr_b16 v[160:161], v244 offset:1536
	ds_read_b64_tr_b16 v[162:163], v244 offset:3584
	s_waitcnt lgkmcnt(8)
	v_mfma_f32_32x32x16_bf16 v[16:31], v[208:211], v[144:147], v[16:31]
	v_exp_f32_e32 v72, v72
	ds_read_b64_tr_b16 v[164:165], v244 offset:5632
	ds_read_b64_tr_b16 v[166:167], v244 offset:7680
	s_waitcnt lgkmcnt(8)
	v_mfma_f32_32x32x16_bf16 v[16:31], v[212:215], v[148:151], v[16:31]
	v_exp_f32_e32 v73, v73
	ds_read_b64_tr_b16 v[168:169], v244 offset:9728
	ds_read_b64_tr_b16 v[170:171], v244 offset:11776
	ds_read_b64_tr_b16 v[172:173], v244 offset:13824
	ds_read_b64_tr_b16 v[174:175], v244 offset:15872
	ds_read_b128 v[144:147], v240 offset:0
	s_waitcnt lgkmcnt(11)
	v_mfma_f32_32x32x16_bf16 v[16:31], v[224:227], v[152:155], v[16:31]
	v_exp_f32_e32 v74, v74
	v_add_u32_e32 v244, 0xffff8000, v244
	ds_read_b128 v[148:151], v240 offset:12288
	s_waitcnt lgkmcnt(10)
	v_mfma_f32_32x32x16_bf16 v[16:31], v[228:231], v[156:159], v[16:31]
	v_exp_f32_e32 v75, v75
	ds_read_b128 v[152:155], v241 offset:0
	s_waitcnt lgkmcnt(9)
	v_mfma_f32_32x32x16_bf16 v[0:15], v[208:211], v[160:163], v[0:15]
	v_exp_f32_e32 v76, v76
	ds_read_b128 v[156:159], v241 offset:12288
	s_waitcnt lgkmcnt(8)
	v_mfma_f32_32x32x16_bf16 v[0:15], v[212:215], v[164:167], v[0:15]
	v_exp_f32_e32 v77, v77
	ds_read_b128 v[160:163], v242 offset:0
	s_waitcnt lgkmcnt(7)
	v_mfma_f32_32x32x16_bf16 v[0:15], v[224:227], v[168:171], v[0:15]
	v_exp_f32_e32 v78, v78
	ds_read_b128 v[164:167], v242 offset:12288
	s_waitcnt lgkmcnt(6)
	v_mfma_f32_32x32x16_bf16 v[0:15], v[228:231], v[172:175], v[0:15]
	v_exp_f32_e32 v79, v79
	s_waitcnt vmcnt(5)
	s_barrier
	ds_read_b128 v[168:171], v243 offset:0
	s_waitcnt lgkmcnt(6)
	v_mfma_f32_32x32x16_bf16 v[208:223], v[144:147], v[96:99], 0
	v_exp_f32_e32 v80, v80
	v_add_f32_e32 v245, v64, v245
	v_exp_f32_e32 v81, v81
	ds_read_b128 v[172:175], v243 offset:12288
	s_waitcnt lgkmcnt(6)
	v_mfma_f32_32x32x16_bf16 v[224:239], v[148:151], v[96:99], 0
	v_add_f32_e32 v246, v65, v246
	v_exp_f32_e32 v82, v82
	v_add_f32_e32 v245, v66, v245
	ds_read_b128 v[144:147], v240 offset:128
	s_waitcnt lgkmcnt(6)
	v_mfma_f32_32x32x16_bf16 v[208:223], v[152:155], v[100:103], v[208:223]
	v_exp_f32_e32 v83, v83
	v_add_f32_e32 v246, v67, v246
	s_add_i32 m0, s60, 0x12000
	s_nop 0
	global_load_lds_dwordx4 v182, s[42:43]
	ds_read_b128 v[148:151], v240 offset:12416
	s_waitcnt lgkmcnt(6)
	v_mfma_f32_32x32x16_bf16 v[224:239], v[156:159], v[100:103], v[224:239]
	v_exp_f32_e32 v84, v84
	v_add_f32_e32 v245, v68, v245
	v_exp_f32_e32 v85, v85
	ds_read_b128 v[152:155], v241 offset:128
	s_waitcnt lgkmcnt(6)
	v_mfma_f32_32x32x16_bf16 v[208:223], v[160:163], v[104:107], v[208:223]
	v_add_f32_e32 v246, v69, v246
	v_exp_f32_e32 v86, v86
	v_add_f32_e32 v245, v70, v245
	ds_read_b128 v[156:159], v241 offset:12416
	s_waitcnt lgkmcnt(6)
	v_mfma_f32_32x32x16_bf16 v[224:239], v[164:167], v[104:107], v[224:239]
	v_exp_f32_e32 v87, v87
	v_add_f32_e32 v246, v71, v246
	s_add_i32 m0, s60, 0x12400
	s_nop 0
	global_load_lds_dwordx4 v183, s[42:43]
	ds_read_b128 v[160:163], v242 offset:128
	s_waitcnt lgkmcnt(6)
	v_mfma_f32_32x32x16_bf16 v[208:223], v[168:171], v[108:111], v[208:223]
	v_exp_f32_e32 v88, v88
	v_add_f32_e32 v245, v72, v245
	v_exp_f32_e32 v89, v89
	ds_read_b128 v[164:167], v242 offset:12416
	s_waitcnt lgkmcnt(6)
	v_mfma_f32_32x32x16_bf16 v[224:239], v[172:175], v[108:111], v[224:239]
	v_add_f32_e32 v246, v73, v246
	v_exp_f32_e32 v90, v90
	v_add_f32_e32 v245, v74, v245
	ds_read_b128 v[168:171], v243 offset:128
	s_waitcnt lgkmcnt(6)
	v_mfma_f32_32x32x16_bf16 v[208:223], v[144:147], v[112:115], v[208:223]
	v_exp_f32_e32 v91, v91
	v_add_f32_e32 v246, v75, v246
	s_add_i32 m0, s60, 0x12800
	s_nop 0
	global_load_lds_dwordx4 v184, s[42:43]
	ds_read_b128 v[172:175], v243 offset:12416
	s_waitcnt lgkmcnt(6)
	v_mfma_f32_32x32x16_bf16 v[224:239], v[148:151], v[112:115], v[224:239]
	v_exp_f32_e32 v92, v92
	v_add_f32_e32 v245, v76, v245
	v_exp_f32_e32 v93, v93
	ds_read_b128 v[144:147], v240 offset:256
	s_waitcnt lgkmcnt(6)
	v_mfma_f32_32x32x16_bf16 v[208:223], v[152:155], v[116:119], v[208:223]
	v_add_f32_e32 v246, v77, v246
	v_exp_f32_e32 v94, v94
	v_add_f32_e32 v245, v78, v245
	ds_read_b128 v[148:151], v240 offset:12544
	s_waitcnt lgkmcnt(6)
	v_mfma_f32_32x32x16_bf16 v[224:239], v[156:159], v[116:119], v[224:239]
	v_exp_f32_e32 v95, v95
	v_add_f32_e32 v246, v79, v246
	s_add_i32 m0, s61, 0x8000
	s_nop 0
	global_load_lds_dwordx4 v185, s[46:47]
	ds_read_b128 v[152:155], v241 offset:256
	s_waitcnt lgkmcnt(6)
	v_mfma_f32_32x32x16_bf16 v[208:223], v[160:163], v[120:123], v[208:223]
	v_add_f32_e32 v245, v80, v245
	v_add_f32_e32 v246, v81, v246
	v_add_f32_e32 v245, v82, v245
	ds_read_b128 v[156:159], v241 offset:12544
	s_waitcnt lgkmcnt(6)
	v_mfma_f32_32x32x16_bf16 v[224:239], v[164:167], v[120:123], v[224:239]
	v_add_f32_e32 v246, v83, v246
	v_add_f32_e32 v245, v84, v245
	v_add_f32_e32 v246, v85, v246
	ds_read_b128 v[160:163], v242 offset:256
	s_waitcnt lgkmcnt(6)
	v_mfma_f32_32x32x16_bf16 v[208:223], v[168:171], v[124:127], v[208:223]
	v_add_f32_e32 v245, v86, v245
	v_add_f32_e32 v246, v87, v246
	s_add_i32 m0, s61, 0x8400
	s_nop 0
	global_load_lds_dwordx4 v186, s[46:47]
	ds_read_b128 v[164:167], v242 offset:12544
	s_waitcnt lgkmcnt(6)
	v_mfma_f32_32x32x16_bf16 v[224:239], v[172:175], v[124:127], v[224:239]
	v_add_f32_e32 v245, v88, v245
	v_add_f32_e32 v246, v89, v246
	v_add_f32_e32 v245, v90, v245
	ds_read_b128 v[168:171], v243 offset:256
	s_waitcnt lgkmcnt(6)
	v_mfma_f32_32x32x16_bf16 v[208:223], v[144:147], v[128:131], v[208:223]
	v_add_f32_e32 v246, v91, v246
	v_add_f32_e32 v245, v92, v245
	v_add_f32_e32 v246, v93, v246
	ds_read_b128 v[172:175], v243 offset:12544
	s_waitcnt lgkmcnt(6)
	v_mfma_f32_32x32x16_bf16 v[224:239], v[148:151], v[128:131], v[224:239]
	v_add_f32_e32 v245, v94, v245
	v_add_f32_e32 v246, v95, v246
	s_add_u32 s42, s42, 0x6000
	s_addc_u32 s43, s43, 0
	v_add_u32_e32 v240, 0x9010, v240
	ds_read_b64_tr_b16 v[144:145], v244 offset:0
	ds_read_b64_tr_b16 v[146:147], v244 offset:2048
	s_waitcnt lgkmcnt(7)
	v_mfma_f32_32x32x16_bf16 v[208:223], v[152:155], v[132:135], v[208:223]
	v_cvt_pk_bf16_f32 v64, v64, v65
	v_cvt_pk_bf16_f32 v65, v66, v67
	v_cvt_pk_bf16_f32 v66, v68, v69
	v_add_u32_e32 v241, 0x9010, v241
	ds_read_b64_tr_b16 v[148:149], v244 offset:4096
	ds_read_b64_tr_b16 v[150:151], v244 offset:6144
	s_waitcnt lgkmcnt(8)
	v_mfma_f32_32x32x16_bf16 v[224:239], v[156:159], v[132:135], v[224:239]
	v_cvt_pk_bf16_f32 v67, v70, v71
	v_cvt_pk_bf16_f32 v68, v72, v73
	v_cvt_pk_bf16_f32 v69, v74, v75
	v_add_u32_e32 v242, 0x9010, v242
	ds_read_b64_tr_b16 v[152:153], v244 offset:8192
	ds_read_b64_tr_b16 v[154:155], v244 offset:10240
	s_waitcnt lgkmcnt(9)
	v_mfma_f32_32x32x16_bf16 v[208:223], v[160:163], v[136:139], v[208:223]
	v_cvt_pk_bf16_f32 v70, v76, v77
	v_cvt_pk_bf16_f32 v71, v78, v79
	s_add_u32 s46, s46, 0x40000
	s_addc_u32 s47, s47, 0
	v_add_u32_e32 v243, 0x9010, v243
	ds_read_b64_tr_b16 v[156:157], v244 offset:12288
	ds_read_b64_tr_b16 v[158:159], v244 offset:14336
	s_waitcnt lgkmcnt(10)
	v_mfma_f32_32x32x16_bf16 v[224:239], v[164:167], v[136:139], v[224:239]
	v_cvt_pk_bf16_f32 v80, v80, v81
	v_cvt_pk_bf16_f32 v81, v82, v83
	v_cvt_pk_bf16_f32 v82, v84, v85
	ds_read_b64_tr_b16 v[160:161], v244 offset:512
	ds_read_b64_tr_b16 v[162:163], v244 offset:2560
	s_waitcnt lgkmcnt(11)
	v_mfma_f32_32x32x16_bf16 v[208:223], v[168:171], v[140:143], v[208:223]
	v_cvt_pk_bf16_f32 v83, v86, v87
	v_cvt_pk_bf16_f32 v84, v88, v89
	v_cvt_pk_bf16_f32 v85, v90, v91
	ds_read_b64_tr_b16 v[164:165], v244 offset:4608
	ds_read_b64_tr_b16 v[166:167], v244 offset:6656
	s_waitcnt lgkmcnt(12)
	v_mfma_f32_32x32x16_bf16 v[224:239], v[172:175], v[140:143], v[224:239]
	v_cvt_pk_bf16_f32 v86, v92, v93
	v_cvt_pk_bf16_f32 v87, v94, v95
	s_waitcnt lgkmcnt(10)
	v_mfma_f32_32x32x16_bf16 v[48:63], v[64:67], v[144:147], v[48:63]
	s_waitcnt lgkmcnt(8)
	v_mfma_f32_32x32x16_bf16 v[48:63], v[68:71], v[148:151], v[48:63]
	ds_read_b64_tr_b16 v[168:169], v244 offset:8704
	ds_read_b64_tr_b16 v[170:171], v244 offset:10752
	s_waitcnt lgkmcnt(8)
	v_mfma_f32_32x32x16_bf16 v[48:63], v[80:83], v[152:155], v[48:63]
	v_exp_f32_e32 v208, v208
	v_exp_f32_e32 v209, v209
	ds_read_b64_tr_b16 v[172:173], v244 offset:12800
	ds_read_b64_tr_b16 v[174:175], v244 offset:14848
	s_waitcnt lgkmcnt(8)
	v_mfma_f32_32x32x16_bf16 v[48:63], v[84:87], v[156:159], v[48:63]
	v_exp_f32_e32 v210, v210
	v_exp_f32_e32 v211, v211
	ds_read_b64_tr_b16 v[144:145], v244 offset:1024
	ds_read_b64_tr_b16 v[146:147], v244 offset:3072
	s_waitcnt lgkmcnt(8)
	v_mfma_f32_32x32x16_bf16 v[32:47], v[64:67], v[160:163], v[32:47]
	v_exp_f32_e32 v212, v212
	ds_read_b64_tr_b16 v[148:149], v244 offset:5120
	ds_read_b64_tr_b16 v[150:151], v244 offset:7168
	s_waitcnt lgkmcnt(8)
	v_mfma_f32_32x32x16_bf16 v[32:47], v[68:71], v[164:167], v[32:47]
	v_exp_f32_e32 v213, v213
	ds_read_b64_tr_b16 v[152:153], v244 offset:9216
	ds_read_b64_tr_b16 v[154:155], v244 offset:11264
	s_waitcnt lgkmcnt(8)
	v_mfma_f32_32x32x16_bf16 v[32:47], v[80:83], v[168:171], v[32:47]
	v_exp_f32_e32 v214, v214
	ds_read_b64_tr_b16 v[156:157], v244 offset:13312
	ds_read_b64_tr_b16 v[158:159], v244 offset:15360
	s_waitcnt lgkmcnt(8)
	v_mfma_f32_32x32x16_bf16 v[32:47], v[84:87], v[172:175], v[32:47]
	v_exp_f32_e32 v215, v215
	ds_read_b64_tr_b16 v[160:161], v244 offset:1536
	ds_read_b64_tr_b16 v[162:163], v244 offset:3584
	s_waitcnt lgkmcnt(8)
	v_mfma_f32_32x32x16_bf16 v[16:31], v[64:67], v[144:147], v[16:31]
	v_exp_f32_e32 v216, v216
	ds_read_b64_tr_b16 v[164:165], v244 offset:5632
	ds_read_b64_tr_b16 v[166:167], v244 offset:7680
	s_waitcnt lgkmcnt(8)
	v_mfma_f32_32x32x16_bf16 v[16:31], v[68:71], v[148:151], v[16:31]
	v_exp_f32_e32 v217, v217
	ds_read_b64_tr_b16 v[168:169], v244 offset:9728
	ds_read_b64_tr_b16 v[170:171], v244 offset:11776
	ds_read_b64_tr_b16 v[172:173], v244 offset:13824
	ds_read_b64_tr_b16 v[174:175], v244 offset:15872
	ds_read_b128 v[144:147], v240 offset:0
	s_waitcnt lgkmcnt(11)
	v_mfma_f32_32x32x16_bf16 v[16:31], v[80:83], v[152:155], v[16:31]
	v_exp_f32_e32 v218, v218
	v_add_u32_e32 v244, 0x4000, v244
	ds_read_b128 v[148:151], v240 offset:12288
	s_waitcnt lgkmcnt(10)
	v_mfma_f32_32x32x16_bf16 v[16:31], v[84:87], v[156:159], v[16:31]
	v_exp_f32_e32 v219, v219
	ds_read_b128 v[152:155], v241 offset:0
	s_waitcnt lgkmcnt(9)
	v_mfma_f32_32x32x16_bf16 v[0:15], v[64:67], v[160:163], v[0:15]
	v_exp_f32_e32 v220, v220
	ds_read_b128 v[156:159], v241 offset:12288
	s_waitcnt lgkmcnt(8)
	v_mfma_f32_32x32x16_bf16 v[0:15], v[68:71], v[164:167], v[0:15]
	v_exp_f32_e32 v221, v221
	ds_read_b128 v[160:163], v242 offset:0
	s_waitcnt lgkmcnt(7)
	v_mfma_f32_32x32x16_bf16 v[0:15], v[80:83], v[168:171], v[0:15]
	v_exp_f32_e32 v222, v222
	ds_read_b128 v[164:167], v242 offset:12288
	s_waitcnt lgkmcnt(6)
	v_mfma_f32_32x32x16_bf16 v[0:15], v[84:87], v[172:175], v[0:15]
	v_exp_f32_e32 v223, v223
	s_waitcnt vmcnt(5)
	s_barrier
	ds_read_b128 v[168:171], v243 offset:0
	s_waitcnt lgkmcnt(6)
	v_mfma_f32_32x32x16_bf16 v[64:79], v[144:147], v[96:99], 0
	v_exp_f32_e32 v224, v224
	v_add_f32_e32 v245, v208, v245
	v_exp_f32_e32 v225, v225
	ds_read_b128 v[172:175], v243 offset:12288
	s_waitcnt lgkmcnt(6)
	v_mfma_f32_32x32x16_bf16 v[80:95], v[148:151], v[96:99], 0
	v_add_f32_e32 v246, v209, v246
	v_exp_f32_e32 v226, v226
	v_add_f32_e32 v245, v210, v245
	ds_read_b128 v[144:147], v240 offset:128
	s_waitcnt lgkmcnt(6)
	v_mfma_f32_32x32x16_bf16 v[64:79], v[152:155], v[100:103], v[64:79]
	v_exp_f32_e32 v227, v227
	v_add_f32_e32 v246, v211, v246
	s_add_i32 m0, s60, 0x18000
	s_nop 0
	global_load_lds_dwordx4 v182, s[42:43]
	ds_read_b128 v[148:151], v240 offset:12416
	s_waitcnt lgkmcnt(6)
	v_mfma_f32_32x32x16_bf16 v[80:95], v[156:159], v[100:103], v[80:95]
	v_exp_f32_e32 v228, v228
	v_add_f32_e32 v245, v212, v245
	v_exp_f32_e32 v229, v229
	ds_read_b128 v[152:155], v241 offset:128
	s_waitcnt lgkmcnt(6)
	v_mfma_f32_32x32x16_bf16 v[64:79], v[160:163], v[104:107], v[64:79]
	v_add_f32_e32 v246, v213, v246
	v_exp_f32_e32 v230, v230
	v_add_f32_e32 v245, v214, v245
	ds_read_b128 v[156:159], v241 offset:12416
	s_waitcnt lgkmcnt(6)
	v_mfma_f32_32x32x16_bf16 v[80:95], v[164:167], v[104:107], v[80:95]
	v_exp_f32_e32 v231, v231
	v_add_f32_e32 v246, v215, v246
	s_add_i32 m0, s60, 0x18400
	s_nop 0
	global_load_lds_dwordx4 v183, s[42:43]
	ds_read_b128 v[160:163], v242 offset:128
	s_waitcnt lgkmcnt(6)
	v_mfma_f32_32x32x16_bf16 v[64:79], v[168:171], v[108:111], v[64:79]
	v_exp_f32_e32 v232, v232
	v_add_f32_e32 v245, v216, v245
	v_exp_f32_e32 v233, v233
	ds_read_b128 v[164:167], v242 offset:12416
	s_waitcnt lgkmcnt(6)
	v_mfma_f32_32x32x16_bf16 v[80:95], v[172:175], v[108:111], v[80:95]
	v_add_f32_e32 v246, v217, v246
	v_exp_f32_e32 v234, v234
	v_add_f32_e32 v245, v218, v245
	ds_read_b128 v[168:171], v243 offset:128
	s_waitcnt lgkmcnt(6)
	v_mfma_f32_32x32x16_bf16 v[64:79], v[144:147], v[112:115], v[64:79]
	v_exp_f32_e32 v235, v235
	v_add_f32_e32 v246, v219, v246
	s_add_i32 m0, s60, 0x18800
	s_nop 0
	global_load_lds_dwordx4 v184, s[42:43]
	ds_read_b128 v[172:175], v243 offset:12416
	s_waitcnt lgkmcnt(6)
	v_mfma_f32_32x32x16_bf16 v[80:95], v[148:151], v[112:115], v[80:95]
	v_exp_f32_e32 v236, v236
	v_add_f32_e32 v245, v220, v245
	v_exp_f32_e32 v237, v237
	ds_read_b128 v[144:147], v240 offset:256
	s_waitcnt lgkmcnt(6)
	v_mfma_f32_32x32x16_bf16 v[64:79], v[152:155], v[116:119], v[64:79]
	v_add_f32_e32 v246, v221, v246
	v_exp_f32_e32 v238, v238
	v_add_f32_e32 v245, v222, v245
	ds_read_b128 v[148:151], v240 offset:12544
	s_waitcnt lgkmcnt(6)
	v_mfma_f32_32x32x16_bf16 v[80:95], v[156:159], v[116:119], v[80:95]
	v_exp_f32_e32 v239, v239
	v_add_f32_e32 v246, v223, v246
	s_add_i32 m0, s61, 0x0
	s_nop 0
	global_load_lds_dwordx4 v185, s[46:47]
	ds_read_b128 v[152:155], v241 offset:256
	s_waitcnt lgkmcnt(6)
	v_mfma_f32_32x32x16_bf16 v[64:79], v[160:163], v[120:123], v[64:79]
	v_add_f32_e32 v245, v224, v245
	v_add_f32_e32 v246, v225, v246
	v_add_f32_e32 v245, v226, v245
	ds_read_b128 v[156:159], v241 offset:12544
	s_waitcnt lgkmcnt(6)
	v_mfma_f32_32x32x16_bf16 v[80:95], v[164:167], v[120:123], v[80:95]
	v_add_f32_e32 v246, v227, v246
	v_add_f32_e32 v245, v228, v245
	v_add_f32_e32 v246, v229, v246
	ds_read_b128 v[160:163], v242 offset:256
	s_waitcnt lgkmcnt(6)
	v_mfma_f32_32x32x16_bf16 v[64:79], v[168:171], v[124:127], v[64:79]
	v_add_f32_e32 v245, v230, v245
	v_add_f32_e32 v246, v231, v246
	s_add_i32 m0, s61, 0x400
	s_nop 0
	global_load_lds_dwordx4 v186, s[46:47]
	ds_read_b128 v[164:167], v242 offset:12544
	s_waitcnt lgkmcnt(6)
	v_mfma_f32_32x32x16_bf16 v[80:95], v[172:175], v[124:127], v[80:95]
	v_add_f32_e32 v245, v232, v245
	v_add_f32_e32 v246, v233, v246
	v_add_f32_e32 v245, v234, v245
	ds_read_b128 v[168:171], v243 offset:256
	s_waitcnt lgkmcnt(6)
	v_mfma_f32_32x32x16_bf16 v[64:79], v[144:147], v[128:131], v[64:79]
	v_add_f32_e32 v246, v235, v246
	v_add_f32_e32 v245, v236, v245
	v_add_f32_e32 v246, v237, v246
	ds_read_b128 v[172:175], v243 offset:12544
	s_waitcnt lgkmcnt(6)
	v_mfma_f32_32x32x16_bf16 v[80:95], v[148:151], v[128:131], v[80:95]
	v_add_f32_e32 v245, v238, v245
	v_add_f32_e32 v246, v239, v246
	s_add_u32 s42, s42, 0x6000
	s_addc_u32 s43, s43, 0
	v_add_u32_e32 v240, 0xfffeaff0, v240
	ds_read_b64_tr_b16 v[144:145], v244 offset:0
	ds_read_b64_tr_b16 v[146:147], v244 offset:2048
	s_waitcnt lgkmcnt(7)
	v_mfma_f32_32x32x16_bf16 v[64:79], v[152:155], v[132:135], v[64:79]
	v_cvt_pk_bf16_f32 v208, v208, v209
	v_cvt_pk_bf16_f32 v209, v210, v211
	v_cvt_pk_bf16_f32 v210, v212, v213
	v_add_u32_e32 v241, 0xfffeaff0, v241
	ds_read_b64_tr_b16 v[148:149], v244 offset:4096
	ds_read_b64_tr_b16 v[150:151], v244 offset:6144
	s_waitcnt lgkmcnt(8)
	v_mfma_f32_32x32x16_bf16 v[80:95], v[156:159], v[132:135], v[80:95]
	v_cvt_pk_bf16_f32 v211, v214, v215
	v_cvt_pk_bf16_f32 v212, v216, v217
	v_cvt_pk_bf16_f32 v213, v218, v219
	v_add_u32_e32 v242, 0xfffeaff0, v242
	ds_read_b64_tr_b16 v[152:153], v244 offset:8192
	ds_read_b64_tr_b16 v[154:155], v244 offset:10240
	s_waitcnt lgkmcnt(9)
	v_mfma_f32_32x32x16_bf16 v[64:79], v[160:163], v[136:139], v[64:79]
	v_cvt_pk_bf16_f32 v214, v220, v221
	v_cvt_pk_bf16_f32 v215, v222, v223
	s_add_u32 s46, s46, 0x40000
	s_addc_u32 s47, s47, 0
	v_add_u32_e32 v243, 0xfffeaff0, v243
	ds_read_b64_tr_b16 v[156:157], v244 offset:12288
	ds_read_b64_tr_b16 v[158:159], v244 offset:14336
	s_waitcnt lgkmcnt(10)
	v_mfma_f32_32x32x16_bf16 v[80:95], v[164:167], v[136:139], v[80:95]
	v_cvt_pk_bf16_f32 v224, v224, v225
	v_cvt_pk_bf16_f32 v225, v226, v227
	v_cvt_pk_bf16_f32 v226, v228, v229
	ds_read_b64_tr_b16 v[160:161], v244 offset:512
	ds_read_b64_tr_b16 v[162:163], v244 offset:2560
	s_waitcnt lgkmcnt(11)
	v_mfma_f32_32x32x16_bf16 v[64:79], v[168:171], v[140:143], v[64:79]
	v_cvt_pk_bf16_f32 v227, v230, v231
	v_cvt_pk_bf16_f32 v228, v232, v233
	v_cvt_pk_bf16_f32 v229, v234, v235
	ds_read_b64_tr_b16 v[164:165], v244 offset:4608
	ds_read_b64_tr_b16 v[166:167], v244 offset:6656
	s_waitcnt lgkmcnt(12)
	v_mfma_f32_32x32x16_bf16 v[80:95], v[172:175], v[140:143], v[80:95]
	v_cvt_pk_bf16_f32 v230, v236, v237
	v_cvt_pk_bf16_f32 v231, v238, v239
	s_waitcnt lgkmcnt(10)
	v_mfma_f32_32x32x16_bf16 v[48:63], v[208:211], v[144:147], v[48:63]
	s_waitcnt lgkmcnt(8)
	v_mfma_f32_32x32x16_bf16 v[48:63], v[212:215], v[148:151], v[48:63]
	ds_read_b64_tr_b16 v[168:169], v244 offset:8704
	ds_read_b64_tr_b16 v[170:171], v244 offset:10752
	s_waitcnt lgkmcnt(8)
	v_mfma_f32_32x32x16_bf16 v[48:63], v[224:227], v[152:155], v[48:63]
	v_exp_f32_e32 v64, v64
	v_exp_f32_e32 v65, v65
	ds_read_b64_tr_b16 v[172:173], v244 offset:12800
	ds_read_b64_tr_b16 v[174:175], v244 offset:14848
	s_waitcnt lgkmcnt(8)
	v_mfma_f32_32x32x16_bf16 v[48:63], v[228:231], v[156:159], v[48:63]
	v_exp_f32_e32 v66, v66
	v_exp_f32_e32 v67, v67
	ds_read_b64_tr_b16 v[144:145], v244 offset:1024
	ds_read_b64_tr_b16 v[146:147], v244 offset:3072
	s_waitcnt lgkmcnt(8)
	v_mfma_f32_32x32x16_bf16 v[32:47], v[208:211], v[160:163], v[32:47]
	v_exp_f32_e32 v68, v68
	ds_read_b64_tr_b16 v[148:149], v244 offset:5120
	ds_read_b64_tr_b16 v[150:151], v244 offset:7168
	s_waitcnt lgkmcnt(8)
	v_mfma_f32_32x32x16_bf16 v[32:47], v[212:215], v[164:167], v[32:47]
	v_exp_f32_e32 v69, v69
	ds_read_b64_tr_b16 v[152:153], v244 offset:9216
	ds_read_b64_tr_b16 v[154:155], v244 offset:11264
	s_waitcnt lgkmcnt(8)
	v_mfma_f32_32x32x16_bf16 v[32:47], v[224:227], v[168:171], v[32:47]
	v_exp_f32_e32 v70, v70
	ds_read_b64_tr_b16 v[156:157], v244 offset:13312
	ds_read_b64_tr_b16 v[158:159], v244 offset:15360
	s_waitcnt lgkmcnt(8)
	v_mfma_f32_32x32x16_bf16 v[32:47], v[228:231], v[172:175], v[32:47]
	v_exp_f32_e32 v71, v71
	ds_read_b64_tr_b16 v[160:161], v244 offset:1536
	ds_read_b64_tr_b16 v[162:163], v244 offset:3584
	s_waitcnt lgkmcnt(8)
	v_mfma_f32_32x32x16_bf16 v[16:31], v[208:211], v[144:147], v[16:31]
	v_exp_f32_e32 v72, v72
	ds_read_b64_tr_b16 v[164:165], v244 offset:5632
	ds_read_b64_tr_b16 v[166:167], v244 offset:7680
	s_waitcnt lgkmcnt(8)
	v_mfma_f32_32x32x16_bf16 v[16:31], v[212:215], v[148:151], v[16:31]
	v_exp_f32_e32 v73, v73
	ds_read_b64_tr_b16 v[168:169], v244 offset:9728
	ds_read_b64_tr_b16 v[170:171], v244 offset:11776
	ds_read_b64_tr_b16 v[172:173], v244 offset:13824
	ds_read_b64_tr_b16 v[174:175], v244 offset:15872
	ds_read_b128 v[144:147], v240 offset:0
	s_waitcnt lgkmcnt(11)
	v_mfma_f32_32x32x16_bf16 v[16:31], v[224:227], v[152:155], v[16:31]
	v_exp_f32_e32 v74, v74
	v_add_u32_e32 v244, 0x4000, v244
	ds_read_b128 v[148:151], v240 offset:12288
	s_waitcnt lgkmcnt(10)
	v_mfma_f32_32x32x16_bf16 v[16:31], v[228:231], v[156:159], v[16:31]
	v_exp_f32_e32 v75, v75
	ds_read_b128 v[152:155], v241 offset:0
	s_waitcnt lgkmcnt(9)
	v_mfma_f32_32x32x16_bf16 v[0:15], v[208:211], v[160:163], v[0:15]
	v_exp_f32_e32 v76, v76
	ds_read_b128 v[156:159], v241 offset:12288
	s_waitcnt lgkmcnt(8)
	v_mfma_f32_32x32x16_bf16 v[0:15], v[212:215], v[164:167], v[0:15]
	v_exp_f32_e32 v77, v77
	ds_read_b128 v[160:163], v242 offset:0
	s_waitcnt lgkmcnt(7)
	v_mfma_f32_32x32x16_bf16 v[0:15], v[224:227], v[168:171], v[0:15]
	v_exp_f32_e32 v78, v78
	ds_read_b128 v[164:167], v242 offset:12288
	s_waitcnt lgkmcnt(6)
	v_mfma_f32_32x32x16_bf16 v[0:15], v[228:231], v[172:175], v[0:15]
	v_exp_f32_e32 v79, v79
	s_waitcnt vmcnt(5)
	s_barrier
	ds_read_b128 v[168:171], v243 offset:0
	s_waitcnt lgkmcnt(6)
	v_mfma_f32_32x32x16_bf16 v[208:223], v[144:147], v[96:99], 0
	v_exp_f32_e32 v80, v80
	v_add_f32_e32 v245, v64, v245
	v_exp_f32_e32 v81, v81
	ds_read_b128 v[172:175], v243 offset:12288
	s_waitcnt lgkmcnt(6)
	v_mfma_f32_32x32x16_bf16 v[224:239], v[148:151], v[96:99], 0
	v_add_f32_e32 v246, v65, v246
	v_exp_f32_e32 v82, v82
	v_add_f32_e32 v245, v66, v245
	ds_read_b128 v[144:147], v240 offset:128
	s_waitcnt lgkmcnt(6)
	v_mfma_f32_32x32x16_bf16 v[208:223], v[152:155], v[100:103], v[208:223]
	v_exp_f32_e32 v83, v83
	v_add_f32_e32 v246, v67, v246
	s_add_i32 m0, s60, 0x21010
	s_nop 0
	global_load_lds_dwordx4 v182, s[42:43]
	ds_read_b128 v[148:151], v240 offset:12416
	s_waitcnt lgkmcnt(6)
	v_mfma_f32_32x32x16_bf16 v[224:239], v[156:159], v[100:103], v[224:239]
	v_exp_f32_e32 v84, v84
	v_add_f32_e32 v245, v68, v245
	v_exp_f32_e32 v85, v85
	ds_read_b128 v[152:155], v241 offset:128
	s_waitcnt lgkmcnt(6)
	v_mfma_f32_32x32x16_bf16 v[208:223], v[160:163], v[104:107], v[208:223]
	v_add_f32_e32 v246, v69, v246
	v_exp_f32_e32 v86, v86
	v_add_f32_e32 v245, v70, v245
	ds_read_b128 v[156:159], v241 offset:12416
	s_waitcnt lgkmcnt(6)
	v_mfma_f32_32x32x16_bf16 v[224:239], v[164:167], v[104:107], v[224:239]
	v_exp_f32_e32 v87, v87
	v_add_f32_e32 v246, v71, v246
	s_add_i32 m0, s60, 0x21410
	s_nop 0
	global_load_lds_dwordx4 v183, s[42:43]
	ds_read_b128 v[160:163], v242 offset:128
	s_waitcnt lgkmcnt(6)
	v_mfma_f32_32x32x16_bf16 v[208:223], v[168:171], v[108:111], v[208:223]
	v_exp_f32_e32 v88, v88
	v_add_f32_e32 v245, v72, v245
	v_exp_f32_e32 v89, v89
	ds_read_b128 v[164:167], v242 offset:12416
	s_waitcnt lgkmcnt(6)
	v_mfma_f32_32x32x16_bf16 v[224:239], v[172:175], v[108:111], v[224:239]
	v_add_f32_e32 v246, v73, v246
	v_exp_f32_e32 v90, v90
	v_add_f32_e32 v245, v74, v245
	ds_read_b128 v[168:171], v243 offset:128
	s_waitcnt lgkmcnt(6)
	v_mfma_f32_32x32x16_bf16 v[208:223], v[144:147], v[112:115], v[208:223]
	v_exp_f32_e32 v91, v91
	v_add_f32_e32 v246, v75, v246
	s_add_i32 m0, s60, 0x21810
	s_nop 0
	global_load_lds_dwordx4 v184, s[42:43]
	ds_read_b128 v[172:175], v243 offset:12416
	s_waitcnt lgkmcnt(6)
	v_mfma_f32_32x32x16_bf16 v[224:239], v[148:151], v[112:115], v[224:239]
	v_exp_f32_e32 v92, v92
	v_add_f32_e32 v245, v76, v245
	v_exp_f32_e32 v93, v93
	ds_read_b128 v[144:147], v240 offset:256
	s_waitcnt lgkmcnt(6)
	v_mfma_f32_32x32x16_bf16 v[208:223], v[152:155], v[116:119], v[208:223]
	v_add_f32_e32 v246, v77, v246
	v_exp_f32_e32 v94, v94
	v_add_f32_e32 v245, v78, v245
	ds_read_b128 v[148:151], v240 offset:12544
	s_waitcnt lgkmcnt(6)
	v_mfma_f32_32x32x16_bf16 v[224:239], v[156:159], v[116:119], v[224:239]
	v_exp_f32_e32 v95, v95
	v_add_f32_e32 v246, v79, v246
	s_add_i32 m0, s61, 0x4000
	s_nop 0
	global_load_lds_dwordx4 v185, s[46:47]
	ds_read_b128 v[152:155], v241 offset:256
	s_waitcnt lgkmcnt(6)
	v_mfma_f32_32x32x16_bf16 v[208:223], v[160:163], v[120:123], v[208:223]
	v_add_f32_e32 v245, v80, v245
	v_add_f32_e32 v246, v81, v246
	v_add_f32_e32 v245, v82, v245
	ds_read_b128 v[156:159], v241 offset:12544
	s_waitcnt lgkmcnt(6)
	v_mfma_f32_32x32x16_bf16 v[224:239], v[164:167], v[120:123], v[224:239]
	v_add_f32_e32 v246, v83, v246
	v_add_f32_e32 v245, v84, v245
	v_add_f32_e32 v246, v85, v246
	ds_read_b128 v[160:163], v242 offset:256
	s_waitcnt lgkmcnt(6)
	v_mfma_f32_32x32x16_bf16 v[208:223], v[168:171], v[124:127], v[208:223]
	v_add_f32_e32 v245, v86, v245
	v_add_f32_e32 v246, v87, v246
	s_add_i32 m0, s61, 0x4400
	s_nop 0
	global_load_lds_dwordx4 v186, s[46:47]
	ds_read_b128 v[164:167], v242 offset:12544
	s_waitcnt lgkmcnt(6)
	v_mfma_f32_32x32x16_bf16 v[224:239], v[172:175], v[124:127], v[224:239]
	v_add_f32_e32 v245, v88, v245
	v_add_f32_e32 v246, v89, v246
	v_add_f32_e32 v245, v90, v245
	ds_read_b128 v[168:171], v243 offset:256
	s_waitcnt lgkmcnt(6)
	v_mfma_f32_32x32x16_bf16 v[208:223], v[144:147], v[128:131], v[208:223]
	v_add_f32_e32 v246, v91, v246
	v_add_f32_e32 v245, v92, v245
	v_add_f32_e32 v246, v93, v246
	ds_read_b128 v[172:175], v243 offset:12544
	s_waitcnt lgkmcnt(6)
	v_mfma_f32_32x32x16_bf16 v[224:239], v[148:151], v[128:131], v[224:239]
	v_add_f32_e32 v245, v94, v245
	v_add_f32_e32 v246, v95, v246
	s_add_u32 s42, s42, 0x6000
	s_addc_u32 s43, s43, 0
	v_add_u32_e32 v240, 0x6000, v240
	ds_read_b64_tr_b16 v[144:145], v244 offset:0
	ds_read_b64_tr_b16 v[146:147], v244 offset:2048
	s_waitcnt lgkmcnt(7)
	v_mfma_f32_32x32x16_bf16 v[208:223], v[152:155], v[132:135], v[208:223]
	v_cvt_pk_bf16_f32 v64, v64, v65
	v_cvt_pk_bf16_f32 v65, v66, v67
	v_cvt_pk_bf16_f32 v66, v68, v69
	v_add_u32_e32 v241, 0x6000, v241
	ds_read_b64_tr_b16 v[148:149], v244 offset:4096
	ds_read_b64_tr_b16 v[150:151], v244 offset:6144
	s_waitcnt lgkmcnt(8)
	v_mfma_f32_32x32x16_bf16 v[224:239], v[156:159], v[132:135], v[224:239]
	v_cvt_pk_bf16_f32 v67, v70, v71
	v_cvt_pk_bf16_f32 v68, v72, v73
	v_cvt_pk_bf16_f32 v69, v74, v75
	v_add_u32_e32 v242, 0x6000, v242
	ds_read_b64_tr_b16 v[152:153], v244 offset:8192
	ds_read_b64_tr_b16 v[154:155], v244 offset:10240
	s_waitcnt lgkmcnt(9)
	v_mfma_f32_32x32x16_bf16 v[208:223], v[160:163], v[136:139], v[208:223]
	v_cvt_pk_bf16_f32 v70, v76, v77
	v_cvt_pk_bf16_f32 v71, v78, v79
	s_add_u32 s46, s46, 0x40000
	s_addc_u32 s47, s47, 0
	v_add_u32_e32 v243, 0x6000, v243
	ds_read_b64_tr_b16 v[156:157], v244 offset:12288
	ds_read_b64_tr_b16 v[158:159], v244 offset:14336
	s_waitcnt lgkmcnt(10)
	v_mfma_f32_32x32x16_bf16 v[224:239], v[164:167], v[136:139], v[224:239]
	v_cvt_pk_bf16_f32 v80, v80, v81
	v_cvt_pk_bf16_f32 v81, v82, v83
	v_cvt_pk_bf16_f32 v82, v84, v85
	ds_read_b64_tr_b16 v[160:161], v244 offset:512
	ds_read_b64_tr_b16 v[162:163], v244 offset:2560
	s_waitcnt lgkmcnt(11)
	v_mfma_f32_32x32x16_bf16 v[208:223], v[168:171], v[140:143], v[208:223]
	v_cvt_pk_bf16_f32 v83, v86, v87
	v_cvt_pk_bf16_f32 v84, v88, v89
	v_cvt_pk_bf16_f32 v85, v90, v91
	ds_read_b64_tr_b16 v[164:165], v244 offset:4608
	ds_read_b64_tr_b16 v[166:167], v244 offset:6656
	s_waitcnt lgkmcnt(12)
	v_mfma_f32_32x32x16_bf16 v[224:239], v[172:175], v[140:143], v[224:239]
	v_cvt_pk_bf16_f32 v86, v92, v93
	v_cvt_pk_bf16_f32 v87, v94, v95
	s_waitcnt lgkmcnt(10)
	v_mfma_f32_32x32x16_bf16 v[48:63], v[64:67], v[144:147], v[48:63]
	s_waitcnt lgkmcnt(8)
	v_mfma_f32_32x32x16_bf16 v[48:63], v[68:71], v[148:151], v[48:63]
	ds_read_b64_tr_b16 v[168:169], v244 offset:8704
	ds_read_b64_tr_b16 v[170:171], v244 offset:10752
	s_waitcnt lgkmcnt(8)
	v_mfma_f32_32x32x16_bf16 v[48:63], v[80:83], v[152:155], v[48:63]
	v_exp_f32_e32 v208, v208
	v_exp_f32_e32 v209, v209
	ds_read_b64_tr_b16 v[172:173], v244 offset:12800
	ds_read_b64_tr_b16 v[174:175], v244 offset:14848
	s_waitcnt lgkmcnt(8)
	v_mfma_f32_32x32x16_bf16 v[48:63], v[84:87], v[156:159], v[48:63]
	v_exp_f32_e32 v210, v210
	v_exp_f32_e32 v211, v211
	ds_read_b64_tr_b16 v[144:145], v244 offset:1024
	ds_read_b64_tr_b16 v[146:147], v244 offset:3072
	s_waitcnt lgkmcnt(8)
	v_mfma_f32_32x32x16_bf16 v[32:47], v[64:67], v[160:163], v[32:47]
	v_exp_f32_e32 v212, v212
	ds_read_b64_tr_b16 v[148:149], v244 offset:5120
	ds_read_b64_tr_b16 v[150:151], v244 offset:7168
	s_waitcnt lgkmcnt(8)
	v_mfma_f32_32x32x16_bf16 v[32:47], v[68:71], v[164:167], v[32:47]
	v_exp_f32_e32 v213, v213
	ds_read_b64_tr_b16 v[152:153], v244 offset:9216
	ds_read_b64_tr_b16 v[154:155], v244 offset:11264
	s_waitcnt lgkmcnt(8)
	v_mfma_f32_32x32x16_bf16 v[32:47], v[80:83], v[168:171], v[32:47]
	v_exp_f32_e32 v214, v214
	ds_read_b64_tr_b16 v[156:157], v244 offset:13312
	ds_read_b64_tr_b16 v[158:159], v244 offset:15360
	s_waitcnt lgkmcnt(8)
	v_mfma_f32_32x32x16_bf16 v[32:47], v[84:87], v[172:175], v[32:47]
	v_exp_f32_e32 v215, v215
	ds_read_b64_tr_b16 v[160:161], v244 offset:1536
	ds_read_b64_tr_b16 v[162:163], v244 offset:3584
	s_waitcnt lgkmcnt(8)
	v_mfma_f32_32x32x16_bf16 v[16:31], v[64:67], v[144:147], v[16:31]
	v_exp_f32_e32 v216, v216
	ds_read_b64_tr_b16 v[164:165], v244 offset:5632
	ds_read_b64_tr_b16 v[166:167], v244 offset:7680
	s_waitcnt lgkmcnt(8)
	v_mfma_f32_32x32x16_bf16 v[16:31], v[68:71], v[148:151], v[16:31]
	v_exp_f32_e32 v217, v217
	ds_read_b64_tr_b16 v[168:169], v244 offset:9728
	ds_read_b64_tr_b16 v[170:171], v244 offset:11776
	ds_read_b64_tr_b16 v[172:173], v244 offset:13824
	ds_read_b64_tr_b16 v[174:175], v244 offset:15872
	ds_read_b128 v[144:147], v240 offset:0
	s_waitcnt lgkmcnt(11)
	v_mfma_f32_32x32x16_bf16 v[16:31], v[80:83], v[152:155], v[16:31]
	v_exp_f32_e32 v218, v218
	v_add_u32_e32 v244, 0xffff8000, v244
	ds_read_b128 v[148:151], v240 offset:12288
	s_waitcnt lgkmcnt(10)
	v_mfma_f32_32x32x16_bf16 v[16:31], v[84:87], v[156:159], v[16:31]
	v_exp_f32_e32 v219, v219
	ds_read_b128 v[152:155], v241 offset:0
	s_waitcnt lgkmcnt(9)
	v_mfma_f32_32x32x16_bf16 v[0:15], v[64:67], v[160:163], v[0:15]
	v_exp_f32_e32 v220, v220
	ds_read_b128 v[156:159], v241 offset:12288
	s_waitcnt lgkmcnt(8)
	v_mfma_f32_32x32x16_bf16 v[0:15], v[68:71], v[164:167], v[0:15]
	v_exp_f32_e32 v221, v221
	ds_read_b128 v[160:163], v242 offset:0
	s_waitcnt lgkmcnt(7)
	v_mfma_f32_32x32x16_bf16 v[0:15], v[80:83], v[168:171], v[0:15]
	v_exp_f32_e32 v222, v222
	ds_read_b128 v[164:167], v242 offset:12288
	s_waitcnt lgkmcnt(6)
	v_mfma_f32_32x32x16_bf16 v[0:15], v[84:87], v[172:175], v[0:15]
	v_exp_f32_e32 v223, v223
	s_waitcnt vmcnt(5)
	s_barrier
	ds_read_b128 v[168:171], v243 offset:0
	s_waitcnt lgkmcnt(6)
	v_mfma_f32_32x32x16_bf16 v[64:79], v[144:147], v[96:99], 0
	v_exp_f32_e32 v224, v224
	v_add_f32_e32 v245, v208, v245
	v_exp_f32_e32 v225, v225
	ds_read_b128 v[172:175], v243 offset:12288
	s_waitcnt lgkmcnt(6)
	v_mfma_f32_32x32x16_bf16 v[80:95], v[148:151], v[96:99], 0
	v_add_f32_e32 v246, v209, v246
	v_exp_f32_e32 v226, v226
	v_add_f32_e32 v245, v210, v245
	ds_read_b128 v[144:147], v240 offset:128
	s_waitcnt lgkmcnt(6)
	v_mfma_f32_32x32x16_bf16 v[64:79], v[152:155], v[100:103], v[64:79]
	v_exp_f32_e32 v227, v227
	v_add_f32_e32 v246, v211, v246
	s_add_i32 m0, s60, 0xc000
	s_nop 0
	global_load_lds_dwordx4 v182, s[42:43]
	ds_read_b128 v[148:151], v240 offset:12416
	s_waitcnt lgkmcnt(6)
	v_mfma_f32_32x32x16_bf16 v[80:95], v[156:159], v[100:103], v[80:95]
	v_exp_f32_e32 v228, v228
	v_add_f32_e32 v245, v212, v245
	v_exp_f32_e32 v229, v229
	ds_read_b128 v[152:155], v241 offset:128
	s_waitcnt lgkmcnt(6)
	v_mfma_f32_32x32x16_bf16 v[64:79], v[160:163], v[104:107], v[64:79]
	v_add_f32_e32 v246, v213, v246
	v_exp_f32_e32 v230, v230
	v_add_f32_e32 v245, v214, v245
	ds_read_b128 v[156:159], v241 offset:12416
	s_waitcnt lgkmcnt(6)
	v_mfma_f32_32x32x16_bf16 v[80:95], v[164:167], v[104:107], v[80:95]
	v_exp_f32_e32 v231, v231
	v_add_f32_e32 v246, v215, v246
	s_add_i32 m0, s60, 0xc400
	s_nop 0
	global_load_lds_dwordx4 v183, s[42:43]
	ds_read_b128 v[160:163], v242 offset:128
	s_waitcnt lgkmcnt(6)
	v_mfma_f32_32x32x16_bf16 v[64:79], v[168:171], v[108:111], v[64:79]
	v_exp_f32_e32 v232, v232
	v_add_f32_e32 v245, v216, v245
	v_exp_f32_e32 v233, v233
	ds_read_b128 v[164:167], v242 offset:12416
	s_waitcnt lgkmcnt(6)
	v_mfma_f32_32x32x16_bf16 v[80:95], v[172:175], v[108:111], v[80:95]
	v_add_f32_e32 v246, v217, v246
	v_exp_f32_e32 v234, v234
	v_add_f32_e32 v245, v218, v245
	ds_read_b128 v[168:171], v243 offset:128
	s_waitcnt lgkmcnt(6)
	v_mfma_f32_32x32x16_bf16 v[64:79], v[144:147], v[112:115], v[64:79]
	v_exp_f32_e32 v235, v235
	v_add_f32_e32 v246, v219, v246
	s_add_i32 m0, s60, 0xc800
	s_nop 0
	global_load_lds_dwordx4 v184, s[42:43]
	ds_read_b128 v[172:175], v243 offset:12416
	s_waitcnt lgkmcnt(6)
	v_mfma_f32_32x32x16_bf16 v[80:95], v[148:151], v[112:115], v[80:95]
	v_exp_f32_e32 v236, v236
	v_add_f32_e32 v245, v220, v245
	v_exp_f32_e32 v237, v237
	ds_read_b128 v[144:147], v240 offset:256
	s_waitcnt lgkmcnt(6)
	v_mfma_f32_32x32x16_bf16 v[64:79], v[152:155], v[116:119], v[64:79]
	v_add_f32_e32 v246, v221, v246
	v_exp_f32_e32 v238, v238
	v_add_f32_e32 v245, v222, v245
	ds_read_b128 v[148:151], v240 offset:12544
	s_waitcnt lgkmcnt(6)
	v_mfma_f32_32x32x16_bf16 v[80:95], v[156:159], v[116:119], v[80:95]
	v_exp_f32_e32 v239, v239
	v_add_f32_e32 v246, v223, v246
	s_add_i32 m0, s61, 0x8000
	s_nop 0
	global_load_lds_dwordx4 v185, s[46:47]
	ds_read_b128 v[152:155], v241 offset:256
	s_waitcnt lgkmcnt(6)
	v_mfma_f32_32x32x16_bf16 v[64:79], v[160:163], v[120:123], v[64:79]
	v_add_f32_e32 v245, v224, v245
	v_add_f32_e32 v246, v225, v246
	v_add_f32_e32 v245, v226, v245
	ds_read_b128 v[156:159], v241 offset:12544
	s_waitcnt lgkmcnt(6)
	v_mfma_f32_32x32x16_bf16 v[80:95], v[164:167], v[120:123], v[80:95]
	v_add_f32_e32 v246, v227, v246
	v_add_f32_e32 v245, v228, v245
	v_add_f32_e32 v246, v229, v246
	ds_read_b128 v[160:163], v242 offset:256
	s_waitcnt lgkmcnt(6)
	v_mfma_f32_32x32x16_bf16 v[64:79], v[168:171], v[124:127], v[64:79]
	v_add_f32_e32 v245, v230, v245
	v_add_f32_e32 v246, v231, v246
	s_add_i32 m0, s61, 0x8400
	s_nop 0
	global_load_lds_dwordx4 v186, s[46:47]
	ds_read_b128 v[164:167], v242 offset:12544
	s_waitcnt lgkmcnt(6)
	v_mfma_f32_32x32x16_bf16 v[80:95], v[172:175], v[124:127], v[80:95]
	v_add_f32_e32 v245, v232, v245
	v_add_f32_e32 v246, v233, v246
	v_add_f32_e32 v245, v234, v245
	ds_read_b128 v[168:171], v243 offset:256
	s_waitcnt lgkmcnt(6)
	v_mfma_f32_32x32x16_bf16 v[64:79], v[144:147], v[128:131], v[64:79]
	v_add_f32_e32 v246, v235, v246
	v_add_f32_e32 v245, v236, v245
	v_add_f32_e32 v246, v237, v246
	ds_read_b128 v[172:175], v243 offset:12544
	s_waitcnt lgkmcnt(6)
	v_mfma_f32_32x32x16_bf16 v[80:95], v[148:151], v[128:131], v[80:95]
	v_add_f32_e32 v245, v238, v245
	v_add_f32_e32 v246, v239, v246
	s_add_u32 s42, s42, 0x6000
	s_addc_u32 s43, s43, 0
	v_add_u32_e32 v240, 0x6000, v240
	ds_read_b64_tr_b16 v[144:145], v244 offset:0
	ds_read_b64_tr_b16 v[146:147], v244 offset:2048
	s_waitcnt lgkmcnt(7)
	v_mfma_f32_32x32x16_bf16 v[64:79], v[152:155], v[132:135], v[64:79]
	v_cvt_pk_bf16_f32 v208, v208, v209
	v_cvt_pk_bf16_f32 v209, v210, v211
	v_cvt_pk_bf16_f32 v210, v212, v213
	v_add_u32_e32 v241, 0x6000, v241
	ds_read_b64_tr_b16 v[148:149], v244 offset:4096
	ds_read_b64_tr_b16 v[150:151], v244 offset:6144
	s_waitcnt lgkmcnt(8)
	v_mfma_f32_32x32x16_bf16 v[80:95], v[156:159], v[132:135], v[80:95]
	v_cvt_pk_bf16_f32 v211, v214, v215
	v_cvt_pk_bf16_f32 v212, v216, v217
	v_cvt_pk_bf16_f32 v213, v218, v219
	v_add_u32_e32 v242, 0x6000, v242
	ds_read_b64_tr_b16 v[152:153], v244 offset:8192
	ds_read_b64_tr_b16 v[154:155], v244 offset:10240
	s_waitcnt lgkmcnt(9)
	v_mfma_f32_32x32x16_bf16 v[64:79], v[160:163], v[136:139], v[64:79]
	v_cvt_pk_bf16_f32 v214, v220, v221
	v_cvt_pk_bf16_f32 v215, v222, v223
	s_add_u32 s46, s46, 0x40000
	s_addc_u32 s47, s47, 0
	v_add_u32_e32 v243, 0x6000, v243
	ds_read_b64_tr_b16 v[156:157], v244 offset:12288
	ds_read_b64_tr_b16 v[158:159], v244 offset:14336
	s_waitcnt lgkmcnt(10)
	v_mfma_f32_32x32x16_bf16 v[80:95], v[164:167], v[136:139], v[80:95]
	v_cvt_pk_bf16_f32 v224, v224, v225
	v_cvt_pk_bf16_f32 v225, v226, v227
	v_cvt_pk_bf16_f32 v226, v228, v229
	ds_read_b64_tr_b16 v[160:161], v244 offset:512
	ds_read_b64_tr_b16 v[162:163], v244 offset:2560
	s_waitcnt lgkmcnt(11)
	v_mfma_f32_32x32x16_bf16 v[64:79], v[168:171], v[140:143], v[64:79]
	v_cvt_pk_bf16_f32 v227, v230, v231
	v_cvt_pk_bf16_f32 v228, v232, v233
	v_cvt_pk_bf16_f32 v229, v234, v235
	ds_read_b64_tr_b16 v[164:165], v244 offset:4608
	ds_read_b64_tr_b16 v[166:167], v244 offset:6656
	s_waitcnt lgkmcnt(12)
	v_mfma_f32_32x32x16_bf16 v[80:95], v[172:175], v[140:143], v[80:95]
	v_cvt_pk_bf16_f32 v230, v236, v237
	v_cvt_pk_bf16_f32 v231, v238, v239
	s_waitcnt lgkmcnt(10)
	v_mfma_f32_32x32x16_bf16 v[48:63], v[208:211], v[144:147], v[48:63]
	s_waitcnt lgkmcnt(8)
	v_mfma_f32_32x32x16_bf16 v[48:63], v[212:215], v[148:151], v[48:63]
	ds_read_b64_tr_b16 v[168:169], v244 offset:8704
	ds_read_b64_tr_b16 v[170:171], v244 offset:10752
	s_waitcnt lgkmcnt(8)
	v_mfma_f32_32x32x16_bf16 v[48:63], v[224:227], v[152:155], v[48:63]
	v_exp_f32_e32 v64, v64
	v_exp_f32_e32 v65, v65
	ds_read_b64_tr_b16 v[172:173], v244 offset:12800
	ds_read_b64_tr_b16 v[174:175], v244 offset:14848
	s_waitcnt lgkmcnt(8)
	v_mfma_f32_32x32x16_bf16 v[48:63], v[228:231], v[156:159], v[48:63]
	v_exp_f32_e32 v66, v66
	v_exp_f32_e32 v67, v67
	ds_read_b64_tr_b16 v[144:145], v244 offset:1024
	ds_read_b64_tr_b16 v[146:147], v244 offset:3072
	s_waitcnt lgkmcnt(8)
	v_mfma_f32_32x32x16_bf16 v[32:47], v[208:211], v[160:163], v[32:47]
	v_exp_f32_e32 v68, v68
	ds_read_b64_tr_b16 v[148:149], v244 offset:5120
	ds_read_b64_tr_b16 v[150:151], v244 offset:7168
	s_waitcnt lgkmcnt(8)
	v_mfma_f32_32x32x16_bf16 v[32:47], v[212:215], v[164:167], v[32:47]
	v_exp_f32_e32 v69, v69
	ds_read_b64_tr_b16 v[152:153], v244 offset:9216
	ds_read_b64_tr_b16 v[154:155], v244 offset:11264
	s_waitcnt lgkmcnt(8)
	v_mfma_f32_32x32x16_bf16 v[32:47], v[224:227], v[168:171], v[32:47]
	v_exp_f32_e32 v70, v70
	ds_read_b64_tr_b16 v[156:157], v244 offset:13312
	ds_read_b64_tr_b16 v[158:159], v244 offset:15360
	s_waitcnt lgkmcnt(8)
	v_mfma_f32_32x32x16_bf16 v[32:47], v[228:231], v[172:175], v[32:47]
	v_exp_f32_e32 v71, v71
	ds_read_b64_tr_b16 v[160:161], v244 offset:1536
	ds_read_b64_tr_b16 v[162:163], v244 offset:3584
	s_waitcnt lgkmcnt(8)
	v_mfma_f32_32x32x16_bf16 v[16:31], v[208:211], v[144:147], v[16:31]
	v_exp_f32_e32 v72, v72
	ds_read_b64_tr_b16 v[164:165], v244 offset:5632
	ds_read_b64_tr_b16 v[166:167], v244 offset:7680
	s_waitcnt lgkmcnt(8)
	v_mfma_f32_32x32x16_bf16 v[16:31], v[212:215], v[148:151], v[16:31]
	v_exp_f32_e32 v73, v73
	ds_read_b64_tr_b16 v[168:169], v244 offset:9728
	ds_read_b64_tr_b16 v[170:171], v244 offset:11776
	ds_read_b64_tr_b16 v[172:173], v244 offset:13824
	ds_read_b64_tr_b16 v[174:175], v244 offset:15872
	ds_read_b128 v[144:147], v240 offset:0
	s_waitcnt lgkmcnt(11)
	v_mfma_f32_32x32x16_bf16 v[16:31], v[224:227], v[152:155], v[16:31]
	v_exp_f32_e32 v74, v74
	v_add_u32_e32 v244, 0x4000, v244
	ds_read_b128 v[148:151], v240 offset:12288
	s_waitcnt lgkmcnt(10)
	v_mfma_f32_32x32x16_bf16 v[16:31], v[228:231], v[156:159], v[16:31]
	v_exp_f32_e32 v75, v75
	ds_read_b128 v[152:155], v241 offset:0
	s_waitcnt lgkmcnt(9)
	v_mfma_f32_32x32x16_bf16 v[0:15], v[208:211], v[160:163], v[0:15]
	v_exp_f32_e32 v76, v76
	ds_read_b128 v[156:159], v241 offset:12288
	s_waitcnt lgkmcnt(8)
	v_mfma_f32_32x32x16_bf16 v[0:15], v[212:215], v[164:167], v[0:15]
	v_exp_f32_e32 v77, v77
	ds_read_b128 v[160:163], v242 offset:0
	s_waitcnt lgkmcnt(7)
	v_mfma_f32_32x32x16_bf16 v[0:15], v[224:227], v[168:171], v[0:15]
	v_exp_f32_e32 v78, v78
	ds_read_b128 v[164:167], v242 offset:12288
	s_waitcnt lgkmcnt(6)
	v_mfma_f32_32x32x16_bf16 v[0:15], v[228:231], v[172:175], v[0:15]
	v_exp_f32_e32 v79, v79
	s_sub_i32 s78, s78, 1
	s_cmp_lg_u32 s78, 0
	s_cbranch_scc1 .Lattn_loop
	s_waitcnt vmcnt(5)
	s_barrier
	ds_read_b128 v[168:171], v243 offset:0
	s_waitcnt lgkmcnt(6)
	v_mfma_f32_32x32x16_bf16 v[208:223], v[144:147], v[96:99], 0
	v_exp_f32_e32 v80, v80
	v_add_f32_e32 v245, v64, v245
	v_exp_f32_e32 v81, v81
	ds_read_b128 v[172:175], v243 offset:12288
	s_waitcnt lgkmcnt(6)
	v_mfma_f32_32x32x16_bf16 v[224:239], v[148:151], v[96:99], 0
	v_add_f32_e32 v246, v65, v246
	v_exp_f32_e32 v82, v82
	v_add_f32_e32 v245, v66, v245
	ds_read_b128 v[144:147], v240 offset:128
	s_waitcnt lgkmcnt(6)
	v_mfma_f32_32x32x16_bf16 v[208:223], v[152:155], v[100:103], v[208:223]
	v_exp_f32_e32 v83, v83
	v_add_f32_e32 v246, v67, v246
	s_add_i32 m0, s60, 0x12000
	s_nop 0
	global_load_lds_dwordx4 v182, s[42:43]
	ds_read_b128 v[148:151], v240 offset:12416
	s_waitcnt lgkmcnt(6)
	v_mfma_f32_32x32x16_bf16 v[224:239], v[156:159], v[100:103], v[224:239]
	v_exp_f32_e32 v84, v84
	v_add_f32_e32 v245, v68, v245
	v_exp_f32_e32 v85, v85
	ds_read_b128 v[152:155], v241 offset:128
	s_waitcnt lgkmcnt(6)
	v_mfma_f32_32x32x16_bf16 v[208:223], v[160:163], v[104:107], v[208:223]
	v_add_f32_e32 v246, v69, v246
	v_exp_f32_e32 v86, v86
	v_add_f32_e32 v245, v70, v245
	ds_read_b128 v[156:159], v241 offset:12416
	s_waitcnt lgkmcnt(6)
	v_mfma_f32_32x32x16_bf16 v[224:239], v[164:167], v[104:107], v[224:239]
	v_exp_f32_e32 v87, v87
	v_add_f32_e32 v246, v71, v246
	s_add_i32 m0, s60, 0x12400
	s_nop 0
	global_load_lds_dwordx4 v183, s[42:43]
	ds_read_b128 v[160:163], v242 offset:128
	s_waitcnt lgkmcnt(6)
	v_mfma_f32_32x32x16_bf16 v[208:223], v[168:171], v[108:111], v[208:223]
	v_exp_f32_e32 v88, v88
	v_add_f32_e32 v245, v72, v245
	v_exp_f32_e32 v89, v89
	ds_read_b128 v[164:167], v242 offset:12416
	s_waitcnt lgkmcnt(6)
	v_mfma_f32_32x32x16_bf16 v[224:239], v[172:175], v[108:111], v[224:239]
	v_add_f32_e32 v246, v73, v246
	v_exp_f32_e32 v90, v90
	v_add_f32_e32 v245, v74, v245
	ds_read_b128 v[168:171], v243 offset:128
	s_waitcnt lgkmcnt(6)
	v_mfma_f32_32x32x16_bf16 v[208:223], v[144:147], v[112:115], v[208:223]
	v_exp_f32_e32 v91, v91
	v_add_f32_e32 v246, v75, v246
	s_add_i32 m0, s60, 0x12800
	s_nop 0
	global_load_lds_dwordx4 v184, s[42:43]
	ds_read_b128 v[172:175], v243 offset:12416
	s_waitcnt lgkmcnt(6)
	v_mfma_f32_32x32x16_bf16 v[224:239], v[148:151], v[112:115], v[224:239]
	v_exp_f32_e32 v92, v92
	v_add_f32_e32 v245, v76, v245
	v_exp_f32_e32 v93, v93
	ds_read_b128 v[144:147], v240 offset:256
	s_waitcnt lgkmcnt(6)
	v_mfma_f32_32x32x16_bf16 v[208:223], v[152:155], v[116:119], v[208:223]
	v_add_f32_e32 v246, v77, v246
	v_exp_f32_e32 v94, v94
	v_add_f32_e32 v245, v78, v245
	ds_read_b128 v[148:151], v240 offset:12544
	s_waitcnt lgkmcnt(6)
	v_mfma_f32_32x32x16_bf16 v[224:239], v[156:159], v[116:119], v[224:239]
	v_exp_f32_e32 v95, v95
	v_add_f32_e32 v246, v79, v246
	s_add_i32 m0, s61, 0x0
	s_nop 0
	global_load_lds_dwordx4 v185, s[46:47]
	ds_read_b128 v[152:155], v241 offset:256
	s_waitcnt lgkmcnt(6)
	v_mfma_f32_32x32x16_bf16 v[208:223], v[160:163], v[120:123], v[208:223]
	v_add_f32_e32 v245, v80, v245
	v_add_f32_e32 v246, v81, v246
	v_add_f32_e32 v245, v82, v245
	ds_read_b128 v[156:159], v241 offset:12544
	s_waitcnt lgkmcnt(6)
	v_mfma_f32_32x32x16_bf16 v[224:239], v[164:167], v[120:123], v[224:239]
	v_add_f32_e32 v246, v83, v246
	v_add_f32_e32 v245, v84, v245
	v_add_f32_e32 v246, v85, v246
	ds_read_b128 v[160:163], v242 offset:256
	s_waitcnt lgkmcnt(6)
	v_mfma_f32_32x32x16_bf16 v[208:223], v[168:171], v[124:127], v[208:223]
	v_add_f32_e32 v245, v86, v245
	v_add_f32_e32 v246, v87, v246
	s_add_i32 m0, s61, 0x400
	s_nop 0
	global_load_lds_dwordx4 v186, s[46:47]
	ds_read_b128 v[164:167], v242 offset:12544
	s_waitcnt lgkmcnt(6)
	v_mfma_f32_32x32x16_bf16 v[224:239], v[172:175], v[124:127], v[224:239]
	v_add_f32_e32 v245, v88, v245
	v_add_f32_e32 v246, v89, v246
	v_add_f32_e32 v245, v90, v245
	ds_read_b128 v[168:171], v243 offset:256
	s_waitcnt lgkmcnt(6)
	v_mfma_f32_32x32x16_bf16 v[208:223], v[144:147], v[128:131], v[208:223]
	v_add_f32_e32 v246, v91, v246
	v_add_f32_e32 v245, v92, v245
	v_add_f32_e32 v246, v93, v246
	ds_read_b128 v[172:175], v243 offset:12544
	s_waitcnt lgkmcnt(6)
	v_mfma_f32_32x32x16_bf16 v[224:239], v[148:151], v[128:131], v[224:239]
	v_add_f32_e32 v245, v94, v245
	v_add_f32_e32 v246, v95, v246
	s_add_u32 s42, s42, 0x6000
	s_addc_u32 s43, s43, 0
	v_add_u32_e32 v240, 0x9010, v240
	ds_read_b64_tr_b16 v[144:145], v244 offset:0
	ds_read_b64_tr_b16 v[146:147], v244 offset:2048
	s_waitcnt lgkmcnt(7)
	v_mfma_f32_32x32x16_bf16 v[208:223], v[152:155], v[132:135], v[208:223]
	v_cvt_pk_bf16_f32 v64, v64, v65
	v_cvt_pk_bf16_f32 v65, v66, v67
	v_cvt_pk_bf16_f32 v66, v68, v69
	v_add_u32_e32 v241, 0x9010, v241
	ds_read_b64_tr_b16 v[148:149], v244 offset:4096
	ds_read_b64_tr_b16 v[150:151], v244 offset:6144
	s_waitcnt lgkmcnt(8)
	v_mfma_f32_32x32x16_bf16 v[224:239], v[156:159], v[132:135], v[224:239]
	v_cvt_pk_bf16_f32 v67, v70, v71
	v_cvt_pk_bf16_f32 v68, v72, v73
	v_cvt_pk_bf16_f32 v69, v74, v75
	v_add_u32_e32 v242, 0x9010, v242
	ds_read_b64_tr_b16 v[152:153], v244 offset:8192
	ds_read_b64_tr_b16 v[154:155], v244 offset:10240
	s_waitcnt lgkmcnt(9)
	v_mfma_f32_32x32x16_bf16 v[208:223], v[160:163], v[136:139], v[208:223]
	v_cvt_pk_bf16_f32 v70, v76, v77
	v_cvt_pk_bf16_f32 v71, v78, v79
	s_add_u32 s46, s46, 0x40000
	s_addc_u32 s47, s47, 0
	v_add_u32_e32 v243, 0x9010, v243
	ds_read_b64_tr_b16 v[156:157], v244 offset:12288
	ds_read_b64_tr_b16 v[158:159], v244 offset:14336
	s_waitcnt lgkmcnt(10)
	v_mfma_f32_32x32x16_bf16 v[224:239], v[164:167], v[136:139], v[224:239]
	v_cvt_pk_bf16_f32 v80, v80, v81
	v_cvt_pk_bf16_f32 v81, v82, v83
	v_cvt_pk_bf16_f32 v82, v84, v85
	ds_read_b64_tr_b16 v[160:161], v244 offset:512
	ds_read_b64_tr_b16 v[162:163], v244 offset:2560
	s_waitcnt lgkmcnt(11)
	v_mfma_f32_32x32x16_bf16 v[208:223], v[168:171], v[140:143], v[208:223]
	v_cvt_pk_bf16_f32 v83, v86, v87
	v_cvt_pk_bf16_f32 v84, v88, v89
	v_cvt_pk_bf16_f32 v85, v90, v91
	ds_read_b64_tr_b16 v[164:165], v244 offset:4608
	ds_read_b64_tr_b16 v[166:167], v244 offset:6656
	s_waitcnt lgkmcnt(12)
	v_mfma_f32_32x32x16_bf16 v[224:239], v[172:175], v[140:143], v[224:239]
	v_cvt_pk_bf16_f32 v86, v92, v93
	v_cvt_pk_bf16_f32 v87, v94, v95
	s_waitcnt lgkmcnt(10)
	v_mfma_f32_32x32x16_bf16 v[48:63], v[64:67], v[144:147], v[48:63]
	s_waitcnt lgkmcnt(8)
	v_mfma_f32_32x32x16_bf16 v[48:63], v[68:71], v[148:151], v[48:63]
	ds_read_b64_tr_b16 v[168:169], v244 offset:8704
	ds_read_b64_tr_b16 v[170:171], v244 offset:10752
	s_waitcnt lgkmcnt(8)
	v_mfma_f32_32x32x16_bf16 v[48:63], v[80:83], v[152:155], v[48:63]
	v_exp_f32_e32 v208, v208
	v_exp_f32_e32 v209, v209
	ds_read_b64_tr_b16 v[172:173], v244 offset:12800
	ds_read_b64_tr_b16 v[174:175], v244 offset:14848
	s_waitcnt lgkmcnt(8)
	v_mfma_f32_32x32x16_bf16 v[48:63], v[84:87], v[156:159], v[48:63]
	v_exp_f32_e32 v210, v210
	v_exp_f32_e32 v211, v211
	ds_read_b64_tr_b16 v[144:145], v244 offset:1024
	ds_read_b64_tr_b16 v[146:147], v244 offset:3072
	s_waitcnt lgkmcnt(8)
	v_mfma_f32_32x32x16_bf16 v[32:47], v[64:67], v[160:163], v[32:47]
	v_exp_f32_e32 v212, v212
	ds_read_b64_tr_b16 v[148:149], v244 offset:5120
	ds_read_b64_tr_b16 v[150:151], v244 offset:7168
	s_waitcnt lgkmcnt(8)
	v_mfma_f32_32x32x16_bf16 v[32:47], v[68:71], v[164:167], v[32:47]
	v_exp_f32_e32 v213, v213
	ds_read_b64_tr_b16 v[152:153], v244 offset:9216
	ds_read_b64_tr_b16 v[154:155], v244 offset:11264
	s_waitcnt lgkmcnt(8)
	v_mfma_f32_32x32x16_bf16 v[32:47], v[80:83], v[168:171], v[32:47]
	v_exp_f32_e32 v214, v214
	ds_read_b64_tr_b16 v[156:157], v244 offset:13312
	ds_read_b64_tr_b16 v[158:159], v244 offset:15360
	s_waitcnt lgkmcnt(8)
	v_mfma_f32_32x32x16_bf16 v[32:47], v[84:87], v[172:175], v[32:47]
	v_exp_f32_e32 v215, v215
	ds_read_b64_tr_b16 v[160:161], v244 offset:1536
	ds_read_b64_tr_b16 v[162:163], v244 offset:3584
	s_waitcnt lgkmcnt(8)
	v_mfma_f32_32x32x16_bf16 v[16:31], v[64:67], v[144:147], v[16:31]
	v_exp_f32_e32 v216, v216
	ds_read_b64_tr_b16 v[164:165], v244 offset:5632
	ds_read_b64_tr_b16 v[166:167], v244 offset:7680
	s_waitcnt lgkmcnt(8)
	v_mfma_f32_32x32x16_bf16 v[16:31], v[68:71], v[148:151], v[16:31]
	v_exp_f32_e32 v217, v217
	ds_read_b64_tr_b16 v[168:169], v244 offset:9728
	ds_read_b64_tr_b16 v[170:171], v244 offset:11776
	ds_read_b64_tr_b16 v[172:173], v244 offset:13824
	ds_read_b64_tr_b16 v[174:175], v244 offset:15872
	ds_read_b128 v[144:147], v240 offset:0
	s_waitcnt lgkmcnt(11)
	v_mfma_f32_32x32x16_bf16 v[16:31], v[80:83], v[152:155], v[16:31]
	v_exp_f32_e32 v218, v218
	v_add_u32_e32 v244, 0x4000, v244
	ds_read_b128 v[148:151], v240 offset:12288
	s_waitcnt lgkmcnt(10)
	v_mfma_f32_32x32x16_bf16 v[16:31], v[84:87], v[156:159], v[16:31]
	v_exp_f32_e32 v219, v219
	ds_read_b128 v[152:155], v241 offset:0
	s_waitcnt lgkmcnt(9)
	v_mfma_f32_32x32x16_bf16 v[0:15], v[64:67], v[160:163], v[0:15]
	v_exp_f32_e32 v220, v220
	ds_read_b128 v[156:159], v241 offset:12288
	s_waitcnt lgkmcnt(8)
	v_mfma_f32_32x32x16_bf16 v[0:15], v[68:71], v[164:167], v[0:15]
	v_exp_f32_e32 v221, v221
	ds_read_b128 v[160:163], v242 offset:0
	s_waitcnt lgkmcnt(7)
	v_mfma_f32_32x32x16_bf16 v[0:15], v[80:83], v[168:171], v[0:15]
	v_exp_f32_e32 v222, v222
	ds_read_b128 v[164:167], v242 offset:12288
	s_waitcnt lgkmcnt(6)
	v_mfma_f32_32x32x16_bf16 v[0:15], v[84:87], v[172:175], v[0:15]
	v_exp_f32_e32 v223, v223
	s_waitcnt vmcnt(5)
	s_barrier
	ds_read_b128 v[168:171], v243 offset:0
	s_waitcnt lgkmcnt(6)
	v_mfma_f32_32x32x16_bf16 v[64:79], v[144:147], v[96:99], 0
	v_exp_f32_e32 v224, v224
	v_add_f32_e32 v245, v208, v245
	v_exp_f32_e32 v225, v225
	ds_read_b128 v[172:175], v243 offset:12288
	s_waitcnt lgkmcnt(6)
	v_mfma_f32_32x32x16_bf16 v[80:95], v[148:151], v[96:99], 0
	v_add_f32_e32 v246, v209, v246
	v_exp_f32_e32 v226, v226
	v_add_f32_e32 v245, v210, v245
	ds_read_b128 v[144:147], v240 offset:128
	s_waitcnt lgkmcnt(6)
	v_mfma_f32_32x32x16_bf16 v[64:79], v[152:155], v[100:103], v[64:79]
	v_exp_f32_e32 v227, v227
	v_add_f32_e32 v246, v211, v246
	s_add_i32 m0, s60, 0x18000
	s_nop 0
	global_load_lds_dwordx4 v182, s[42:43]
	ds_read_b128 v[148:151], v240 offset:12416
	s_waitcnt lgkmcnt(6)
	v_mfma_f32_32x32x16_bf16 v[80:95], v[156:159], v[100:103], v[80:95]
	v_exp_f32_e32 v228, v228
	v_add_f32_e32 v245, v212, v245
	v_exp_f32_e32 v229, v229
	ds_read_b128 v[152:155], v241 offset:128
	s_waitcnt lgkmcnt(6)
	v_mfma_f32_32x32x16_bf16 v[64:79], v[160:163], v[104:107], v[64:79]
	v_add_f32_e32 v246, v213, v246
	v_exp_f32_e32 v230, v230
	v_add_f32_e32 v245, v214, v245
	ds_read_b128 v[156:159], v241 offset:12416
	s_waitcnt lgkmcnt(6)
	v_mfma_f32_32x32x16_bf16 v[80:95], v[164:167], v[104:107], v[80:95]
	v_exp_f32_e32 v231, v231
	v_add_f32_e32 v246, v215, v246
	s_add_i32 m0, s60, 0x18400
	s_nop 0
	global_load_lds_dwordx4 v183, s[42:43]
	ds_read_b128 v[160:163], v242 offset:128
	s_waitcnt lgkmcnt(6)
	v_mfma_f32_32x32x16_bf16 v[64:79], v[168:171], v[108:111], v[64:79]
	v_exp_f32_e32 v232, v232
	v_add_f32_e32 v245, v216, v245
	v_exp_f32_e32 v233, v233
	ds_read_b128 v[164:167], v242 offset:12416
	s_waitcnt lgkmcnt(6)
	v_mfma_f32_32x32x16_bf16 v[80:95], v[172:175], v[108:111], v[80:95]
	v_add_f32_e32 v246, v217, v246
	v_exp_f32_e32 v234, v234
	v_add_f32_e32 v245, v218, v245
	ds_read_b128 v[168:171], v243 offset:128
	s_waitcnt lgkmcnt(6)
	v_mfma_f32_32x32x16_bf16 v[64:79], v[144:147], v[112:115], v[64:79]
	v_exp_f32_e32 v235, v235
	v_add_f32_e32 v246, v219, v246
	s_add_i32 m0, s60, 0x18800
	s_nop 0
	global_load_lds_dwordx4 v184, s[42:43]
	ds_read_b128 v[172:175], v243 offset:12416
	s_waitcnt lgkmcnt(6)
	v_mfma_f32_32x32x16_bf16 v[80:95], v[148:151], v[112:115], v[80:95]
	v_exp_f32_e32 v236, v236
	v_add_f32_e32 v245, v220, v245
	v_exp_f32_e32 v237, v237
	ds_read_b128 v[144:147], v240 offset:256
	s_waitcnt lgkmcnt(6)
	v_mfma_f32_32x32x16_bf16 v[64:79], v[152:155], v[116:119], v[64:79]
	v_add_f32_e32 v246, v221, v246
	v_exp_f32_e32 v238, v238
	v_add_f32_e32 v245, v222, v245
	ds_read_b128 v[148:151], v240 offset:12544
	s_waitcnt lgkmcnt(6)
	v_mfma_f32_32x32x16_bf16 v[80:95], v[156:159], v[116:119], v[80:95]
	v_exp_f32_e32 v239, v239
	v_add_f32_e32 v246, v223, v246
	s_add_i32 m0, s61, 0x4000
	s_nop 0
	global_load_lds_dwordx4 v185, s[46:47]
	ds_read_b128 v[152:155], v241 offset:256
	s_waitcnt lgkmcnt(6)
	v_mfma_f32_32x32x16_bf16 v[64:79], v[160:163], v[120:123], v[64:79]
	v_add_f32_e32 v245, v224, v245
	v_add_f32_e32 v246, v225, v246
	v_add_f32_e32 v245, v226, v245
	ds_read_b128 v[156:159], v241 offset:12544
	s_waitcnt lgkmcnt(6)
	v_mfma_f32_32x32x16_bf16 v[80:95], v[164:167], v[120:123], v[80:95]
	v_add_f32_e32 v246, v227, v246
	v_add_f32_e32 v245, v228, v245
	v_add_f32_e32 v246, v229, v246
	ds_read_b128 v[160:163], v242 offset:256
	s_waitcnt lgkmcnt(6)
	v_mfma_f32_32x32x16_bf16 v[64:79], v[168:171], v[124:127], v[64:79]
	v_add_f32_e32 v245, v230, v245
	v_add_f32_e32 v246, v231, v246
	s_add_i32 m0, s61, 0x4400
	s_nop 0
	global_load_lds_dwordx4 v186, s[46:47]
	ds_read_b128 v[164:167], v242 offset:12544
	s_waitcnt lgkmcnt(6)
	v_mfma_f32_32x32x16_bf16 v[80:95], v[172:175], v[124:127], v[80:95]
	v_add_f32_e32 v245, v232, v245
	v_add_f32_e32 v246, v233, v246
	v_add_f32_e32 v245, v234, v245
	ds_read_b128 v[168:171], v243 offset:256
	s_waitcnt lgkmcnt(6)
	v_mfma_f32_32x32x16_bf16 v[64:79], v[144:147], v[128:131], v[64:79]
	v_add_f32_e32 v246, v235, v246
	v_add_f32_e32 v245, v236, v245
	v_add_f32_e32 v246, v237, v246
	ds_read_b128 v[172:175], v243 offset:12544
	s_waitcnt lgkmcnt(6)
	v_mfma_f32_32x32x16_bf16 v[80:95], v[148:151], v[128:131], v[80:95]
	v_add_f32_e32 v245, v238, v245
	v_add_f32_e32 v246, v239, v246
	s_add_u32 s42, s42, 0x6000
	s_addc_u32 s43, s43, 0
	v_add_u32_e32 v240, 0xfffeaff0, v240
	ds_read_b64_tr_b16 v[144:145], v244 offset:0
	ds_read_b64_tr_b16 v[146:147], v244 offset:2048
	s_waitcnt lgkmcnt(7)
	v_mfma_f32_32x32x16_bf16 v[64:79], v[152:155], v[132:135], v[64:79]
	v_cvt_pk_bf16_f32 v208, v208, v209
	v_cvt_pk_bf16_f32 v209, v210, v211
	v_cvt_pk_bf16_f32 v210, v212, v213
	v_add_u32_e32 v241, 0xfffeaff0, v241
	ds_read_b64_tr_b16 v[148:149], v244 offset:4096
	ds_read_b64_tr_b16 v[150:151], v244 offset:6144
	s_waitcnt lgkmcnt(8)
	v_mfma_f32_32x32x16_bf16 v[80:95], v[156:159], v[132:135], v[80:95]
	v_cvt_pk_bf16_f32 v211, v214, v215
	v_cvt_pk_bf16_f32 v212, v216, v217
	v_cvt_pk_bf16_f32 v213, v218, v219
	v_add_u32_e32 v242, 0xfffeaff0, v242
	ds_read_b64_tr_b16 v[152:153], v244 offset:8192
	ds_read_b64_tr_b16 v[154:155], v244 offset:10240
	s_waitcnt lgkmcnt(9)
	v_mfma_f32_32x32x16_bf16 v[64:79], v[160:163], v[136:139], v[64:79]
	v_cvt_pk_bf16_f32 v214, v220, v221
	v_cvt_pk_bf16_f32 v215, v222, v223
	s_add_u32 s46, s46, 0x40000
	s_addc_u32 s47, s47, 0
	v_add_u32_e32 v243, 0xfffeaff0, v243
	ds_read_b64_tr_b16 v[156:157], v244 offset:12288
	ds_read_b64_tr_b16 v[158:159], v244 offset:14336
	s_waitcnt lgkmcnt(10)
	v_mfma_f32_32x32x16_bf16 v[80:95], v[164:167], v[136:139], v[80:95]
	v_cvt_pk_bf16_f32 v224, v224, v225
	v_cvt_pk_bf16_f32 v225, v226, v227
	v_cvt_pk_bf16_f32 v226, v228, v229
	ds_read_b64_tr_b16 v[160:161], v244 offset:512
	ds_read_b64_tr_b16 v[162:163], v244 offset:2560
	s_waitcnt lgkmcnt(11)
	v_mfma_f32_32x32x16_bf16 v[64:79], v[168:171], v[140:143], v[64:79]
	v_cvt_pk_bf16_f32 v227, v230, v231
	v_cvt_pk_bf16_f32 v228, v232, v233
	v_cvt_pk_bf16_f32 v229, v234, v235
	ds_read_b64_tr_b16 v[164:165], v244 offset:4608
	ds_read_b64_tr_b16 v[166:167], v244 offset:6656
	s_waitcnt lgkmcnt(12)
	v_mfma_f32_32x32x16_bf16 v[80:95], v[172:175], v[140:143], v[80:95]
	v_cvt_pk_bf16_f32 v230, v236, v237
	v_cvt_pk_bf16_f32 v231, v238, v239
	s_waitcnt lgkmcnt(10)
	v_mfma_f32_32x32x16_bf16 v[48:63], v[208:211], v[144:147], v[48:63]
	s_waitcnt lgkmcnt(8)
	v_mfma_f32_32x32x16_bf16 v[48:63], v[212:215], v[148:151], v[48:63]
	ds_read_b64_tr_b16 v[168:169], v244 offset:8704
	ds_read_b64_tr_b16 v[170:171], v244 offset:10752
	s_waitcnt lgkmcnt(8)
	v_mfma_f32_32x32x16_bf16 v[48:63], v[224:227], v[152:155], v[48:63]
	v_exp_f32_e32 v64, v64
	v_exp_f32_e32 v65, v65
	ds_read_b64_tr_b16 v[172:173], v244 offset:12800
	ds_read_b64_tr_b16 v[174:175], v244 offset:14848
	s_waitcnt lgkmcnt(8)
	v_mfma_f32_32x32x16_bf16 v[48:63], v[228:231], v[156:159], v[48:63]
	v_exp_f32_e32 v66, v66
	v_exp_f32_e32 v67, v67
	ds_read_b64_tr_b16 v[144:145], v244 offset:1024
	ds_read_b64_tr_b16 v[146:147], v244 offset:3072
	s_waitcnt lgkmcnt(8)
	v_mfma_f32_32x32x16_bf16 v[32:47], v[208:211], v[160:163], v[32:47]
	v_exp_f32_e32 v68, v68
	ds_read_b64_tr_b16 v[148:149], v244 offset:5120
	ds_read_b64_tr_b16 v[150:151], v244 offset:7168
	s_waitcnt lgkmcnt(8)
	v_mfma_f32_32x32x16_bf16 v[32:47], v[212:215], v[164:167], v[32:47]
	v_exp_f32_e32 v69, v69
	ds_read_b64_tr_b16 v[152:153], v244 offset:9216
	ds_read_b64_tr_b16 v[154:155], v244 offset:11264
	s_waitcnt lgkmcnt(8)
	v_mfma_f32_32x32x16_bf16 v[32:47], v[224:227], v[168:171], v[32:47]
	v_exp_f32_e32 v70, v70
	ds_read_b64_tr_b16 v[156:157], v244 offset:13312
	ds_read_b64_tr_b16 v[158:159], v244 offset:15360
	s_waitcnt lgkmcnt(8)
	v_mfma_f32_32x32x16_bf16 v[32:47], v[228:231], v[172:175], v[32:47]
	v_exp_f32_e32 v71, v71
	ds_read_b64_tr_b16 v[160:161], v244 offset:1536
	ds_read_b64_tr_b16 v[162:163], v244 offset:3584
	s_waitcnt lgkmcnt(8)
	v_mfma_f32_32x32x16_bf16 v[16:31], v[208:211], v[144:147], v[16:31]
	v_exp_f32_e32 v72, v72
	ds_read_b64_tr_b16 v[164:165], v244 offset:5632
	ds_read_b64_tr_b16 v[166:167], v244 offset:7680
	s_waitcnt lgkmcnt(8)
	v_mfma_f32_32x32x16_bf16 v[16:31], v[212:215], v[148:151], v[16:31]
	v_exp_f32_e32 v73, v73
	ds_read_b64_tr_b16 v[168:169], v244 offset:9728
	ds_read_b64_tr_b16 v[170:171], v244 offset:11776
	ds_read_b64_tr_b16 v[172:173], v244 offset:13824
	ds_read_b64_tr_b16 v[174:175], v244 offset:15872
	ds_read_b128 v[144:147], v240 offset:0
	s_waitcnt lgkmcnt(11)
	v_mfma_f32_32x32x16_bf16 v[16:31], v[224:227], v[152:155], v[16:31]
	v_exp_f32_e32 v74, v74
	v_add_u32_e32 v244, 0xffff8000, v244
	ds_read_b128 v[148:151], v240 offset:12288
	s_waitcnt lgkmcnt(10)
	v_mfma_f32_32x32x16_bf16 v[16:31], v[228:231], v[156:159], v[16:31]
	v_exp_f32_e32 v75, v75
	ds_read_b128 v[152:155], v241 offset:0
	s_waitcnt lgkmcnt(9)
	v_mfma_f32_32x32x16_bf16 v[0:15], v[208:211], v[160:163], v[0:15]
	v_exp_f32_e32 v76, v76
	ds_read_b128 v[156:159], v241 offset:12288
	s_waitcnt lgkmcnt(8)
	v_mfma_f32_32x32x16_bf16 v[0:15], v[212:215], v[164:167], v[0:15]
	v_exp_f32_e32 v77, v77
	ds_read_b128 v[160:163], v242 offset:0
	s_waitcnt lgkmcnt(7)
	v_mfma_f32_32x32x16_bf16 v[0:15], v[224:227], v[168:171], v[0:15]
	v_exp_f32_e32 v78, v78
	ds_read_b128 v[164:167], v242 offset:12288
	s_waitcnt lgkmcnt(6)
	v_mfma_f32_32x32x16_bf16 v[0:15], v[228:231], v[172:175], v[0:15]
	v_exp_f32_e32 v79, v79
	s_waitcnt vmcnt(5)
	s_barrier
	ds_read_b128 v[168:171], v243 offset:0
	s_waitcnt lgkmcnt(6)
	v_mfma_f32_32x32x16_bf16 v[208:223], v[144:147], v[96:99], 0
	v_exp_f32_e32 v80, v80
	v_add_f32_e32 v245, v64, v245
	v_exp_f32_e32 v81, v81
	ds_read_b128 v[172:175], v243 offset:12288
	s_waitcnt lgkmcnt(6)
	v_mfma_f32_32x32x16_bf16 v[224:239], v[148:151], v[96:99], 0
	v_add_f32_e32 v246, v65, v246
	v_exp_f32_e32 v82, v82
	v_add_f32_e32 v245, v66, v245
	ds_read_b128 v[144:147], v240 offset:128
	s_waitcnt lgkmcnt(6)
	v_mfma_f32_32x32x16_bf16 v[208:223], v[152:155], v[100:103], v[208:223]
	v_exp_f32_e32 v83, v83
	v_add_f32_e32 v246, v67, v246
	s_add_i32 m0, s60, 0x21010
	s_nop 0
	global_load_lds_dwordx4 v182, s[42:43]
	ds_read_b128 v[148:151], v240 offset:12416
	s_waitcnt lgkmcnt(6)
	v_mfma_f32_32x32x16_bf16 v[224:239], v[156:159], v[100:103], v[224:239]
	v_exp_f32_e32 v84, v84
	v_add_f32_e32 v245, v68, v245
	v_exp_f32_e32 v85, v85
	ds_read_b128 v[152:155], v241 offset:128
	s_waitcnt lgkmcnt(6)
	v_mfma_f32_32x32x16_bf16 v[208:223], v[160:163], v[104:107], v[208:223]
	v_add_f32_e32 v246, v69, v246
	v_exp_f32_e32 v86, v86
	v_add_f32_e32 v245, v70, v245
	ds_read_b128 v[156:159], v241 offset:12416
	s_waitcnt lgkmcnt(6)
	v_mfma_f32_32x32x16_bf16 v[224:239], v[164:167], v[104:107], v[224:239]
	v_exp_f32_e32 v87, v87
	v_add_f32_e32 v246, v71, v246
	s_add_i32 m0, s60, 0x21410
	s_nop 0
	global_load_lds_dwordx4 v183, s[42:43]
	ds_read_b128 v[160:163], v242 offset:128
	s_waitcnt lgkmcnt(6)
	v_mfma_f32_32x32x16_bf16 v[208:223], v[168:171], v[108:111], v[208:223]
	v_exp_f32_e32 v88, v88
	v_add_f32_e32 v245, v72, v245
	v_exp_f32_e32 v89, v89
	ds_read_b128 v[164:167], v242 offset:12416
	s_waitcnt lgkmcnt(6)
	v_mfma_f32_32x32x16_bf16 v[224:239], v[172:175], v[108:111], v[224:239]
	v_add_f32_e32 v246, v73, v246
	v_exp_f32_e32 v90, v90
	v_add_f32_e32 v245, v74, v245
	ds_read_b128 v[168:171], v243 offset:128
	s_waitcnt lgkmcnt(6)
	v_mfma_f32_32x32x16_bf16 v[208:223], v[144:147], v[112:115], v[208:223]
	v_exp_f32_e32 v91, v91
	v_add_f32_e32 v246, v75, v246
	s_add_i32 m0, s60, 0x21810
	s_nop 0
	global_load_lds_dwordx4 v184, s[42:43]
	ds_read_b128 v[172:175], v243 offset:12416
	s_waitcnt lgkmcnt(6)
	v_mfma_f32_32x32x16_bf16 v[224:239], v[148:151], v[112:115], v[224:239]
	v_exp_f32_e32 v92, v92
	v_add_f32_e32 v245, v76, v245
	v_exp_f32_e32 v93, v93
	ds_read_b128 v[144:147], v240 offset:256
	s_waitcnt lgkmcnt(6)
	v_mfma_f32_32x32x16_bf16 v[208:223], v[152:155], v[116:119], v[208:223]
	v_add_f32_e32 v246, v77, v246
	v_exp_f32_e32 v94, v94
	v_add_f32_e32 v245, v78, v245
	ds_read_b128 v[148:151], v240 offset:12544
	s_waitcnt lgkmcnt(6)
	v_mfma_f32_32x32x16_bf16 v[224:239], v[156:159], v[116:119], v[224:239]
	v_exp_f32_e32 v95, v95
	v_add_f32_e32 v246, v79, v246
	s_add_i32 m0, s61, 0x8000
	s_nop 0
	global_load_lds_dwordx4 v185, s[46:47]
	ds_read_b128 v[152:155], v241 offset:256
	s_waitcnt lgkmcnt(6)
	v_mfma_f32_32x32x16_bf16 v[208:223], v[160:163], v[120:123], v[208:223]
	v_add_f32_e32 v245, v80, v245
	v_add_f32_e32 v246, v81, v246
	v_add_f32_e32 v245, v82, v245
	ds_read_b128 v[156:159], v241 offset:12544
	s_waitcnt lgkmcnt(6)
	v_mfma_f32_32x32x16_bf16 v[224:239], v[164:167], v[120:123], v[224:239]
	v_add_f32_e32 v246, v83, v246
	v_add_f32_e32 v245, v84, v245
	v_add_f32_e32 v246, v85, v246
	ds_read_b128 v[160:163], v242 offset:256
	s_waitcnt lgkmcnt(6)
	v_mfma_f32_32x32x16_bf16 v[208:223], v[168:171], v[124:127], v[208:223]
	v_add_f32_e32 v245, v86, v245
	v_add_f32_e32 v246, v87, v246
	s_add_i32 m0, s61, 0x8400
	s_nop 0
	global_load_lds_dwordx4 v186, s[46:47]
	ds_read_b128 v[164:167], v242 offset:12544
	s_waitcnt lgkmcnt(6)
	v_mfma_f32_32x32x16_bf16 v[224:239], v[172:175], v[124:127], v[224:239]
	v_add_f32_e32 v245, v88, v245
	v_add_f32_e32 v246, v89, v246
	v_add_f32_e32 v245, v90, v245
	ds_read_b128 v[168:171], v243 offset:256
	s_waitcnt lgkmcnt(6)
	v_mfma_f32_32x32x16_bf16 v[208:223], v[144:147], v[128:131], v[208:223]
	v_add_f32_e32 v246, v91, v246
	v_add_f32_e32 v245, v92, v245
	v_add_f32_e32 v246, v93, v246
	ds_read_b128 v[172:175], v243 offset:12544
	s_waitcnt lgkmcnt(6)
	v_mfma_f32_32x32x16_bf16 v[224:239], v[148:151], v[128:131], v[224:239]
	v_add_f32_e32 v245, v94, v245
	v_add_f32_e32 v246, v95, v246
	s_add_u32 s42, s42, 0x6000
	s_addc_u32 s43, s43, 0
	v_add_u32_e32 v240, 0x6000, v240
	ds_read_b64_tr_b16 v[144:145], v244 offset:0
	ds_read_b64_tr_b16 v[146:147], v244 offset:2048
	s_waitcnt lgkmcnt(7)
	v_mfma_f32_32x32x16_bf16 v[208:223], v[152:155], v[132:135], v[208:223]
	v_cvt_pk_bf16_f32 v64, v64, v65
	v_cvt_pk_bf16_f32 v65, v66, v67
	v_cvt_pk_bf16_f32 v66, v68, v69
	v_add_u32_e32 v241, 0x6000, v241
	ds_read_b64_tr_b16 v[148:149], v244 offset:4096
	ds_read_b64_tr_b16 v[150:151], v244 offset:6144
	s_waitcnt lgkmcnt(8)
	v_mfma_f32_32x32x16_bf16 v[224:239], v[156:159], v[132:135], v[224:239]
	v_cvt_pk_bf16_f32 v67, v70, v71
	v_cvt_pk_bf16_f32 v68, v72, v73
	v_cvt_pk_bf16_f32 v69, v74, v75
	v_add_u32_e32 v242, 0x6000, v242
	ds_read_b64_tr_b16 v[152:153], v244 offset:8192
	ds_read_b64_tr_b16 v[154:155], v244 offset:10240
	s_waitcnt lgkmcnt(9)
	v_mfma_f32_32x32x16_bf16 v[208:223], v[160:163], v[136:139], v[208:223]
	v_cvt_pk_bf16_f32 v70, v76, v77
	v_cvt_pk_bf16_f32 v71, v78, v79
	s_add_u32 s46, s46, 0x40000
	s_addc_u32 s47, s47, 0
	v_add_u32_e32 v243, 0x6000, v243
	ds_read_b64_tr_b16 v[156:157], v244 offset:12288
	ds_read_b64_tr_b16 v[158:159], v244 offset:14336
	s_waitcnt lgkmcnt(10)
	v_mfma_f32_32x32x16_bf16 v[224:239], v[164:167], v[136:139], v[224:239]
	v_cvt_pk_bf16_f32 v80, v80, v81
	v_cvt_pk_bf16_f32 v81, v82, v83
	v_cvt_pk_bf16_f32 v82, v84, v85
	ds_read_b64_tr_b16 v[160:161], v244 offset:512
	ds_read_b64_tr_b16 v[162:163], v244 offset:2560
	s_waitcnt lgkmcnt(11)
	v_mfma_f32_32x32x16_bf16 v[208:223], v[168:171], v[140:143], v[208:223]
	v_cvt_pk_bf16_f32 v83, v86, v87
	v_cvt_pk_bf16_f32 v84, v88, v89
	v_cvt_pk_bf16_f32 v85, v90, v91
	ds_read_b64_tr_b16 v[164:165], v244 offset:4608
	ds_read_b64_tr_b16 v[166:167], v244 offset:6656
	s_waitcnt lgkmcnt(12)
	v_mfma_f32_32x32x16_bf16 v[224:239], v[172:175], v[140:143], v[224:239]
	v_cvt_pk_bf16_f32 v86, v92, v93
	v_cvt_pk_bf16_f32 v87, v94, v95
	s_waitcnt lgkmcnt(10)
	v_mfma_f32_32x32x16_bf16 v[48:63], v[64:67], v[144:147], v[48:63]
	s_waitcnt lgkmcnt(8)
	v_mfma_f32_32x32x16_bf16 v[48:63], v[68:71], v[148:151], v[48:63]
	ds_read_b64_tr_b16 v[168:169], v244 offset:8704
	ds_read_b64_tr_b16 v[170:171], v244 offset:10752
	s_waitcnt lgkmcnt(8)
	v_mfma_f32_32x32x16_bf16 v[48:63], v[80:83], v[152:155], v[48:63]
	v_exp_f32_e32 v208, v208
	v_exp_f32_e32 v209, v209
	ds_read_b64_tr_b16 v[172:173], v244 offset:12800
	ds_read_b64_tr_b16 v[174:175], v244 offset:14848
	s_waitcnt lgkmcnt(8)
	v_mfma_f32_32x32x16_bf16 v[48:63], v[84:87], v[156:159], v[48:63]
	v_exp_f32_e32 v210, v210
	v_exp_f32_e32 v211, v211
	ds_read_b64_tr_b16 v[144:145], v244 offset:1024
	ds_read_b64_tr_b16 v[146:147], v244 offset:3072
	s_waitcnt lgkmcnt(8)
	v_mfma_f32_32x32x16_bf16 v[32:47], v[64:67], v[160:163], v[32:47]
	v_exp_f32_e32 v212, v212
	ds_read_b64_tr_b16 v[148:149], v244 offset:5120
	ds_read_b64_tr_b16 v[150:151], v244 offset:7168
	s_waitcnt lgkmcnt(8)
	v_mfma_f32_32x32x16_bf16 v[32:47], v[68:71], v[164:167], v[32:47]
	v_exp_f32_e32 v213, v213
	ds_read_b64_tr_b16 v[152:153], v244 offset:9216
	ds_read_b64_tr_b16 v[154:155], v244 offset:11264
	s_waitcnt lgkmcnt(8)
	v_mfma_f32_32x32x16_bf16 v[32:47], v[80:83], v[168:171], v[32:47]
	v_exp_f32_e32 v214, v214
	ds_read_b64_tr_b16 v[156:157], v244 offset:13312
	ds_read_b64_tr_b16 v[158:159], v244 offset:15360
	s_waitcnt lgkmcnt(8)
	v_mfma_f32_32x32x16_bf16 v[32:47], v[84:87], v[172:175], v[32:47]
	v_exp_f32_e32 v215, v215
	ds_read_b64_tr_b16 v[160:161], v244 offset:1536
	ds_read_b64_tr_b16 v[162:163], v244 offset:3584
	s_waitcnt lgkmcnt(8)
	v_mfma_f32_32x32x16_bf16 v[16:31], v[64:67], v[144:147], v[16:31]
	v_exp_f32_e32 v216, v216
	ds_read_b64_tr_b16 v[164:165], v244 offset:5632
	ds_read_b64_tr_b16 v[166:167], v244 offset:7680
	s_waitcnt lgkmcnt(8)
	v_mfma_f32_32x32x16_bf16 v[16:31], v[68:71], v[148:151], v[16:31]
	v_exp_f32_e32 v217, v217
	ds_read_b64_tr_b16 v[168:169], v244 offset:9728
	ds_read_b64_tr_b16 v[170:171], v244 offset:11776
	ds_read_b64_tr_b16 v[172:173], v244 offset:13824
	ds_read_b64_tr_b16 v[174:175], v244 offset:15872
	ds_read_b128 v[144:147], v240 offset:0
	s_waitcnt lgkmcnt(11)
	v_mfma_f32_32x32x16_bf16 v[16:31], v[80:83], v[152:155], v[16:31]
	v_exp_f32_e32 v218, v218
	v_add_u32_e32 v244, 0x4000, v244
	ds_read_b128 v[148:151], v240 offset:12288
	s_waitcnt lgkmcnt(10)
	v_mfma_f32_32x32x16_bf16 v[16:31], v[84:87], v[156:159], v[16:31]
	v_exp_f32_e32 v219, v219
	ds_read_b128 v[152:155], v241 offset:0
	s_waitcnt lgkmcnt(9)
	v_mfma_f32_32x32x16_bf16 v[0:15], v[64:67], v[160:163], v[0:15]
	v_exp_f32_e32 v220, v220
	ds_read_b128 v[156:159], v241 offset:12288
	s_waitcnt lgkmcnt(8)
	v_mfma_f32_32x32x16_bf16 v[0:15], v[68:71], v[164:167], v[0:15]
	v_exp_f32_e32 v221, v221
	ds_read_b128 v[160:163], v242 offset:0
	s_waitcnt lgkmcnt(7)
	v_mfma_f32_32x32x16_bf16 v[0:15], v[80:83], v[168:171], v[0:15]
	v_exp_f32_e32 v222, v222
	ds_read_b128 v[164:167], v242 offset:12288
	s_waitcnt lgkmcnt(6)
	v_mfma_f32_32x32x16_bf16 v[0:15], v[84:87], v[172:175], v[0:15]
	v_exp_f32_e32 v223, v223
	s_waitcnt vmcnt(5)
	s_barrier
	ds_read_b128 v[168:171], v243 offset:0
	s_waitcnt lgkmcnt(6)
	v_mfma_f32_32x32x16_bf16 v[64:79], v[144:147], v[96:99], 0
	v_exp_f32_e32 v224, v224
	v_add_f32_e32 v245, v208, v245
	v_exp_f32_e32 v225, v225
	ds_read_b128 v[172:175], v243 offset:12288
	s_waitcnt lgkmcnt(6)
	v_mfma_f32_32x32x16_bf16 v[80:95], v[148:151], v[96:99], 0
	v_add_f32_e32 v246, v209, v246
	v_exp_f32_e32 v226, v226
	v_add_f32_e32 v245, v210, v245
	ds_read_b128 v[144:147], v240 offset:128
	s_waitcnt lgkmcnt(6)
	v_mfma_f32_32x32x16_bf16 v[64:79], v[152:155], v[100:103], v[64:79]
	v_exp_f32_e32 v227, v227
	v_add_f32_e32 v246, v211, v246
	s_add_i32 m0, s60, 0xc000
	s_nop 0
	global_load_lds_dwordx4 v182, s[42:43]
	ds_read_b128 v[148:151], v240 offset:12416
	s_waitcnt lgkmcnt(6)
	v_mfma_f32_32x32x16_bf16 v[80:95], v[156:159], v[100:103], v[80:95]
	v_exp_f32_e32 v228, v228
	v_add_f32_e32 v245, v212, v245
	v_exp_f32_e32 v229, v229
	ds_read_b128 v[152:155], v241 offset:128
	s_waitcnt lgkmcnt(6)
	v_mfma_f32_32x32x16_bf16 v[64:79], v[160:163], v[104:107], v[64:79]
	v_add_f32_e32 v246, v213, v246
	v_exp_f32_e32 v230, v230
	v_add_f32_e32 v245, v214, v245
	ds_read_b128 v[156:159], v241 offset:12416
	s_waitcnt lgkmcnt(6)
	v_mfma_f32_32x32x16_bf16 v[80:95], v[164:167], v[104:107], v[80:95]
	v_exp_f32_e32 v231, v231
	v_add_f32_e32 v246, v215, v246
	s_add_i32 m0, s60, 0xc400
	s_nop 0
	global_load_lds_dwordx4 v183, s[42:43]
	ds_read_b128 v[160:163], v242 offset:128
	s_waitcnt lgkmcnt(6)
	v_mfma_f32_32x32x16_bf16 v[64:79], v[168:171], v[108:111], v[64:79]
	v_exp_f32_e32 v232, v232
	v_add_f32_e32 v245, v216, v245
	v_exp_f32_e32 v233, v233
	ds_read_b128 v[164:167], v242 offset:12416
	s_waitcnt lgkmcnt(6)
	v_mfma_f32_32x32x16_bf16 v[80:95], v[172:175], v[108:111], v[80:95]
	v_add_f32_e32 v246, v217, v246
	v_exp_f32_e32 v234, v234
	v_add_f32_e32 v245, v218, v245
	ds_read_b128 v[168:171], v243 offset:128
	s_waitcnt lgkmcnt(6)
	v_mfma_f32_32x32x16_bf16 v[64:79], v[144:147], v[112:115], v[64:79]
	v_exp_f32_e32 v235, v235
	v_add_f32_e32 v246, v219, v246
	s_add_i32 m0, s60, 0xc800
	s_nop 0
	global_load_lds_dwordx4 v184, s[42:43]
	ds_read_b128 v[172:175], v243 offset:12416
	s_waitcnt lgkmcnt(6)
	v_mfma_f32_32x32x16_bf16 v[80:95], v[148:151], v[112:115], v[80:95]
	v_exp_f32_e32 v236, v236
	v_add_f32_e32 v245, v220, v245
	v_exp_f32_e32 v237, v237
	ds_read_b128 v[144:147], v240 offset:256
	s_waitcnt lgkmcnt(6)
	v_mfma_f32_32x32x16_bf16 v[64:79], v[152:155], v[116:119], v[64:79]
	v_add_f32_e32 v246, v221, v246
	v_exp_f32_e32 v238, v238
	v_add_f32_e32 v245, v222, v245
	ds_read_b128 v[148:151], v240 offset:12544
	s_waitcnt lgkmcnt(6)
	v_mfma_f32_32x32x16_bf16 v[80:95], v[156:159], v[116:119], v[80:95]
	v_exp_f32_e32 v239, v239
	v_add_f32_e32 v246, v223, v246
	s_add_i32 m0, s61, 0x0
	s_nop 0
	global_load_lds_dwordx4 v185, s[46:47]
	ds_read_b128 v[152:155], v241 offset:256
	s_waitcnt lgkmcnt(6)
	v_mfma_f32_32x32x16_bf16 v[64:79], v[160:163], v[120:123], v[64:79]
	v_add_f32_e32 v245, v224, v245
	v_add_f32_e32 v246, v225, v246
	v_add_f32_e32 v245, v226, v245
	ds_read_b128 v[156:159], v241 offset:12544
	s_waitcnt lgkmcnt(6)
	v_mfma_f32_32x32x16_bf16 v[80:95], v[164:167], v[120:123], v[80:95]
	v_add_f32_e32 v246, v227, v246
	v_add_f32_e32 v245, v228, v245
	v_add_f32_e32 v246, v229, v246
	ds_read_b128 v[160:163], v242 offset:256
	s_waitcnt lgkmcnt(6)
	v_mfma_f32_32x32x16_bf16 v[64:79], v[168:171], v[124:127], v[64:79]
	v_add_f32_e32 v245, v230, v245
	v_add_f32_e32 v246, v231, v246
	s_add_i32 m0, s61, 0x400
	s_nop 0
	global_load_lds_dwordx4 v186, s[46:47]
	ds_read_b128 v[164:167], v242 offset:12544
	s_waitcnt lgkmcnt(6)
	v_mfma_f32_32x32x16_bf16 v[80:95], v[172:175], v[124:127], v[80:95]
	v_add_f32_e32 v245, v232, v245
	v_add_f32_e32 v246, v233, v246
	v_add_f32_e32 v245, v234, v245
	ds_read_b128 v[168:171], v243 offset:256
	s_waitcnt lgkmcnt(6)
	v_mfma_f32_32x32x16_bf16 v[64:79], v[144:147], v[128:131], v[64:79]
	v_add_f32_e32 v246, v235, v246
	v_add_f32_e32 v245, v236, v245
	v_add_f32_e32 v246, v237, v246
	ds_read_b128 v[172:175], v243 offset:12544
	s_waitcnt lgkmcnt(6)
	v_mfma_f32_32x32x16_bf16 v[80:95], v[148:151], v[128:131], v[80:95]
	v_add_f32_e32 v245, v238, v245
	v_add_f32_e32 v246, v239, v246
	s_add_u32 s42, s42, 0x6000
	s_addc_u32 s43, s43, 0
	v_add_u32_e32 v240, 0x6000, v240
	ds_read_b64_tr_b16 v[144:145], v244 offset:0
	ds_read_b64_tr_b16 v[146:147], v244 offset:2048
	s_waitcnt lgkmcnt(7)
	v_mfma_f32_32x32x16_bf16 v[64:79], v[152:155], v[132:135], v[64:79]
	v_cvt_pk_bf16_f32 v208, v208, v209
	v_cvt_pk_bf16_f32 v209, v210, v211
	v_cvt_pk_bf16_f32 v210, v212, v213
	v_add_u32_e32 v241, 0x6000, v241
	ds_read_b64_tr_b16 v[148:149], v244 offset:4096
	ds_read_b64_tr_b16 v[150:151], v244 offset:6144
	s_waitcnt lgkmcnt(8)
	v_mfma_f32_32x32x16_bf16 v[80:95], v[156:159], v[132:135], v[80:95]
	v_cvt_pk_bf16_f32 v211, v214, v215
	v_cvt_pk_bf16_f32 v212, v216, v217
	v_cvt_pk_bf16_f32 v213, v218, v219
	v_add_u32_e32 v242, 0x6000, v242
	ds_read_b64_tr_b16 v[152:153], v244 offset:8192
	ds_read_b64_tr_b16 v[154:155], v244 offset:10240
	s_waitcnt lgkmcnt(9)
	v_mfma_f32_32x32x16_bf16 v[64:79], v[160:163], v[136:139], v[64:79]
	v_cvt_pk_bf16_f32 v214, v220, v221
	v_cvt_pk_bf16_f32 v215, v222, v223
	s_add_u32 s46, s46, 0x40000
	s_addc_u32 s47, s47, 0
	v_add_u32_e32 v243, 0x6000, v243
	ds_read_b64_tr_b16 v[156:157], v244 offset:12288
	ds_read_b64_tr_b16 v[158:159], v244 offset:14336
	s_waitcnt lgkmcnt(10)
	v_mfma_f32_32x32x16_bf16 v[80:95], v[164:167], v[136:139], v[80:95]
	v_cvt_pk_bf16_f32 v224, v224, v225
	v_cvt_pk_bf16_f32 v225, v226, v227
	v_cvt_pk_bf16_f32 v226, v228, v229
	ds_read_b64_tr_b16 v[160:161], v244 offset:512
	ds_read_b64_tr_b16 v[162:163], v244 offset:2560
	s_waitcnt lgkmcnt(11)
	v_mfma_f32_32x32x16_bf16 v[64:79], v[168:171], v[140:143], v[64:79]
	v_cvt_pk_bf16_f32 v227, v230, v231
	v_cvt_pk_bf16_f32 v228, v232, v233
	v_cvt_pk_bf16_f32 v229, v234, v235
	ds_read_b64_tr_b16 v[164:165], v244 offset:4608
	ds_read_b64_tr_b16 v[166:167], v244 offset:6656
	s_waitcnt lgkmcnt(12)
	v_mfma_f32_32x32x16_bf16 v[80:95], v[172:175], v[140:143], v[80:95]
	v_cvt_pk_bf16_f32 v230, v236, v237
	v_cvt_pk_bf16_f32 v231, v238, v239
	s_waitcnt lgkmcnt(10)
	v_mfma_f32_32x32x16_bf16 v[48:63], v[208:211], v[144:147], v[48:63]
	s_waitcnt lgkmcnt(8)
	v_mfma_f32_32x32x16_bf16 v[48:63], v[212:215], v[148:151], v[48:63]
	ds_read_b64_tr_b16 v[168:169], v244 offset:8704
	ds_read_b64_tr_b16 v[170:171], v244 offset:10752
	s_waitcnt lgkmcnt(8)
	v_mfma_f32_32x32x16_bf16 v[48:63], v[224:227], v[152:155], v[48:63]
	v_exp_f32_e32 v64, v64
	v_exp_f32_e32 v65, v65
	ds_read_b64_tr_b16 v[172:173], v244 offset:12800
	ds_read_b64_tr_b16 v[174:175], v244 offset:14848
	s_waitcnt lgkmcnt(8)
	v_mfma_f32_32x32x16_bf16 v[48:63], v[228:231], v[156:159], v[48:63]
	v_exp_f32_e32 v66, v66
	v_exp_f32_e32 v67, v67
	ds_read_b64_tr_b16 v[144:145], v244 offset:1024
	ds_read_b64_tr_b16 v[146:147], v244 offset:3072
	s_waitcnt lgkmcnt(8)
	v_mfma_f32_32x32x16_bf16 v[32:47], v[208:211], v[160:163], v[32:47]
	v_exp_f32_e32 v68, v68
	ds_read_b64_tr_b16 v[148:149], v244 offset:5120
	ds_read_b64_tr_b16 v[150:151], v244 offset:7168
	s_waitcnt lgkmcnt(8)
	v_mfma_f32_32x32x16_bf16 v[32:47], v[212:215], v[164:167], v[32:47]
	v_exp_f32_e32 v69, v69
	ds_read_b64_tr_b16 v[152:153], v244 offset:9216
	ds_read_b64_tr_b16 v[154:155], v244 offset:11264
	s_waitcnt lgkmcnt(8)
	v_mfma_f32_32x32x16_bf16 v[32:47], v[224:227], v[168:171], v[32:47]
	v_exp_f32_e32 v70, v70
	ds_read_b64_tr_b16 v[156:157], v244 offset:13312
	ds_read_b64_tr_b16 v[158:159], v244 offset:15360
	s_waitcnt lgkmcnt(8)
	v_mfma_f32_32x32x16_bf16 v[32:47], v[228:231], v[172:175], v[32:47]
	v_exp_f32_e32 v71, v71
	ds_read_b64_tr_b16 v[160:161], v244 offset:1536
	ds_read_b64_tr_b16 v[162:163], v244 offset:3584
	s_waitcnt lgkmcnt(8)
	v_mfma_f32_32x32x16_bf16 v[16:31], v[208:211], v[144:147], v[16:31]
	v_exp_f32_e32 v72, v72
	ds_read_b64_tr_b16 v[164:165], v244 offset:5632
	ds_read_b64_tr_b16 v[166:167], v244 offset:7680
	s_waitcnt lgkmcnt(8)
	v_mfma_f32_32x32x16_bf16 v[16:31], v[212:215], v[148:151], v[16:31]
	v_exp_f32_e32 v73, v73
	ds_read_b64_tr_b16 v[168:169], v244 offset:9728
	ds_read_b64_tr_b16 v[170:171], v244 offset:11776
	ds_read_b64_tr_b16 v[172:173], v244 offset:13824
	ds_read_b64_tr_b16 v[174:175], v244 offset:15872
	ds_read_b128 v[144:147], v240 offset:0
	s_waitcnt lgkmcnt(11)
	v_mfma_f32_32x32x16_bf16 v[16:31], v[224:227], v[152:155], v[16:31]
	v_exp_f32_e32 v74, v74
	v_add_u32_e32 v244, 0x4000, v244
	ds_read_b128 v[148:151], v240 offset:12288
	s_waitcnt lgkmcnt(10)
	v_mfma_f32_32x32x16_bf16 v[16:31], v[228:231], v[156:159], v[16:31]
	v_exp_f32_e32 v75, v75
	ds_read_b128 v[152:155], v241 offset:0
	s_waitcnt lgkmcnt(9)
	v_mfma_f32_32x32x16_bf16 v[0:15], v[208:211], v[160:163], v[0:15]
	v_exp_f32_e32 v76, v76
	ds_read_b128 v[156:159], v241 offset:12288
	s_waitcnt lgkmcnt(8)
	v_mfma_f32_32x32x16_bf16 v[0:15], v[212:215], v[164:167], v[0:15]
	v_exp_f32_e32 v77, v77
	ds_read_b128 v[160:163], v242 offset:0
	s_waitcnt lgkmcnt(7)
	v_mfma_f32_32x32x16_bf16 v[0:15], v[224:227], v[168:171], v[0:15]
	v_exp_f32_e32 v78, v78
	ds_read_b128 v[164:167], v242 offset:12288
	s_waitcnt lgkmcnt(6)
	v_mfma_f32_32x32x16_bf16 v[0:15], v[228:231], v[172:175], v[0:15]
	v_exp_f32_e32 v79, v79
	s_waitcnt vmcnt(5)
	s_barrier
	ds_read_b128 v[168:171], v243 offset:0
	s_waitcnt lgkmcnt(6)
	v_mfma_f32_32x32x16_bf16 v[208:223], v[144:147], v[96:99], 0
	v_exp_f32_e32 v80, v80
	v_add_f32_e32 v245, v64, v245
	v_exp_f32_e32 v81, v81
	ds_read_b128 v[172:175], v243 offset:12288
	s_waitcnt lgkmcnt(6)
	v_mfma_f32_32x32x16_bf16 v[224:239], v[148:151], v[96:99], 0
	v_add_f32_e32 v246, v65, v246
	v_exp_f32_e32 v82, v82
	v_add_f32_e32 v245, v66, v245
	ds_read_b128 v[144:147], v240 offset:128
	s_waitcnt lgkmcnt(6)
	v_mfma_f32_32x32x16_bf16 v[208:223], v[152:155], v[100:103], v[208:223]
	v_exp_f32_e32 v83, v83
	v_add_f32_e32 v246, v67, v246
	s_add_i32 m0, s60, 0x12000
	s_nop 0
	global_load_lds_dwordx4 v182, s[42:43]
	ds_read_b128 v[148:151], v240 offset:12416
	s_waitcnt lgkmcnt(6)
	v_mfma_f32_32x32x16_bf16 v[224:239], v[156:159], v[100:103], v[224:239]
	v_exp_f32_e32 v84, v84
	v_add_f32_e32 v245, v68, v245
	v_exp_f32_e32 v85, v85
	ds_read_b128 v[152:155], v241 offset:128
	s_waitcnt lgkmcnt(6)
	v_mfma_f32_32x32x16_bf16 v[208:223], v[160:163], v[104:107], v[208:223]
	v_add_f32_e32 v246, v69, v246
	v_exp_f32_e32 v86, v86
	v_add_f32_e32 v245, v70, v245
	ds_read_b128 v[156:159], v241 offset:12416
	s_waitcnt lgkmcnt(6)
	v_mfma_f32_32x32x16_bf16 v[224:239], v[164:167], v[104:107], v[224:239]
	v_exp_f32_e32 v87, v87
	v_add_f32_e32 v246, v71, v246
	s_add_i32 m0, s60, 0x12400
	s_nop 0
	global_load_lds_dwordx4 v183, s[42:43]
	ds_read_b128 v[160:163], v242 offset:128
	s_waitcnt lgkmcnt(6)
	v_mfma_f32_32x32x16_bf16 v[208:223], v[168:171], v[108:111], v[208:223]
	v_exp_f32_e32 v88, v88
	v_add_f32_e32 v245, v72, v245
	v_exp_f32_e32 v89, v89
	ds_read_b128 v[164:167], v242 offset:12416
	s_waitcnt lgkmcnt(6)
	v_mfma_f32_32x32x16_bf16 v[224:239], v[172:175], v[108:111], v[224:239]
	v_add_f32_e32 v246, v73, v246
	v_exp_f32_e32 v90, v90
	v_add_f32_e32 v245, v74, v245
	ds_read_b128 v[168:171], v243 offset:128
	s_waitcnt lgkmcnt(6)
	v_mfma_f32_32x32x16_bf16 v[208:223], v[144:147], v[112:115], v[208:223]
	v_exp_f32_e32 v91, v91
	v_add_f32_e32 v246, v75, v246
	s_add_i32 m0, s60, 0x12800
	s_nop 0
	global_load_lds_dwordx4 v184, s[42:43]
	ds_read_b128 v[172:175], v243 offset:12416
	s_waitcnt lgkmcnt(6)
	v_mfma_f32_32x32x16_bf16 v[224:239], v[148:151], v[112:115], v[224:239]
	v_exp_f32_e32 v92, v92
	v_add_f32_e32 v245, v76, v245
	v_exp_f32_e32 v93, v93
	ds_read_b128 v[144:147], v240 offset:256
	s_waitcnt lgkmcnt(6)
	v_mfma_f32_32x32x16_bf16 v[208:223], v[152:155], v[116:119], v[208:223]
	v_add_f32_e32 v246, v77, v246
	v_exp_f32_e32 v94, v94
	v_add_f32_e32 v245, v78, v245
	ds_read_b128 v[148:151], v240 offset:12544
	s_waitcnt lgkmcnt(6)
	v_mfma_f32_32x32x16_bf16 v[224:239], v[156:159], v[116:119], v[224:239]
	v_exp_f32_e32 v95, v95
	v_add_f32_e32 v246, v79, v246
	s_add_i32 m0, s61, 0x4000
	s_nop 0
	global_load_lds_dwordx4 v185, s[46:47]
	ds_read_b128 v[152:155], v241 offset:256
	s_waitcnt lgkmcnt(6)
	v_mfma_f32_32x32x16_bf16 v[208:223], v[160:163], v[120:123], v[208:223]
	v_add_f32_e32 v245, v80, v245
	v_add_f32_e32 v246, v81, v246
	v_add_f32_e32 v245, v82, v245
	ds_read_b128 v[156:159], v241 offset:12544
	s_waitcnt lgkmcnt(6)
	v_mfma_f32_32x32x16_bf16 v[224:239], v[164:167], v[120:123], v[224:239]
	v_add_f32_e32 v246, v83, v246
	v_add_f32_e32 v245, v84, v245
	v_add_f32_e32 v246, v85, v246
	ds_read_b128 v[160:163], v242 offset:256
	s_waitcnt lgkmcnt(6)
	v_mfma_f32_32x32x16_bf16 v[208:223], v[168:171], v[124:127], v[208:223]
	v_add_f32_e32 v245, v86, v245
	v_add_f32_e32 v246, v87, v246
	s_add_i32 m0, s61, 0x4400
	s_nop 0
	global_load_lds_dwordx4 v186, s[46:47]
	ds_read_b128 v[164:167], v242 offset:12544
	s_waitcnt lgkmcnt(6)
	v_mfma_f32_32x32x16_bf16 v[224:239], v[172:175], v[124:127], v[224:239]
	v_add_f32_e32 v245, v88, v245
	v_add_f32_e32 v246, v89, v246
	v_add_f32_e32 v245, v90, v245
	ds_read_b128 v[168:171], v243 offset:256
	s_waitcnt lgkmcnt(6)
	v_mfma_f32_32x32x16_bf16 v[208:223], v[144:147], v[128:131], v[208:223]
	v_add_f32_e32 v246, v91, v246
	v_add_f32_e32 v245, v92, v245
	v_add_f32_e32 v246, v93, v246
	ds_read_b128 v[172:175], v243 offset:12544
	s_waitcnt lgkmcnt(6)
	v_mfma_f32_32x32x16_bf16 v[224:239], v[148:151], v[128:131], v[224:239]
	v_add_f32_e32 v245, v94, v245
	v_add_f32_e32 v246, v95, v246
	s_add_u32 s42, s42, 0x6000
	s_addc_u32 s43, s43, 0
	v_add_u32_e32 v240, 0x9010, v240
	ds_read_b64_tr_b16 v[144:145], v244 offset:0
	ds_read_b64_tr_b16 v[146:147], v244 offset:2048
	s_waitcnt lgkmcnt(7)
	v_mfma_f32_32x32x16_bf16 v[208:223], v[152:155], v[132:135], v[208:223]
	v_cvt_pk_bf16_f32 v64, v64, v65
	v_cvt_pk_bf16_f32 v65, v66, v67
	v_cvt_pk_bf16_f32 v66, v68, v69
	v_add_u32_e32 v241, 0x9010, v241
	ds_read_b64_tr_b16 v[148:149], v244 offset:4096
	ds_read_b64_tr_b16 v[150:151], v244 offset:6144
	s_waitcnt lgkmcnt(8)
	v_mfma_f32_32x32x16_bf16 v[224:239], v[156:159], v[132:135], v[224:239]
	v_cvt_pk_bf16_f32 v67, v70, v71
	v_cvt_pk_bf16_f32 v68, v72, v73
	v_cvt_pk_bf16_f32 v69, v74, v75
	v_add_u32_e32 v242, 0x9010, v242
	ds_read_b64_tr_b16 v[152:153], v244 offset:8192
	ds_read_b64_tr_b16 v[154:155], v244 offset:10240
	s_waitcnt lgkmcnt(9)
	v_mfma_f32_32x32x16_bf16 v[208:223], v[160:163], v[136:139], v[208:223]
	v_cvt_pk_bf16_f32 v70, v76, v77
	v_cvt_pk_bf16_f32 v71, v78, v79
	s_add_u32 s46, s46, 0x40000
	s_addc_u32 s47, s47, 0
	v_add_u32_e32 v243, 0x9010, v243
	ds_read_b64_tr_b16 v[156:157], v244 offset:12288
	ds_read_b64_tr_b16 v[158:159], v244 offset:14336
	s_waitcnt lgkmcnt(10)
	v_mfma_f32_32x32x16_bf16 v[224:239], v[164:167], v[136:139], v[224:239]
	v_cvt_pk_bf16_f32 v80, v80, v81
	v_cvt_pk_bf16_f32 v81, v82, v83
	v_cvt_pk_bf16_f32 v82, v84, v85
	ds_read_b64_tr_b16 v[160:161], v244 offset:512
	ds_read_b64_tr_b16 v[162:163], v244 offset:2560
	s_waitcnt lgkmcnt(11)
	v_mfma_f32_32x32x16_bf16 v[208:223], v[168:171], v[140:143], v[208:223]
	v_cvt_pk_bf16_f32 v83, v86, v87
	v_cvt_pk_bf16_f32 v84, v88, v89
	v_cvt_pk_bf16_f32 v85, v90, v91
	ds_read_b64_tr_b16 v[164:165], v244 offset:4608
	ds_read_b64_tr_b16 v[166:167], v244 offset:6656
	s_waitcnt lgkmcnt(12)
	v_mfma_f32_32x32x16_bf16 v[224:239], v[172:175], v[140:143], v[224:239]
	v_cvt_pk_bf16_f32 v86, v92, v93
	v_cvt_pk_bf16_f32 v87, v94, v95
	s_waitcnt lgkmcnt(10)
	v_mfma_f32_32x32x16_bf16 v[48:63], v[64:67], v[144:147], v[48:63]
	s_waitcnt lgkmcnt(8)
	v_mfma_f32_32x32x16_bf16 v[48:63], v[68:71], v[148:151], v[48:63]
	ds_read_b64_tr_b16 v[168:169], v244 offset:8704
	ds_read_b64_tr_b16 v[170:171], v244 offset:10752
	s_waitcnt lgkmcnt(8)
	v_mfma_f32_32x32x16_bf16 v[48:63], v[80:83], v[152:155], v[48:63]
	v_exp_f32_e32 v208, v208
	v_exp_f32_e32 v209, v209
	ds_read_b64_tr_b16 v[172:173], v244 offset:12800
	ds_read_b64_tr_b16 v[174:175], v244 offset:14848
	s_waitcnt lgkmcnt(8)
	v_mfma_f32_32x32x16_bf16 v[48:63], v[84:87], v[156:159], v[48:63]
	v_exp_f32_e32 v210, v210
	v_exp_f32_e32 v211, v211
	ds_read_b64_tr_b16 v[144:145], v244 offset:1024
	ds_read_b64_tr_b16 v[146:147], v244 offset:3072
	s_waitcnt lgkmcnt(8)
	v_mfma_f32_32x32x16_bf16 v[32:47], v[64:67], v[160:163], v[32:47]
	v_exp_f32_e32 v212, v212
	ds_read_b64_tr_b16 v[148:149], v244 offset:5120
	ds_read_b64_tr_b16 v[150:151], v244 offset:7168
	s_waitcnt lgkmcnt(8)
	v_mfma_f32_32x32x16_bf16 v[32:47], v[68:71], v[164:167], v[32:47]
	v_exp_f32_e32 v213, v213
	ds_read_b64_tr_b16 v[152:153], v244 offset:9216
	ds_read_b64_tr_b16 v[154:155], v244 offset:11264
	s_waitcnt lgkmcnt(8)
	v_mfma_f32_32x32x16_bf16 v[32:47], v[80:83], v[168:171], v[32:47]
	v_exp_f32_e32 v214, v214
	ds_read_b64_tr_b16 v[156:157], v244 offset:13312
	ds_read_b64_tr_b16 v[158:159], v244 offset:15360
	s_waitcnt lgkmcnt(8)
	v_mfma_f32_32x32x16_bf16 v[32:47], v[84:87], v[172:175], v[32:47]
	v_exp_f32_e32 v215, v215
	ds_read_b64_tr_b16 v[160:161], v244 offset:1536
	ds_read_b64_tr_b16 v[162:163], v244 offset:3584
	s_waitcnt lgkmcnt(8)
	v_mfma_f32_32x32x16_bf16 v[16:31], v[64:67], v[144:147], v[16:31]
	v_exp_f32_e32 v216, v216
	ds_read_b64_tr_b16 v[164:165], v244 offset:5632
	ds_read_b64_tr_b16 v[166:167], v244 offset:7680
	s_waitcnt lgkmcnt(8)
	v_mfma_f32_32x32x16_bf16 v[16:31], v[68:71], v[148:151], v[16:31]
	v_exp_f32_e32 v217, v217
	ds_read_b64_tr_b16 v[168:169], v244 offset:9728
	ds_read_b64_tr_b16 v[170:171], v244 offset:11776
	ds_read_b64_tr_b16 v[172:173], v244 offset:13824
	ds_read_b64_tr_b16 v[174:175], v244 offset:15872
	ds_read_b128 v[144:147], v240 offset:0
	s_waitcnt lgkmcnt(11)
	v_mfma_f32_32x32x16_bf16 v[16:31], v[80:83], v[152:155], v[16:31]
	v_exp_f32_e32 v218, v218
	v_add_u32_e32 v244, 0xffff8000, v244
	ds_read_b128 v[148:151], v240 offset:12288
	s_waitcnt lgkmcnt(10)
	v_mfma_f32_32x32x16_bf16 v[16:31], v[84:87], v[156:159], v[16:31]
	v_exp_f32_e32 v219, v219
	ds_read_b128 v[152:155], v241 offset:0
	s_waitcnt lgkmcnt(9)
	v_mfma_f32_32x32x16_bf16 v[0:15], v[64:67], v[160:163], v[0:15]
	v_exp_f32_e32 v220, v220
	ds_read_b128 v[156:159], v241 offset:12288
	s_waitcnt lgkmcnt(8)
	v_mfma_f32_32x32x16_bf16 v[0:15], v[68:71], v[164:167], v[0:15]
	v_exp_f32_e32 v221, v221
	ds_read_b128 v[160:163], v242 offset:0
	s_waitcnt lgkmcnt(7)
	v_mfma_f32_32x32x16_bf16 v[0:15], v[80:83], v[168:171], v[0:15]
	v_exp_f32_e32 v222, v222
	ds_read_b128 v[164:167], v242 offset:12288
	s_waitcnt lgkmcnt(6)
	v_mfma_f32_32x32x16_bf16 v[0:15], v[84:87], v[172:175], v[0:15]
	v_exp_f32_e32 v223, v223
	s_waitcnt vmcnt(0)
	s_barrier
	ds_read_b128 v[168:171], v243 offset:0
	s_waitcnt lgkmcnt(6)
	v_mfma_f32_32x32x16_bf16 v[64:79], v[144:147], v[96:99], 0
	v_exp_f32_e32 v224, v224
	v_add_f32_e32 v245, v208, v245
	v_exp_f32_e32 v225, v225
	ds_read_b128 v[172:175], v243 offset:12288
	s_waitcnt lgkmcnt(6)
	v_mfma_f32_32x32x16_bf16 v[80:95], v[148:151], v[96:99], 0
	v_add_f32_e32 v246, v209, v246
	v_exp_f32_e32 v226, v226
	v_add_f32_e32 v245, v210, v245
	ds_read_b128 v[144:147], v240 offset:128
	s_waitcnt lgkmcnt(6)
	v_mfma_f32_32x32x16_bf16 v[64:79], v[152:155], v[100:103], v[64:79]
	v_exp_f32_e32 v227, v227
	v_add_f32_e32 v246, v211, v246
	v_exp_f32_e32 v228, v228
	ds_read_b128 v[148:151], v240 offset:12416
	s_waitcnt lgkmcnt(6)
	v_mfma_f32_32x32x16_bf16 v[80:95], v[156:159], v[100:103], v[80:95]
	v_add_f32_e32 v245, v212, v245
	v_exp_f32_e32 v229, v229
	v_add_f32_e32 v246, v213, v246
	ds_read_b128 v[152:155], v241 offset:128
	s_waitcnt lgkmcnt(6)
	v_mfma_f32_32x32x16_bf16 v[64:79], v[160:163], v[104:107], v[64:79]
	v_exp_f32_e32 v230, v230
	v_add_f32_e32 v245, v214, v245
	v_exp_f32_e32 v231, v231
	ds_read_b128 v[156:159], v241 offset:12416
	s_waitcnt lgkmcnt(6)
	v_mfma_f32_32x32x16_bf16 v[80:95], v[164:167], v[104:107], v[80:95]
	v_add_f32_e32 v246, v215, v246
	v_exp_f32_e32 v232, v232
	v_add_f32_e32 v245, v216, v245
	ds_read_b128 v[160:163], v242 offset:128
	s_waitcnt lgkmcnt(6)
	v_mfma_f32_32x32x16_bf16 v[64:79], v[168:171], v[108:111], v[64:79]
	v_exp_f32_e32 v233, v233
	v_add_f32_e32 v246, v217, v246
	v_exp_f32_e32 v234, v234
	ds_read_b128 v[164:167], v242 offset:12416
	s_waitcnt lgkmcnt(6)
	v_mfma_f32_32x32x16_bf16 v[80:95], v[172:175], v[108:111], v[80:95]
	v_add_f32_e32 v245, v218, v245
	v_exp_f32_e32 v235, v235
	v_add_f32_e32 v246, v219, v246
	ds_read_b128 v[168:171], v243 offset:128
	s_waitcnt lgkmcnt(6)
	v_mfma_f32_32x32x16_bf16 v[64:79], v[144:147], v[112:115], v[64:79]
	v_exp_f32_e32 v236, v236
	v_add_f32_e32 v245, v220, v245
	v_exp_f32_e32 v237, v237
	ds_read_b128 v[172:175], v243 offset:12416
	s_waitcnt lgkmcnt(6)
	v_mfma_f32_32x32x16_bf16 v[80:95], v[148:151], v[112:115], v[80:95]
	v_add_f32_e32 v246, v221, v246
	v_exp_f32_e32 v238, v238
	v_add_f32_e32 v245, v222, v245
	ds_read_b128 v[144:147], v240 offset:256
	s_waitcnt lgkmcnt(6)
	v_mfma_f32_32x32x16_bf16 v[64:79], v[152:155], v[116:119], v[64:79]
	v_exp_f32_e32 v239, v239
	v_add_f32_e32 v246, v223, v246
	v_add_f32_e32 v245, v224, v245
	ds_read_b128 v[148:151], v240 offset:12544
	s_waitcnt lgkmcnt(6)
	v_mfma_f32_32x32x16_bf16 v[80:95], v[156:159], v[116:119], v[80:95]
	v_add_f32_e32 v246, v225, v246
	v_add_f32_e32 v245, v226, v245
	v_add_f32_e32 v246, v227, v246
	ds_read_b128 v[152:155], v241 offset:256
	s_waitcnt lgkmcnt(6)
	v_mfma_f32_32x32x16_bf16 v[64:79], v[160:163], v[120:123], v[64:79]
	v_add_f32_e32 v245, v228, v245
	v_add_f32_e32 v246, v229, v246
	v_add_f32_e32 v245, v230, v245
	ds_read_b128 v[156:159], v241 offset:12544
	s_waitcnt lgkmcnt(6)
	v_mfma_f32_32x32x16_bf16 v[80:95], v[164:167], v[120:123], v[80:95]
	v_add_f32_e32 v246, v231, v246
	v_add_f32_e32 v245, v232, v245
	v_add_f32_e32 v246, v233, v246
	ds_read_b128 v[160:163], v242 offset:256
	s_waitcnt lgkmcnt(6)
	v_mfma_f32_32x32x16_bf16 v[64:79], v[168:171], v[124:127], v[64:79]
	v_add_f32_e32 v245, v234, v245
	v_add_f32_e32 v246, v235, v246
	v_add_f32_e32 v245, v236, v245
	ds_read_b128 v[164:167], v242 offset:12544
	s_waitcnt lgkmcnt(6)
	v_mfma_f32_32x32x16_bf16 v[80:95], v[172:175], v[124:127], v[80:95]
	v_add_f32_e32 v246, v237, v246
	v_add_f32_e32 v245, v238, v245
	v_add_f32_e32 v246, v239, v246
	ds_read_b128 v[168:171], v243 offset:256
	s_waitcnt lgkmcnt(6)
	v_mfma_f32_32x32x16_bf16 v[64:79], v[144:147], v[128:131], v[64:79]
	v_cvt_pk_bf16_f32 v208, v208, v209
	v_cvt_pk_bf16_f32 v209, v210, v211
	ds_read_b128 v[172:175], v243 offset:12544
	s_waitcnt lgkmcnt(6)
	v_mfma_f32_32x32x16_bf16 v[80:95], v[148:151], v[128:131], v[80:95]
	v_cvt_pk_bf16_f32 v210, v212, v213
	v_cvt_pk_bf16_f32 v211, v214, v215
	ds_read_b64_tr_b16 v[144:145], v244 offset:0
	ds_read_b64_tr_b16 v[146:147], v244 offset:2048
	s_waitcnt lgkmcnt(7)
	v_mfma_f32_32x32x16_bf16 v[64:79], v[152:155], v[132:135], v[64:79]
	v_cvt_pk_bf16_f32 v212, v216, v217
	v_cvt_pk_bf16_f32 v213, v218, v219
	ds_read_b64_tr_b16 v[148:149], v244 offset:4096
	ds_read_b64_tr_b16 v[150:151], v244 offset:6144
	s_waitcnt lgkmcnt(8)
	v_mfma_f32_32x32x16_bf16 v[80:95], v[156:159], v[132:135], v[80:95]
	v_cvt_pk_bf16_f32 v214, v220, v221
	v_cvt_pk_bf16_f32 v215, v222, v223
	ds_read_b64_tr_b16 v[152:153], v244 offset:8192
	ds_read_b64_tr_b16 v[154:155], v244 offset:10240
	s_waitcnt lgkmcnt(9)
	v_mfma_f32_32x32x16_bf16 v[64:79], v[160:163], v[136:139], v[64:79]
	v_cvt_pk_bf16_f32 v224, v224, v225
	v_cvt_pk_bf16_f32 v225, v226, v227
	ds_read_b64_tr_b16 v[156:157], v244 offset:12288
	ds_read_b64_tr_b16 v[158:159], v244 offset:14336
	s_waitcnt lgkmcnt(10)
	v_mfma_f32_32x32x16_bf16 v[80:95], v[164:167], v[136:139], v[80:95]
	v_cvt_pk_bf16_f32 v226, v228, v229
	v_cvt_pk_bf16_f32 v227, v230, v231
	ds_read_b64_tr_b16 v[160:161], v244 offset:512
	ds_read_b64_tr_b16 v[162:163], v244 offset:2560
	s_waitcnt lgkmcnt(11)
	v_mfma_f32_32x32x16_bf16 v[64:79], v[168:171], v[140:143], v[64:79]
	v_cvt_pk_bf16_f32 v228, v232, v233
	v_cvt_pk_bf16_f32 v229, v234, v235
	ds_read_b64_tr_b16 v[164:165], v244 offset:4608
	ds_read_b64_tr_b16 v[166:167], v244 offset:6656
	s_waitcnt lgkmcnt(12)
	v_mfma_f32_32x32x16_bf16 v[80:95], v[172:175], v[140:143], v[80:95]
	v_cvt_pk_bf16_f32 v230, v236, v237
	v_cvt_pk_bf16_f32 v231, v238, v239
	s_waitcnt lgkmcnt(10)
	v_mfma_f32_32x32x16_bf16 v[48:63], v[208:211], v[144:147], v[48:63]
	s_waitcnt lgkmcnt(8)
	v_mfma_f32_32x32x16_bf16 v[48:63], v[212:215], v[148:151], v[48:63]
	ds_read_b64_tr_b16 v[168:169], v244 offset:8704
	ds_read_b64_tr_b16 v[170:171], v244 offset:10752
	s_waitcnt lgkmcnt(8)
	v_mfma_f32_32x32x16_bf16 v[48:63], v[224:227], v[152:155], v[48:63]
	v_exp_f32_e32 v64, v64
	v_exp_f32_e32 v65, v65
	ds_read_b64_tr_b16 v[172:173], v244 offset:12800
	ds_read_b64_tr_b16 v[174:175], v244 offset:14848
	s_waitcnt lgkmcnt(8)
	v_mfma_f32_32x32x16_bf16 v[48:63], v[228:231], v[156:159], v[48:63]
	v_exp_f32_e32 v66, v66
	v_exp_f32_e32 v67, v67
	ds_read_b64_tr_b16 v[144:145], v244 offset:1024
	ds_read_b64_tr_b16 v[146:147], v244 offset:3072
	s_waitcnt lgkmcnt(8)
	v_mfma_f32_32x32x16_bf16 v[32:47], v[208:211], v[160:163], v[32:47]
	v_exp_f32_e32 v68, v68
	ds_read_b64_tr_b16 v[148:149], v244 offset:5120
	ds_read_b64_tr_b16 v[150:151], v244 offset:7168
	s_waitcnt lgkmcnt(8)
	v_mfma_f32_32x32x16_bf16 v[32:47], v[212:215], v[164:167], v[32:47]
	v_exp_f32_e32 v69, v69
	ds_read_b64_tr_b16 v[152:153], v244 offset:9216
	ds_read_b64_tr_b16 v[154:155], v244 offset:11264
	s_waitcnt lgkmcnt(8)
	v_mfma_f32_32x32x16_bf16 v[32:47], v[224:227], v[168:171], v[32:47]
	v_exp_f32_e32 v70, v70
	ds_read_b64_tr_b16 v[156:157], v244 offset:13312
	ds_read_b64_tr_b16 v[158:159], v244 offset:15360
	s_waitcnt lgkmcnt(8)
	v_mfma_f32_32x32x16_bf16 v[32:47], v[228:231], v[172:175], v[32:47]
	v_exp_f32_e32 v71, v71
	ds_read_b64_tr_b16 v[160:161], v244 offset:1536
	ds_read_b64_tr_b16 v[162:163], v244 offset:3584
	s_waitcnt lgkmcnt(8)
	v_mfma_f32_32x32x16_bf16 v[16:31], v[208:211], v[144:147], v[16:31]
	v_exp_f32_e32 v72, v72
	ds_read_b64_tr_b16 v[164:165], v244 offset:5632
	ds_read_b64_tr_b16 v[166:167], v244 offset:7680
	s_waitcnt lgkmcnt(8)
	v_mfma_f32_32x32x16_bf16 v[16:31], v[212:215], v[148:151], v[16:31]
	v_exp_f32_e32 v73, v73
	ds_read_b64_tr_b16 v[168:169], v244 offset:9728
	ds_read_b64_tr_b16 v[170:171], v244 offset:11776
	s_waitcnt lgkmcnt(8)
	v_mfma_f32_32x32x16_bf16 v[16:31], v[224:227], v[152:155], v[16:31]
	v_exp_f32_e32 v74, v74
	ds_read_b64_tr_b16 v[172:173], v244 offset:13824
	ds_read_b64_tr_b16 v[174:175], v244 offset:15872
	s_waitcnt lgkmcnt(8)
	v_mfma_f32_32x32x16_bf16 v[16:31], v[228:231], v[156:159], v[16:31]
	v_exp_f32_e32 v75, v75
	v_add_u32_e32 v244, 0x4000, v244
	s_waitcnt lgkmcnt(6)
	v_mfma_f32_32x32x16_bf16 v[0:15], v[208:211], v[160:163], v[0:15]
	v_exp_f32_e32 v76, v76
	s_waitcnt lgkmcnt(4)
	v_mfma_f32_32x32x16_bf16 v[0:15], v[212:215], v[164:167], v[0:15]
	v_exp_f32_e32 v77, v77
	s_waitcnt lgkmcnt(2)
	v_mfma_f32_32x32x16_bf16 v[0:15], v[224:227], v[168:171], v[0:15]
	v_exp_f32_e32 v78, v78
	s_waitcnt lgkmcnt(0)
	v_mfma_f32_32x32x16_bf16 v[0:15], v[228:231], v[172:175], v[0:15]
	v_exp_f32_e32 v79, v79
	ds_read_b64_tr_b16 v[144:145], v244 offset:0
	ds_read_b64_tr_b16 v[146:147], v244 offset:2048
	ds_read_b64_tr_b16 v[148:149], v244 offset:4096
	ds_read_b64_tr_b16 v[150:151], v244 offset:6144
	ds_read_b64_tr_b16 v[152:153], v244 offset:8192
	ds_read_b64_tr_b16 v[154:155], v244 offset:10240
	ds_read_b64_tr_b16 v[156:157], v244 offset:12288
	ds_read_b64_tr_b16 v[158:159], v244 offset:14336
	v_exp_f32_e32 v80, v80
	v_add_f32_e32 v245, v64, v245
	v_exp_f32_e32 v81, v81
	v_add_f32_e32 v246, v65, v246
	v_exp_f32_e32 v82, v82
	v_add_f32_e32 v245, v66, v245
	v_exp_f32_e32 v83, v83
	v_add_f32_e32 v246, v67, v246
	v_exp_f32_e32 v84, v84
	v_add_f32_e32 v245, v68, v245
	v_exp_f32_e32 v85, v85
	v_add_f32_e32 v246, v69, v246
	v_exp_f32_e32 v86, v86
	v_add_f32_e32 v245, v70, v245
	v_exp_f32_e32 v87, v87
	v_add_f32_e32 v246, v71, v246
	v_exp_f32_e32 v88, v88
	v_add_f32_e32 v245, v72, v245
	v_exp_f32_e32 v89, v89
	v_add_f32_e32 v246, v73, v246
	v_exp_f32_e32 v90, v90
	v_add_f32_e32 v245, v74, v245
	v_exp_f32_e32 v91, v91
	v_add_f32_e32 v246, v75, v246
	v_exp_f32_e32 v92, v92
	v_add_f32_e32 v245, v76, v245
	v_exp_f32_e32 v93, v93
	v_add_f32_e32 v246, v77, v246
	v_exp_f32_e32 v94, v94
	v_add_f32_e32 v245, v78, v245
	v_exp_f32_e32 v95, v95
	v_add_f32_e32 v246, v79, v246
	v_add_f32_e32 v245, v80, v245
	v_add_f32_e32 v246, v81, v246
	v_add_f32_e32 v245, v82, v245
	v_add_f32_e32 v246, v83, v246
	v_add_f32_e32 v245, v84, v245
	v_add_f32_e32 v246, v85, v246
	v_add_f32_e32 v245, v86, v245
	v_add_f32_e32 v246, v87, v246
	v_add_f32_e32 v245, v88, v245
	v_add_f32_e32 v246, v89, v246
	v_add_f32_e32 v245, v90, v245
	v_add_f32_e32 v246, v91, v246
	v_add_f32_e32 v245, v92, v245
	v_add_f32_e32 v246, v93, v246
	v_add_f32_e32 v245, v94, v245
	v_add_f32_e32 v246, v95, v246
	v_cvt_pk_bf16_f32 v64, v64, v65
	v_cvt_pk_bf16_f32 v65, v66, v67
	v_cvt_pk_bf16_f32 v66, v68, v69
	v_cvt_pk_bf16_f32 v67, v70, v71
	v_cvt_pk_bf16_f32 v68, v72, v73
	v_cvt_pk_bf16_f32 v69, v74, v75
	v_cvt_pk_bf16_f32 v70, v76, v77
	v_cvt_pk_bf16_f32 v71, v78, v79
	v_cvt_pk_bf16_f32 v80, v80, v81
	v_cvt_pk_bf16_f32 v81, v82, v83
	v_cvt_pk_bf16_f32 v82, v84, v85
	v_cvt_pk_bf16_f32 v83, v86, v87
	v_cvt_pk_bf16_f32 v84, v88, v89
	v_cvt_pk_bf16_f32 v85, v90, v91
	v_cvt_pk_bf16_f32 v86, v92, v93
	v_cvt_pk_bf16_f32 v87, v94, v95
	ds_read_b64_tr_b16 v[160:161], v244 offset:512
	ds_read_b64_tr_b16 v[162:163], v244 offset:2560
	s_waitcnt lgkmcnt(8)
	v_mfma_f32_32x32x16_bf16 v[48:63], v[64:67], v[144:147], v[48:63]
	ds_read_b64_tr_b16 v[164:165], v244 offset:4608
	ds_read_b64_tr_b16 v[166:167], v244 offset:6656
	s_waitcnt lgkmcnt(8)
	v_mfma_f32_32x32x16_bf16 v[48:63], v[68:71], v[148:151], v[48:63]
	ds_read_b64_tr_b16 v[168:169], v244 offset:8704
	ds_read_b64_tr_b16 v[170:171], v244 offset:10752
	s_waitcnt lgkmcnt(8)
	v_mfma_f32_32x32x16_bf16 v[48:63], v[80:83], v[152:155], v[48:63]
	ds_read_b64_tr_b16 v[172:173], v244 offset:12800
	ds_read_b64_tr_b16 v[174:175], v244 offset:14848
	s_waitcnt lgkmcnt(8)
	v_mfma_f32_32x32x16_bf16 v[48:63], v[84:87], v[156:159], v[48:63]
	ds_read_b64_tr_b16 v[144:145], v244 offset:1024
	ds_read_b64_tr_b16 v[146:147], v244 offset:3072
	s_waitcnt lgkmcnt(8)
	v_mfma_f32_32x32x16_bf16 v[32:47], v[64:67], v[160:163], v[32:47]
	ds_read_b64_tr_b16 v[148:149], v244 offset:5120
	ds_read_b64_tr_b16 v[150:151], v244 offset:7168
	s_waitcnt lgkmcnt(8)
	v_mfma_f32_32x32x16_bf16 v[32:47], v[68:71], v[164:167], v[32:47]
	ds_read_b64_tr_b16 v[152:153], v244 offset:9216
	ds_read_b64_tr_b16 v[154:155], v244 offset:11264
	s_waitcnt lgkmcnt(8)
	v_mfma_f32_32x32x16_bf16 v[32:47], v[80:83], v[168:171], v[32:47]
	ds_read_b64_tr_b16 v[156:157], v244 offset:13312
	ds_read_b64_tr_b16 v[158:159], v244 offset:15360
	s_waitcnt lgkmcnt(8)
	v_mfma_f32_32x32x16_bf16 v[32:47], v[84:87], v[172:175], v[32:47]
	ds_read_b64_tr_b16 v[160:161], v244 offset:1536
	ds_read_b64_tr_b16 v[162:163], v244 offset:3584
	s_waitcnt lgkmcnt(8)
	v_mfma_f32_32x32x16_bf16 v[16:31], v[64:67], v[144:147], v[16:31]
	ds_read_b64_tr_b16 v[164:165], v244 offset:5632
	ds_read_b64_tr_b16 v[166:167], v244 offset:7680
	s_waitcnt lgkmcnt(8)
	v_mfma_f32_32x32x16_bf16 v[16:31], v[68:71], v[148:151], v[16:31]
	ds_read_b64_tr_b16 v[168:169], v244 offset:9728
	ds_read_b64_tr_b16 v[170:171], v244 offset:11776
	s_waitcnt lgkmcnt(8)
	v_mfma_f32_32x32x16_bf16 v[16:31], v[80:83], v[152:155], v[16:31]
	ds_read_b64_tr_b16 v[172:173], v244 offset:13824
	ds_read_b64_tr_b16 v[174:175], v244 offset:15872
	s_waitcnt lgkmcnt(8)
	v_mfma_f32_32x32x16_bf16 v[16:31], v[84:87], v[156:159], v[16:31]
	s_waitcnt lgkmcnt(6)
	v_mfma_f32_32x32x16_bf16 v[0:15], v[64:67], v[160:163], v[0:15]
	s_waitcnt lgkmcnt(4)
	v_mfma_f32_32x32x16_bf16 v[0:15], v[68:71], v[164:167], v[0:15]
	s_waitcnt lgkmcnt(2)
	v_mfma_f32_32x32x16_bf16 v[0:15], v[80:83], v[168:171], v[0:15]
	s_waitcnt lgkmcnt(0)
	v_mfma_f32_32x32x16_bf16 v[0:15], v[84:87], v[172:175], v[0:15]
	v_add_f32_e32 v245, v245, v246
	v_mov_b32_e32 v246, v245
	s_nop 1
	v_permlane32_swap_b32_e32 v245, v246
	v_add_f32_e32 v245, v245, v246
	v_cmp_gt_u32_e32 vcc, 32, v200
	v_lshl_add_u32 v247, v196, 2, s44
	s_and_saveexec_b64 s[42:43], vcc
	ds_write_b32 v247, v245
	s_or_b64 exec, exec, s[42:43]
	s_lshl_b64 s[2:3], s[40:41], 13
	s_or_b64 s[12:13], s[2:3], s[34:35]
	s_mul_i32 s1, s13, 0x3600
	s_mul_hi_u32 s2, s12, 0x3600
	s_add_i32 s1, s2, s1
	s_mul_i32 s14, s12, 0x3600
	s_lshl_b64 s[2:3], s[12:13], 12
	s_lshl_b64 s[12:13], s[12:13], 5
	s_add_u32 s14, s38, s14
	s_addc_u32 s1, s39, s1
	s_add_u32 s15, s72, s2
	s_addc_u32 s30, s73, s3
	s_lshl_b32 s31, s49, 8
	v_lshl_or_b32 v164, v198, 2, s52
	s_add_u32 s2, s14, s31
	s_addc_u32 s3, s1, 0
	s_add_u32 s2, s2, 0x11802c80
	s_addc_u32 s3, s3, 0
	v_subrev_u32_e32 v165, s52, v164
	v_lshl_add_u32 v166, v165, 2, s44
	s_add_u32 s14, s15, s31
	s_addc_u32 s15, s30, 0
	s_add_u32 s1, s74, s12
	s_addc_u32 s12, s75, s13
	s_lshl_b32 s13, s49, 2
	s_add_u32 s42, s1, s13
	s_addc_u32 s43, s12, 0
	v_lshlrev_b32_e32 v167, 1, v196
	v_mul_u32_u24_e32 v168, 0x3600, v164
	v_lshl_add_u32 v169, v164, 12, v167
	v_add_u32_e32 v168, v168, v167
	v_lshlrev_b32_e32 v170, 5, v164
	s_waitcnt lgkmcnt(0)
	ds_read_b32 v128, v166 offset:0
	ds_read_b32 v129, v166 offset:4
	ds_read_b32 v130, v166 offset:8
	ds_read_b32 v131, v166 offset:12
	ds_read_b32 v132, v166 offset:32
	ds_read_b32 v133, v166 offset:36
	ds_read_b32 v134, v166 offset:40
	ds_read_b32 v135, v166 offset:44
	ds_read_b32 v136, v166 offset:64
	ds_read_b32 v137, v166 offset:68
	ds_read_b32 v138, v166 offset:72
	ds_read_b32 v139, v166 offset:76
	ds_read_b32 v140, v166 offset:96
	ds_read_b32 v141, v166 offset:100
	ds_read_b32 v142, v166 offset:104
	ds_read_b32 v143, v166 offset:108
	v_mov_b32_e32 v171, v168
	global_load_ushort v64, v171, s[2:3] offset:0
	global_load_ushort v65, v171, s[2:3] offset:64
	global_load_ushort v66, v171, s[2:3] offset:128
	global_load_ushort v67, v171, s[2:3] offset:192
	v_add_u32_e32 v172, 0x3600, v168
	global_load_ushort v68, v172, s[2:3] offset:0
	global_load_ushort v69, v172, s[2:3] offset:64
	global_load_ushort v70, v172, s[2:3] offset:128
	global_load_ushort v71, v172, s[2:3] offset:192
	v_add_u32_e32 v173, 0x6c00, v168
	global_load_ushort v72, v173, s[2:3] offset:0
	global_load_ushort v73, v173, s[2:3] offset:64
	global_load_ushort v74, v173, s[2:3] offset:128
	global_load_ushort v75, v173, s[2:3] offset:192
	v_add_u32_e32 v174, 0xa200, v168
	global_load_ushort v76, v174, s[2:3] offset:0
	global_load_ushort v77, v174, s[2:3] offset:64
	global_load_ushort v78, v174, s[2:3] offset:128
	global_load_ushort v79, v174, s[2:3] offset:192
	v_add_u32_e32 v171, 0x1b000, v168
	global_load_ushort v80, v171, s[2:3] offset:0
	global_load_ushort v81, v171, s[2:3] offset:64
	global_load_ushort v82, v171, s[2:3] offset:128
	global_load_ushort v83, v171, s[2:3] offset:192
	v_add_u32_e32 v172, 0x1e600, v168
	global_load_ushort v84, v172, s[2:3] offset:0
	global_load_ushort v85, v172, s[2:3] offset:64
	global_load_ushort v86, v172, s[2:3] offset:128
	global_load_ushort v87, v172, s[2:3] offset:192
	v_add_u32_e32 v173, 0x21c00, v168
	global_load_ushort v88, v173, s[2:3] offset:0
	global_load_ushort v89, v173, s[2:3] offset:64
	global_load_ushort v90, v173, s[2:3] offset:128
	global_load_ushort v91, v173, s[2:3] offset:192
	v_add_u32_e32 v174, 0x25200, v168
	global_load_ushort v92, v174, s[2:3] offset:0
	global_load_ushort v93, v174, s[2:3] offset:64
	global_load_ushort v94, v174, s[2:3] offset:128
	global_load_ushort v95, v174, s[2:3] offset:192
	v_add_u32_e32 v171, 0x36000, v168
	global_load_ushort v96, v171, s[2:3] offset:0
	global_load_ushort v97, v171, s[2:3] offset:64
	global_load_ushort v98, v171, s[2:3] offset:128
	global_load_ushort v99, v171, s[2:3] offset:192
	v_add_u32_e32 v172, 0x39600, v168
	global_load_ushort v100, v172, s[2:3] offset:0
	global_load_ushort v101, v172, s[2:3] offset:64
	global_load_ushort v102, v172, s[2:3] offset:128
	global_load_ushort v103, v172, s[2:3] offset:192
	v_add_u32_e32 v173, 0x3cc00, v168
	global_load_ushort v104, v173, s[2:3] offset:0
	global_load_ushort v105, v173, s[2:3] offset:64
	global_load_ushort v106, v173, s[2:3] offset:128
	global_load_ushort v107, v173, s[2:3] offset:192
	v_add_u32_e32 v174, 0x40200, v168
	global_load_ushort v108, v174, s[2:3] offset:0
	global_load_ushort v109, v174, s[2:3] offset:64
	global_load_ushort v110, v174, s[2:3] offset:128
	global_load_ushort v111, v174, s[2:3] offset:192
	v_add_u32_e32 v171, 0x51000, v168
	global_load_ushort v112, v171, s[2:3] offset:0
	global_load_ushort v113, v171, s[2:3] offset:64
	global_load_ushort v114, v171, s[2:3] offset:128
	global_load_ushort v115, v171, s[2:3] offset:192
	v_add_u32_e32 v172, 0x54600, v168
	global_load_ushort v116, v172, s[2:3] offset:0
	global_load_ushort v117, v172, s[2:3] offset:64
	global_load_ushort v118, v172, s[2:3] offset:128
	global_load_ushort v119, v172, s[2:3] offset:192
	v_add_u32_e32 v173, 0x57c00, v168
	global_load_ushort v120, v173, s[2:3] offset:0
	global_load_ushort v121, v173, s[2:3] offset:64
	global_load_ushort v122, v173, s[2:3] offset:128
	global_load_ushort v123, v173, s[2:3] offset:192
	v_add_u32_e32 v174, 0x5b200, v168
	global_load_ushort v124, v174, s[2:3] offset:0
	global_load_ushort v125, v174, s[2:3] offset:64
	global_load_ushort v126, v174, s[2:3] offset:128
	global_load_ushort v127, v174, s[2:3] offset:192
	s_waitcnt lgkmcnt(0)
	v_rcp_f32_e32 v128, v128
	v_rcp_f32_e32 v129, v129
	v_rcp_f32_e32 v130, v130
	v_rcp_f32_e32 v131, v131
	v_rcp_f32_e32 v132, v132
	v_rcp_f32_e32 v133, v133
	v_rcp_f32_e32 v134, v134
	v_rcp_f32_e32 v135, v135
	v_rcp_f32_e32 v136, v136
	v_rcp_f32_e32 v137, v137
	v_rcp_f32_e32 v138, v138
	v_rcp_f32_e32 v139, v139
	v_rcp_f32_e32 v140, v140
	v_rcp_f32_e32 v141, v141
	v_rcp_f32_e32 v142, v142
	v_rcp_f32_e32 v143, v143
	v_mul_f32_e32 v48, v48, v128
	v_mul_f32_e32 v32, v32, v128
	v_mul_f32_e32 v16, v16, v128
	v_mul_f32_e32 v0, v0, v128
	v_mul_f32_e32 v49, v49, v129
	v_mul_f32_e32 v33, v33, v129
	v_mul_f32_e32 v17, v17, v129
	v_mul_f32_e32 v1, v1, v129
	v_mul_f32_e32 v50, v50, v130
	v_mul_f32_e32 v34, v34, v130
	v_mul_f32_e32 v18, v18, v130
	v_mul_f32_e32 v2, v2, v130
	v_mul_f32_e32 v51, v51, v131
	v_mul_f32_e32 v35, v35, v131
	v_mul_f32_e32 v19, v19, v131
	v_mul_f32_e32 v3, v3, v131
	v_mul_f32_e32 v52, v52, v132
	v_mul_f32_e32 v36, v36, v132
	v_mul_f32_e32 v20, v20, v132
	v_mul_f32_e32 v4, v4, v132
	v_mul_f32_e32 v53, v53, v133
	v_mul_f32_e32 v37, v37, v133
	v_mul_f32_e32 v21, v21, v133
	v_mul_f32_e32 v5, v5, v133
	v_mul_f32_e32 v54, v54, v134
	v_mul_f32_e32 v38, v38, v134
	v_mul_f32_e32 v22, v22, v134
	v_mul_f32_e32 v6, v6, v134
	v_mul_f32_e32 v55, v55, v135
	v_mul_f32_e32 v39, v39, v135
	v_mul_f32_e32 v23, v23, v135
	v_mul_f32_e32 v7, v7, v135
	v_mul_f32_e32 v56, v56, v136
	v_mul_f32_e32 v40, v40, v136
	v_mul_f32_e32 v24, v24, v136
	v_mul_f32_e32 v8, v8, v136
	v_mul_f32_e32 v57, v57, v137
	v_mul_f32_e32 v41, v41, v137
	v_mul_f32_e32 v25, v25, v137
	v_mul_f32_e32 v9, v9, v137
	v_mul_f32_e32 v58, v58, v138
	v_mul_f32_e32 v42, v42, v138
	v_mul_f32_e32 v26, v26, v138
	v_mul_f32_e32 v10, v10, v138
	v_mul_f32_e32 v59, v59, v139
	v_mul_f32_e32 v43, v43, v139
	v_mul_f32_e32 v27, v27, v139
	v_mul_f32_e32 v11, v11, v139
	v_mul_f32_e32 v60, v60, v140
	v_mul_f32_e32 v44, v44, v140
	v_mul_f32_e32 v28, v28, v140
	v_mul_f32_e32 v12, v12, v140
	v_mul_f32_e32 v61, v61, v141
	v_mul_f32_e32 v45, v45, v141
	v_mul_f32_e32 v29, v29, v141
	v_mul_f32_e32 v13, v13, v141
	v_mul_f32_e32 v62, v62, v142
	v_mul_f32_e32 v46, v46, v142
	v_mul_f32_e32 v30, v30, v142
	v_mul_f32_e32 v14, v14, v142
	v_mul_f32_e32 v63, v63, v143
	v_mul_f32_e32 v47, v47, v143
	v_mul_f32_e32 v31, v31, v143
	v_mul_f32_e32 v15, v15, v143
	s_waitcnt vmcnt(60)
	v_mov_b32_e32 v182, v169
	v_lshlrev_b32_e32 v64, 16, v64
	v_lshlrev_b32_e32 v65, 16, v65
	v_lshlrev_b32_e32 v66, 16, v66
	v_lshlrev_b32_e32 v67, 16, v67
	v_mul_f32_e32 v208, 0xbfb8aa3b, v64
	v_mul_f32_e32 v214, 0xbfb8aa3b, v65
	v_mul_f32_e32 v220, 0xbfb8aa3b, v66
	v_mul_f32_e32 v226, 0xbfb8aa3b, v67
	v_exp_f32_e32 v208, v208
	v_exp_f32_e32 v214, v214
	v_exp_f32_e32 v220, v220
	v_exp_f32_e32 v226, v226
	v_add_f32_e32 v208, 1.0, v208
	v_add_f32_e32 v214, 1.0, v214
	v_add_f32_e32 v220, 1.0, v220
	v_add_f32_e32 v226, 1.0, v226
	v_div_scale_f32 v209, s[12:13], v208, v208, v64
	v_div_scale_f32 v215, s[12:13], v214, v214, v65
	v_div_scale_f32 v221, s[12:13], v220, v220, v66
	v_div_scale_f32 v227, s[12:13], v226, v226, v67
	v_rcp_f32_e32 v210, v209
	v_rcp_f32_e32 v216, v215
	v_rcp_f32_e32 v222, v221
	v_rcp_f32_e32 v228, v227
	v_fma_f32 v211, -v209, v210, 1.0
	v_fma_f32 v217, -v215, v216, 1.0
	v_fma_f32 v223, -v221, v222, 1.0
	v_fma_f32 v229, -v227, v228, 1.0
	v_fmac_f32_e32 v210, v211, v210
	v_fmac_f32_e32 v216, v217, v216
	v_fmac_f32_e32 v222, v223, v222
	v_fmac_f32_e32 v228, v229, v228
	v_div_scale_f32 v211, vcc, v64, v208, v64
	v_mul_f32_e32 v212, v211, v210
	v_fma_f32 v213, -v209, v212, v211
	v_fmac_f32_e32 v212, v213, v210
	v_fma_f32 v209, -v209, v212, v211
	v_div_fmas_f32 v209, v209, v210, v212
	v_div_fixup_f32 v64, v209, v208, v64
	v_div_scale_f32 v217, vcc, v65, v214, v65
	v_mul_f32_e32 v218, v217, v216
	v_fma_f32 v219, -v215, v218, v217
	v_fmac_f32_e32 v218, v219, v216
	v_fma_f32 v215, -v215, v218, v217
	v_div_fmas_f32 v215, v215, v216, v218
	v_div_fixup_f32 v65, v215, v214, v65
	v_div_scale_f32 v223, vcc, v66, v220, v66
	v_mul_f32_e32 v224, v223, v222
	v_fma_f32 v225, -v221, v224, v223
	v_fmac_f32_e32 v224, v225, v222
	v_fma_f32 v221, -v221, v224, v223
	v_div_fmas_f32 v221, v221, v222, v224
	v_div_fixup_f32 v66, v221, v220, v66
	v_div_scale_f32 v229, vcc, v67, v226, v67
	v_mul_f32_e32 v230, v229, v228
	v_fma_f32 v231, -v227, v230, v229
	v_fmac_f32_e32 v230, v231, v228
	v_fma_f32 v227, -v227, v230, v229
	v_div_fmas_f32 v227, v227, v228, v230
	v_div_fixup_f32 v67, v227, v226, v67
	v_mul_f32_e32 v48, v48, v64
	v_mul_f32_e32 v32, v32, v65
	v_mul_f32_e32 v16, v16, v66
	v_mul_f32_e32 v0, v0, v67
	v_mul_f32_e32 v148, v32, v32
	v_fmac_f32_e32 v148, v48, v48
	v_fmac_f32_e32 v148, v16, v16
	v_fmac_f32_e32 v148, v0, v0
	v_cvt_pk_bf16_f32 v64, v48, v177
	v_cvt_pk_bf16_f32 v65, v32, v177
	v_cvt_pk_bf16_f32 v66, v16, v177
	v_cvt_pk_bf16_f32 v67, v0, v177
	global_store_short v182, v64, s[14:15] offset:0
	global_store_short v182, v65, s[14:15] offset:64
	global_store_short v182, v66, s[14:15] offset:128
	global_store_short v182, v67, s[14:15] offset:192
	s_waitcnt vmcnt(60)
	v_add_u32_e32 v175, 0x1000, v169
	v_lshlrev_b32_e32 v68, 16, v68
	v_lshlrev_b32_e32 v69, 16, v69
	v_lshlrev_b32_e32 v70, 16, v70
	v_lshlrev_b32_e32 v71, 16, v71
	v_mul_f32_e32 v208, 0xbfb8aa3b, v68
	v_mul_f32_e32 v214, 0xbfb8aa3b, v69
	v_mul_f32_e32 v220, 0xbfb8aa3b, v70
	v_mul_f32_e32 v226, 0xbfb8aa3b, v71
	v_exp_f32_e32 v208, v208
	v_exp_f32_e32 v214, v214
	v_exp_f32_e32 v220, v220
	v_exp_f32_e32 v226, v226
	v_add_f32_e32 v208, 1.0, v208
	v_add_f32_e32 v214, 1.0, v214
	v_add_f32_e32 v220, 1.0, v220
	v_add_f32_e32 v226, 1.0, v226
	v_div_scale_f32 v209, s[12:13], v208, v208, v68
	v_div_scale_f32 v215, s[12:13], v214, v214, v69
	v_div_scale_f32 v221, s[12:13], v220, v220, v70
	v_div_scale_f32 v227, s[12:13], v226, v226, v71
	v_rcp_f32_e32 v210, v209
	v_rcp_f32_e32 v216, v215
	v_rcp_f32_e32 v222, v221
	v_rcp_f32_e32 v228, v227
	v_fma_f32 v211, -v209, v210, 1.0
	v_fma_f32 v217, -v215, v216, 1.0
	v_fma_f32 v223, -v221, v222, 1.0
	v_fma_f32 v229, -v227, v228, 1.0
	v_fmac_f32_e32 v210, v211, v210
	v_fmac_f32_e32 v216, v217, v216
	v_fmac_f32_e32 v222, v223, v222
	v_fmac_f32_e32 v228, v229, v228
	v_div_scale_f32 v211, vcc, v68, v208, v68
	v_mul_f32_e32 v212, v211, v210
	v_fma_f32 v213, -v209, v212, v211
	v_fmac_f32_e32 v212, v213, v210
	v_fma_f32 v209, -v209, v212, v211
	v_div_fmas_f32 v209, v209, v210, v212
	v_div_fixup_f32 v68, v209, v208, v68
	v_div_scale_f32 v217, vcc, v69, v214, v69
	v_mul_f32_e32 v218, v217, v216
	v_fma_f32 v219, -v215, v218, v217
	v_fmac_f32_e32 v218, v219, v216
	v_fma_f32 v215, -v215, v218, v217
	v_div_fmas_f32 v215, v215, v216, v218
	v_div_fixup_f32 v69, v215, v214, v69
	v_div_scale_f32 v223, vcc, v70, v220, v70
	v_mul_f32_e32 v224, v223, v222
	v_fma_f32 v225, -v221, v224, v223
	v_fmac_f32_e32 v224, v225, v222
	v_fma_f32 v221, -v221, v224, v223
	v_div_fmas_f32 v221, v221, v222, v224
	v_div_fixup_f32 v70, v221, v220, v70
	v_div_scale_f32 v229, vcc, v71, v226, v71
	v_mul_f32_e32 v230, v229, v228
	v_fma_f32 v231, -v227, v230, v229
	v_fmac_f32_e32 v230, v231, v228
	v_fma_f32 v227, -v227, v230, v229
	v_div_fmas_f32 v227, v227, v228, v230
	v_div_fixup_f32 v71, v227, v226, v71
	v_mul_f32_e32 v49, v49, v68
	v_mul_f32_e32 v33, v33, v69
	v_mul_f32_e32 v17, v17, v70
	v_mul_f32_e32 v1, v1, v71
	v_mul_f32_e32 v149, v33, v33
	v_fmac_f32_e32 v149, v49, v49
	v_fmac_f32_e32 v149, v17, v17
	v_fmac_f32_e32 v149, v1, v1
	v_cvt_pk_bf16_f32 v68, v49, v177
	v_cvt_pk_bf16_f32 v69, v33, v177
	v_cvt_pk_bf16_f32 v70, v17, v177
	v_cvt_pk_bf16_f32 v71, v1, v177
	global_store_short v175, v68, s[14:15] offset:0
	global_store_short v175, v69, s[14:15] offset:64
	global_store_short v175, v70, s[14:15] offset:128
	global_store_short v175, v71, s[14:15] offset:192
	s_waitcnt vmcnt(60)
	v_add_u32_e32 v182, 0x2000, v169
	v_lshlrev_b32_e32 v72, 16, v72
	v_lshlrev_b32_e32 v73, 16, v73
	v_lshlrev_b32_e32 v74, 16, v74
	v_lshlrev_b32_e32 v75, 16, v75
	v_mul_f32_e32 v208, 0xbfb8aa3b, v72
	v_mul_f32_e32 v214, 0xbfb8aa3b, v73
	v_mul_f32_e32 v220, 0xbfb8aa3b, v74
	v_mul_f32_e32 v226, 0xbfb8aa3b, v75
	v_exp_f32_e32 v208, v208
	v_exp_f32_e32 v214, v214
	v_exp_f32_e32 v220, v220
	v_exp_f32_e32 v226, v226
	v_add_f32_e32 v208, 1.0, v208
	v_add_f32_e32 v214, 1.0, v214
	v_add_f32_e32 v220, 1.0, v220
	v_add_f32_e32 v226, 1.0, v226
	v_div_scale_f32 v209, s[12:13], v208, v208, v72
	v_div_scale_f32 v215, s[12:13], v214, v214, v73
	v_div_scale_f32 v221, s[12:13], v220, v220, v74
	v_div_scale_f32 v227, s[12:13], v226, v226, v75
	v_rcp_f32_e32 v210, v209
	v_rcp_f32_e32 v216, v215
	v_rcp_f32_e32 v222, v221
	v_rcp_f32_e32 v228, v227
	v_fma_f32 v211, -v209, v210, 1.0
	v_fma_f32 v217, -v215, v216, 1.0
	v_fma_f32 v223, -v221, v222, 1.0
	v_fma_f32 v229, -v227, v228, 1.0
	v_fmac_f32_e32 v210, v211, v210
	v_fmac_f32_e32 v216, v217, v216
	v_fmac_f32_e32 v222, v223, v222
	v_fmac_f32_e32 v228, v229, v228
	v_div_scale_f32 v211, vcc, v72, v208, v72
	v_mul_f32_e32 v212, v211, v210
	v_fma_f32 v213, -v209, v212, v211
	v_fmac_f32_e32 v212, v213, v210
	v_fma_f32 v209, -v209, v212, v211
	v_div_fmas_f32 v209, v209, v210, v212
	v_div_fixup_f32 v72, v209, v208, v72
	v_div_scale_f32 v217, vcc, v73, v214, v73
	v_mul_f32_e32 v218, v217, v216
	v_fma_f32 v219, -v215, v218, v217
	v_fmac_f32_e32 v218, v219, v216
	v_fma_f32 v215, -v215, v218, v217
	v_div_fmas_f32 v215, v215, v216, v218
	v_div_fixup_f32 v73, v215, v214, v73
	v_div_scale_f32 v223, vcc, v74, v220, v74
	v_mul_f32_e32 v224, v223, v222
	v_fma_f32 v225, -v221, v224, v223
	v_fmac_f32_e32 v224, v225, v222
	v_fma_f32 v221, -v221, v224, v223
	v_div_fmas_f32 v221, v221, v222, v224
	v_div_fixup_f32 v74, v221, v220, v74
	v_div_scale_f32 v229, vcc, v75, v226, v75
	v_mul_f32_e32 v230, v229, v228
	v_fma_f32 v231, -v227, v230, v229
	v_fmac_f32_e32 v230, v231, v228
	v_fma_f32 v227, -v227, v230, v229
	v_div_fmas_f32 v227, v227, v228, v230
	v_div_fixup_f32 v75, v227, v226, v75
	v_mul_f32_e32 v50, v50, v72
	v_mul_f32_e32 v34, v34, v73
	v_mul_f32_e32 v18, v18, v74
	v_mul_f32_e32 v2, v2, v75
	v_mul_f32_e32 v150, v34, v34
	v_fmac_f32_e32 v150, v50, v50
	v_fmac_f32_e32 v150, v18, v18
	v_fmac_f32_e32 v150, v2, v2
	v_cvt_pk_bf16_f32 v72, v50, v177
	v_cvt_pk_bf16_f32 v73, v34, v177
	v_cvt_pk_bf16_f32 v74, v18, v177
	v_cvt_pk_bf16_f32 v75, v2, v177
	global_store_short v182, v72, s[14:15] offset:0
	global_store_short v182, v73, s[14:15] offset:64
	global_store_short v182, v74, s[14:15] offset:128
	global_store_short v182, v75, s[14:15] offset:192
	s_waitcnt vmcnt(60)
	v_add_u32_e32 v175, 0x3000, v169
	v_lshlrev_b32_e32 v76, 16, v76
	v_lshlrev_b32_e32 v77, 16, v77
	v_lshlrev_b32_e32 v78, 16, v78
	v_lshlrev_b32_e32 v79, 16, v79
	v_mul_f32_e32 v208, 0xbfb8aa3b, v76
	v_mul_f32_e32 v214, 0xbfb8aa3b, v77
	v_mul_f32_e32 v220, 0xbfb8aa3b, v78
	v_mul_f32_e32 v226, 0xbfb8aa3b, v79
	v_exp_f32_e32 v208, v208
	v_exp_f32_e32 v214, v214
	v_exp_f32_e32 v220, v220
	v_exp_f32_e32 v226, v226
	v_add_f32_e32 v208, 1.0, v208
	v_add_f32_e32 v214, 1.0, v214
	v_add_f32_e32 v220, 1.0, v220
	v_add_f32_e32 v226, 1.0, v226
	v_div_scale_f32 v209, s[12:13], v208, v208, v76
	v_div_scale_f32 v215, s[12:13], v214, v214, v77
	v_div_scale_f32 v221, s[12:13], v220, v220, v78
	v_div_scale_f32 v227, s[12:13], v226, v226, v79
	v_rcp_f32_e32 v210, v209
	v_rcp_f32_e32 v216, v215
	v_rcp_f32_e32 v222, v221
	v_rcp_f32_e32 v228, v227
	v_fma_f32 v211, -v209, v210, 1.0
	v_fma_f32 v217, -v215, v216, 1.0
	v_fma_f32 v223, -v221, v222, 1.0
	v_fma_f32 v229, -v227, v228, 1.0
	v_fmac_f32_e32 v210, v211, v210
	v_fmac_f32_e32 v216, v217, v216
	v_fmac_f32_e32 v222, v223, v222
	v_fmac_f32_e32 v228, v229, v228
	v_div_scale_f32 v211, vcc, v76, v208, v76
	v_mul_f32_e32 v212, v211, v210
	v_fma_f32 v213, -v209, v212, v211
	v_fmac_f32_e32 v212, v213, v210
	v_fma_f32 v209, -v209, v212, v211
	v_div_fmas_f32 v209, v209, v210, v212
	v_div_fixup_f32 v76, v209, v208, v76
	v_div_scale_f32 v217, vcc, v77, v214, v77
	v_mul_f32_e32 v218, v217, v216
	v_fma_f32 v219, -v215, v218, v217
	v_fmac_f32_e32 v218, v219, v216
	v_fma_f32 v215, -v215, v218, v217
	v_div_fmas_f32 v215, v215, v216, v218
	v_div_fixup_f32 v77, v215, v214, v77
	v_div_scale_f32 v223, vcc, v78, v220, v78
	v_mul_f32_e32 v224, v223, v222
	v_fma_f32 v225, -v221, v224, v223
	v_fmac_f32_e32 v224, v225, v222
	v_fma_f32 v221, -v221, v224, v223
	v_div_fmas_f32 v221, v221, v222, v224
	v_div_fixup_f32 v78, v221, v220, v78
	v_div_scale_f32 v229, vcc, v79, v226, v79
	v_mul_f32_e32 v230, v229, v228
	v_fma_f32 v231, -v227, v230, v229
	v_fmac_f32_e32 v230, v231, v228
	v_fma_f32 v227, -v227, v230, v229
	v_div_fmas_f32 v227, v227, v228, v230
	v_div_fixup_f32 v79, v227, v226, v79
	v_mul_f32_e32 v51, v51, v76
	v_mul_f32_e32 v35, v35, v77
	v_mul_f32_e32 v19, v19, v78
	v_mul_f32_e32 v3, v3, v79
	v_mul_f32_e32 v151, v35, v35
	v_fmac_f32_e32 v151, v51, v51
	v_fmac_f32_e32 v151, v19, v19
	v_fmac_f32_e32 v151, v3, v3
	v_cvt_pk_bf16_f32 v76, v51, v177
	v_cvt_pk_bf16_f32 v77, v35, v177
	v_cvt_pk_bf16_f32 v78, v19, v177
	v_cvt_pk_bf16_f32 v79, v3, v177
	global_store_short v175, v76, s[14:15] offset:0
	global_store_short v175, v77, s[14:15] offset:64
	global_store_short v175, v78, s[14:15] offset:128
	global_store_short v175, v79, s[14:15] offset:192
	s_waitcnt vmcnt(60)
	v_add_u32_e32 v182, 0x8000, v169
	v_lshlrev_b32_e32 v80, 16, v80
	v_lshlrev_b32_e32 v81, 16, v81
	v_lshlrev_b32_e32 v82, 16, v82
	v_lshlrev_b32_e32 v83, 16, v83
	v_mul_f32_e32 v208, 0xbfb8aa3b, v80
	v_mul_f32_e32 v214, 0xbfb8aa3b, v81
	v_mul_f32_e32 v220, 0xbfb8aa3b, v82
	v_mul_f32_e32 v226, 0xbfb8aa3b, v83
	v_exp_f32_e32 v208, v208
	v_exp_f32_e32 v214, v214
	v_exp_f32_e32 v220, v220
	v_exp_f32_e32 v226, v226
	v_add_f32_e32 v208, 1.0, v208
	v_add_f32_e32 v214, 1.0, v214
	v_add_f32_e32 v220, 1.0, v220
	v_add_f32_e32 v226, 1.0, v226
	v_div_scale_f32 v209, s[12:13], v208, v208, v80
	v_div_scale_f32 v215, s[12:13], v214, v214, v81
	v_div_scale_f32 v221, s[12:13], v220, v220, v82
	v_div_scale_f32 v227, s[12:13], v226, v226, v83
	v_rcp_f32_e32 v210, v209
	v_rcp_f32_e32 v216, v215
	v_rcp_f32_e32 v222, v221
	v_rcp_f32_e32 v228, v227
	v_fma_f32 v211, -v209, v210, 1.0
	v_fma_f32 v217, -v215, v216, 1.0
	v_fma_f32 v223, -v221, v222, 1.0
	v_fma_f32 v229, -v227, v228, 1.0
	v_fmac_f32_e32 v210, v211, v210
	v_fmac_f32_e32 v216, v217, v216
	v_fmac_f32_e32 v222, v223, v222
	v_fmac_f32_e32 v228, v229, v228
	v_div_scale_f32 v211, vcc, v80, v208, v80
	v_mul_f32_e32 v212, v211, v210
	v_fma_f32 v213, -v209, v212, v211
	v_fmac_f32_e32 v212, v213, v210
	v_fma_f32 v209, -v209, v212, v211
	v_div_fmas_f32 v209, v209, v210, v212
	v_div_fixup_f32 v80, v209, v208, v80
	v_div_scale_f32 v217, vcc, v81, v214, v81
	v_mul_f32_e32 v218, v217, v216
	v_fma_f32 v219, -v215, v218, v217
	v_fmac_f32_e32 v218, v219, v216
	v_fma_f32 v215, -v215, v218, v217
	v_div_fmas_f32 v215, v215, v216, v218
	v_div_fixup_f32 v81, v215, v214, v81
	v_div_scale_f32 v223, vcc, v82, v220, v82
	v_mul_f32_e32 v224, v223, v222
	v_fma_f32 v225, -v221, v224, v223
	v_fmac_f32_e32 v224, v225, v222
	v_fma_f32 v221, -v221, v224, v223
	v_div_fmas_f32 v221, v221, v222, v224
	v_div_fixup_f32 v82, v221, v220, v82
	v_div_scale_f32 v229, vcc, v83, v226, v83
	v_mul_f32_e32 v230, v229, v228
	v_fma_f32 v231, -v227, v230, v229
	v_fmac_f32_e32 v230, v231, v228
	v_fma_f32 v227, -v227, v230, v229
	v_div_fmas_f32 v227, v227, v228, v230
	v_div_fixup_f32 v83, v227, v226, v83
	v_mul_f32_e32 v52, v52, v80
	v_mul_f32_e32 v36, v36, v81
	v_mul_f32_e32 v20, v20, v82
	v_mul_f32_e32 v4, v4, v83
	v_mul_f32_e32 v152, v36, v36
	v_fmac_f32_e32 v152, v52, v52
	v_fmac_f32_e32 v152, v20, v20
	v_fmac_f32_e32 v152, v4, v4
	v_cvt_pk_bf16_f32 v80, v52, v177
	v_cvt_pk_bf16_f32 v81, v36, v177
	v_cvt_pk_bf16_f32 v82, v20, v177
	v_cvt_pk_bf16_f32 v83, v4, v177
	global_store_short v182, v80, s[14:15] offset:0
	global_store_short v182, v81, s[14:15] offset:64
	global_store_short v182, v82, s[14:15] offset:128
	global_store_short v182, v83, s[14:15] offset:192
	s_waitcnt vmcnt(60)
	v_add_u32_e32 v175, 0x9000, v169
	v_lshlrev_b32_e32 v84, 16, v84
	v_lshlrev_b32_e32 v85, 16, v85
	v_lshlrev_b32_e32 v86, 16, v86
	v_lshlrev_b32_e32 v87, 16, v87
	v_mul_f32_e32 v208, 0xbfb8aa3b, v84
	v_mul_f32_e32 v214, 0xbfb8aa3b, v85
	v_mul_f32_e32 v220, 0xbfb8aa3b, v86
	v_mul_f32_e32 v226, 0xbfb8aa3b, v87
	v_exp_f32_e32 v208, v208
	v_exp_f32_e32 v214, v214
	v_exp_f32_e32 v220, v220
	v_exp_f32_e32 v226, v226
	v_add_f32_e32 v208, 1.0, v208
	v_add_f32_e32 v214, 1.0, v214
	v_add_f32_e32 v220, 1.0, v220
	v_add_f32_e32 v226, 1.0, v226
	v_div_scale_f32 v209, s[12:13], v208, v208, v84
	v_div_scale_f32 v215, s[12:13], v214, v214, v85
	v_div_scale_f32 v221, s[12:13], v220, v220, v86
	v_div_scale_f32 v227, s[12:13], v226, v226, v87
	v_rcp_f32_e32 v210, v209
	v_rcp_f32_e32 v216, v215
	v_rcp_f32_e32 v222, v221
	v_rcp_f32_e32 v228, v227
	v_fma_f32 v211, -v209, v210, 1.0
	v_fma_f32 v217, -v215, v216, 1.0
	v_fma_f32 v223, -v221, v222, 1.0
	v_fma_f32 v229, -v227, v228, 1.0
	v_fmac_f32_e32 v210, v211, v210
	v_fmac_f32_e32 v216, v217, v216
	v_fmac_f32_e32 v222, v223, v222
	v_fmac_f32_e32 v228, v229, v228
	v_div_scale_f32 v211, vcc, v84, v208, v84
	v_mul_f32_e32 v212, v211, v210
	v_fma_f32 v213, -v209, v212, v211
	v_fmac_f32_e32 v212, v213, v210
	v_fma_f32 v209, -v209, v212, v211
	v_div_fmas_f32 v209, v209, v210, v212
	v_div_fixup_f32 v84, v209, v208, v84
	v_div_scale_f32 v217, vcc, v85, v214, v85
	v_mul_f32_e32 v218, v217, v216
	v_fma_f32 v219, -v215, v218, v217
	v_fmac_f32_e32 v218, v219, v216
	v_fma_f32 v215, -v215, v218, v217
	v_div_fmas_f32 v215, v215, v216, v218
	v_div_fixup_f32 v85, v215, v214, v85
	v_div_scale_f32 v223, vcc, v86, v220, v86
	v_mul_f32_e32 v224, v223, v222
	v_fma_f32 v225, -v221, v224, v223
	v_fmac_f32_e32 v224, v225, v222
	v_fma_f32 v221, -v221, v224, v223
	v_div_fmas_f32 v221, v221, v222, v224
	v_div_fixup_f32 v86, v221, v220, v86
	v_div_scale_f32 v229, vcc, v87, v226, v87
	v_mul_f32_e32 v230, v229, v228
	v_fma_f32 v231, -v227, v230, v229
	v_fmac_f32_e32 v230, v231, v228
	v_fma_f32 v227, -v227, v230, v229
	v_div_fmas_f32 v227, v227, v228, v230
	v_div_fixup_f32 v87, v227, v226, v87
	v_mul_f32_e32 v53, v53, v84
	v_mul_f32_e32 v37, v37, v85
	v_mul_f32_e32 v21, v21, v86
	v_mul_f32_e32 v5, v5, v87
	v_mul_f32_e32 v153, v37, v37
	v_fmac_f32_e32 v153, v53, v53
	v_fmac_f32_e32 v153, v21, v21
	v_fmac_f32_e32 v153, v5, v5
	v_cvt_pk_bf16_f32 v84, v53, v177
	v_cvt_pk_bf16_f32 v85, v37, v177
	v_cvt_pk_bf16_f32 v86, v21, v177
	v_cvt_pk_bf16_f32 v87, v5, v177
	global_store_short v175, v84, s[14:15] offset:0
	global_store_short v175, v85, s[14:15] offset:64
	global_store_short v175, v86, s[14:15] offset:128
	global_store_short v175, v87, s[14:15] offset:192
	s_waitcnt vmcnt(60)
	v_add_u32_e32 v182, 0xa000, v169
	v_lshlrev_b32_e32 v88, 16, v88
	v_lshlrev_b32_e32 v89, 16, v89
	v_lshlrev_b32_e32 v90, 16, v90
	v_lshlrev_b32_e32 v91, 16, v91
	v_mul_f32_e32 v208, 0xbfb8aa3b, v88
	v_mul_f32_e32 v214, 0xbfb8aa3b, v89
	v_mul_f32_e32 v220, 0xbfb8aa3b, v90
	v_mul_f32_e32 v226, 0xbfb8aa3b, v91
	v_exp_f32_e32 v208, v208
	v_exp_f32_e32 v214, v214
	v_exp_f32_e32 v220, v220
	v_exp_f32_e32 v226, v226
	v_add_f32_e32 v208, 1.0, v208
	v_add_f32_e32 v214, 1.0, v214
	v_add_f32_e32 v220, 1.0, v220
	v_add_f32_e32 v226, 1.0, v226
	v_div_scale_f32 v209, s[12:13], v208, v208, v88
	v_div_scale_f32 v215, s[12:13], v214, v214, v89
	v_div_scale_f32 v221, s[12:13], v220, v220, v90
	v_div_scale_f32 v227, s[12:13], v226, v226, v91
	v_rcp_f32_e32 v210, v209
	v_rcp_f32_e32 v216, v215
	v_rcp_f32_e32 v222, v221
	v_rcp_f32_e32 v228, v227
	v_fma_f32 v211, -v209, v210, 1.0
	v_fma_f32 v217, -v215, v216, 1.0
	v_fma_f32 v223, -v221, v222, 1.0
	v_fma_f32 v229, -v227, v228, 1.0
	v_fmac_f32_e32 v210, v211, v210
	v_fmac_f32_e32 v216, v217, v216
	v_fmac_f32_e32 v222, v223, v222
	v_fmac_f32_e32 v228, v229, v228
	v_div_scale_f32 v211, vcc, v88, v208, v88
	v_mul_f32_e32 v212, v211, v210
	v_fma_f32 v213, -v209, v212, v211
	v_fmac_f32_e32 v212, v213, v210
	v_fma_f32 v209, -v209, v212, v211
	v_div_fmas_f32 v209, v209, v210, v212
	v_div_fixup_f32 v88, v209, v208, v88
	v_div_scale_f32 v217, vcc, v89, v214, v89
	v_mul_f32_e32 v218, v217, v216
	v_fma_f32 v219, -v215, v218, v217
	v_fmac_f32_e32 v218, v219, v216
	v_fma_f32 v215, -v215, v218, v217
	v_div_fmas_f32 v215, v215, v216, v218
	v_div_fixup_f32 v89, v215, v214, v89
	v_div_scale_f32 v223, vcc, v90, v220, v90
	v_mul_f32_e32 v224, v223, v222
	v_fma_f32 v225, -v221, v224, v223
	v_fmac_f32_e32 v224, v225, v222
	v_fma_f32 v221, -v221, v224, v223
	v_div_fmas_f32 v221, v221, v222, v224
	v_div_fixup_f32 v90, v221, v220, v90
	v_div_scale_f32 v229, vcc, v91, v226, v91
	v_mul_f32_e32 v230, v229, v228
	v_fma_f32 v231, -v227, v230, v229
	v_fmac_f32_e32 v230, v231, v228
	v_fma_f32 v227, -v227, v230, v229
	v_div_fmas_f32 v227, v227, v228, v230
	v_div_fixup_f32 v91, v227, v226, v91
	v_mul_f32_e32 v54, v54, v88
	v_mul_f32_e32 v38, v38, v89
	v_mul_f32_e32 v22, v22, v90
	v_mul_f32_e32 v6, v6, v91
	v_mul_f32_e32 v154, v38, v38
	v_fmac_f32_e32 v154, v54, v54
	v_fmac_f32_e32 v154, v22, v22
	v_fmac_f32_e32 v154, v6, v6
	v_cvt_pk_bf16_f32 v88, v54, v177
	v_cvt_pk_bf16_f32 v89, v38, v177
	v_cvt_pk_bf16_f32 v90, v22, v177
	v_cvt_pk_bf16_f32 v91, v6, v177
	global_store_short v182, v88, s[14:15] offset:0
	global_store_short v182, v89, s[14:15] offset:64
	global_store_short v182, v90, s[14:15] offset:128
	global_store_short v182, v91, s[14:15] offset:192
	s_waitcnt vmcnt(60)
	v_add_u32_e32 v175, 0xb000, v169
	v_lshlrev_b32_e32 v92, 16, v92
	v_lshlrev_b32_e32 v93, 16, v93
	v_lshlrev_b32_e32 v94, 16, v94
	v_lshlrev_b32_e32 v95, 16, v95
	v_mul_f32_e32 v208, 0xbfb8aa3b, v92
	v_mul_f32_e32 v214, 0xbfb8aa3b, v93
	v_mul_f32_e32 v220, 0xbfb8aa3b, v94
	v_mul_f32_e32 v226, 0xbfb8aa3b, v95
	v_exp_f32_e32 v208, v208
	v_exp_f32_e32 v214, v214
	v_exp_f32_e32 v220, v220
	v_exp_f32_e32 v226, v226
	v_add_f32_e32 v208, 1.0, v208
	v_add_f32_e32 v214, 1.0, v214
	v_add_f32_e32 v220, 1.0, v220
	v_add_f32_e32 v226, 1.0, v226
	v_div_scale_f32 v209, s[12:13], v208, v208, v92
	v_div_scale_f32 v215, s[12:13], v214, v214, v93
	v_div_scale_f32 v221, s[12:13], v220, v220, v94
	v_div_scale_f32 v227, s[12:13], v226, v226, v95
	v_rcp_f32_e32 v210, v209
	v_rcp_f32_e32 v216, v215
	v_rcp_f32_e32 v222, v221
	v_rcp_f32_e32 v228, v227
	v_fma_f32 v211, -v209, v210, 1.0
	v_fma_f32 v217, -v215, v216, 1.0
	v_fma_f32 v223, -v221, v222, 1.0
	v_fma_f32 v229, -v227, v228, 1.0
	v_fmac_f32_e32 v210, v211, v210
	v_fmac_f32_e32 v216, v217, v216
	v_fmac_f32_e32 v222, v223, v222
	v_fmac_f32_e32 v228, v229, v228
	v_div_scale_f32 v211, vcc, v92, v208, v92
	v_mul_f32_e32 v212, v211, v210
	v_fma_f32 v213, -v209, v212, v211
	v_fmac_f32_e32 v212, v213, v210
	v_fma_f32 v209, -v209, v212, v211
	v_div_fmas_f32 v209, v209, v210, v212
	v_div_fixup_f32 v92, v209, v208, v92
	v_div_scale_f32 v217, vcc, v93, v214, v93
	v_mul_f32_e32 v218, v217, v216
	v_fma_f32 v219, -v215, v218, v217
	v_fmac_f32_e32 v218, v219, v216
	v_fma_f32 v215, -v215, v218, v217
	v_div_fmas_f32 v215, v215, v216, v218
	v_div_fixup_f32 v93, v215, v214, v93
	v_div_scale_f32 v223, vcc, v94, v220, v94
	v_mul_f32_e32 v224, v223, v222
	v_fma_f32 v225, -v221, v224, v223
	v_fmac_f32_e32 v224, v225, v222
	v_fma_f32 v221, -v221, v224, v223
	v_div_fmas_f32 v221, v221, v222, v224
	v_div_fixup_f32 v94, v221, v220, v94
	v_div_scale_f32 v229, vcc, v95, v226, v95
	v_mul_f32_e32 v230, v229, v228
	v_fma_f32 v231, -v227, v230, v229
	v_fmac_f32_e32 v230, v231, v228
	v_fma_f32 v227, -v227, v230, v229
	v_div_fmas_f32 v227, v227, v228, v230
	v_div_fixup_f32 v95, v227, v226, v95
	v_mul_f32_e32 v55, v55, v92
	v_mul_f32_e32 v39, v39, v93
	v_mul_f32_e32 v23, v23, v94
	v_mul_f32_e32 v7, v7, v95
	v_mul_f32_e32 v155, v39, v39
	v_fmac_f32_e32 v155, v55, v55
	v_fmac_f32_e32 v155, v23, v23
	v_fmac_f32_e32 v155, v7, v7
	v_cvt_pk_bf16_f32 v92, v55, v177
	v_cvt_pk_bf16_f32 v93, v39, v177
	v_cvt_pk_bf16_f32 v94, v23, v177
	v_cvt_pk_bf16_f32 v95, v7, v177
	global_store_short v175, v92, s[14:15] offset:0
	global_store_short v175, v93, s[14:15] offset:64
	global_store_short v175, v94, s[14:15] offset:128
	global_store_short v175, v95, s[14:15] offset:192
	s_waitcnt vmcnt(60)
	v_add_u32_e32 v182, 0x10000, v169
	v_lshlrev_b32_e32 v96, 16, v96
	v_lshlrev_b32_e32 v97, 16, v97
	v_lshlrev_b32_e32 v98, 16, v98
	v_lshlrev_b32_e32 v99, 16, v99
	v_mul_f32_e32 v208, 0xbfb8aa3b, v96
	v_mul_f32_e32 v214, 0xbfb8aa3b, v97
	v_mul_f32_e32 v220, 0xbfb8aa3b, v98
	v_mul_f32_e32 v226, 0xbfb8aa3b, v99
	v_exp_f32_e32 v208, v208
	v_exp_f32_e32 v214, v214
	v_exp_f32_e32 v220, v220
	v_exp_f32_e32 v226, v226
	v_add_f32_e32 v208, 1.0, v208
	v_add_f32_e32 v214, 1.0, v214
	v_add_f32_e32 v220, 1.0, v220
	v_add_f32_e32 v226, 1.0, v226
	v_div_scale_f32 v209, s[12:13], v208, v208, v96
	v_div_scale_f32 v215, s[12:13], v214, v214, v97
	v_div_scale_f32 v221, s[12:13], v220, v220, v98
	v_div_scale_f32 v227, s[12:13], v226, v226, v99
	v_rcp_f32_e32 v210, v209
	v_rcp_f32_e32 v216, v215
	v_rcp_f32_e32 v222, v221
	v_rcp_f32_e32 v228, v227
	v_fma_f32 v211, -v209, v210, 1.0
	v_fma_f32 v217, -v215, v216, 1.0
	v_fma_f32 v223, -v221, v222, 1.0
	v_fma_f32 v229, -v227, v228, 1.0
	v_fmac_f32_e32 v210, v211, v210
	v_fmac_f32_e32 v216, v217, v216
	v_fmac_f32_e32 v222, v223, v222
	v_fmac_f32_e32 v228, v229, v228
	v_div_scale_f32 v211, vcc, v96, v208, v96
	v_mul_f32_e32 v212, v211, v210
	v_fma_f32 v213, -v209, v212, v211
	v_fmac_f32_e32 v212, v213, v210
	v_fma_f32 v209, -v209, v212, v211
	v_div_fmas_f32 v209, v209, v210, v212
	v_div_fixup_f32 v96, v209, v208, v96
	v_div_scale_f32 v217, vcc, v97, v214, v97
	v_mul_f32_e32 v218, v217, v216
	v_fma_f32 v219, -v215, v218, v217
	v_fmac_f32_e32 v218, v219, v216
	v_fma_f32 v215, -v215, v218, v217
	v_div_fmas_f32 v215, v215, v216, v218
	v_div_fixup_f32 v97, v215, v214, v97
	v_div_scale_f32 v223, vcc, v98, v220, v98
	v_mul_f32_e32 v224, v223, v222
	v_fma_f32 v225, -v221, v224, v223
	v_fmac_f32_e32 v224, v225, v222
	v_fma_f32 v221, -v221, v224, v223
	v_div_fmas_f32 v221, v221, v222, v224
	v_div_fixup_f32 v98, v221, v220, v98
	v_div_scale_f32 v229, vcc, v99, v226, v99
	v_mul_f32_e32 v230, v229, v228
	v_fma_f32 v231, -v227, v230, v229
	v_fmac_f32_e32 v230, v231, v228
	v_fma_f32 v227, -v227, v230, v229
	v_div_fmas_f32 v227, v227, v228, v230
	v_div_fixup_f32 v99, v227, v226, v99
	v_mul_f32_e32 v56, v56, v96
	v_mul_f32_e32 v40, v40, v97
	v_mul_f32_e32 v24, v24, v98
	v_mul_f32_e32 v8, v8, v99
	v_mul_f32_e32 v156, v40, v40
	v_fmac_f32_e32 v156, v56, v56
	v_fmac_f32_e32 v156, v24, v24
	v_fmac_f32_e32 v156, v8, v8
	v_cvt_pk_bf16_f32 v96, v56, v177
	v_cvt_pk_bf16_f32 v97, v40, v177
	v_cvt_pk_bf16_f32 v98, v24, v177
	v_cvt_pk_bf16_f32 v99, v8, v177
	global_store_short v182, v96, s[14:15] offset:0
	global_store_short v182, v97, s[14:15] offset:64
	global_store_short v182, v98, s[14:15] offset:128
	global_store_short v182, v99, s[14:15] offset:192
	s_waitcnt vmcnt(60)
	v_add_u32_e32 v175, 0x11000, v169
	v_lshlrev_b32_e32 v100, 16, v100
	v_lshlrev_b32_e32 v101, 16, v101
	v_lshlrev_b32_e32 v102, 16, v102
	v_lshlrev_b32_e32 v103, 16, v103
	v_mul_f32_e32 v208, 0xbfb8aa3b, v100
	v_mul_f32_e32 v214, 0xbfb8aa3b, v101
	v_mul_f32_e32 v220, 0xbfb8aa3b, v102
	v_mul_f32_e32 v226, 0xbfb8aa3b, v103
	v_exp_f32_e32 v208, v208
	v_exp_f32_e32 v214, v214
	v_exp_f32_e32 v220, v220
	v_exp_f32_e32 v226, v226
	v_add_f32_e32 v208, 1.0, v208
	v_add_f32_e32 v214, 1.0, v214
	v_add_f32_e32 v220, 1.0, v220
	v_add_f32_e32 v226, 1.0, v226
	v_div_scale_f32 v209, s[12:13], v208, v208, v100
	v_div_scale_f32 v215, s[12:13], v214, v214, v101
	v_div_scale_f32 v221, s[12:13], v220, v220, v102
	v_div_scale_f32 v227, s[12:13], v226, v226, v103
	v_rcp_f32_e32 v210, v209
	v_rcp_f32_e32 v216, v215
	v_rcp_f32_e32 v222, v221
	v_rcp_f32_e32 v228, v227
	v_fma_f32 v211, -v209, v210, 1.0
	v_fma_f32 v217, -v215, v216, 1.0
	v_fma_f32 v223, -v221, v222, 1.0
	v_fma_f32 v229, -v227, v228, 1.0
	v_fmac_f32_e32 v210, v211, v210
	v_fmac_f32_e32 v216, v217, v216
	v_fmac_f32_e32 v222, v223, v222
	v_fmac_f32_e32 v228, v229, v228
	v_div_scale_f32 v211, vcc, v100, v208, v100
	v_mul_f32_e32 v212, v211, v210
	v_fma_f32 v213, -v209, v212, v211
	v_fmac_f32_e32 v212, v213, v210
	v_fma_f32 v209, -v209, v212, v211
	v_div_fmas_f32 v209, v209, v210, v212
	v_div_fixup_f32 v100, v209, v208, v100
	v_div_scale_f32 v217, vcc, v101, v214, v101
	v_mul_f32_e32 v218, v217, v216
	v_fma_f32 v219, -v215, v218, v217
	v_fmac_f32_e32 v218, v219, v216
	v_fma_f32 v215, -v215, v218, v217
	v_div_fmas_f32 v215, v215, v216, v218
	v_div_fixup_f32 v101, v215, v214, v101
	v_div_scale_f32 v223, vcc, v102, v220, v102
	v_mul_f32_e32 v224, v223, v222
	v_fma_f32 v225, -v221, v224, v223
	v_fmac_f32_e32 v224, v225, v222
	v_fma_f32 v221, -v221, v224, v223
	v_div_fmas_f32 v221, v221, v222, v224
	v_div_fixup_f32 v102, v221, v220, v102
	v_div_scale_f32 v229, vcc, v103, v226, v103
	v_mul_f32_e32 v230, v229, v228
	v_fma_f32 v231, -v227, v230, v229
	v_fmac_f32_e32 v230, v231, v228
	v_fma_f32 v227, -v227, v230, v229
	v_div_fmas_f32 v227, v227, v228, v230
	v_div_fixup_f32 v103, v227, v226, v103
	v_mul_f32_e32 v57, v57, v100
	v_mul_f32_e32 v41, v41, v101
	v_mul_f32_e32 v25, v25, v102
	v_mul_f32_e32 v9, v9, v103
	v_mul_f32_e32 v157, v41, v41
	v_fmac_f32_e32 v157, v57, v57
	v_fmac_f32_e32 v157, v25, v25
	v_fmac_f32_e32 v157, v9, v9
	v_cvt_pk_bf16_f32 v100, v57, v177
	v_cvt_pk_bf16_f32 v101, v41, v177
	v_cvt_pk_bf16_f32 v102, v25, v177
	v_cvt_pk_bf16_f32 v103, v9, v177
	global_store_short v175, v100, s[14:15] offset:0
	global_store_short v175, v101, s[14:15] offset:64
	global_store_short v175, v102, s[14:15] offset:128
	global_store_short v175, v103, s[14:15] offset:192
	s_waitcnt vmcnt(60)
	v_add_u32_e32 v182, 0x12000, v169
	v_lshlrev_b32_e32 v104, 16, v104
	v_lshlrev_b32_e32 v105, 16, v105
	v_lshlrev_b32_e32 v106, 16, v106
	v_lshlrev_b32_e32 v107, 16, v107
	v_mul_f32_e32 v208, 0xbfb8aa3b, v104
	v_mul_f32_e32 v214, 0xbfb8aa3b, v105
	v_mul_f32_e32 v220, 0xbfb8aa3b, v106
	v_mul_f32_e32 v226, 0xbfb8aa3b, v107
	v_exp_f32_e32 v208, v208
	v_exp_f32_e32 v214, v214
	v_exp_f32_e32 v220, v220
	v_exp_f32_e32 v226, v226
	v_add_f32_e32 v208, 1.0, v208
	v_add_f32_e32 v214, 1.0, v214
	v_add_f32_e32 v220, 1.0, v220
	v_add_f32_e32 v226, 1.0, v226
	v_div_scale_f32 v209, s[12:13], v208, v208, v104
	v_div_scale_f32 v215, s[12:13], v214, v214, v105
	v_div_scale_f32 v221, s[12:13], v220, v220, v106
	v_div_scale_f32 v227, s[12:13], v226, v226, v107
	v_rcp_f32_e32 v210, v209
	v_rcp_f32_e32 v216, v215
	v_rcp_f32_e32 v222, v221
	v_rcp_f32_e32 v228, v227
	v_fma_f32 v211, -v209, v210, 1.0
	v_fma_f32 v217, -v215, v216, 1.0
	v_fma_f32 v223, -v221, v222, 1.0
	v_fma_f32 v229, -v227, v228, 1.0
	v_fmac_f32_e32 v210, v211, v210
	v_fmac_f32_e32 v216, v217, v216
	v_fmac_f32_e32 v222, v223, v222
	v_fmac_f32_e32 v228, v229, v228
	v_div_scale_f32 v211, vcc, v104, v208, v104
	v_mul_f32_e32 v212, v211, v210
	v_fma_f32 v213, -v209, v212, v211
	v_fmac_f32_e32 v212, v213, v210
	v_fma_f32 v209, -v209, v212, v211
	v_div_fmas_f32 v209, v209, v210, v212
	v_div_fixup_f32 v104, v209, v208, v104
	v_div_scale_f32 v217, vcc, v105, v214, v105
	v_mul_f32_e32 v218, v217, v216
	v_fma_f32 v219, -v215, v218, v217
	v_fmac_f32_e32 v218, v219, v216
	v_fma_f32 v215, -v215, v218, v217
	v_div_fmas_f32 v215, v215, v216, v218
	v_div_fixup_f32 v105, v215, v214, v105
	v_div_scale_f32 v223, vcc, v106, v220, v106
	v_mul_f32_e32 v224, v223, v222
	v_fma_f32 v225, -v221, v224, v223
	v_fmac_f32_e32 v224, v225, v222
	v_fma_f32 v221, -v221, v224, v223
	v_div_fmas_f32 v221, v221, v222, v224
	v_div_fixup_f32 v106, v221, v220, v106
	v_div_scale_f32 v229, vcc, v107, v226, v107
	v_mul_f32_e32 v230, v229, v228
	v_fma_f32 v231, -v227, v230, v229
	v_fmac_f32_e32 v230, v231, v228
	v_fma_f32 v227, -v227, v230, v229
	v_div_fmas_f32 v227, v227, v228, v230
	v_div_fixup_f32 v107, v227, v226, v107
	v_mul_f32_e32 v58, v58, v104
	v_mul_f32_e32 v42, v42, v105
	v_mul_f32_e32 v26, v26, v106
	v_mul_f32_e32 v10, v10, v107
	v_mul_f32_e32 v158, v42, v42
	v_fmac_f32_e32 v158, v58, v58
	v_fmac_f32_e32 v158, v26, v26
	v_fmac_f32_e32 v158, v10, v10
	v_cvt_pk_bf16_f32 v104, v58, v177
	v_cvt_pk_bf16_f32 v105, v42, v177
	v_cvt_pk_bf16_f32 v106, v26, v177
	v_cvt_pk_bf16_f32 v107, v10, v177
	global_store_short v182, v104, s[14:15] offset:0
	global_store_short v182, v105, s[14:15] offset:64
	global_store_short v182, v106, s[14:15] offset:128
	global_store_short v182, v107, s[14:15] offset:192
	s_waitcnt vmcnt(60)
	v_add_u32_e32 v175, 0x13000, v169
	v_lshlrev_b32_e32 v108, 16, v108
	v_lshlrev_b32_e32 v109, 16, v109
	v_lshlrev_b32_e32 v110, 16, v110
	v_lshlrev_b32_e32 v111, 16, v111
	v_mul_f32_e32 v208, 0xbfb8aa3b, v108
	v_mul_f32_e32 v214, 0xbfb8aa3b, v109
	v_mul_f32_e32 v220, 0xbfb8aa3b, v110
	v_mul_f32_e32 v226, 0xbfb8aa3b, v111
	v_exp_f32_e32 v208, v208
	v_exp_f32_e32 v214, v214
	v_exp_f32_e32 v220, v220
	v_exp_f32_e32 v226, v226
	v_add_f32_e32 v208, 1.0, v208
	v_add_f32_e32 v214, 1.0, v214
	v_add_f32_e32 v220, 1.0, v220
	v_add_f32_e32 v226, 1.0, v226
	v_div_scale_f32 v209, s[12:13], v208, v208, v108
	v_div_scale_f32 v215, s[12:13], v214, v214, v109
	v_div_scale_f32 v221, s[12:13], v220, v220, v110
	v_div_scale_f32 v227, s[12:13], v226, v226, v111
	v_rcp_f32_e32 v210, v209
	v_rcp_f32_e32 v216, v215
	v_rcp_f32_e32 v222, v221
	v_rcp_f32_e32 v228, v227
	v_fma_f32 v211, -v209, v210, 1.0
	v_fma_f32 v217, -v215, v216, 1.0
	v_fma_f32 v223, -v221, v222, 1.0
	v_fma_f32 v229, -v227, v228, 1.0
	v_fmac_f32_e32 v210, v211, v210
	v_fmac_f32_e32 v216, v217, v216
	v_fmac_f32_e32 v222, v223, v222
	v_fmac_f32_e32 v228, v229, v228
	v_div_scale_f32 v211, vcc, v108, v208, v108
	v_mul_f32_e32 v212, v211, v210
	v_fma_f32 v213, -v209, v212, v211
	v_fmac_f32_e32 v212, v213, v210
	v_fma_f32 v209, -v209, v212, v211
	v_div_fmas_f32 v209, v209, v210, v212
	v_div_fixup_f32 v108, v209, v208, v108
	v_div_scale_f32 v217, vcc, v109, v214, v109
	v_mul_f32_e32 v218, v217, v216
	v_fma_f32 v219, -v215, v218, v217
	v_fmac_f32_e32 v218, v219, v216
	v_fma_f32 v215, -v215, v218, v217
	v_div_fmas_f32 v215, v215, v216, v218
	v_div_fixup_f32 v109, v215, v214, v109
	v_div_scale_f32 v223, vcc, v110, v220, v110
	v_mul_f32_e32 v224, v223, v222
	v_fma_f32 v225, -v221, v224, v223
	v_fmac_f32_e32 v224, v225, v222
	v_fma_f32 v221, -v221, v224, v223
	v_div_fmas_f32 v221, v221, v222, v224
	v_div_fixup_f32 v110, v221, v220, v110
	v_div_scale_f32 v229, vcc, v111, v226, v111
	v_mul_f32_e32 v230, v229, v228
	v_fma_f32 v231, -v227, v230, v229
	v_fmac_f32_e32 v230, v231, v228
	v_fma_f32 v227, -v227, v230, v229
	v_div_fmas_f32 v227, v227, v228, v230
	v_div_fixup_f32 v111, v227, v226, v111
	v_mul_f32_e32 v59, v59, v108
	v_mul_f32_e32 v43, v43, v109
	v_mul_f32_e32 v27, v27, v110
	v_mul_f32_e32 v11, v11, v111
	v_mul_f32_e32 v159, v43, v43
	v_fmac_f32_e32 v159, v59, v59
	v_fmac_f32_e32 v159, v27, v27
	v_fmac_f32_e32 v159, v11, v11
	v_cvt_pk_bf16_f32 v108, v59, v177
	v_cvt_pk_bf16_f32 v109, v43, v177
	v_cvt_pk_bf16_f32 v110, v27, v177
	v_cvt_pk_bf16_f32 v111, v11, v177
	global_store_short v175, v108, s[14:15] offset:0
	global_store_short v175, v109, s[14:15] offset:64
	global_store_short v175, v110, s[14:15] offset:128
	global_store_short v175, v111, s[14:15] offset:192
	s_waitcnt vmcnt(60)
	v_add_u32_e32 v182, 0x18000, v169
	v_lshlrev_b32_e32 v112, 16, v112
	v_lshlrev_b32_e32 v113, 16, v113
	v_lshlrev_b32_e32 v114, 16, v114
	v_lshlrev_b32_e32 v115, 16, v115
	v_mul_f32_e32 v208, 0xbfb8aa3b, v112
	v_mul_f32_e32 v214, 0xbfb8aa3b, v113
	v_mul_f32_e32 v220, 0xbfb8aa3b, v114
	v_mul_f32_e32 v226, 0xbfb8aa3b, v115
	v_exp_f32_e32 v208, v208
	v_exp_f32_e32 v214, v214
	v_exp_f32_e32 v220, v220
	v_exp_f32_e32 v226, v226
	v_add_f32_e32 v208, 1.0, v208
	v_add_f32_e32 v214, 1.0, v214
	v_add_f32_e32 v220, 1.0, v220
	v_add_f32_e32 v226, 1.0, v226
	v_div_scale_f32 v209, s[12:13], v208, v208, v112
	v_div_scale_f32 v215, s[12:13], v214, v214, v113
	v_div_scale_f32 v221, s[12:13], v220, v220, v114
	v_div_scale_f32 v227, s[12:13], v226, v226, v115
	v_rcp_f32_e32 v210, v209
	v_rcp_f32_e32 v216, v215
	v_rcp_f32_e32 v222, v221
	v_rcp_f32_e32 v228, v227
	v_fma_f32 v211, -v209, v210, 1.0
	v_fma_f32 v217, -v215, v216, 1.0
	v_fma_f32 v223, -v221, v222, 1.0
	v_fma_f32 v229, -v227, v228, 1.0
	v_fmac_f32_e32 v210, v211, v210
	v_fmac_f32_e32 v216, v217, v216
	v_fmac_f32_e32 v222, v223, v222
	v_fmac_f32_e32 v228, v229, v228
	v_div_scale_f32 v211, vcc, v112, v208, v112
	v_mul_f32_e32 v212, v211, v210
	v_fma_f32 v213, -v209, v212, v211
	v_fmac_f32_e32 v212, v213, v210
	v_fma_f32 v209, -v209, v212, v211
	v_div_fmas_f32 v209, v209, v210, v212
	v_div_fixup_f32 v112, v209, v208, v112
	v_div_scale_f32 v217, vcc, v113, v214, v113
	v_mul_f32_e32 v218, v217, v216
	v_fma_f32 v219, -v215, v218, v217
	v_fmac_f32_e32 v218, v219, v216
	v_fma_f32 v215, -v215, v218, v217
	v_div_fmas_f32 v215, v215, v216, v218
	v_div_fixup_f32 v113, v215, v214, v113
	v_div_scale_f32 v223, vcc, v114, v220, v114
	v_mul_f32_e32 v224, v223, v222
	v_fma_f32 v225, -v221, v224, v223
	v_fmac_f32_e32 v224, v225, v222
	v_fma_f32 v221, -v221, v224, v223
	v_div_fmas_f32 v221, v221, v222, v224
	v_div_fixup_f32 v114, v221, v220, v114
	v_div_scale_f32 v229, vcc, v115, v226, v115
	v_mul_f32_e32 v230, v229, v228
	v_fma_f32 v231, -v227, v230, v229
	v_fmac_f32_e32 v230, v231, v228
	v_fma_f32 v227, -v227, v230, v229
	v_div_fmas_f32 v227, v227, v228, v230
	v_div_fixup_f32 v115, v227, v226, v115
	v_mul_f32_e32 v60, v60, v112
	v_mul_f32_e32 v44, v44, v113
	v_mul_f32_e32 v28, v28, v114
	v_mul_f32_e32 v12, v12, v115
	v_mul_f32_e32 v160, v44, v44
	v_fmac_f32_e32 v160, v60, v60
	v_fmac_f32_e32 v160, v28, v28
	v_fmac_f32_e32 v160, v12, v12
	v_cvt_pk_bf16_f32 v112, v60, v177
	v_cvt_pk_bf16_f32 v113, v44, v177
	v_cvt_pk_bf16_f32 v114, v28, v177
	v_cvt_pk_bf16_f32 v115, v12, v177
	global_store_short v182, v112, s[14:15] offset:0
	global_store_short v182, v113, s[14:15] offset:64
	global_store_short v182, v114, s[14:15] offset:128
	global_store_short v182, v115, s[14:15] offset:192
	s_waitcnt vmcnt(60)
	v_add_u32_e32 v175, 0x19000, v169
	v_lshlrev_b32_e32 v116, 16, v116
	v_lshlrev_b32_e32 v117, 16, v117
	v_lshlrev_b32_e32 v118, 16, v118
	v_lshlrev_b32_e32 v119, 16, v119
	v_mul_f32_e32 v208, 0xbfb8aa3b, v116
	v_mul_f32_e32 v214, 0xbfb8aa3b, v117
	v_mul_f32_e32 v220, 0xbfb8aa3b, v118
	v_mul_f32_e32 v226, 0xbfb8aa3b, v119
	v_exp_f32_e32 v208, v208
	v_exp_f32_e32 v214, v214
	v_exp_f32_e32 v220, v220
	v_exp_f32_e32 v226, v226
	v_add_f32_e32 v208, 1.0, v208
	v_add_f32_e32 v214, 1.0, v214
	v_add_f32_e32 v220, 1.0, v220
	v_add_f32_e32 v226, 1.0, v226
	v_div_scale_f32 v209, s[12:13], v208, v208, v116
	v_div_scale_f32 v215, s[12:13], v214, v214, v117
	v_div_scale_f32 v221, s[12:13], v220, v220, v118
	v_div_scale_f32 v227, s[12:13], v226, v226, v119
	v_rcp_f32_e32 v210, v209
	v_rcp_f32_e32 v216, v215
	v_rcp_f32_e32 v222, v221
	v_rcp_f32_e32 v228, v227
	v_fma_f32 v211, -v209, v210, 1.0
	v_fma_f32 v217, -v215, v216, 1.0
	v_fma_f32 v223, -v221, v222, 1.0
	v_fma_f32 v229, -v227, v228, 1.0
	v_fmac_f32_e32 v210, v211, v210
	v_fmac_f32_e32 v216, v217, v216
	v_fmac_f32_e32 v222, v223, v222
	v_fmac_f32_e32 v228, v229, v228
	v_div_scale_f32 v211, vcc, v116, v208, v116
	v_mul_f32_e32 v212, v211, v210
	v_fma_f32 v213, -v209, v212, v211
	v_fmac_f32_e32 v212, v213, v210
	v_fma_f32 v209, -v209, v212, v211
	v_div_fmas_f32 v209, v209, v210, v212
	v_div_fixup_f32 v116, v209, v208, v116
	v_div_scale_f32 v217, vcc, v117, v214, v117
	v_mul_f32_e32 v218, v217, v216
	v_fma_f32 v219, -v215, v218, v217
	v_fmac_f32_e32 v218, v219, v216
	v_fma_f32 v215, -v215, v218, v217
	v_div_fmas_f32 v215, v215, v216, v218
	v_div_fixup_f32 v117, v215, v214, v117
	v_div_scale_f32 v223, vcc, v118, v220, v118
	v_mul_f32_e32 v224, v223, v222
	v_fma_f32 v225, -v221, v224, v223
	v_fmac_f32_e32 v224, v225, v222
	v_fma_f32 v221, -v221, v224, v223
	v_div_fmas_f32 v221, v221, v222, v224
	v_div_fixup_f32 v118, v221, v220, v118
	v_div_scale_f32 v229, vcc, v119, v226, v119
	v_mul_f32_e32 v230, v229, v228
	v_fma_f32 v231, -v227, v230, v229
	v_fmac_f32_e32 v230, v231, v228
	v_fma_f32 v227, -v227, v230, v229
	v_div_fmas_f32 v227, v227, v228, v230
	v_div_fixup_f32 v119, v227, v226, v119
	v_mul_f32_e32 v61, v61, v116
	v_mul_f32_e32 v45, v45, v117
	v_mul_f32_e32 v29, v29, v118
	v_mul_f32_e32 v13, v13, v119
	v_mul_f32_e32 v161, v45, v45
	v_fmac_f32_e32 v161, v61, v61
	v_fmac_f32_e32 v161, v29, v29
	v_fmac_f32_e32 v161, v13, v13
	v_cvt_pk_bf16_f32 v116, v61, v177
	v_cvt_pk_bf16_f32 v117, v45, v177
	v_cvt_pk_bf16_f32 v118, v29, v177
	v_cvt_pk_bf16_f32 v119, v13, v177
	global_store_short v175, v116, s[14:15] offset:0
	global_store_short v175, v117, s[14:15] offset:64
	global_store_short v175, v118, s[14:15] offset:128
	global_store_short v175, v119, s[14:15] offset:192
	s_waitcnt vmcnt(60)
	v_add_u32_e32 v182, 0x1a000, v169
	v_lshlrev_b32_e32 v120, 16, v120
	v_lshlrev_b32_e32 v121, 16, v121
	v_lshlrev_b32_e32 v122, 16, v122
	v_lshlrev_b32_e32 v123, 16, v123
	v_mul_f32_e32 v208, 0xbfb8aa3b, v120
	v_mul_f32_e32 v214, 0xbfb8aa3b, v121
	v_mul_f32_e32 v220, 0xbfb8aa3b, v122
	v_mul_f32_e32 v226, 0xbfb8aa3b, v123
	v_exp_f32_e32 v208, v208
	v_exp_f32_e32 v214, v214
	v_exp_f32_e32 v220, v220
	v_exp_f32_e32 v226, v226
	v_add_f32_e32 v208, 1.0, v208
	v_add_f32_e32 v214, 1.0, v214
	v_add_f32_e32 v220, 1.0, v220
	v_add_f32_e32 v226, 1.0, v226
	v_div_scale_f32 v209, s[12:13], v208, v208, v120
	v_div_scale_f32 v215, s[12:13], v214, v214, v121
	v_div_scale_f32 v221, s[12:13], v220, v220, v122
	v_div_scale_f32 v227, s[12:13], v226, v226, v123
	v_rcp_f32_e32 v210, v209
	v_rcp_f32_e32 v216, v215
	v_rcp_f32_e32 v222, v221
	v_rcp_f32_e32 v228, v227
	v_fma_f32 v211, -v209, v210, 1.0
	v_fma_f32 v217, -v215, v216, 1.0
	v_fma_f32 v223, -v221, v222, 1.0
	v_fma_f32 v229, -v227, v228, 1.0
	v_fmac_f32_e32 v210, v211, v210
	v_fmac_f32_e32 v216, v217, v216
	v_fmac_f32_e32 v222, v223, v222
	v_fmac_f32_e32 v228, v229, v228
	v_div_scale_f32 v211, vcc, v120, v208, v120
	v_mul_f32_e32 v212, v211, v210
	v_fma_f32 v213, -v209, v212, v211
	v_fmac_f32_e32 v212, v213, v210
	v_fma_f32 v209, -v209, v212, v211
	v_div_fmas_f32 v209, v209, v210, v212
	v_div_fixup_f32 v120, v209, v208, v120
	v_div_scale_f32 v217, vcc, v121, v214, v121
	v_mul_f32_e32 v218, v217, v216
	v_fma_f32 v219, -v215, v218, v217
	v_fmac_f32_e32 v218, v219, v216
	v_fma_f32 v215, -v215, v218, v217
	v_div_fmas_f32 v215, v215, v216, v218
	v_div_fixup_f32 v121, v215, v214, v121
	v_div_scale_f32 v223, vcc, v122, v220, v122
	v_mul_f32_e32 v224, v223, v222
	v_fma_f32 v225, -v221, v224, v223
	v_fmac_f32_e32 v224, v225, v222
	v_fma_f32 v221, -v221, v224, v223
	v_div_fmas_f32 v221, v221, v222, v224
	v_div_fixup_f32 v122, v221, v220, v122
	v_div_scale_f32 v229, vcc, v123, v226, v123
	v_mul_f32_e32 v230, v229, v228
	v_fma_f32 v231, -v227, v230, v229
	v_fmac_f32_e32 v230, v231, v228
	v_fma_f32 v227, -v227, v230, v229
	v_div_fmas_f32 v227, v227, v228, v230
	v_div_fixup_f32 v123, v227, v226, v123
	v_mul_f32_e32 v62, v62, v120
	v_mul_f32_e32 v46, v46, v121
	v_mul_f32_e32 v30, v30, v122
	v_mul_f32_e32 v14, v14, v123
	v_mul_f32_e32 v162, v46, v46
	v_fmac_f32_e32 v162, v62, v62
	v_fmac_f32_e32 v162, v30, v30
	v_fmac_f32_e32 v162, v14, v14
	v_cvt_pk_bf16_f32 v120, v62, v177
	v_cvt_pk_bf16_f32 v121, v46, v177
	v_cvt_pk_bf16_f32 v122, v30, v177
	v_cvt_pk_bf16_f32 v123, v14, v177
	global_store_short v182, v120, s[14:15] offset:0
	global_store_short v182, v121, s[14:15] offset:64
	global_store_short v182, v122, s[14:15] offset:128
	global_store_short v182, v123, s[14:15] offset:192
	s_waitcnt vmcnt(60)
	v_add_u32_e32 v175, 0x1b000, v169
	v_lshlrev_b32_e32 v124, 16, v124
	v_lshlrev_b32_e32 v125, 16, v125
	v_lshlrev_b32_e32 v126, 16, v126
	v_lshlrev_b32_e32 v127, 16, v127
	v_mul_f32_e32 v208, 0xbfb8aa3b, v124
	v_mul_f32_e32 v214, 0xbfb8aa3b, v125
	v_mul_f32_e32 v220, 0xbfb8aa3b, v126
	v_mul_f32_e32 v226, 0xbfb8aa3b, v127
	v_exp_f32_e32 v208, v208
	v_exp_f32_e32 v214, v214
	v_exp_f32_e32 v220, v220
	v_exp_f32_e32 v226, v226
	v_add_f32_e32 v208, 1.0, v208
	v_add_f32_e32 v214, 1.0, v214
	v_add_f32_e32 v220, 1.0, v220
	v_add_f32_e32 v226, 1.0, v226
	v_div_scale_f32 v209, s[12:13], v208, v208, v124
	v_div_scale_f32 v215, s[12:13], v214, v214, v125
	v_div_scale_f32 v221, s[12:13], v220, v220, v126
	v_div_scale_f32 v227, s[12:13], v226, v226, v127
	v_rcp_f32_e32 v210, v209
	v_rcp_f32_e32 v216, v215
	v_rcp_f32_e32 v222, v221
	v_rcp_f32_e32 v228, v227
	v_fma_f32 v211, -v209, v210, 1.0
	v_fma_f32 v217, -v215, v216, 1.0
	v_fma_f32 v223, -v221, v222, 1.0
	v_fma_f32 v229, -v227, v228, 1.0
	v_fmac_f32_e32 v210, v211, v210
	v_fmac_f32_e32 v216, v217, v216
	v_fmac_f32_e32 v222, v223, v222
	v_fmac_f32_e32 v228, v229, v228
	v_div_scale_f32 v211, vcc, v124, v208, v124
	v_mul_f32_e32 v212, v211, v210
	v_fma_f32 v213, -v209, v212, v211
	v_fmac_f32_e32 v212, v213, v210
	v_fma_f32 v209, -v209, v212, v211
	v_div_fmas_f32 v209, v209, v210, v212
	v_div_fixup_f32 v124, v209, v208, v124
	v_div_scale_f32 v217, vcc, v125, v214, v125
	v_mul_f32_e32 v218, v217, v216
	v_fma_f32 v219, -v215, v218, v217
	v_fmac_f32_e32 v218, v219, v216
	v_fma_f32 v215, -v215, v218, v217
	v_div_fmas_f32 v215, v215, v216, v218
	v_div_fixup_f32 v125, v215, v214, v125
	v_div_scale_f32 v223, vcc, v126, v220, v126
	v_mul_f32_e32 v224, v223, v222
	v_fma_f32 v225, -v221, v224, v223
	v_fmac_f32_e32 v224, v225, v222
	v_fma_f32 v221, -v221, v224, v223
	v_div_fmas_f32 v221, v221, v222, v224
	v_div_fixup_f32 v126, v221, v220, v126
	v_div_scale_f32 v229, vcc, v127, v226, v127
	v_mul_f32_e32 v230, v229, v228
	v_fma_f32 v231, -v227, v230, v229
	v_fmac_f32_e32 v230, v231, v228
	v_fma_f32 v227, -v227, v230, v229
	v_div_fmas_f32 v227, v227, v228, v230
	v_div_fixup_f32 v127, v227, v226, v127
	v_mul_f32_e32 v63, v63, v124
	v_mul_f32_e32 v47, v47, v125
	v_mul_f32_e32 v31, v31, v126
	v_mul_f32_e32 v15, v15, v127
	v_mul_f32_e32 v163, v47, v47
	v_fmac_f32_e32 v163, v63, v63
	v_fmac_f32_e32 v163, v31, v31
	v_fmac_f32_e32 v163, v15, v15
	v_cvt_pk_bf16_f32 v124, v63, v177
	v_cvt_pk_bf16_f32 v125, v47, v177
	v_cvt_pk_bf16_f32 v126, v31, v177
	v_cvt_pk_bf16_f32 v127, v15, v177
	global_store_short v175, v124, s[14:15] offset:0
	global_store_short v175, v125, s[14:15] offset:64
	global_store_short v175, v126, s[14:15] offset:128
	global_store_short v175, v127, s[14:15] offset:192
	v_add_f32_dpp v148, v148, v148 quad_perm:[1,0,3,2] row_mask:0xf bank_mask:0xf
	v_add_f32_dpp v149, v149, v149 quad_perm:[1,0,3,2] row_mask:0xf bank_mask:0xf
	v_add_f32_dpp v150, v150, v150 quad_perm:[1,0,3,2] row_mask:0xf bank_mask:0xf
	v_add_f32_dpp v151, v151, v151 quad_perm:[1,0,3,2] row_mask:0xf bank_mask:0xf
	v_add_f32_dpp v152, v152, v152 quad_perm:[1,0,3,2] row_mask:0xf bank_mask:0xf
	v_add_f32_dpp v153, v153, v153 quad_perm:[1,0,3,2] row_mask:0xf bank_mask:0xf
	v_add_f32_dpp v154, v154, v154 quad_perm:[1,0,3,2] row_mask:0xf bank_mask:0xf
	v_add_f32_dpp v155, v155, v155 quad_perm:[1,0,3,2] row_mask:0xf bank_mask:0xf
	v_add_f32_dpp v156, v156, v156 quad_perm:[1,0,3,2] row_mask:0xf bank_mask:0xf
	v_add_f32_dpp v157, v157, v157 quad_perm:[1,0,3,2] row_mask:0xf bank_mask:0xf
	v_add_f32_dpp v158, v158, v158 quad_perm:[1,0,3,2] row_mask:0xf bank_mask:0xf
	v_add_f32_dpp v159, v159, v159 quad_perm:[1,0,3,2] row_mask:0xf bank_mask:0xf
	v_add_f32_dpp v160, v160, v160 quad_perm:[1,0,3,2] row_mask:0xf bank_mask:0xf
	v_add_f32_dpp v161, v161, v161 quad_perm:[1,0,3,2] row_mask:0xf bank_mask:0xf
	v_add_f32_dpp v162, v162, v162 quad_perm:[1,0,3,2] row_mask:0xf bank_mask:0xf
	v_add_f32_dpp v163, v163, v163 quad_perm:[1,0,3,2] row_mask:0xf bank_mask:0xf
	v_add_f32_dpp v148, v148, v148 quad_perm:[2,3,0,1] row_mask:0xf bank_mask:0xf
	v_add_f32_dpp v149, v149, v149 quad_perm:[2,3,0,1] row_mask:0xf bank_mask:0xf
	v_add_f32_dpp v150, v150, v150 quad_perm:[2,3,0,1] row_mask:0xf bank_mask:0xf
	v_add_f32_dpp v151, v151, v151 quad_perm:[2,3,0,1] row_mask:0xf bank_mask:0xf
	v_add_f32_dpp v152, v152, v152 quad_perm:[2,3,0,1] row_mask:0xf bank_mask:0xf
	v_add_f32_dpp v153, v153, v153 quad_perm:[2,3,0,1] row_mask:0xf bank_mask:0xf
	v_add_f32_dpp v154, v154, v154 quad_perm:[2,3,0,1] row_mask:0xf bank_mask:0xf
	v_add_f32_dpp v155, v155, v155 quad_perm:[2,3,0,1] row_mask:0xf bank_mask:0xf
	v_add_f32_dpp v156, v156, v156 quad_perm:[2,3,0,1] row_mask:0xf bank_mask:0xf
	v_add_f32_dpp v157, v157, v157 quad_perm:[2,3,0,1] row_mask:0xf bank_mask:0xf
	v_add_f32_dpp v158, v158, v158 quad_perm:[2,3,0,1] row_mask:0xf bank_mask:0xf
	v_add_f32_dpp v159, v159, v159 quad_perm:[2,3,0,1] row_mask:0xf bank_mask:0xf
	v_add_f32_dpp v160, v160, v160 quad_perm:[2,3,0,1] row_mask:0xf bank_mask:0xf
	v_add_f32_dpp v161, v161, v161 quad_perm:[2,3,0,1] row_mask:0xf bank_mask:0xf
	v_add_f32_dpp v162, v162, v162 quad_perm:[2,3,0,1] row_mask:0xf bank_mask:0xf
	v_add_f32_dpp v163, v163, v163 quad_perm:[2,3,0,1] row_mask:0xf bank_mask:0xf
	v_add_f32_dpp v148, v148, v148 row_half_mirror row_mask:0xf bank_mask:0xf
	v_add_f32_dpp v149, v149, v149 row_half_mirror row_mask:0xf bank_mask:0xf
	v_add_f32_dpp v150, v150, v150 row_half_mirror row_mask:0xf bank_mask:0xf
	v_add_f32_dpp v151, v151, v151 row_half_mirror row_mask:0xf bank_mask:0xf
	v_add_f32_dpp v152, v152, v152 row_half_mirror row_mask:0xf bank_mask:0xf
	v_add_f32_dpp v153, v153, v153 row_half_mirror row_mask:0xf bank_mask:0xf
	v_add_f32_dpp v154, v154, v154 row_half_mirror row_mask:0xf bank_mask:0xf
	v_add_f32_dpp v155, v155, v155 row_half_mirror row_mask:0xf bank_mask:0xf
	v_add_f32_dpp v156, v156, v156 row_half_mirror row_mask:0xf bank_mask:0xf
	v_add_f32_dpp v157, v157, v157 row_half_mirror row_mask:0xf bank_mask:0xf
	v_add_f32_dpp v158, v158, v158 row_half_mirror row_mask:0xf bank_mask:0xf
	v_add_f32_dpp v159, v159, v159 row_half_mirror row_mask:0xf bank_mask:0xf
	v_add_f32_dpp v160, v160, v160 row_half_mirror row_mask:0xf bank_mask:0xf
	v_add_f32_dpp v161, v161, v161 row_half_mirror row_mask:0xf bank_mask:0xf
	v_add_f32_dpp v162, v162, v162 row_half_mirror row_mask:0xf bank_mask:0xf
	v_add_f32_dpp v163, v163, v163 row_half_mirror row_mask:0xf bank_mask:0xf
	v_add_f32_dpp v148, v148, v148 row_mirror row_mask:0xf bank_mask:0xf
	v_add_f32_dpp v149, v149, v149 row_mirror row_mask:0xf bank_mask:0xf
	v_add_f32_dpp v150, v150, v150 row_mirror row_mask:0xf bank_mask:0xf
	v_add_f32_dpp v151, v151, v151 row_mirror row_mask:0xf bank_mask:0xf
	v_add_f32_dpp v152, v152, v152 row_mirror row_mask:0xf bank_mask:0xf
	v_add_f32_dpp v153, v153, v153 row_mirror row_mask:0xf bank_mask:0xf
	v_add_f32_dpp v154, v154, v154 row_mirror row_mask:0xf bank_mask:0xf
	v_add_f32_dpp v155, v155, v155 row_mirror row_mask:0xf bank_mask:0xf
	v_add_f32_dpp v156, v156, v156 row_mirror row_mask:0xf bank_mask:0xf
	v_add_f32_dpp v157, v157, v157 row_mirror row_mask:0xf bank_mask:0xf
	v_add_f32_dpp v158, v158, v158 row_mirror row_mask:0xf bank_mask:0xf
	v_add_f32_dpp v159, v159, v159 row_mirror row_mask:0xf bank_mask:0xf
	v_add_f32_dpp v160, v160, v160 row_mirror row_mask:0xf bank_mask:0xf
	v_add_f32_dpp v161, v161, v161 row_mirror row_mask:0xf bank_mask:0xf
	v_add_f32_dpp v162, v162, v162 row_mirror row_mask:0xf bank_mask:0xf
	v_add_f32_dpp v163, v163, v163 row_mirror row_mask:0xf bank_mask:0xf
	ds_bpermute_b32 v208, v207, v148
	ds_bpermute_b32 v209, v207, v149
	ds_bpermute_b32 v210, v207, v150
	ds_bpermute_b32 v211, v207, v151
	ds_bpermute_b32 v212, v207, v152
	ds_bpermute_b32 v213, v207, v153
	ds_bpermute_b32 v214, v207, v154
	ds_bpermute_b32 v215, v207, v155
	ds_bpermute_b32 v216, v207, v156
	ds_bpermute_b32 v217, v207, v157
	ds_bpermute_b32 v218, v207, v158
	ds_bpermute_b32 v219, v207, v159
	ds_bpermute_b32 v220, v207, v160
	ds_bpermute_b32 v221, v207, v161
	ds_bpermute_b32 v222, v207, v162
	ds_bpermute_b32 v223, v207, v163
	v_cmp_eq_u32_e64 s[40:41], 0, v196
	s_waitcnt lgkmcnt(0)
	v_add_f32_e32 v148, v148, v208
	v_add_f32_e32 v149, v149, v209
	v_add_f32_e32 v150, v150, v210
	v_add_f32_e32 v151, v151, v211
	v_add_f32_e32 v152, v152, v212
	v_add_f32_e32 v153, v153, v213
	v_add_f32_e32 v154, v154, v214
	v_add_f32_e32 v155, v155, v215
	v_add_f32_e32 v156, v156, v216
	v_add_f32_e32 v157, v157, v217
	v_add_f32_e32 v158, v158, v218
	v_add_f32_e32 v159, v159, v219
	v_add_f32_e32 v160, v160, v220
	v_add_f32_e32 v161, v161, v221
	v_add_f32_e32 v162, v162, v222
	v_add_f32_e32 v163, v163, v223
	s_and_saveexec_b64 s[44:45], s[40:41]
	v_mov_b32_e32 v171, v170
	global_store_dword v171, v148, s[42:43]
	v_add_u32_e32 v172, 0x20, v170
	global_store_dword v172, v149, s[42:43]
	v_add_u32_e32 v173, 0x40, v170
	global_store_dword v173, v150, s[42:43]
	v_add_u32_e32 v174, 0x60, v170
	global_store_dword v174, v151, s[42:43]
	v_add_u32_e32 v171, 0x100, v170
	global_store_dword v171, v152, s[42:43]
	v_add_u32_e32 v172, 0x120, v170
	global_store_dword v172, v153, s[42:43]
	v_add_u32_e32 v173, 0x140, v170
	global_store_dword v173, v154, s[42:43]
	v_add_u32_e32 v174, 0x160, v170
	global_store_dword v174, v155, s[42:43]
	v_add_u32_e32 v171, 0x200, v170
	global_store_dword v171, v156, s[42:43]
	v_add_u32_e32 v172, 0x220, v170
	global_store_dword v172, v157, s[42:43]
	v_add_u32_e32 v173, 0x240, v170
	global_store_dword v173, v158, s[42:43]
	v_add_u32_e32 v174, 0x260, v170
	global_store_dword v174, v159, s[42:43]
	v_add_u32_e32 v171, 0x300, v170
	global_store_dword v171, v160, s[42:43]
	v_add_u32_e32 v172, 0x320, v170
	global_store_dword v172, v161, s[42:43]
	v_add_u32_e32 v173, 0x340, v170
	global_store_dword v173, v162, s[42:43]
	v_add_u32_e32 v174, 0x360, v170
	global_store_dword v174, v163, s[42:43]
	s_or_b64 exec, exec, s[44:45]
	s_branch .LBB0_416

.LBB0_525:
	ds_read_b128 v[100:103], v213
	ds_read_b128 v[104:107], v213 offset:1024
	ds_read_b128 v[108:111], v213 offset:2048
	ds_read_b128 v[112:115], v213 offset:3072
	s_add_u32 s1, s72, 0xfff80080
	s_addc_u32 s2, s73, -1
	s_cmp_eq_u32 vcc_lo, 28
	s_cselect_b32 s75, s53, s2
	s_cselect_b32 s74, s69, s1
	s_cselect_b32 s71, s30, s97
	s_cselect_b32 s70, s31, s39
	s_mov_b32 m0, s90
	v_lshl_add_u64 v[190:191], s[72:73], 0, v[184:185]
	ds_read_b128 v[116:119], v211
	ds_read_b128 v[120:123], v211 offset:1024
	ds_read_b128 v[124:127], v211 offset:2048
	ds_read_b128 v[128:131], v211 offset:3072
	ds_read_b128 v[140:143], v211 offset:4096
	ds_read_b128 v[144:147], v211 offset:5120
	ds_read_b128 v[148:151], v211 offset:6144
	ds_read_b128 v[152:155], v211 offset:7168
	global_load_lds_dwordx4 v[190:191], off
	v_lshl_add_u64 v[190:191], s[72:73], 0, v[186:187]
	s_mov_b32 m0, s91
	s_nop 0
	global_load_lds_dwordx4 v[190:191], off
	s_waitcnt lgkmcnt(8)
	s_barrier
	s_waitcnt lgkmcnt(0)
	s_setprio 1
	s_waitcnt lgkmcnt(0)
	v_mfma_f32_16x16x32_bf16 v[172:175], v[100:103], v[116:119], v[172:175]
	v_mfma_f32_16x16x32_bf16 v[168:171], v[108:111], v[116:119], v[168:171]
	v_mfma_f32_16x16x32_bf16 v[156:159], v[100:103], v[124:127], v[156:159]
	v_mfma_f32_16x16x32_bf16 v[136:139], v[108:111], v[124:127], v[136:139]
	v_mfma_f32_16x16x32_bf16 v[92:95], v[100:103], v[140:143], v[92:95]
	v_mfma_f32_16x16x32_bf16 v[88:91], v[108:111], v[140:143], v[88:91]
	v_mfma_f32_16x16x32_bf16 v[76:79], v[100:103], v[148:151], v[76:79]
	v_mfma_f32_16x16x32_bf16 v[72:75], v[108:111], v[148:151], v[72:75]
	v_mfma_f32_16x16x32_bf16 v[172:175], v[104:107], v[120:123], v[172:175]
	v_mfma_f32_16x16x32_bf16 v[168:171], v[112:115], v[120:123], v[168:171]
	v_mfma_f32_16x16x32_bf16 v[156:159], v[104:107], v[128:131], v[156:159]
	v_mfma_f32_16x16x32_bf16 v[136:139], v[112:115], v[128:131], v[136:139]
	v_mfma_f32_16x16x32_bf16 v[92:95], v[104:107], v[144:147], v[92:95]
	v_mfma_f32_16x16x32_bf16 v[88:91], v[112:115], v[144:147], v[88:91]
	v_mfma_f32_16x16x32_bf16 v[76:79], v[104:107], v[152:155], v[76:79]
	v_mfma_f32_16x16x32_bf16 v[72:75], v[112:115], v[152:155], v[72:75]
	s_setprio 0
	s_barrier
	s_mov_b32 m0, s92
	v_lshl_add_u64 v[190:191], s[70:71], 0, v[176:177]
	ds_read_b128 v[200:203], v214
	ds_read_b128 v[218:221], v214 offset:1024
	ds_read_b128 v[222:225], v214 offset:2048
	ds_read_b128 v[226:229], v214 offset:3072
	global_load_lds_dwordx4 v[190:191], off
	v_lshl_add_u64 v[194:195], s[70:71], 0, v[182:183]
	s_mov_b32 m0, s93
	s_nop 0
	global_load_lds_dwordx4 v[194:195], off
	s_barrier
	s_waitcnt lgkmcnt(0)
	s_setprio 1
	s_waitcnt lgkmcnt(0)
	v_mfma_f32_16x16x32_bf16 v[164:167], v[200:203], v[116:119], v[164:167]
	v_mfma_f32_16x16x32_bf16 v[116:119], v[222:225], v[116:119], v[160:163]
	v_mfma_f32_16x16x32_bf16 v[96:99], v[222:225], v[124:127], v[96:99]
	v_mfma_f32_16x16x32_bf16 v[84:87], v[200:203], v[140:143], v[84:87]
	v_mfma_f32_16x16x32_bf16 v[80:83], v[222:225], v[140:143], v[80:83]
	v_mfma_f32_16x16x32_bf16 v[68:71], v[200:203], v[148:151], v[68:71]
	v_mfma_f32_16x16x32_bf16 v[64:67], v[222:225], v[148:151], v[64:67]
	v_mfma_f32_16x16x32_bf16 v[164:167], v[218:221], v[120:123], v[164:167]
	v_mfma_f32_16x16x32_bf16 v[116:119], v[226:229], v[120:123], v[116:119]
	v_mfma_f32_16x16x32_bf16 v[120:123], v[200:203], v[124:127], v[132:135]
	v_mfma_f32_16x16x32_bf16 v[96:99], v[226:229], v[128:131], v[96:99]
	v_mfma_f32_16x16x32_bf16 v[84:87], v[218:221], v[144:147], v[84:87]
	v_mfma_f32_16x16x32_bf16 v[80:83], v[226:229], v[144:147], v[80:83]
	v_mfma_f32_16x16x32_bf16 v[68:71], v[218:221], v[152:155], v[68:71]
	v_mfma_f32_16x16x32_bf16 v[64:67], v[226:229], v[152:155], v[64:67]
	v_mfma_f32_16x16x32_bf16 v[120:123], v[218:221], v[128:131], v[120:123]
	s_setprio 0
	s_mov_b32 m0, s79
	v_lshl_add_u64 v[204:205], s[74:75], 0, v[176:177]
	s_barrier
	ds_read_b128 v[124:127], v211 offset:16384
	ds_read_b128 v[128:131], v211 offset:17408
	ds_read_b128 v[132:135], v211 offset:18432
	ds_read_b128 v[140:143], v211 offset:19456
	ds_read_b128 v[144:147], v211 offset:20480
	ds_read_b128 v[148:151], v211 offset:21504
	ds_read_b128 v[152:155], v211 offset:22528
	ds_read_b128 v[160:163], v211 offset:23552
	global_load_lds_dwordx4 v[204:205], off
	v_lshl_add_u64 v[238:239], s[74:75], 0, v[182:183]
	s_mov_b32 m0, s80
	s_nop 0
	global_load_lds_dwordx4 v[238:239], off
	s_barrier
	s_waitcnt lgkmcnt(0)
	s_setprio 1
	s_waitcnt lgkmcnt(0)
	v_mfma_f32_16x16x32_bf16 v[60:63], v[100:103], v[124:127], v[60:63]
	v_mfma_f32_16x16x32_bf16 v[56:59], v[108:111], v[124:127], v[56:59]
	v_mfma_f32_16x16x32_bf16 v[44:47], v[100:103], v[132:135], v[44:47]
	v_mfma_f32_16x16x32_bf16 v[40:43], v[108:111], v[132:135], v[40:43]
	v_mfma_f32_16x16x32_bf16 v[28:31], v[100:103], v[144:147], v[28:31]
	v_mfma_f32_16x16x32_bf16 v[24:27], v[108:111], v[144:147], v[24:27]
	v_mfma_f32_16x16x32_bf16 v[12:15], v[100:103], v[152:155], v[12:15]
	v_mfma_f32_16x16x32_bf16 v[8:11], v[108:111], v[152:155], v[8:11]
	v_mfma_f32_16x16x32_bf16 v[60:63], v[104:107], v[128:131], v[60:63]
	v_mfma_f32_16x16x32_bf16 v[56:59], v[112:115], v[128:131], v[56:59]
	v_mfma_f32_16x16x32_bf16 v[44:47], v[104:107], v[140:143], v[44:47]
	v_mfma_f32_16x16x32_bf16 v[40:43], v[112:115], v[140:143], v[40:43]
	v_mfma_f32_16x16x32_bf16 v[28:31], v[104:107], v[148:151], v[28:31]
	v_mfma_f32_16x16x32_bf16 v[24:27], v[112:115], v[148:151], v[24:27]
	v_mfma_f32_16x16x32_bf16 v[12:15], v[104:107], v[160:163], v[12:15]
	v_mfma_f32_16x16x32_bf16 v[8:11], v[112:115], v[160:163], v[8:11]
	s_setprio 0
	s_barrier
	s_add_u32 s2, s70, 0x80000
	s_addc_u32 s3, s71, 0
	s_mov_b32 m0, s94
	v_lshl_add_u64 v[100:101], s[2:3], 0, v[176:177]
	global_load_lds_dwordx4 v[100:101], off
	v_lshl_add_u64 v[100:101], s[2:3], 0, v[182:183]
	s_mov_b32 m0, s95
	s_nop 0
	global_load_lds_dwordx4 v[100:101], off
	s_waitcnt vmcnt(6)
	s_barrier
	s_setprio 1
	v_mfma_f32_16x16x32_bf16 v[52:55], v[200:203], v[124:127], v[52:55]
	v_mfma_f32_16x16x32_bf16 v[48:51], v[222:225], v[124:127], v[48:51]
	v_mfma_f32_16x16x32_bf16 v[36:39], v[200:203], v[132:135], v[36:39]
	v_mfma_f32_16x16x32_bf16 v[32:35], v[222:225], v[132:135], v[32:35]
	v_mfma_f32_16x16x32_bf16 v[20:23], v[200:203], v[144:147], v[20:23]
	v_mfma_f32_16x16x32_bf16 v[16:19], v[222:225], v[144:147], v[16:19]
	v_mfma_f32_16x16x32_bf16 v[4:7], v[200:203], v[152:155], v[4:7]
	v_mfma_f32_16x16x32_bf16 v[0:3], v[222:225], v[152:155], v[0:3]
	v_mfma_f32_16x16x32_bf16 v[52:55], v[218:221], v[128:131], v[52:55]
	v_mfma_f32_16x16x32_bf16 v[48:51], v[226:229], v[128:131], v[48:51]
	v_mfma_f32_16x16x32_bf16 v[36:39], v[218:221], v[140:143], v[36:39]
	v_mfma_f32_16x16x32_bf16 v[32:35], v[226:229], v[140:143], v[32:35]
	v_mfma_f32_16x16x32_bf16 v[20:23], v[218:221], v[148:151], v[20:23]
	v_mfma_f32_16x16x32_bf16 v[16:19], v[226:229], v[148:151], v[16:19]
	v_mfma_f32_16x16x32_bf16 v[4:7], v[218:221], v[160:163], v[4:7]
	v_mfma_f32_16x16x32_bf16 v[0:3], v[226:229], v[160:163], v[0:3]
	s_setprio 0
	s_barrier
	ds_read_b128 v[100:103], v215
	ds_read_b128 v[104:107], v215 offset:1024
	ds_read_b128 v[108:111], v215 offset:2048
	ds_read_b128 v[112:115], v215 offset:3072
	s_add_u32 s2, s74, 0x80000
	s_addc_u32 s3, s75, 0
	s_mov_b32 m0, s81
	v_lshl_add_u64 v[132:133], s[2:3], 0, v[176:177]
	ds_read_b128 v[124:127], v211 offset:32768
	ds_read_b128 v[128:131], v211 offset:33792
	ds_read_b128 v[140:143], v211 offset:34816
	ds_read_b128 v[144:147], v211 offset:35840
	ds_read_b128 v[148:151], v211 offset:36864
	ds_read_b128 v[152:155], v211 offset:37888
	ds_read_b128 v[200:203], v211 offset:38912
	ds_read_b128 v[218:221], v211 offset:39936
	global_load_lds_dwordx4 v[132:133], off
	v_lshl_add_u64 v[132:133], s[2:3], 0, v[182:183]
	s_mov_b32 m0, s82
	s_nop 0
	global_load_lds_dwordx4 v[132:133], off
	s_waitcnt lgkmcnt(8)
	s_barrier
	s_waitcnt lgkmcnt(0)
	s_setprio 1
	s_waitcnt lgkmcnt(0)
	v_mfma_f32_16x16x32_bf16 v[132:135], v[100:103], v[124:127], v[172:175]
	v_mfma_f32_16x16x32_bf16 v[172:175], v[104:107], v[128:131], v[132:135]
	v_mfma_f32_16x16x32_bf16 v[132:135], v[108:111], v[124:127], v[168:171]
	v_mfma_f32_16x16x32_bf16 v[168:171], v[112:115], v[128:131], v[132:135]
	v_mfma_f32_16x16x32_bf16 v[132:135], v[100:103], v[140:143], v[156:159]
	v_mfma_f32_16x16x32_bf16 v[156:159], v[104:107], v[144:147], v[132:135]
	v_mfma_f32_16x16x32_bf16 v[132:135], v[108:111], v[140:143], v[136:139]
	v_mfma_f32_16x16x32_bf16 v[92:95], v[100:103], v[148:151], v[92:95]
	v_mfma_f32_16x16x32_bf16 v[88:91], v[108:111], v[148:151], v[88:91]
	v_mfma_f32_16x16x32_bf16 v[76:79], v[100:103], v[200:203], v[76:79]
	v_mfma_f32_16x16x32_bf16 v[72:75], v[108:111], v[200:203], v[72:75]
	v_mfma_f32_16x16x32_bf16 v[136:139], v[112:115], v[144:147], v[132:135]
	v_mfma_f32_16x16x32_bf16 v[92:95], v[104:107], v[152:155], v[92:95]
	v_mfma_f32_16x16x32_bf16 v[88:91], v[112:115], v[152:155], v[88:91]
	v_mfma_f32_16x16x32_bf16 v[76:79], v[104:107], v[218:221], v[76:79]
	v_mfma_f32_16x16x32_bf16 v[72:75], v[112:115], v[218:221], v[72:75]
	s_setprio 0
	s_barrier
	s_mov_b32 m0, s96
	v_lshl_add_u64 v[132:133], v[190:191], 0, s[20:21]
	ds_read_b128 v[222:225], v216
	ds_read_b128 v[226:229], v216 offset:1024
	ds_read_b128 v[230:233], v216 offset:2048
	ds_read_b128 v[234:237], v216 offset:3072
	global_load_lds_dwordx4 v[132:133], off
	v_lshl_add_u64 v[132:133], v[194:195], 0, s[20:21]
	s_mov_b32 m0, s60
	s_nop 0
	global_load_lds_dwordx4 v[132:133], off
	s_barrier
	s_waitcnt lgkmcnt(0)
	s_setprio 1
	s_waitcnt lgkmcnt(0)
	v_mfma_f32_16x16x32_bf16 v[116:119], v[230:233], v[124:127], v[116:119]
	v_mfma_f32_16x16x32_bf16 v[132:135], v[222:225], v[124:127], v[164:167]
	v_mfma_f32_16x16x32_bf16 v[160:163], v[234:237], v[128:131], v[116:119]
	v_mfma_f32_16x16x32_bf16 v[116:119], v[222:225], v[140:143], v[120:123]
	v_mfma_f32_16x16x32_bf16 v[96:99], v[230:233], v[140:143], v[96:99]
	v_mfma_f32_16x16x32_bf16 v[84:87], v[222:225], v[148:151], v[84:87]
	v_mfma_f32_16x16x32_bf16 v[80:83], v[230:233], v[148:151], v[80:83]
	v_mfma_f32_16x16x32_bf16 v[68:71], v[222:225], v[200:203], v[68:71]
	v_mfma_f32_16x16x32_bf16 v[64:67], v[230:233], v[200:203], v[64:67]
	v_mfma_f32_16x16x32_bf16 v[164:167], v[226:229], v[128:131], v[132:135]
	v_mfma_f32_16x16x32_bf16 v[132:135], v[226:229], v[144:147], v[116:119]
	v_mfma_f32_16x16x32_bf16 v[96:99], v[234:237], v[144:147], v[96:99]
	v_mfma_f32_16x16x32_bf16 v[84:87], v[226:229], v[152:155], v[84:87]
	v_mfma_f32_16x16x32_bf16 v[80:83], v[234:237], v[152:155], v[80:83]
	v_mfma_f32_16x16x32_bf16 v[68:71], v[226:229], v[218:221], v[68:71]
	v_mfma_f32_16x16x32_bf16 v[64:67], v[234:237], v[218:221], v[64:67]
	s_setprio 0
	s_mov_b32 m0, s87
	v_lshl_add_u64 v[190:191], v[204:205], 0, s[20:21]
	s_barrier
	ds_read_b128 v[116:119], v211 offset:49152
	ds_read_b128 v[120:123], v211 offset:50176
	ds_read_b128 v[124:127], v211 offset:51200
	ds_read_b128 v[128:131], v211 offset:52224
	ds_read_b128 v[140:143], v211 offset:53248
	ds_read_b128 v[144:147], v211 offset:54272
	ds_read_b128 v[148:151], v211 offset:55296
	ds_read_b128 v[152:155], v211 offset:56320
	global_load_lds_dwordx4 v[190:191], off
	v_lshl_add_u64 v[190:191], v[238:239], 0, s[20:21]
	s_mov_b32 m0, s88
	s_nop 0
	global_load_lds_dwordx4 v[190:191], off
	s_barrier
	s_waitcnt lgkmcnt(0)
	s_setprio 1
	s_waitcnt lgkmcnt(0)
	v_mfma_f32_16x16x32_bf16 v[60:63], v[100:103], v[116:119], v[60:63]
	v_mfma_f32_16x16x32_bf16 v[56:59], v[108:111], v[116:119], v[56:59]
	v_mfma_f32_16x16x32_bf16 v[44:47], v[100:103], v[124:127], v[44:47]
	v_mfma_f32_16x16x32_bf16 v[40:43], v[108:111], v[124:127], v[40:43]
	v_mfma_f32_16x16x32_bf16 v[28:31], v[100:103], v[140:143], v[28:31]
	v_mfma_f32_16x16x32_bf16 v[24:27], v[108:111], v[140:143], v[24:27]
	v_mfma_f32_16x16x32_bf16 v[12:15], v[100:103], v[148:151], v[12:15]
	v_mfma_f32_16x16x32_bf16 v[8:11], v[108:111], v[148:151], v[8:11]
	v_mfma_f32_16x16x32_bf16 v[60:63], v[104:107], v[120:123], v[60:63]
	v_mfma_f32_16x16x32_bf16 v[56:59], v[112:115], v[120:123], v[56:59]
	v_mfma_f32_16x16x32_bf16 v[44:47], v[104:107], v[128:131], v[44:47]
	v_mfma_f32_16x16x32_bf16 v[40:43], v[112:115], v[128:131], v[40:43]
	v_mfma_f32_16x16x32_bf16 v[28:31], v[104:107], v[144:147], v[28:31]
	v_mfma_f32_16x16x32_bf16 v[24:27], v[112:115], v[144:147], v[24:27]
	v_mfma_f32_16x16x32_bf16 v[12:15], v[104:107], v[152:155], v[12:15]
	v_mfma_f32_16x16x32_bf16 v[8:11], v[112:115], v[152:155], v[8:11]
	s_setprio 0
	s_barrier
	s_add_u32 s2, s70, 0x80080
	s_addc_u32 s3, s71, 0
	s_mov_b32 m0, s61
	v_lshl_add_u64 v[100:101], s[2:3], 0, v[176:177]
	global_load_lds_dwordx4 v[100:101], off
	v_lshl_add_u64 v[100:101], s[2:3], 0, v[182:183]
	s_mov_b32 m0, s49
	s_nop 0
	global_load_lds_dwordx4 v[100:101], off
	s_waitcnt vmcnt(6)
	s_barrier
	s_setprio 1
	v_mfma_f32_16x16x32_bf16 v[52:55], v[222:225], v[116:119], v[52:55]
	v_mfma_f32_16x16x32_bf16 v[48:51], v[230:233], v[116:119], v[48:51]
	v_mfma_f32_16x16x32_bf16 v[36:39], v[222:225], v[124:127], v[36:39]
	v_mfma_f32_16x16x32_bf16 v[32:35], v[230:233], v[124:127], v[32:35]
	v_mfma_f32_16x16x32_bf16 v[20:23], v[222:225], v[140:143], v[20:23]
	v_mfma_f32_16x16x32_bf16 v[16:19], v[230:233], v[140:143], v[16:19]
	v_mfma_f32_16x16x32_bf16 v[4:7], v[222:225], v[148:151], v[4:7]
	v_mfma_f32_16x16x32_bf16 v[0:3], v[230:233], v[148:151], v[0:3]
	v_mfma_f32_16x16x32_bf16 v[52:55], v[226:229], v[120:123], v[52:55]
	v_mfma_f32_16x16x32_bf16 v[48:51], v[234:237], v[120:123], v[48:51]
	v_mfma_f32_16x16x32_bf16 v[36:39], v[226:229], v[128:131], v[36:39]
	v_mfma_f32_16x16x32_bf16 v[32:35], v[234:237], v[128:131], v[32:35]
	v_mfma_f32_16x16x32_bf16 v[20:23], v[226:229], v[144:147], v[20:23]
	v_mfma_f32_16x16x32_bf16 v[16:19], v[234:237], v[144:147], v[16:19]
	v_mfma_f32_16x16x32_bf16 v[4:7], v[226:229], v[152:155], v[4:7]
	v_mfma_f32_16x16x32_bf16 v[0:3], v[234:237], v[152:155], v[0:3]
	s_setprio 0
	s_add_i32 vcc_lo, vcc_lo, 2
	s_add_u32 s72, s72, 0x100
	s_addc_u32 s73, s73, 0
	s_add_u32 s39, s39, 0x100
	s_addc_u32 s97, s97, 0
	s_cmp_lt_u32 vcc_lo, 30
	s_barrier
	s_cbranch_scc1 .LBB0_525
	v_readlane_b32 s90, v255, 23
	v_readlane_b32 s96, v255, 17
	v_readlane_b32 s94, v255, 19
	v_readlane_b32 s48, v255, 21
	v_readlane_b32 s91, v255, 24
	v_readlane_b32 s93, v255, 25
	v_readlane_b32 s92, v255, 26
	v_readlane_b32 s97, v255, 18
	v_readlane_b32 s95, v255, 20
	v_readlane_b32 s49, v255, 22
	v_readlane_b32 s30, v255, 27
	v_readlane_b32 s31, v255, 28
	s_movk_i32 s14, 0x3fff
	v_add_u32_e32 v213, s52, v209
	v_lshl_or_b32 v252, s76, 8, v212
	v_lshlrev_b32_e32 v196, 12, v213
	v_lshl_add_u32 v196, v252, 1, v196
	v_mov_b32_e32 v192, v196
	global_load_dwordx2 v[100:101], v192, s[62:63] offset:0
	global_load_dwordx2 v[102:103], v192, s[62:63] offset:32
	global_load_dwordx2 v[104:105], v192, s[62:63] offset:256
	global_load_dwordx2 v[106:107], v192, s[62:63] offset:288
	v_add_u32_e32 v124, 0x10000, v196
	global_load_dwordx2 v[108:109], v124, s[62:63] offset:0
	global_load_dwordx2 v[110:111], v124, s[62:63] offset:32
	global_load_dwordx2 v[112:113], v124, s[62:63] offset:256
	global_load_dwordx2 v[114:115], v124, s[62:63] offset:288
	v_add_u32_e32 v192, 0x20000, v196
	global_load_dwordx2 v[200:201], v192, s[62:63] offset:0
	global_load_dwordx2 v[202:203], v192, s[62:63] offset:32
	global_load_dwordx2 v[204:205], v192, s[62:63] offset:256
	global_load_dwordx2 v[214:215], v192, s[62:63] offset:288
	v_add_u32_e32 v124, 0x30000, v196
	global_load_dwordx2 v[216:217], v124, s[62:63] offset:0
	global_load_dwordx2 v[218:219], v124, s[62:63] offset:32
	global_load_dwordx2 v[220:221], v124, s[62:63] offset:256
	global_load_dwordx2 v[222:223], v124, s[62:63] offset:288
	v_add_u32_e32 v192, 0x80000, v196
	global_load_dwordx2 v[224:225], v192, s[62:63] offset:0
	global_load_dwordx2 v[226:227], v192, s[62:63] offset:32
	global_load_dwordx2 v[228:229], v192, s[62:63] offset:256
	global_load_dwordx2 v[230:231], v192, s[62:63] offset:288
	v_add_u32_e32 v124, 0x90000, v196
	global_load_dwordx2 v[232:233], v124, s[62:63] offset:0
	global_load_dwordx2 v[234:235], v124, s[62:63] offset:32
	global_load_dwordx2 v[236:237], v124, s[62:63] offset:256
	global_load_dwordx2 v[238:239], v124, s[62:63] offset:288
	v_add_u32_e32 v192, 0xa0000, v196
	global_load_dwordx2 v[240:241], v192, s[62:63] offset:0
	global_load_dwordx2 v[242:243], v192, s[62:63] offset:32
	global_load_dwordx2 v[244:245], v192, s[62:63] offset:256
	global_load_dwordx2 v[246:247], v192, s[62:63] offset:288
	v_add_u32_e32 v124, 0xb0000, v196
	global_load_dwordx2 v[248:249], v124, s[62:63] offset:0
	global_load_dwordx2 v[190:191], v124, s[62:63] offset:32
	global_load_dwordx2 v[194:195], v124, s[62:63] offset:256
	global_load_dwordx2 v[146:147], v124, s[62:63] offset:288
	s_lshl_b32 s1, s76, 2
	s_or_b32 s1, s1, s83
	s_lshl_b32 s1, s1, 2
	v_lshl_add_u32 v188, v213, 7, s1
	s_waitcnt vmcnt(28)
	v_mov_b32_e32 v192, v196
	v_lshlrev_b32_e32 v198, 16, v100
	v_and_b32_e32 v100, 0xffff0000, v100
	v_lshlrev_b32_e32 v155, 16, v101
	v_and_b32_e32 v101, 0xffff0000, v101
	v_add_f32_e32 v172, v172, v198
	v_add_f32_e32 v173, v173, v100
	v_add_f32_e32 v174, v174, v155
	v_add_f32_e32 v175, v175, v101
	v_cvt_pk_bf16_f32 v100, v172, v173
	v_cvt_pk_bf16_f32 v101, v174, v175
	global_store_dwordx2 v192, v[100:101], s[58:59] offset:0
	v_mul_f32_e32 v198, v173, v173
	v_fmac_f32_e32 v198, v172, v172
	v_fmac_f32_e32 v198, v174, v174
	v_fmac_f32_e32 v198, v175, v175
	v_mov_b32_e32 v172, v198
	v_lshlrev_b32_e32 v198, 16, v102
	v_and_b32_e32 v102, 0xffff0000, v102
	v_lshlrev_b32_e32 v155, 16, v103
	v_and_b32_e32 v103, 0xffff0000, v103
	v_add_f32_e32 v168, v168, v198
	v_add_f32_e32 v169, v169, v102
	v_add_f32_e32 v170, v170, v155
	v_add_f32_e32 v171, v171, v103
	v_cvt_pk_bf16_f32 v102, v168, v169
	v_cvt_pk_bf16_f32 v103, v170, v171
	global_store_dwordx2 v192, v[102:103], s[58:59] offset:32
	v_fmac_f32_e32 v172, v168, v168
	v_fmac_f32_e32 v172, v169, v169
	v_fmac_f32_e32 v172, v170, v170
	v_fmac_f32_e32 v172, v171, v171
	v_lshlrev_b32_e32 v198, 16, v104
	v_and_b32_e32 v104, 0xffff0000, v104
	v_lshlrev_b32_e32 v155, 16, v105
	v_and_b32_e32 v105, 0xffff0000, v105
	v_add_f32_e32 v164, v164, v198
	v_add_f32_e32 v165, v165, v104
	v_add_f32_e32 v166, v166, v155
	v_add_f32_e32 v167, v167, v105
	v_cvt_pk_bf16_f32 v104, v164, v165
	v_cvt_pk_bf16_f32 v105, v166, v167
	global_store_dwordx2 v192, v[104:105], s[58:59] offset:256
	v_fmac_f32_e32 v172, v164, v164
	v_fmac_f32_e32 v172, v165, v165
	v_fmac_f32_e32 v172, v166, v166
	v_fmac_f32_e32 v172, v167, v167
	v_lshlrev_b32_e32 v198, 16, v106
	v_and_b32_e32 v106, 0xffff0000, v106
	v_lshlrev_b32_e32 v155, 16, v107
	v_and_b32_e32 v107, 0xffff0000, v107
	v_add_f32_e32 v160, v160, v198
	v_add_f32_e32 v161, v161, v106
	v_add_f32_e32 v162, v162, v155
	v_add_f32_e32 v163, v163, v107
	v_cvt_pk_bf16_f32 v106, v160, v161
	v_cvt_pk_bf16_f32 v107, v162, v163
	global_store_dwordx2 v192, v[106:107], s[58:59] offset:288
	v_fmac_f32_e32 v172, v160, v160
	v_fmac_f32_e32 v172, v161, v161
	v_fmac_f32_e32 v172, v162, v162
	v_fmac_f32_e32 v172, v163, v163
	s_waitcnt vmcnt(28)
	v_add_u32_e32 v124, 0x10000, v196
	v_lshlrev_b32_e32 v198, 16, v108
	v_and_b32_e32 v108, 0xffff0000, v108
	v_lshlrev_b32_e32 v155, 16, v109
	v_and_b32_e32 v109, 0xffff0000, v109
	v_add_f32_e32 v156, v156, v198
	v_add_f32_e32 v157, v157, v108
	v_add_f32_e32 v158, v158, v155
	v_add_f32_e32 v159, v159, v109
	v_cvt_pk_bf16_f32 v108, v156, v157
	v_cvt_pk_bf16_f32 v109, v158, v159
	global_store_dwordx2 v124, v[108:109], s[58:59] offset:0
	v_mul_f32_e32 v198, v157, v157
	v_fmac_f32_e32 v198, v156, v156
	v_fmac_f32_e32 v198, v158, v158
	v_fmac_f32_e32 v198, v159, v159
	v_mov_b32_e32 v156, v198
	v_lshlrev_b32_e32 v198, 16, v110
	v_and_b32_e32 v110, 0xffff0000, v110
	v_lshlrev_b32_e32 v155, 16, v111
	v_and_b32_e32 v111, 0xffff0000, v111
	v_add_f32_e32 v136, v136, v198
	v_add_f32_e32 v137, v137, v110
	v_add_f32_e32 v138, v138, v155
	v_add_f32_e32 v139, v139, v111
	v_cvt_pk_bf16_f32 v110, v136, v137
	v_cvt_pk_bf16_f32 v111, v138, v139
	global_store_dwordx2 v124, v[110:111], s[58:59] offset:32
	v_fmac_f32_e32 v156, v136, v136
	v_fmac_f32_e32 v156, v137, v137
	v_fmac_f32_e32 v156, v138, v138
	v_fmac_f32_e32 v156, v139, v139
	v_lshlrev_b32_e32 v198, 16, v112
	v_and_b32_e32 v112, 0xffff0000, v112
	v_lshlrev_b32_e32 v155, 16, v113
	v_and_b32_e32 v113, 0xffff0000, v113
	v_add_f32_e32 v132, v132, v198
	v_add_f32_e32 v133, v133, v112
	v_add_f32_e32 v134, v134, v155
	v_add_f32_e32 v135, v135, v113
	v_cvt_pk_bf16_f32 v112, v132, v133
	v_cvt_pk_bf16_f32 v113, v134, v135
	global_store_dwordx2 v124, v[112:113], s[58:59] offset:256
	v_fmac_f32_e32 v156, v132, v132
	v_fmac_f32_e32 v156, v133, v133
	v_fmac_f32_e32 v156, v134, v134
	v_fmac_f32_e32 v156, v135, v135
	v_lshlrev_b32_e32 v198, 16, v114
	v_and_b32_e32 v114, 0xffff0000, v114
	v_lshlrev_b32_e32 v155, 16, v115
	v_and_b32_e32 v115, 0xffff0000, v115
	v_add_f32_e32 v96, v96, v198
	v_add_f32_e32 v97, v97, v114
	v_add_f32_e32 v98, v98, v155
	v_add_f32_e32 v99, v99, v115
	v_cvt_pk_bf16_f32 v114, v96, v97
	v_cvt_pk_bf16_f32 v115, v98, v99
	global_store_dwordx2 v124, v[114:115], s[58:59] offset:288
	v_fmac_f32_e32 v156, v96, v96
	v_fmac_f32_e32 v156, v97, v97
	v_fmac_f32_e32 v156, v98, v98
	v_fmac_f32_e32 v156, v99, v99
	s_waitcnt vmcnt(28)
	v_add_u32_e32 v192, 0x20000, v196
	v_lshlrev_b32_e32 v198, 16, v200
	v_and_b32_e32 v200, 0xffff0000, v200
	v_lshlrev_b32_e32 v155, 16, v201
	v_and_b32_e32 v201, 0xffff0000, v201
	v_add_f32_e32 v92, v92, v198
	v_add_f32_e32 v93, v93, v200
	v_add_f32_e32 v94, v94, v155
	v_add_f32_e32 v95, v95, v201
	v_cvt_pk_bf16_f32 v200, v92, v93
	v_cvt_pk_bf16_f32 v201, v94, v95
	global_store_dwordx2 v192, v[200:201], s[58:59] offset:0
	v_mul_f32_e32 v198, v93, v93
	v_fmac_f32_e32 v198, v92, v92
	v_fmac_f32_e32 v198, v94, v94
	v_fmac_f32_e32 v198, v95, v95
	v_mov_b32_e32 v92, v198
	v_lshlrev_b32_e32 v198, 16, v202
	v_and_b32_e32 v202, 0xffff0000, v202
	v_lshlrev_b32_e32 v155, 16, v203
	v_and_b32_e32 v203, 0xffff0000, v203
	v_add_f32_e32 v88, v88, v198
	v_add_f32_e32 v89, v89, v202
	v_add_f32_e32 v90, v90, v155
	v_add_f32_e32 v91, v91, v203
	v_cvt_pk_bf16_f32 v202, v88, v89
	v_cvt_pk_bf16_f32 v203, v90, v91
	global_store_dwordx2 v192, v[202:203], s[58:59] offset:32
	v_fmac_f32_e32 v92, v88, v88
	v_fmac_f32_e32 v92, v89, v89
	v_fmac_f32_e32 v92, v90, v90
	v_fmac_f32_e32 v92, v91, v91
	v_lshlrev_b32_e32 v198, 16, v204
	v_and_b32_e32 v204, 0xffff0000, v204
	v_lshlrev_b32_e32 v155, 16, v205
	v_and_b32_e32 v205, 0xffff0000, v205
	v_add_f32_e32 v84, v84, v198
	v_add_f32_e32 v85, v85, v204
	v_add_f32_e32 v86, v86, v155
	v_add_f32_e32 v87, v87, v205
	v_cvt_pk_bf16_f32 v204, v84, v85
	v_cvt_pk_bf16_f32 v205, v86, v87
	global_store_dwordx2 v192, v[204:205], s[58:59] offset:256
	v_fmac_f32_e32 v92, v84, v84
	v_fmac_f32_e32 v92, v85, v85
	v_fmac_f32_e32 v92, v86, v86
	v_fmac_f32_e32 v92, v87, v87
	v_lshlrev_b32_e32 v198, 16, v214
	v_and_b32_e32 v214, 0xffff0000, v214
	v_lshlrev_b32_e32 v155, 16, v215
	v_and_b32_e32 v215, 0xffff0000, v215
	v_add_f32_e32 v80, v80, v198
	v_add_f32_e32 v81, v81, v214
	v_add_f32_e32 v82, v82, v155
	v_add_f32_e32 v83, v83, v215
	v_cvt_pk_bf16_f32 v214, v80, v81
	v_cvt_pk_bf16_f32 v215, v82, v83
	global_store_dwordx2 v192, v[214:215], s[58:59] offset:288
	v_fmac_f32_e32 v92, v80, v80
	v_fmac_f32_e32 v92, v81, v81
	v_fmac_f32_e32 v92, v82, v82
	v_fmac_f32_e32 v92, v83, v83
	s_waitcnt vmcnt(28)
	v_add_u32_e32 v124, 0x30000, v196
	v_lshlrev_b32_e32 v198, 16, v216
	v_and_b32_e32 v216, 0xffff0000, v216
	v_lshlrev_b32_e32 v155, 16, v217
	v_and_b32_e32 v217, 0xffff0000, v217
	v_add_f32_e32 v76, v76, v198
	v_add_f32_e32 v77, v77, v216
	v_add_f32_e32 v78, v78, v155
	v_add_f32_e32 v79, v79, v217
	v_cvt_pk_bf16_f32 v216, v76, v77
	v_cvt_pk_bf16_f32 v217, v78, v79
	global_store_dwordx2 v124, v[216:217], s[58:59] offset:0
	v_mul_f32_e32 v198, v77, v77
	v_fmac_f32_e32 v198, v76, v76
	v_fmac_f32_e32 v198, v78, v78
	v_fmac_f32_e32 v198, v79, v79
	v_mov_b32_e32 v76, v198
	v_lshlrev_b32_e32 v198, 16, v218
	v_and_b32_e32 v218, 0xffff0000, v218
	v_lshlrev_b32_e32 v155, 16, v219
	v_and_b32_e32 v219, 0xffff0000, v219
	v_add_f32_e32 v72, v72, v198
	v_add_f32_e32 v73, v73, v218
	v_add_f32_e32 v74, v74, v155
	v_add_f32_e32 v75, v75, v219
	v_cvt_pk_bf16_f32 v218, v72, v73
	v_cvt_pk_bf16_f32 v219, v74, v75
	global_store_dwordx2 v124, v[218:219], s[58:59] offset:32
	v_fmac_f32_e32 v76, v72, v72
	v_fmac_f32_e32 v76, v73, v73
	v_fmac_f32_e32 v76, v74, v74
	v_fmac_f32_e32 v76, v75, v75
	v_lshlrev_b32_e32 v198, 16, v220
	v_and_b32_e32 v220, 0xffff0000, v220
	v_lshlrev_b32_e32 v155, 16, v221
	v_and_b32_e32 v221, 0xffff0000, v221
	v_add_f32_e32 v68, v68, v198
	v_add_f32_e32 v69, v69, v220
	v_add_f32_e32 v70, v70, v155
	v_add_f32_e32 v71, v71, v221
	v_cvt_pk_bf16_f32 v220, v68, v69
	v_cvt_pk_bf16_f32 v221, v70, v71
	global_store_dwordx2 v124, v[220:221], s[58:59] offset:256
	v_fmac_f32_e32 v76, v68, v68
	v_fmac_f32_e32 v76, v69, v69
	v_fmac_f32_e32 v76, v70, v70
	v_fmac_f32_e32 v76, v71, v71
	v_lshlrev_b32_e32 v198, 16, v222
	v_and_b32_e32 v222, 0xffff0000, v222
	v_lshlrev_b32_e32 v155, 16, v223
	v_and_b32_e32 v223, 0xffff0000, v223
	v_add_f32_e32 v64, v64, v198
	v_add_f32_e32 v65, v65, v222
	v_add_f32_e32 v66, v66, v155
	v_add_f32_e32 v67, v67, v223
	v_cvt_pk_bf16_f32 v222, v64, v65
	v_cvt_pk_bf16_f32 v223, v66, v67
	global_store_dwordx2 v124, v[222:223], s[58:59] offset:288
	v_fmac_f32_e32 v76, v64, v64
	v_fmac_f32_e32 v76, v65, v65
	v_fmac_f32_e32 v76, v66, v66
	v_fmac_f32_e32 v76, v67, v67
	s_waitcnt vmcnt(28)
	v_add_u32_e32 v192, 0x80000, v196
	v_lshlrev_b32_e32 v198, 16, v224
	v_and_b32_e32 v224, 0xffff0000, v224
	v_lshlrev_b32_e32 v155, 16, v225
	v_and_b32_e32 v225, 0xffff0000, v225
	v_add_f32_e32 v60, v60, v198
	v_add_f32_e32 v61, v61, v224
	v_add_f32_e32 v62, v62, v155
	v_add_f32_e32 v63, v63, v225
	v_cvt_pk_bf16_f32 v224, v60, v61
	v_cvt_pk_bf16_f32 v225, v62, v63
	global_store_dwordx2 v192, v[224:225], s[58:59] offset:0
	v_mul_f32_e32 v198, v61, v61
	v_fmac_f32_e32 v198, v60, v60
	v_fmac_f32_e32 v198, v62, v62
	v_fmac_f32_e32 v198, v63, v63
	v_mov_b32_e32 v60, v198
	v_lshlrev_b32_e32 v198, 16, v226
	v_and_b32_e32 v226, 0xffff0000, v226
	v_lshlrev_b32_e32 v155, 16, v227
	v_and_b32_e32 v227, 0xffff0000, v227
	v_add_f32_e32 v56, v56, v198
	v_add_f32_e32 v57, v57, v226
	v_add_f32_e32 v58, v58, v155
	v_add_f32_e32 v59, v59, v227
	v_cvt_pk_bf16_f32 v226, v56, v57
	v_cvt_pk_bf16_f32 v227, v58, v59
	global_store_dwordx2 v192, v[226:227], s[58:59] offset:32
	v_fmac_f32_e32 v60, v56, v56
	v_fmac_f32_e32 v60, v57, v57
	v_fmac_f32_e32 v60, v58, v58
	v_fmac_f32_e32 v60, v59, v59
	v_lshlrev_b32_e32 v198, 16, v228
	v_and_b32_e32 v228, 0xffff0000, v228
	v_lshlrev_b32_e32 v155, 16, v229
	v_and_b32_e32 v229, 0xffff0000, v229
	v_add_f32_e32 v52, v52, v198
	v_add_f32_e32 v53, v53, v228
	v_add_f32_e32 v54, v54, v155
	v_add_f32_e32 v55, v55, v229
	v_cvt_pk_bf16_f32 v228, v52, v53
	v_cvt_pk_bf16_f32 v229, v54, v55
	global_store_dwordx2 v192, v[228:229], s[58:59] offset:256
	v_fmac_f32_e32 v60, v52, v52
	v_fmac_f32_e32 v60, v53, v53
	v_fmac_f32_e32 v60, v54, v54
	v_fmac_f32_e32 v60, v55, v55
	v_lshlrev_b32_e32 v198, 16, v230
	v_and_b32_e32 v230, 0xffff0000, v230
	v_lshlrev_b32_e32 v155, 16, v231
	v_and_b32_e32 v231, 0xffff0000, v231
	v_add_f32_e32 v48, v48, v198
	v_add_f32_e32 v49, v49, v230
	v_add_f32_e32 v50, v50, v155
	v_add_f32_e32 v51, v51, v231
	v_cvt_pk_bf16_f32 v230, v48, v49
	v_cvt_pk_bf16_f32 v231, v50, v51
	global_store_dwordx2 v192, v[230:231], s[58:59] offset:288
	v_fmac_f32_e32 v60, v48, v48
	v_fmac_f32_e32 v60, v49, v49
	v_fmac_f32_e32 v60, v50, v50
	v_fmac_f32_e32 v60, v51, v51
	s_waitcnt vmcnt(28)
	v_add_u32_e32 v124, 0x90000, v196
	v_lshlrev_b32_e32 v198, 16, v232
	v_and_b32_e32 v232, 0xffff0000, v232
	v_lshlrev_b32_e32 v155, 16, v233
	v_and_b32_e32 v233, 0xffff0000, v233
	v_add_f32_e32 v44, v44, v198
	v_add_f32_e32 v45, v45, v232
	v_add_f32_e32 v46, v46, v155
	v_add_f32_e32 v47, v47, v233
	v_cvt_pk_bf16_f32 v232, v44, v45
	v_cvt_pk_bf16_f32 v233, v46, v47
	global_store_dwordx2 v124, v[232:233], s[58:59] offset:0
	v_mul_f32_e32 v198, v45, v45
	v_fmac_f32_e32 v198, v44, v44
	v_fmac_f32_e32 v198, v46, v46
	v_fmac_f32_e32 v198, v47, v47
	v_mov_b32_e32 v44, v198
	v_lshlrev_b32_e32 v198, 16, v234
	v_and_b32_e32 v234, 0xffff0000, v234
	v_lshlrev_b32_e32 v155, 16, v235
	v_and_b32_e32 v235, 0xffff0000, v235
	v_add_f32_e32 v40, v40, v198
	v_add_f32_e32 v41, v41, v234
	v_add_f32_e32 v42, v42, v155
	v_add_f32_e32 v43, v43, v235
	v_cvt_pk_bf16_f32 v234, v40, v41
	v_cvt_pk_bf16_f32 v235, v42, v43
	global_store_dwordx2 v124, v[234:235], s[58:59] offset:32
	v_fmac_f32_e32 v44, v40, v40
	v_fmac_f32_e32 v44, v41, v41
	v_fmac_f32_e32 v44, v42, v42
	v_fmac_f32_e32 v44, v43, v43
	v_lshlrev_b32_e32 v198, 16, v236
	v_and_b32_e32 v236, 0xffff0000, v236
	v_lshlrev_b32_e32 v155, 16, v237
	v_and_b32_e32 v237, 0xffff0000, v237
	v_add_f32_e32 v36, v36, v198
	v_add_f32_e32 v37, v37, v236
	v_add_f32_e32 v38, v38, v155
	v_add_f32_e32 v39, v39, v237
	v_cvt_pk_bf16_f32 v236, v36, v37
	v_cvt_pk_bf16_f32 v237, v38, v39
	global_store_dwordx2 v124, v[236:237], s[58:59] offset:256
	v_fmac_f32_e32 v44, v36, v36
	v_fmac_f32_e32 v44, v37, v37
	v_fmac_f32_e32 v44, v38, v38
	v_fmac_f32_e32 v44, v39, v39
	v_lshlrev_b32_e32 v198, 16, v238
	v_and_b32_e32 v238, 0xffff0000, v238
	v_lshlrev_b32_e32 v155, 16, v239
	v_and_b32_e32 v239, 0xffff0000, v239
	v_add_f32_e32 v32, v32, v198
	v_add_f32_e32 v33, v33, v238
	v_add_f32_e32 v34, v34, v155
	v_add_f32_e32 v35, v35, v239
	v_cvt_pk_bf16_f32 v238, v32, v33
	v_cvt_pk_bf16_f32 v239, v34, v35
	global_store_dwordx2 v124, v[238:239], s[58:59] offset:288
	v_fmac_f32_e32 v44, v32, v32
	v_fmac_f32_e32 v44, v33, v33
	v_fmac_f32_e32 v44, v34, v34
	v_fmac_f32_e32 v44, v35, v35
	s_waitcnt vmcnt(28)
	v_add_u32_e32 v192, 0xa0000, v196
	v_lshlrev_b32_e32 v198, 16, v240
	v_and_b32_e32 v240, 0xffff0000, v240
	v_lshlrev_b32_e32 v155, 16, v241
	v_and_b32_e32 v241, 0xffff0000, v241
	v_add_f32_e32 v28, v28, v198
	v_add_f32_e32 v29, v29, v240
	v_add_f32_e32 v30, v30, v155
	v_add_f32_e32 v31, v31, v241
	v_cvt_pk_bf16_f32 v240, v28, v29
	v_cvt_pk_bf16_f32 v241, v30, v31
	global_store_dwordx2 v192, v[240:241], s[58:59] offset:0
	v_mul_f32_e32 v198, v29, v29
	v_fmac_f32_e32 v198, v28, v28
	v_fmac_f32_e32 v198, v30, v30
	v_fmac_f32_e32 v198, v31, v31
	v_mov_b32_e32 v28, v198
	v_lshlrev_b32_e32 v198, 16, v242
	v_and_b32_e32 v242, 0xffff0000, v242
	v_lshlrev_b32_e32 v155, 16, v243
	v_and_b32_e32 v243, 0xffff0000, v243
	v_add_f32_e32 v24, v24, v198
	v_add_f32_e32 v25, v25, v242
	v_add_f32_e32 v26, v26, v155
	v_add_f32_e32 v27, v27, v243
	v_cvt_pk_bf16_f32 v242, v24, v25
	v_cvt_pk_bf16_f32 v243, v26, v27
	global_store_dwordx2 v192, v[242:243], s[58:59] offset:32
	v_fmac_f32_e32 v28, v24, v24
	v_fmac_f32_e32 v28, v25, v25
	v_fmac_f32_e32 v28, v26, v26
	v_fmac_f32_e32 v28, v27, v27
	v_lshlrev_b32_e32 v198, 16, v244
	v_and_b32_e32 v244, 0xffff0000, v244
	v_lshlrev_b32_e32 v155, 16, v245
	v_and_b32_e32 v245, 0xffff0000, v245
	v_add_f32_e32 v20, v20, v198
	v_add_f32_e32 v21, v21, v244
	v_add_f32_e32 v22, v22, v155
	v_add_f32_e32 v23, v23, v245
	v_cvt_pk_bf16_f32 v244, v20, v21
	v_cvt_pk_bf16_f32 v245, v22, v23
	global_store_dwordx2 v192, v[244:245], s[58:59] offset:256
	v_fmac_f32_e32 v28, v20, v20
	v_fmac_f32_e32 v28, v21, v21
	v_fmac_f32_e32 v28, v22, v22
	v_fmac_f32_e32 v28, v23, v23
	v_lshlrev_b32_e32 v198, 16, v246
	v_and_b32_e32 v246, 0xffff0000, v246
	v_lshlrev_b32_e32 v155, 16, v247
	v_and_b32_e32 v247, 0xffff0000, v247
	v_add_f32_e32 v16, v16, v198
	v_add_f32_e32 v17, v17, v246
	v_add_f32_e32 v18, v18, v155
	v_add_f32_e32 v19, v19, v247
	v_cvt_pk_bf16_f32 v246, v16, v17
	v_cvt_pk_bf16_f32 v247, v18, v19
	global_store_dwordx2 v192, v[246:247], s[58:59] offset:288
	v_fmac_f32_e32 v28, v16, v16
	v_fmac_f32_e32 v28, v17, v17
	v_fmac_f32_e32 v28, v18, v18
	v_fmac_f32_e32 v28, v19, v19
	s_waitcnt vmcnt(28)
	v_add_u32_e32 v124, 0xb0000, v196
	v_lshlrev_b32_e32 v198, 16, v248
	v_and_b32_e32 v248, 0xffff0000, v248
	v_lshlrev_b32_e32 v155, 16, v249
	v_and_b32_e32 v249, 0xffff0000, v249
	v_add_f32_e32 v12, v12, v198
	v_add_f32_e32 v13, v13, v248
	v_add_f32_e32 v14, v14, v155
	v_add_f32_e32 v15, v15, v249
	v_cvt_pk_bf16_f32 v248, v12, v13
	v_cvt_pk_bf16_f32 v249, v14, v15
	global_store_dwordx2 v124, v[248:249], s[58:59] offset:0
	v_mul_f32_e32 v198, v13, v13
	v_fmac_f32_e32 v198, v12, v12
	v_fmac_f32_e32 v198, v14, v14
	v_fmac_f32_e32 v198, v15, v15
	v_mov_b32_e32 v12, v198
	v_lshlrev_b32_e32 v198, 16, v190
	v_and_b32_e32 v190, 0xffff0000, v190
	v_lshlrev_b32_e32 v155, 16, v191
	v_and_b32_e32 v191, 0xffff0000, v191
	v_add_f32_e32 v8, v8, v198
	v_add_f32_e32 v9, v9, v190
	v_add_f32_e32 v10, v10, v155
	v_add_f32_e32 v11, v11, v191
	v_cvt_pk_bf16_f32 v190, v8, v9
	v_cvt_pk_bf16_f32 v191, v10, v11
	global_store_dwordx2 v124, v[190:191], s[58:59] offset:32
	v_fmac_f32_e32 v12, v8, v8
	v_fmac_f32_e32 v12, v9, v9
	v_fmac_f32_e32 v12, v10, v10
	v_fmac_f32_e32 v12, v11, v11
	v_lshlrev_b32_e32 v198, 16, v194
	v_and_b32_e32 v194, 0xffff0000, v194
	v_lshlrev_b32_e32 v155, 16, v195
	v_and_b32_e32 v195, 0xffff0000, v195
	v_add_f32_e32 v4, v4, v198
	v_add_f32_e32 v5, v5, v194
	v_add_f32_e32 v6, v6, v155
	v_add_f32_e32 v7, v7, v195
	v_cvt_pk_bf16_f32 v194, v4, v5
	v_cvt_pk_bf16_f32 v195, v6, v7
	global_store_dwordx2 v124, v[194:195], s[58:59] offset:256
	v_fmac_f32_e32 v12, v4, v4
	v_fmac_f32_e32 v12, v5, v5
	v_fmac_f32_e32 v12, v6, v6
	v_fmac_f32_e32 v12, v7, v7
	v_lshlrev_b32_e32 v198, 16, v146
	v_and_b32_e32 v146, 0xffff0000, v146
	v_lshlrev_b32_e32 v155, 16, v147
	v_and_b32_e32 v147, 0xffff0000, v147
	v_add_f32_e32 v0, v0, v198
	v_add_f32_e32 v1, v1, v146
	v_add_f32_e32 v2, v2, v155
	v_add_f32_e32 v3, v3, v147
	v_cvt_pk_bf16_f32 v146, v0, v1
	v_cvt_pk_bf16_f32 v147, v2, v3
	global_store_dwordx2 v124, v[146:147], s[58:59] offset:288
	v_fmac_f32_e32 v12, v0, v0
	v_fmac_f32_e32 v12, v1, v1
	v_fmac_f32_e32 v12, v2, v2
	v_fmac_f32_e32 v12, v3, v3
	ds_bpermute_b32 v100, v207, v172
	ds_bpermute_b32 v101, v207, v156
	ds_bpermute_b32 v102, v207, v92
	ds_bpermute_b32 v103, v207, v76
	ds_bpermute_b32 v104, v207, v60
	ds_bpermute_b32 v105, v207, v44
	ds_bpermute_b32 v106, v207, v28
	ds_bpermute_b32 v107, v207, v12
	s_waitcnt lgkmcnt(0)
	v_add_f32_e32 v172, v172, v100
	v_add_f32_e32 v156, v156, v101
	v_add_f32_e32 v92, v92, v102
	v_add_f32_e32 v76, v76, v103
	v_add_f32_e32 v60, v60, v104
	v_add_f32_e32 v44, v44, v105
	v_add_f32_e32 v28, v28, v106
	v_add_f32_e32 v12, v12, v107
	ds_bpermute_b32 v100, v206, v172
	ds_bpermute_b32 v101, v206, v156
	ds_bpermute_b32 v102, v206, v92
	ds_bpermute_b32 v103, v206, v76
	ds_bpermute_b32 v104, v206, v60
	ds_bpermute_b32 v105, v206, v44
	ds_bpermute_b32 v106, v206, v28
	ds_bpermute_b32 v107, v206, v12
	s_waitcnt lgkmcnt(0)
	v_add_f32_e32 v172, v172, v100
	v_add_f32_e32 v156, v156, v101
	v_add_f32_e32 v92, v92, v102
	v_add_f32_e32 v76, v76, v103
	v_add_f32_e32 v60, v60, v104
	v_add_f32_e32 v44, v44, v105
	v_add_f32_e32 v28, v28, v106
	v_add_f32_e32 v12, v12, v107
	s_and_saveexec_b64 s[2:3], s[40:41]
	v_mov_b32_e32 v192, v188
	global_store_dword v192, v172, s[16:17]
	v_add_u32_e32 v124, 0x800, v188
	global_store_dword v124, v156, s[16:17]
	v_add_u32_e32 v192, 0x1000, v188
	global_store_dword v192, v92, s[16:17]
	v_add_u32_e32 v124, 0x1800, v188
	global_store_dword v124, v76, s[16:17]
	v_add_u32_e32 v192, 0x4000, v188
	global_store_dword v192, v60, s[16:17]
	v_add_u32_e32 v124, 0x4800, v188
	global_store_dword v124, v44, s[16:17]
	v_add_u32_e32 v192, 0x5000, v188
	global_store_dword v192, v28, s[16:17]
	v_add_u32_e32 v124, 0x5800, v188
	global_store_dword v124, v12, s[16:17]
	s_or_b64 exec, exec, s[2:3]
	s_branch .LBB0_513

.LBB0_563:
	ds_read_b128 v[96:99], v213
	ds_read_b128 v[100:103], v213 offset:1024
	ds_read_b128 v[104:107], v213 offset:2048
	ds_read_b128 v[108:111], v213 offset:3072
	s_add_u32 s1, s74, 0xfff80080
	s_addc_u32 s2, s75, -1
	s_cmp_eq_u32 s88, 28
	s_cselect_b32 s77, s71, s2
	s_cselect_b32 s76, s30, s1
	s_cselect_b32 s73, s31, vcc_hi
	s_cselect_b32 s72, s69, vcc_lo
	s_mov_b32 m0, s81
	v_lshl_add_u64 v[190:191], s[74:75], 0, v[184:185]
	ds_read_b128 v[112:115], v211
	ds_read_b128 v[116:119], v211 offset:1024
	ds_read_b128 v[120:123], v211 offset:2048
	ds_read_b128 v[124:127], v211 offset:3072
	ds_read_b128 v[132:135], v211 offset:4096
	ds_read_b128 v[136:139], v211 offset:5120
	ds_read_b128 v[140:143], v211 offset:6144
	ds_read_b128 v[144:147], v211 offset:7168
	global_load_lds_dwordx4 v[190:191], off
	v_lshl_add_u64 v[190:191], s[74:75], 0, v[186:187]
	s_mov_b32 m0, s93
	s_nop 0
	global_load_lds_dwordx4 v[190:191], off
	s_waitcnt lgkmcnt(8)
	s_barrier
	s_waitcnt lgkmcnt(0)
	s_setprio 1
	s_waitcnt lgkmcnt(0)
	v_mfma_f32_16x16x32_bf16 v[172:175], v[96:99], v[112:115], v[172:175]
	v_mfma_f32_16x16x32_bf16 v[168:171], v[104:107], v[112:115], v[168:171]
	v_mfma_f32_16x16x32_bf16 v[156:159], v[96:99], v[120:123], v[156:159]
	v_mfma_f32_16x16x32_bf16 v[152:155], v[104:107], v[120:123], v[152:155]
	v_mfma_f32_16x16x32_bf16 v[92:95], v[96:99], v[132:135], v[92:95]
	v_mfma_f32_16x16x32_bf16 v[88:91], v[104:107], v[132:135], v[88:91]
	v_mfma_f32_16x16x32_bf16 v[76:79], v[96:99], v[140:143], v[76:79]
	v_mfma_f32_16x16x32_bf16 v[72:75], v[104:107], v[140:143], v[72:75]
	v_mfma_f32_16x16x32_bf16 v[172:175], v[100:103], v[116:119], v[172:175]
	v_mfma_f32_16x16x32_bf16 v[168:171], v[108:111], v[116:119], v[168:171]
	v_mfma_f32_16x16x32_bf16 v[156:159], v[100:103], v[124:127], v[156:159]
	v_mfma_f32_16x16x32_bf16 v[152:155], v[108:111], v[124:127], v[152:155]
	v_mfma_f32_16x16x32_bf16 v[92:95], v[100:103], v[136:139], v[92:95]
	v_mfma_f32_16x16x32_bf16 v[88:91], v[108:111], v[136:139], v[88:91]
	v_mfma_f32_16x16x32_bf16 v[76:79], v[100:103], v[144:147], v[76:79]
	v_mfma_f32_16x16x32_bf16 v[72:75], v[108:111], v[144:147], v[72:75]
	s_setprio 0
	s_barrier
	s_mov_b32 m0, s94
	v_lshl_add_u64 v[190:191], s[72:73], 0, v[176:177]
	ds_read_b128 v[200:203], v214
	ds_read_b128 v[218:221], v214 offset:1024
	ds_read_b128 v[222:225], v214 offset:2048
	ds_read_b128 v[226:229], v214 offset:3072
	global_load_lds_dwordx4 v[190:191], off
	v_lshl_add_u64 v[194:195], s[72:73], 0, v[182:183]
	s_mov_b32 m0, s95
	s_nop 0
	global_load_lds_dwordx4 v[194:195], off
	s_barrier
	s_waitcnt lgkmcnt(0)
	s_setprio 1
	s_waitcnt lgkmcnt(0)
	v_mfma_f32_16x16x32_bf16 v[164:167], v[200:203], v[112:115], v[164:167]
	v_mfma_f32_16x16x32_bf16 v[112:115], v[222:225], v[112:115], v[160:163]
	v_mfma_f32_16x16x32_bf16 v[84:87], v[200:203], v[132:135], v[84:87]
	v_mfma_f32_16x16x32_bf16 v[80:83], v[222:225], v[132:135], v[80:83]
	v_mfma_f32_16x16x32_bf16 v[68:71], v[200:203], v[140:143], v[68:71]
	v_mfma_f32_16x16x32_bf16 v[64:67], v[222:225], v[140:143], v[64:67]
	v_mfma_f32_16x16x32_bf16 v[164:167], v[218:221], v[116:119], v[164:167]
	v_mfma_f32_16x16x32_bf16 v[112:115], v[226:229], v[116:119], v[112:115]
	v_mfma_f32_16x16x32_bf16 v[116:119], v[200:203], v[120:123], v[148:151]
	v_mfma_f32_16x16x32_bf16 v[120:123], v[222:225], v[120:123], v[128:131]
	v_mfma_f32_16x16x32_bf16 v[84:87], v[218:221], v[136:139], v[84:87]
	v_mfma_f32_16x16x32_bf16 v[80:83], v[226:229], v[136:139], v[80:83]
	v_mfma_f32_16x16x32_bf16 v[68:71], v[218:221], v[144:147], v[68:71]
	v_mfma_f32_16x16x32_bf16 v[64:67], v[226:229], v[144:147], v[64:67]
	v_mfma_f32_16x16x32_bf16 v[116:119], v[218:221], v[124:127], v[116:119]
	v_mfma_f32_16x16x32_bf16 v[120:123], v[226:229], v[124:127], v[120:123]
	s_setprio 0
	s_mov_b32 m0, s92
	v_lshl_add_u64 v[204:205], s[76:77], 0, v[176:177]
	s_barrier
	ds_read_b128 v[124:127], v211 offset:16384
	ds_read_b128 v[128:131], v211 offset:17408
	ds_read_b128 v[132:135], v211 offset:18432
	ds_read_b128 v[136:139], v211 offset:19456
	ds_read_b128 v[140:143], v211 offset:20480
	ds_read_b128 v[144:147], v211 offset:21504
	ds_read_b128 v[148:151], v211 offset:22528
	ds_read_b128 v[160:163], v211 offset:23552
	global_load_lds_dwordx4 v[204:205], off
	v_lshl_add_u64 v[238:239], s[76:77], 0, v[182:183]
	s_mov_b32 m0, s82
	s_nop 0
	global_load_lds_dwordx4 v[238:239], off
	s_barrier
	s_waitcnt lgkmcnt(0)
	s_setprio 1
	s_waitcnt lgkmcnt(0)
	v_mfma_f32_16x16x32_bf16 v[60:63], v[96:99], v[124:127], v[60:63]
	v_mfma_f32_16x16x32_bf16 v[56:59], v[104:107], v[124:127], v[56:59]
	v_mfma_f32_16x16x32_bf16 v[44:47], v[96:99], v[132:135], v[44:47]
	v_mfma_f32_16x16x32_bf16 v[40:43], v[104:107], v[132:135], v[40:43]
	v_mfma_f32_16x16x32_bf16 v[28:31], v[96:99], v[140:143], v[28:31]
	v_mfma_f32_16x16x32_bf16 v[24:27], v[104:107], v[140:143], v[24:27]
	v_mfma_f32_16x16x32_bf16 v[12:15], v[96:99], v[148:151], v[12:15]
	v_mfma_f32_16x16x32_bf16 v[8:11], v[104:107], v[148:151], v[8:11]
	v_mfma_f32_16x16x32_bf16 v[60:63], v[100:103], v[128:131], v[60:63]
	v_mfma_f32_16x16x32_bf16 v[56:59], v[108:111], v[128:131], v[56:59]
	v_mfma_f32_16x16x32_bf16 v[44:47], v[100:103], v[136:139], v[44:47]
	v_mfma_f32_16x16x32_bf16 v[40:43], v[108:111], v[136:139], v[40:43]
	v_mfma_f32_16x16x32_bf16 v[28:31], v[100:103], v[144:147], v[28:31]
	v_mfma_f32_16x16x32_bf16 v[24:27], v[108:111], v[144:147], v[24:27]
	v_mfma_f32_16x16x32_bf16 v[12:15], v[100:103], v[160:163], v[12:15]
	v_mfma_f32_16x16x32_bf16 v[8:11], v[108:111], v[160:163], v[8:11]
	s_setprio 0
	s_barrier
	s_add_u32 s2, s72, 0x80000
	s_addc_u32 s3, s73, 0
	s_mov_b32 m0, s96
	v_lshl_add_u64 v[96:97], s[2:3], 0, v[176:177]
	global_load_lds_dwordx4 v[96:97], off
	v_lshl_add_u64 v[96:97], s[2:3], 0, v[182:183]
	s_mov_b32 m0, s97
	s_nop 0
	global_load_lds_dwordx4 v[96:97], off
	s_waitcnt vmcnt(6)
	s_barrier
	s_setprio 1
	v_mfma_f32_16x16x32_bf16 v[52:55], v[200:203], v[124:127], v[52:55]
	v_mfma_f32_16x16x32_bf16 v[48:51], v[222:225], v[124:127], v[48:51]
	v_mfma_f32_16x16x32_bf16 v[36:39], v[200:203], v[132:135], v[36:39]
	v_mfma_f32_16x16x32_bf16 v[32:35], v[222:225], v[132:135], v[32:35]
	v_mfma_f32_16x16x32_bf16 v[20:23], v[200:203], v[140:143], v[20:23]
	v_mfma_f32_16x16x32_bf16 v[16:19], v[222:225], v[140:143], v[16:19]
	v_mfma_f32_16x16x32_bf16 v[4:7], v[200:203], v[148:151], v[4:7]
	v_mfma_f32_16x16x32_bf16 v[0:3], v[222:225], v[148:151], v[0:3]
	v_mfma_f32_16x16x32_bf16 v[52:55], v[218:221], v[128:131], v[52:55]
	v_mfma_f32_16x16x32_bf16 v[48:51], v[226:229], v[128:131], v[48:51]
	v_mfma_f32_16x16x32_bf16 v[36:39], v[218:221], v[136:139], v[36:39]
	v_mfma_f32_16x16x32_bf16 v[32:35], v[226:229], v[136:139], v[32:35]
	v_mfma_f32_16x16x32_bf16 v[20:23], v[218:221], v[144:147], v[20:23]
	v_mfma_f32_16x16x32_bf16 v[16:19], v[226:229], v[144:147], v[16:19]
	v_mfma_f32_16x16x32_bf16 v[4:7], v[218:221], v[160:163], v[4:7]
	v_mfma_f32_16x16x32_bf16 v[0:3], v[226:229], v[160:163], v[0:3]
	s_setprio 0
	s_barrier
	ds_read_b128 v[96:99], v215
	ds_read_b128 v[100:103], v215 offset:1024
	ds_read_b128 v[104:107], v215 offset:2048
	ds_read_b128 v[108:111], v215 offset:3072
	s_add_u32 s2, s76, 0x80000
	s_addc_u32 s3, s77, 0
	s_mov_b32 m0, s83
	v_lshl_add_u64 v[148:149], s[2:3], 0, v[176:177]
	ds_read_b128 v[124:127], v211 offset:32768
	ds_read_b128 v[128:131], v211 offset:33792
	ds_read_b128 v[132:135], v211 offset:34816
	ds_read_b128 v[136:139], v211 offset:35840
	ds_read_b128 v[140:143], v211 offset:36864
	ds_read_b128 v[144:147], v211 offset:37888
	ds_read_b128 v[200:203], v211 offset:38912
	ds_read_b128 v[218:221], v211 offset:39936
	global_load_lds_dwordx4 v[148:149], off
	v_lshl_add_u64 v[148:149], s[2:3], 0, v[182:183]
	s_mov_b32 m0, s86
	s_nop 0
	global_load_lds_dwordx4 v[148:149], off
	s_waitcnt lgkmcnt(8)
	s_barrier
	s_waitcnt lgkmcnt(0)
	s_setprio 1
	s_waitcnt lgkmcnt(0)
	v_mfma_f32_16x16x32_bf16 v[148:151], v[96:99], v[124:127], v[172:175]
	v_mfma_f32_16x16x32_bf16 v[172:175], v[100:103], v[128:131], v[148:151]
	v_mfma_f32_16x16x32_bf16 v[148:151], v[104:107], v[124:127], v[168:171]
	v_mfma_f32_16x16x32_bf16 v[168:171], v[108:111], v[128:131], v[148:151]
	v_mfma_f32_16x16x32_bf16 v[148:151], v[96:99], v[132:135], v[156:159]
	v_mfma_f32_16x16x32_bf16 v[156:159], v[100:103], v[136:139], v[148:151]
	v_mfma_f32_16x16x32_bf16 v[148:151], v[104:107], v[132:135], v[152:155]
	v_mfma_f32_16x16x32_bf16 v[92:95], v[96:99], v[140:143], v[92:95]
	v_mfma_f32_16x16x32_bf16 v[88:91], v[104:107], v[140:143], v[88:91]
	v_mfma_f32_16x16x32_bf16 v[76:79], v[96:99], v[200:203], v[76:79]
	v_mfma_f32_16x16x32_bf16 v[72:75], v[104:107], v[200:203], v[72:75]
	v_mfma_f32_16x16x32_bf16 v[152:155], v[108:111], v[136:139], v[148:151]
	v_mfma_f32_16x16x32_bf16 v[92:95], v[100:103], v[144:147], v[92:95]
	v_mfma_f32_16x16x32_bf16 v[88:91], v[108:111], v[144:147], v[88:91]
	v_mfma_f32_16x16x32_bf16 v[76:79], v[100:103], v[218:221], v[76:79]
	v_mfma_f32_16x16x32_bf16 v[72:75], v[108:111], v[218:221], v[72:75]
	s_setprio 0
	s_barrier
	s_mov_b32 m0, s60
	v_lshl_add_u64 v[148:149], v[190:191], 0, s[20:21]
	ds_read_b128 v[222:225], v216
	ds_read_b128 v[226:229], v216 offset:1024
	ds_read_b128 v[230:233], v216 offset:2048
	ds_read_b128 v[234:237], v216 offset:3072
	global_load_lds_dwordx4 v[148:149], off
	v_lshl_add_u64 v[148:149], v[194:195], 0, s[20:21]
	s_mov_b32 m0, s61
	s_nop 0
	global_load_lds_dwordx4 v[148:149], off
	s_barrier
	s_waitcnt lgkmcnt(0)
	s_setprio 1
	s_waitcnt lgkmcnt(0)
	v_mfma_f32_16x16x32_bf16 v[112:115], v[230:233], v[124:127], v[112:115]
	v_mfma_f32_16x16x32_bf16 v[148:151], v[222:225], v[124:127], v[164:167]
	v_mfma_f32_16x16x32_bf16 v[160:163], v[234:237], v[128:131], v[112:115]
	v_mfma_f32_16x16x32_bf16 v[112:115], v[222:225], v[132:135], v[116:119]
	v_mfma_f32_16x16x32_bf16 v[164:167], v[226:229], v[128:131], v[148:151]
	v_mfma_f32_16x16x32_bf16 v[148:151], v[226:229], v[136:139], v[112:115]
	v_mfma_f32_16x16x32_bf16 v[112:115], v[230:233], v[132:135], v[120:123]
	v_mfma_f32_16x16x32_bf16 v[84:87], v[222:225], v[140:143], v[84:87]
	v_mfma_f32_16x16x32_bf16 v[80:83], v[230:233], v[140:143], v[80:83]
	v_mfma_f32_16x16x32_bf16 v[68:71], v[222:225], v[200:203], v[68:71]
	v_mfma_f32_16x16x32_bf16 v[64:67], v[230:233], v[200:203], v[64:67]
	v_mfma_f32_16x16x32_bf16 v[128:131], v[234:237], v[136:139], v[112:115]
	v_mfma_f32_16x16x32_bf16 v[84:87], v[226:229], v[144:147], v[84:87]
	v_mfma_f32_16x16x32_bf16 v[80:83], v[234:237], v[144:147], v[80:83]
	v_mfma_f32_16x16x32_bf16 v[68:71], v[226:229], v[218:221], v[68:71]
	v_mfma_f32_16x16x32_bf16 v[64:67], v[234:237], v[218:221], v[64:67]
	s_setprio 0
	s_mov_b32 m0, s89
	v_lshl_add_u64 v[190:191], v[204:205], 0, s[20:21]
	s_barrier
	ds_read_b128 v[112:115], v211 offset:49152
	ds_read_b128 v[116:119], v211 offset:50176
	ds_read_b128 v[120:123], v211 offset:51200
	ds_read_b128 v[124:127], v211 offset:52224
	ds_read_b128 v[132:135], v211 offset:53248
	ds_read_b128 v[136:139], v211 offset:54272
	ds_read_b128 v[140:143], v211 offset:55296
	ds_read_b128 v[144:147], v211 offset:56320
	global_load_lds_dwordx4 v[190:191], off
	v_lshl_add_u64 v[190:191], v[238:239], 0, s[20:21]
	s_mov_b32 m0, s79
	s_nop 0
	global_load_lds_dwordx4 v[190:191], off
	s_barrier
	s_waitcnt lgkmcnt(0)
	s_setprio 1
	s_waitcnt lgkmcnt(0)
	v_mfma_f32_16x16x32_bf16 v[60:63], v[96:99], v[112:115], v[60:63]
	v_mfma_f32_16x16x32_bf16 v[56:59], v[104:107], v[112:115], v[56:59]
	v_mfma_f32_16x16x32_bf16 v[44:47], v[96:99], v[120:123], v[44:47]
	v_mfma_f32_16x16x32_bf16 v[40:43], v[104:107], v[120:123], v[40:43]
	v_mfma_f32_16x16x32_bf16 v[28:31], v[96:99], v[132:135], v[28:31]
	v_mfma_f32_16x16x32_bf16 v[24:27], v[104:107], v[132:135], v[24:27]
	v_mfma_f32_16x16x32_bf16 v[12:15], v[96:99], v[140:143], v[12:15]
	v_mfma_f32_16x16x32_bf16 v[8:11], v[104:107], v[140:143], v[8:11]
	v_mfma_f32_16x16x32_bf16 v[60:63], v[100:103], v[116:119], v[60:63]
	v_mfma_f32_16x16x32_bf16 v[56:59], v[108:111], v[116:119], v[56:59]
	v_mfma_f32_16x16x32_bf16 v[44:47], v[100:103], v[124:127], v[44:47]
	v_mfma_f32_16x16x32_bf16 v[40:43], v[108:111], v[124:127], v[40:43]
	v_mfma_f32_16x16x32_bf16 v[28:31], v[100:103], v[136:139], v[28:31]
	v_mfma_f32_16x16x32_bf16 v[24:27], v[108:111], v[136:139], v[24:27]
	v_mfma_f32_16x16x32_bf16 v[12:15], v[100:103], v[144:147], v[12:15]
	v_mfma_f32_16x16x32_bf16 v[8:11], v[108:111], v[144:147], v[8:11]
	s_setprio 0
	s_barrier
	s_add_u32 s2, s72, 0x80080
	s_addc_u32 s3, s73, 0
	s_mov_b32 m0, s49
	v_lshl_add_u64 v[96:97], s[2:3], 0, v[176:177]
	global_load_lds_dwordx4 v[96:97], off
	v_lshl_add_u64 v[96:97], s[2:3], 0, v[182:183]
	s_mov_b32 m0, s52
	s_nop 0
	global_load_lds_dwordx4 v[96:97], off
	s_waitcnt vmcnt(6)
	s_barrier
	s_setprio 1
	v_mfma_f32_16x16x32_bf16 v[52:55], v[222:225], v[112:115], v[52:55]
	v_mfma_f32_16x16x32_bf16 v[48:51], v[230:233], v[112:115], v[48:51]
	v_mfma_f32_16x16x32_bf16 v[36:39], v[222:225], v[120:123], v[36:39]
	v_mfma_f32_16x16x32_bf16 v[32:35], v[230:233], v[120:123], v[32:35]
	v_mfma_f32_16x16x32_bf16 v[20:23], v[222:225], v[132:135], v[20:23]
	v_mfma_f32_16x16x32_bf16 v[16:19], v[230:233], v[132:135], v[16:19]
	v_mfma_f32_16x16x32_bf16 v[4:7], v[222:225], v[140:143], v[4:7]
	v_mfma_f32_16x16x32_bf16 v[0:3], v[230:233], v[140:143], v[0:3]
	v_mfma_f32_16x16x32_bf16 v[52:55], v[226:229], v[116:119], v[52:55]
	v_mfma_f32_16x16x32_bf16 v[48:51], v[234:237], v[116:119], v[48:51]
	v_mfma_f32_16x16x32_bf16 v[36:39], v[226:229], v[124:127], v[36:39]
	v_mfma_f32_16x16x32_bf16 v[32:35], v[234:237], v[124:127], v[32:35]
	v_mfma_f32_16x16x32_bf16 v[20:23], v[226:229], v[136:139], v[20:23]
	v_mfma_f32_16x16x32_bf16 v[16:19], v[234:237], v[136:139], v[16:19]
	v_mfma_f32_16x16x32_bf16 v[4:7], v[226:229], v[144:147], v[4:7]
	v_mfma_f32_16x16x32_bf16 v[0:3], v[234:237], v[144:147], v[0:3]
	s_setprio 0
	s_add_i32 s88, s88, 2
	s_add_u32 s74, s74, 0x100
	s_addc_u32 s75, s75, 0
	s_add_u32 vcc_lo, vcc_lo, 0x100
	s_addc_u32 vcc_hi, vcc_hi, 0
	s_cmp_lt_u32 s88, 30
	s_barrier
	s_cbranch_scc1 .LBB0_563
	v_readlane_b32 s96, v255, 17
	v_readlane_b32 s94, v255, 19
	v_readlane_b32 s93, v255, 25
	v_readlane_b32 s97, v255, 18
	v_readlane_b32 s95, v255, 20
	s_movk_i32 s14, 0x3fff
	v_add_u32_e32 v213, s53, v209
	v_lshl_or_b32 v252, s91, 8, v212
	v_lshl_add_u32 v198, v213, 11, v252
	v_lshlrev_b32_e32 v196, 2, v198
	v_lshlrev_b32_e32 v198, 1, v198
	s_lshl_b32 s1, s91, 2
	s_or_b32 s1, s1, s87
	s_lshl_b32 s1, s1, 2
	v_lshl_add_u32 v188, v213, 7, s1
	v_mov_b32_e32 v192, v196
	global_load_dwordx4 v[96:99], v192, s[38:39] offset:0
	global_load_dwordx4 v[100:103], v192, s[38:39] offset:64
	global_load_dwordx4 v[104:107], v192, s[38:39] offset:512
	global_load_dwordx4 v[108:111], v192, s[38:39] offset:576
	v_add_u32_e32 v124, 0x20000, v196
	global_load_dwordx4 v[200:203], v124, s[38:39] offset:0
	global_load_dwordx4 v[214:217], v124, s[38:39] offset:64
	global_load_dwordx4 v[218:221], v124, s[38:39] offset:512
	global_load_dwordx4 v[222:225], v124, s[38:39] offset:576
	v_add_u32_e32 v190, 0x40000, v196
	global_load_dwordx4 v[226:229], v190, s[38:39] offset:0
	global_load_dwordx4 v[230:233], v190, s[38:39] offset:64
	global_load_dwordx4 v[234:237], v190, s[38:39] offset:512
	global_load_dwordx4 v[238:241], v190, s[38:39] offset:576
	v_add_u32_e32 v194, 0x60000, v196
	global_load_dwordx4 v[242:245], v194, s[38:39] offset:0
	global_load_dwordx4 v[246:249], v194, s[38:39] offset:64
	s_waitcnt vmcnt(10)
	v_mov_b32_e32 v205, v198
	v_add_f32_e32 v172, v172, v96
	v_add_f32_e32 v173, v173, v97
	v_add_f32_e32 v174, v174, v98
	v_add_f32_e32 v175, v175, v99
	v_cvt_pk_bf16_f32 v96, v172, v173
	v_cvt_pk_bf16_f32 v97, v174, v175
	global_store_dwordx2 v205, v[96:97], s[58:59] offset:0
	v_mul_f32_e32 v146, v173, v173
	v_fmac_f32_e32 v146, v172, v172
	v_fmac_f32_e32 v146, v174, v174
	v_fmac_f32_e32 v146, v175, v175
	v_mov_b32_e32 v172, v146
	v_add_f32_e32 v168, v168, v100
	v_add_f32_e32 v169, v169, v101
	v_add_f32_e32 v170, v170, v102
	v_add_f32_e32 v171, v171, v103
	v_cvt_pk_bf16_f32 v100, v168, v169
	v_cvt_pk_bf16_f32 v101, v170, v171
	global_store_dwordx2 v205, v[100:101], s[58:59] offset:32
	v_fmac_f32_e32 v172, v168, v168
	v_fmac_f32_e32 v172, v169, v169
	v_fmac_f32_e32 v172, v170, v170
	v_fmac_f32_e32 v172, v171, v171
	v_add_f32_e32 v164, v164, v104
	v_add_f32_e32 v165, v165, v105
	v_add_f32_e32 v166, v166, v106
	v_add_f32_e32 v167, v167, v107
	v_cvt_pk_bf16_f32 v104, v164, v165
	v_cvt_pk_bf16_f32 v105, v166, v167
	global_store_dwordx2 v205, v[104:105], s[58:59] offset:256
	v_fmac_f32_e32 v172, v164, v164
	v_fmac_f32_e32 v172, v165, v165
	v_fmac_f32_e32 v172, v166, v166
	v_fmac_f32_e32 v172, v167, v167
	v_add_f32_e32 v160, v160, v108
	v_add_f32_e32 v161, v161, v109
	v_add_f32_e32 v162, v162, v110
	v_add_f32_e32 v163, v163, v111
	v_cvt_pk_bf16_f32 v108, v160, v161
	v_cvt_pk_bf16_f32 v109, v162, v163
	global_store_dwordx2 v205, v[108:109], s[58:59] offset:288
	v_fmac_f32_e32 v172, v160, v160
	v_fmac_f32_e32 v172, v161, v161
	v_fmac_f32_e32 v172, v162, v162
	v_fmac_f32_e32 v172, v163, v163
	global_load_dwordx4 v[96:99], v194, s[38:39] offset:512
	global_load_dwordx4 v[100:103], v194, s[38:39] offset:576
	v_add_u32_e32 v192, 0x100000, v196
	global_load_dwordx4 v[168:171], v192, s[38:39] offset:0
	global_load_dwordx4 v[104:107], v192, s[38:39] offset:64
	global_load_dwordx4 v[164:167], v192, s[38:39] offset:512
	global_load_dwordx4 v[108:111], v192, s[38:39] offset:576
	v_add_u32_e32 v124, 0x120000, v196
	global_load_dwordx4 v[160:163], v124, s[38:39] offset:0
	s_waitcnt vmcnt(17)
	v_add_u32_e32 v204, 0x10000, v198
	v_add_f32_e32 v156, v156, v200
	v_add_f32_e32 v157, v157, v201
	v_add_f32_e32 v158, v158, v202
	v_add_f32_e32 v159, v159, v203
	v_cvt_pk_bf16_f32 v200, v156, v157
	v_cvt_pk_bf16_f32 v201, v158, v159
	global_store_dwordx2 v204, v[200:201], s[58:59] offset:0
	v_mul_f32_e32 v146, v157, v157
	v_fmac_f32_e32 v146, v156, v156
	v_fmac_f32_e32 v146, v158, v158
	v_fmac_f32_e32 v146, v159, v159
	v_mov_b32_e32 v156, v146
	v_add_f32_e32 v152, v152, v214
	v_add_f32_e32 v153, v153, v215
	v_add_f32_e32 v154, v154, v216
	v_add_f32_e32 v155, v155, v217
	v_cvt_pk_bf16_f32 v214, v152, v153
	v_cvt_pk_bf16_f32 v215, v154, v155
	global_store_dwordx2 v204, v[214:215], s[58:59] offset:32
	v_fmac_f32_e32 v156, v152, v152
	v_fmac_f32_e32 v156, v153, v153
	v_fmac_f32_e32 v156, v154, v154
	v_fmac_f32_e32 v156, v155, v155
	v_add_f32_e32 v148, v148, v218
	v_add_f32_e32 v149, v149, v219
	v_add_f32_e32 v150, v150, v220
	v_add_f32_e32 v151, v151, v221
	v_cvt_pk_bf16_f32 v218, v148, v149
	v_cvt_pk_bf16_f32 v219, v150, v151
	global_store_dwordx2 v204, v[218:219], s[58:59] offset:256
	v_fmac_f32_e32 v156, v148, v148
	v_fmac_f32_e32 v156, v149, v149
	v_fmac_f32_e32 v156, v150, v150
	v_fmac_f32_e32 v156, v151, v151
	v_add_f32_e32 v128, v128, v222
	v_add_f32_e32 v129, v129, v223
	v_add_f32_e32 v130, v130, v224
	v_add_f32_e32 v131, v131, v225
	v_cvt_pk_bf16_f32 v222, v128, v129
	v_cvt_pk_bf16_f32 v223, v130, v131
	global_store_dwordx2 v204, v[222:223], s[58:59] offset:288
	v_fmac_f32_e32 v156, v128, v128
	v_fmac_f32_e32 v156, v129, v129
	v_fmac_f32_e32 v156, v130, v130
	v_fmac_f32_e32 v156, v131, v131
	global_load_dwordx4 v[200:203], v124, s[38:39] offset:64
	global_load_dwordx4 v[214:217], v124, s[38:39] offset:512
	global_load_dwordx4 v[152:155], v124, s[38:39] offset:576
	v_add_u32_e32 v190, 0x140000, v196
	global_load_dwordx4 v[218:221], v190, s[38:39] offset:0
	global_load_dwordx4 v[148:151], v190, s[38:39] offset:64
	global_load_dwordx4 v[222:225], v190, s[38:39] offset:512
	global_load_dwordx4 v[128:131], v190, s[38:39] offset:576
	s_waitcnt vmcnt(24)
	v_add_u32_e32 v205, 0x20000, v198
	v_add_f32_e32 v92, v92, v226
	v_add_f32_e32 v93, v93, v227
	v_add_f32_e32 v94, v94, v228
	v_add_f32_e32 v95, v95, v229
	v_cvt_pk_bf16_f32 v226, v92, v93
	v_cvt_pk_bf16_f32 v227, v94, v95
	global_store_dwordx2 v205, v[226:227], s[58:59] offset:0
	v_mul_f32_e32 v146, v93, v93
	v_fmac_f32_e32 v146, v92, v92
	v_fmac_f32_e32 v146, v94, v94
	v_fmac_f32_e32 v146, v95, v95
	v_mov_b32_e32 v92, v146
	v_add_f32_e32 v88, v88, v230
	v_add_f32_e32 v89, v89, v231
	v_add_f32_e32 v90, v90, v232
	v_add_f32_e32 v91, v91, v233
	v_cvt_pk_bf16_f32 v230, v88, v89
	v_cvt_pk_bf16_f32 v231, v90, v91
	global_store_dwordx2 v205, v[230:231], s[58:59] offset:32
	v_fmac_f32_e32 v92, v88, v88
	v_fmac_f32_e32 v92, v89, v89
	v_fmac_f32_e32 v92, v90, v90
	v_fmac_f32_e32 v92, v91, v91
	v_add_f32_e32 v84, v84, v234
	v_add_f32_e32 v85, v85, v235
	v_add_f32_e32 v86, v86, v236
	v_add_f32_e32 v87, v87, v237
	v_cvt_pk_bf16_f32 v234, v84, v85
	v_cvt_pk_bf16_f32 v235, v86, v87
	global_store_dwordx2 v205, v[234:235], s[58:59] offset:256
	v_fmac_f32_e32 v92, v84, v84
	v_fmac_f32_e32 v92, v85, v85
	v_fmac_f32_e32 v92, v86, v86
	v_fmac_f32_e32 v92, v87, v87
	v_add_f32_e32 v80, v80, v238
	v_add_f32_e32 v81, v81, v239
	v_add_f32_e32 v82, v82, v240
	v_add_f32_e32 v83, v83, v241
	v_cvt_pk_bf16_f32 v238, v80, v81
	v_cvt_pk_bf16_f32 v239, v82, v83
	global_store_dwordx2 v205, v[238:239], s[58:59] offset:288
	v_fmac_f32_e32 v92, v80, v80
	v_fmac_f32_e32 v92, v81, v81
	v_fmac_f32_e32 v92, v82, v82
	v_fmac_f32_e32 v92, v83, v83
	v_add_u32_e32 v194, 0x160000, v196
	global_load_dwordx4 v[226:229], v194, s[38:39] offset:0
	global_load_dwordx4 v[230:233], v194, s[38:39] offset:64
	global_load_dwordx4 v[88:91], v194, s[38:39] offset:512
	global_load_dwordx4 v[234:237], v194, s[38:39] offset:576
	s_waitcnt vmcnt(24)
	v_add_u32_e32 v204, 0x30000, v198
	v_add_f32_e32 v76, v76, v242
	v_add_f32_e32 v77, v77, v243
	v_add_f32_e32 v78, v78, v244
	v_add_f32_e32 v79, v79, v245
	v_cvt_pk_bf16_f32 v242, v76, v77
	v_cvt_pk_bf16_f32 v243, v78, v79
	global_store_dwordx2 v204, v[242:243], s[58:59] offset:0
	v_mul_f32_e32 v146, v77, v77
	v_fmac_f32_e32 v146, v76, v76
	v_fmac_f32_e32 v146, v78, v78
	v_fmac_f32_e32 v146, v79, v79
	v_mov_b32_e32 v76, v146
	v_add_f32_e32 v72, v72, v246
	v_add_f32_e32 v73, v73, v247
	v_add_f32_e32 v74, v74, v248
	v_add_f32_e32 v75, v75, v249
	v_cvt_pk_bf16_f32 v246, v72, v73
	v_cvt_pk_bf16_f32 v247, v74, v75
	global_store_dwordx2 v204, v[246:247], s[58:59] offset:32
	v_fmac_f32_e32 v76, v72, v72
	v_fmac_f32_e32 v76, v73, v73
	v_fmac_f32_e32 v76, v74, v74
	v_fmac_f32_e32 v76, v75, v75
	v_add_f32_e32 v68, v68, v96
	v_add_f32_e32 v69, v69, v97
	v_add_f32_e32 v70, v70, v98
	v_add_f32_e32 v71, v71, v99
	v_cvt_pk_bf16_f32 v96, v68, v69
	v_cvt_pk_bf16_f32 v97, v70, v71
	global_store_dwordx2 v204, v[96:97], s[58:59] offset:256
	v_fmac_f32_e32 v76, v68, v68
	v_fmac_f32_e32 v76, v69, v69
	v_fmac_f32_e32 v76, v70, v70
	v_fmac_f32_e32 v76, v71, v71
	v_add_f32_e32 v64, v64, v100
	v_add_f32_e32 v65, v65, v101
	v_add_f32_e32 v66, v66, v102
	v_add_f32_e32 v67, v67, v103
	v_cvt_pk_bf16_f32 v100, v64, v65
	v_cvt_pk_bf16_f32 v101, v66, v67
	global_store_dwordx2 v204, v[100:101], s[58:59] offset:288
	v_fmac_f32_e32 v76, v64, v64
	v_fmac_f32_e32 v76, v65, v65
	v_fmac_f32_e32 v76, v66, v66
	v_fmac_f32_e32 v76, v67, v67
	s_waitcnt vmcnt(24)
	v_add_u32_e32 v205, 0x80000, v198
	v_add_f32_e32 v60, v60, v168
	v_add_f32_e32 v61, v61, v169
	v_add_f32_e32 v62, v62, v170
	v_add_f32_e32 v63, v63, v171
	v_cvt_pk_bf16_f32 v168, v60, v61
	v_cvt_pk_bf16_f32 v169, v62, v63
	global_store_dwordx2 v205, v[168:169], s[58:59] offset:0
	v_mul_f32_e32 v146, v61, v61
	v_fmac_f32_e32 v146, v60, v60
	v_fmac_f32_e32 v146, v62, v62
	v_fmac_f32_e32 v146, v63, v63
	v_mov_b32_e32 v60, v146
	v_add_f32_e32 v56, v56, v104
	v_add_f32_e32 v57, v57, v105
	v_add_f32_e32 v58, v58, v106
	v_add_f32_e32 v59, v59, v107
	v_cvt_pk_bf16_f32 v104, v56, v57
	v_cvt_pk_bf16_f32 v105, v58, v59
	global_store_dwordx2 v205, v[104:105], s[58:59] offset:32
	v_fmac_f32_e32 v60, v56, v56
	v_fmac_f32_e32 v60, v57, v57
	v_fmac_f32_e32 v60, v58, v58
	v_fmac_f32_e32 v60, v59, v59
	v_add_f32_e32 v52, v52, v164
	v_add_f32_e32 v53, v53, v165
	v_add_f32_e32 v54, v54, v166
	v_add_f32_e32 v55, v55, v167
	v_cvt_pk_bf16_f32 v164, v52, v53
	v_cvt_pk_bf16_f32 v165, v54, v55
	global_store_dwordx2 v205, v[164:165], s[58:59] offset:256
	v_fmac_f32_e32 v60, v52, v52
	v_fmac_f32_e32 v60, v53, v53
	v_fmac_f32_e32 v60, v54, v54
	v_fmac_f32_e32 v60, v55, v55
	v_add_f32_e32 v48, v48, v108
	v_add_f32_e32 v49, v49, v109
	v_add_f32_e32 v50, v50, v110
	v_add_f32_e32 v51, v51, v111
	v_cvt_pk_bf16_f32 v108, v48, v49
	v_cvt_pk_bf16_f32 v109, v50, v51
	global_store_dwordx2 v205, v[108:109], s[58:59] offset:288
	v_fmac_f32_e32 v60, v48, v48
	v_fmac_f32_e32 v60, v49, v49
	v_fmac_f32_e32 v60, v50, v50
	v_fmac_f32_e32 v60, v51, v51
	s_waitcnt vmcnt(20)
	v_add_u32_e32 v204, 0x90000, v198
	v_add_f32_e32 v44, v44, v160
	v_add_f32_e32 v45, v45, v161
	v_add_f32_e32 v46, v46, v162
	v_add_f32_e32 v47, v47, v163
	v_cvt_pk_bf16_f32 v160, v44, v45
	v_cvt_pk_bf16_f32 v161, v46, v47
	global_store_dwordx2 v204, v[160:161], s[58:59] offset:0
	v_mul_f32_e32 v146, v45, v45
	v_fmac_f32_e32 v146, v44, v44
	v_fmac_f32_e32 v146, v46, v46
	v_fmac_f32_e32 v146, v47, v47
	v_mov_b32_e32 v44, v146
	v_add_f32_e32 v40, v40, v200
	v_add_f32_e32 v41, v41, v201
	v_add_f32_e32 v42, v42, v202
	v_add_f32_e32 v43, v43, v203
	v_cvt_pk_bf16_f32 v200, v40, v41
	v_cvt_pk_bf16_f32 v201, v42, v43
	global_store_dwordx2 v204, v[200:201], s[58:59] offset:32
	v_fmac_f32_e32 v44, v40, v40
	v_fmac_f32_e32 v44, v41, v41
	v_fmac_f32_e32 v44, v42, v42
	v_fmac_f32_e32 v44, v43, v43
	v_add_f32_e32 v36, v36, v214
	v_add_f32_e32 v37, v37, v215
	v_add_f32_e32 v38, v38, v216
	v_add_f32_e32 v39, v39, v217
	v_cvt_pk_bf16_f32 v214, v36, v37
	v_cvt_pk_bf16_f32 v215, v38, v39
	global_store_dwordx2 v204, v[214:215], s[58:59] offset:256
	v_fmac_f32_e32 v44, v36, v36
	v_fmac_f32_e32 v44, v37, v37
	v_fmac_f32_e32 v44, v38, v38
	v_fmac_f32_e32 v44, v39, v39
	v_add_f32_e32 v32, v32, v152
	v_add_f32_e32 v33, v33, v153
	v_add_f32_e32 v34, v34, v154
	v_add_f32_e32 v35, v35, v155
	v_cvt_pk_bf16_f32 v152, v32, v33
	v_cvt_pk_bf16_f32 v153, v34, v35
	global_store_dwordx2 v204, v[152:153], s[58:59] offset:288
	v_fmac_f32_e32 v44, v32, v32
	v_fmac_f32_e32 v44, v33, v33
	v_fmac_f32_e32 v44, v34, v34
	v_fmac_f32_e32 v44, v35, v35
	s_waitcnt vmcnt(20)
	v_add_u32_e32 v205, 0xa0000, v198
	v_add_f32_e32 v28, v28, v218
	v_add_f32_e32 v29, v29, v219
	v_add_f32_e32 v30, v30, v220
	v_add_f32_e32 v31, v31, v221
	v_cvt_pk_bf16_f32 v218, v28, v29
	v_cvt_pk_bf16_f32 v219, v30, v31
	global_store_dwordx2 v205, v[218:219], s[58:59] offset:0
	v_mul_f32_e32 v146, v29, v29
	v_fmac_f32_e32 v146, v28, v28
	v_fmac_f32_e32 v146, v30, v30
	v_fmac_f32_e32 v146, v31, v31
	v_mov_b32_e32 v28, v146
	v_add_f32_e32 v24, v24, v148
	v_add_f32_e32 v25, v25, v149
	v_add_f32_e32 v26, v26, v150
	v_add_f32_e32 v27, v27, v151
	v_cvt_pk_bf16_f32 v148, v24, v25
	v_cvt_pk_bf16_f32 v149, v26, v27
	global_store_dwordx2 v205, v[148:149], s[58:59] offset:32
	v_fmac_f32_e32 v28, v24, v24
	v_fmac_f32_e32 v28, v25, v25
	v_fmac_f32_e32 v28, v26, v26
	v_fmac_f32_e32 v28, v27, v27
	v_add_f32_e32 v20, v20, v222
	v_add_f32_e32 v21, v21, v223
	v_add_f32_e32 v22, v22, v224
	v_add_f32_e32 v23, v23, v225
	v_cvt_pk_bf16_f32 v222, v20, v21
	v_cvt_pk_bf16_f32 v223, v22, v23
	global_store_dwordx2 v205, v[222:223], s[58:59] offset:256
	v_fmac_f32_e32 v28, v20, v20
	v_fmac_f32_e32 v28, v21, v21
	v_fmac_f32_e32 v28, v22, v22
	v_fmac_f32_e32 v28, v23, v23
	v_add_f32_e32 v16, v16, v128
	v_add_f32_e32 v17, v17, v129
	v_add_f32_e32 v18, v18, v130
	v_add_f32_e32 v19, v19, v131
	v_cvt_pk_bf16_f32 v128, v16, v17
	v_cvt_pk_bf16_f32 v129, v18, v19
	global_store_dwordx2 v205, v[128:129], s[58:59] offset:288
	v_fmac_f32_e32 v28, v16, v16
	v_fmac_f32_e32 v28, v17, v17
	v_fmac_f32_e32 v28, v18, v18
	v_fmac_f32_e32 v28, v19, v19
	s_waitcnt vmcnt(16)
	v_add_u32_e32 v204, 0xb0000, v198
	v_add_f32_e32 v12, v12, v226
	v_add_f32_e32 v13, v13, v227
	v_add_f32_e32 v14, v14, v228
	v_add_f32_e32 v15, v15, v229
	v_cvt_pk_bf16_f32 v226, v12, v13
	v_cvt_pk_bf16_f32 v227, v14, v15
	global_store_dwordx2 v204, v[226:227], s[58:59] offset:0
	v_mul_f32_e32 v146, v13, v13
	v_fmac_f32_e32 v146, v12, v12
	v_fmac_f32_e32 v146, v14, v14
	v_fmac_f32_e32 v146, v15, v15
	v_mov_b32_e32 v12, v146
	v_add_f32_e32 v8, v8, v230
	v_add_f32_e32 v9, v9, v231
	v_add_f32_e32 v10, v10, v232
	v_add_f32_e32 v11, v11, v233
	v_cvt_pk_bf16_f32 v230, v8, v9
	v_cvt_pk_bf16_f32 v231, v10, v11
	global_store_dwordx2 v204, v[230:231], s[58:59] offset:32
	v_fmac_f32_e32 v12, v8, v8
	v_fmac_f32_e32 v12, v9, v9
	v_fmac_f32_e32 v12, v10, v10
	v_fmac_f32_e32 v12, v11, v11
	v_add_f32_e32 v4, v4, v88
	v_add_f32_e32 v5, v5, v89
	v_add_f32_e32 v6, v6, v90
	v_add_f32_e32 v7, v7, v91
	v_cvt_pk_bf16_f32 v88, v4, v5
	v_cvt_pk_bf16_f32 v89, v6, v7
	global_store_dwordx2 v204, v[88:89], s[58:59] offset:256
	v_fmac_f32_e32 v12, v4, v4
	v_fmac_f32_e32 v12, v5, v5
	v_fmac_f32_e32 v12, v6, v6
	v_fmac_f32_e32 v12, v7, v7
	v_add_f32_e32 v0, v0, v234
	v_add_f32_e32 v1, v1, v235
	v_add_f32_e32 v2, v2, v236
	v_add_f32_e32 v3, v3, v237
	v_cvt_pk_bf16_f32 v234, v0, v1
	v_cvt_pk_bf16_f32 v235, v2, v3
	global_store_dwordx2 v204, v[234:235], s[58:59] offset:288
	v_fmac_f32_e32 v12, v0, v0
	v_fmac_f32_e32 v12, v1, v1
	v_fmac_f32_e32 v12, v2, v2
	v_fmac_f32_e32 v12, v3, v3
	ds_bpermute_b32 v96, v207, v172
	ds_bpermute_b32 v97, v207, v156
	ds_bpermute_b32 v98, v207, v92
	ds_bpermute_b32 v99, v207, v76
	ds_bpermute_b32 v100, v207, v60
	ds_bpermute_b32 v101, v207, v44
	ds_bpermute_b32 v102, v207, v28
	ds_bpermute_b32 v103, v207, v12
	s_waitcnt lgkmcnt(0)
	v_add_f32_e32 v172, v172, v96
	v_add_f32_e32 v156, v156, v97
	v_add_f32_e32 v92, v92, v98
	v_add_f32_e32 v76, v76, v99
	v_add_f32_e32 v60, v60, v100
	v_add_f32_e32 v44, v44, v101
	v_add_f32_e32 v28, v28, v102
	v_add_f32_e32 v12, v12, v103
	ds_bpermute_b32 v96, v206, v172
	ds_bpermute_b32 v97, v206, v156
	ds_bpermute_b32 v98, v206, v92
	ds_bpermute_b32 v99, v206, v76
	ds_bpermute_b32 v100, v206, v60
	ds_bpermute_b32 v101, v206, v44
	ds_bpermute_b32 v102, v206, v28
	ds_bpermute_b32 v103, v206, v12
	s_waitcnt lgkmcnt(0)
	v_add_f32_e32 v172, v172, v96
	v_add_f32_e32 v156, v156, v97
	v_add_f32_e32 v92, v92, v98
	v_add_f32_e32 v76, v76, v99
	v_add_f32_e32 v60, v60, v100
	v_add_f32_e32 v44, v44, v101
	v_add_f32_e32 v28, v28, v102
	v_add_f32_e32 v12, v12, v103
	s_and_saveexec_b64 s[2:3], s[40:41]
	v_mov_b32_e32 v192, v188
	global_store_dword v192, v172, s[16:17]
	v_add_u32_e32 v124, 0x800, v188
	global_store_dword v124, v156, s[16:17]
	v_add_u32_e32 v192, 0x1000, v188
	global_store_dword v192, v92, s[16:17]
	v_add_u32_e32 v124, 0x1800, v188
	global_store_dword v124, v76, s[16:17]
	v_add_u32_e32 v192, 0x4000, v188
	global_store_dword v192, v60, s[16:17]
	v_add_u32_e32 v124, 0x4800, v188
	global_store_dword v124, v44, s[16:17]
	v_add_u32_e32 v192, 0x5000, v188
	global_store_dword v192, v28, s[16:17]
	v_add_u32_e32 v124, 0x5800, v188
	global_store_dword v124, v12, s[16:17]
	s_or_b64 exec, exec, s[2:3]
	s_branch .LBB0_551

.LBB0_647:
	s_add_u32 s1, s42, 0xfff80080
	s_addc_u32 s2, s43, -1
	s_add_i32 s3, 0, 0x10000
	v_add_u32_e32 v138, s3, v141
	ds_read_b128 v[134:137], v138
	ds_read_b128 v[142:145], v138 offset:1024
	ds_read_b128 v[150:153], v138 offset:2048
	ds_read_b128 v[154:157], v138 offset:3072
	s_cmp_eq_u32 s88, 28
	s_cselect_b32 s73, s45, s2
	s_cselect_b32 s72, s53, s1
	s_cselect_b32 s71, s47, s87
	s_cselect_b32 s70, s60, s61
	v_lshl_add_u64 v[138:139], s[42:43], 0, v[130:131]
	s_add_i32 m0, s77, 0xc000
	ds_read_b128 v[158:161], v149
	ds_read_b128 v[162:165], v149 offset:1024
	ds_read_b128 v[166:169], v149 offset:2048
	ds_read_b128 v[170:173], v149 offset:3072
	ds_read_b128 v[182:185], v149 offset:4096
	ds_read_b128 v[200:203], v149 offset:5120
	ds_read_b128 v[208:211], v149 offset:6144
	ds_read_b128 v[212:215], v149 offset:7168
	global_load_lds_dwordx4 v[138:139], off
	v_lshl_add_u64 v[138:139], s[42:43], 0, v[132:133]
	s_add_i32 m0, s77, 0xe000
	s_nop 0
	global_load_lds_dwordx4 v[138:139], off
	s_waitcnt lgkmcnt(8)
	s_barrier
	s_waitcnt lgkmcnt(0)
	s_setprio 1
	s_waitcnt lgkmcnt(0)
	v_mfma_f32_16x16x32_bf16 v[124:127], v[134:137], v[158:161], v[124:127]
	v_mfma_f32_16x16x32_bf16 v[120:123], v[150:153], v[158:161], v[120:123]
	v_mfma_f32_16x16x32_bf16 v[108:111], v[134:137], v[166:169], v[108:111]
	v_mfma_f32_16x16x32_bf16 v[104:107], v[150:153], v[166:169], v[104:107]
	v_mfma_f32_16x16x32_bf16 v[92:95], v[134:137], v[182:185], v[92:95]
	v_mfma_f32_16x16x32_bf16 v[88:91], v[150:153], v[182:185], v[88:91]
	v_mfma_f32_16x16x32_bf16 v[76:79], v[134:137], v[208:211], v[76:79]
	v_mfma_f32_16x16x32_bf16 v[72:75], v[150:153], v[208:211], v[72:75]
	v_mfma_f32_16x16x32_bf16 v[124:127], v[142:145], v[162:165], v[124:127]
	v_mfma_f32_16x16x32_bf16 v[120:123], v[154:157], v[162:165], v[120:123]
	v_mfma_f32_16x16x32_bf16 v[108:111], v[142:145], v[170:173], v[108:111]
	v_mfma_f32_16x16x32_bf16 v[104:107], v[154:157], v[170:173], v[104:107]
	v_mfma_f32_16x16x32_bf16 v[92:95], v[142:145], v[200:203], v[92:95]
	v_mfma_f32_16x16x32_bf16 v[88:91], v[154:157], v[200:203], v[88:91]
	v_mfma_f32_16x16x32_bf16 v[76:79], v[142:145], v[212:215], v[76:79]
	v_mfma_f32_16x16x32_bf16 v[72:75], v[154:157], v[212:215], v[72:75]
	s_setprio 0
	s_barrier
	s_add_i32 s1, 0, 0x14000
	v_add_u32_e32 v138, s1, v141
	s_add_i32 s2, s3, s75
	ds_read_b128 v[216:219], v138
	ds_read_b128 v[220:223], v138 offset:1024
	ds_read_b128 v[224:227], v138 offset:2048
	ds_read_b128 v[228:231], v138 offset:3072
	v_lshl_add_u64 v[138:139], s[70:71], 0, v[176:177]
	s_mov_b32 m0, s2
	v_lshl_add_u64 v[174:175], s[70:71], 0, v[128:129]
	global_load_lds_dwordx4 v[138:139], off
	s_add_i32 m0, s2, 0x2000
	s_nop 0
	global_load_lds_dwordx4 v[174:175], off
	s_barrier
	s_waitcnt lgkmcnt(0)
	s_setprio 1
	s_waitcnt lgkmcnt(0)
	v_mfma_f32_16x16x32_bf16 v[116:119], v[216:219], v[158:161], v[116:119]
	v_mfma_f32_16x16x32_bf16 v[112:115], v[224:227], v[158:161], v[112:115]
	v_mfma_f32_16x16x32_bf16 v[100:103], v[216:219], v[166:169], v[100:103]
	v_mfma_f32_16x16x32_bf16 v[96:99], v[224:227], v[166:169], v[96:99]
	v_mfma_f32_16x16x32_bf16 v[84:87], v[216:219], v[182:185], v[84:87]
	v_mfma_f32_16x16x32_bf16 v[80:83], v[224:227], v[182:185], v[80:83]
	v_mfma_f32_16x16x32_bf16 v[68:71], v[216:219], v[208:211], v[68:71]
	v_mfma_f32_16x16x32_bf16 v[64:67], v[224:227], v[208:211], v[64:67]
	v_mfma_f32_16x16x32_bf16 v[116:119], v[220:223], v[162:165], v[116:119]
	v_mfma_f32_16x16x32_bf16 v[112:115], v[228:231], v[162:165], v[112:115]
	v_mfma_f32_16x16x32_bf16 v[100:103], v[220:223], v[170:173], v[100:103]
	v_mfma_f32_16x16x32_bf16 v[96:99], v[228:231], v[170:173], v[96:99]
	v_mfma_f32_16x16x32_bf16 v[84:87], v[220:223], v[200:203], v[84:87]
	v_mfma_f32_16x16x32_bf16 v[80:83], v[228:231], v[200:203], v[80:83]
	v_mfma_f32_16x16x32_bf16 v[68:71], v[220:223], v[212:215], v[68:71]
	v_mfma_f32_16x16x32_bf16 v[64:67], v[228:231], v[212:215], v[64:67]
	s_setprio 0
	s_mov_b32 m0, s77
	v_lshl_add_u64 v[186:187], s[72:73], 0, v[176:177]
	s_barrier
	ds_read_b128 v[158:161], v149 offset:16384
	ds_read_b128 v[162:165], v149 offset:17408
	ds_read_b128 v[166:169], v149 offset:18432
	ds_read_b128 v[170:173], v149 offset:19456
	ds_read_b128 v[182:185], v149 offset:20480
	ds_read_b128 v[200:203], v149 offset:21504
	ds_read_b128 v[208:211], v149 offset:22528
	ds_read_b128 v[212:215], v149 offset:23552
	global_load_lds_dwordx4 v[186:187], off
	v_lshl_add_u64 v[190:191], s[72:73], 0, v[128:129]
	s_mov_b32 m0, s78
	s_nop 0
	global_load_lds_dwordx4 v[190:191], off
	s_barrier
	s_waitcnt lgkmcnt(0)
	s_setprio 1
	s_waitcnt lgkmcnt(0)
	v_mfma_f32_16x16x32_bf16 v[60:63], v[134:137], v[158:161], v[60:63]
	v_mfma_f32_16x16x32_bf16 v[56:59], v[150:153], v[158:161], v[56:59]
	v_mfma_f32_16x16x32_bf16 v[44:47], v[134:137], v[166:169], v[44:47]
	v_mfma_f32_16x16x32_bf16 v[40:43], v[150:153], v[166:169], v[40:43]
	v_mfma_f32_16x16x32_bf16 v[28:31], v[134:137], v[182:185], v[28:31]
	v_mfma_f32_16x16x32_bf16 v[24:27], v[150:153], v[182:185], v[24:27]
	v_mfma_f32_16x16x32_bf16 v[12:15], v[134:137], v[208:211], v[12:15]
	v_mfma_f32_16x16x32_bf16 v[8:11], v[150:153], v[208:211], v[8:11]
	v_mfma_f32_16x16x32_bf16 v[60:63], v[142:145], v[162:165], v[60:63]
	v_mfma_f32_16x16x32_bf16 v[56:59], v[154:157], v[162:165], v[56:59]
	v_mfma_f32_16x16x32_bf16 v[44:47], v[142:145], v[170:173], v[44:47]
	v_mfma_f32_16x16x32_bf16 v[40:43], v[154:157], v[170:173], v[40:43]
	v_mfma_f32_16x16x32_bf16 v[28:31], v[142:145], v[200:203], v[28:31]
	v_mfma_f32_16x16x32_bf16 v[24:27], v[154:157], v[200:203], v[24:27]
	v_mfma_f32_16x16x32_bf16 v[12:15], v[142:145], v[212:215], v[12:15]
	v_mfma_f32_16x16x32_bf16 v[8:11], v[154:157], v[212:215], v[8:11]
	s_setprio 0
	s_barrier
	s_add_u32 s2, s70, 0x80000
	s_addc_u32 s3, s71, 0
	s_add_i32 s1, s1, s75
	v_lshl_add_u64 v[134:135], s[2:3], 0, v[176:177]
	s_mov_b32 m0, s1
	s_nop 0
	global_load_lds_dwordx4 v[134:135], off
	v_lshl_add_u64 v[134:135], s[2:3], 0, v[128:129]
	s_add_i32 m0, s1, 0x2000
	s_nop 0
	global_load_lds_dwordx4 v[134:135], off
	s_waitcnt vmcnt(6)
	s_barrier
	s_setprio 1
	v_mfma_f32_16x16x32_bf16 v[52:55], v[216:219], v[158:161], v[52:55]
	v_mfma_f32_16x16x32_bf16 v[48:51], v[224:227], v[158:161], v[48:51]
	v_mfma_f32_16x16x32_bf16 v[36:39], v[216:219], v[166:169], v[36:39]
	v_mfma_f32_16x16x32_bf16 v[32:35], v[224:227], v[166:169], v[32:35]
	v_mfma_f32_16x16x32_bf16 v[20:23], v[216:219], v[182:185], v[20:23]
	v_mfma_f32_16x16x32_bf16 v[16:19], v[224:227], v[182:185], v[16:19]
	v_mfma_f32_16x16x32_bf16 v[4:7], v[216:219], v[208:211], v[4:7]
	v_mfma_f32_16x16x32_bf16 v[0:3], v[224:227], v[208:211], v[0:3]
	v_mfma_f32_16x16x32_bf16 v[52:55], v[220:223], v[162:165], v[52:55]
	v_mfma_f32_16x16x32_bf16 v[48:51], v[228:231], v[162:165], v[48:51]
	v_mfma_f32_16x16x32_bf16 v[36:39], v[220:223], v[170:173], v[36:39]
	v_mfma_f32_16x16x32_bf16 v[32:35], v[228:231], v[170:173], v[32:35]
	v_mfma_f32_16x16x32_bf16 v[20:23], v[220:223], v[200:203], v[20:23]
	v_mfma_f32_16x16x32_bf16 v[16:19], v[228:231], v[200:203], v[16:19]
	v_mfma_f32_16x16x32_bf16 v[4:7], v[220:223], v[212:215], v[4:7]
	v_mfma_f32_16x16x32_bf16 v[0:3], v[228:231], v[212:215], v[0:3]
	s_setprio 0
	s_add_i32 s1, 0, 0x18000
	v_add_u32_e32 v140, s1, v141
	s_barrier
	ds_read_b128 v[134:137], v140
	ds_read_b128 v[142:145], v140 offset:1024
	ds_read_b128 v[150:153], v140 offset:2048
	ds_read_b128 v[154:157], v140 offset:3072
	s_add_u32 s2, s72, 0x80000
	s_addc_u32 s3, s73, 0
	s_mov_b32 m0, s79
	v_lshl_add_u64 v[194:195], s[2:3], 0, v[176:177]
	ds_read_b128 v[158:161], v149 offset:32768
	ds_read_b128 v[162:165], v149 offset:33792
	ds_read_b128 v[166:169], v149 offset:34816
	ds_read_b128 v[170:173], v149 offset:35840
	ds_read_b128 v[182:185], v149 offset:36864
	ds_read_b128 v[200:203], v149 offset:37888
	ds_read_b128 v[208:211], v149 offset:38912
	ds_read_b128 v[212:215], v149 offset:39936
	global_load_lds_dwordx4 v[194:195], off
	v_lshl_add_u64 v[194:195], s[2:3], 0, v[128:129]
	s_mov_b32 m0, s80
	s_nop 0
	global_load_lds_dwordx4 v[194:195], off
	s_waitcnt lgkmcnt(8)
	s_barrier
	s_waitcnt lgkmcnt(0)
	s_setprio 1
	s_waitcnt lgkmcnt(0)
	v_mfma_f32_16x16x32_bf16 v[124:127], v[134:137], v[158:161], v[124:127]
	v_mfma_f32_16x16x32_bf16 v[120:123], v[150:153], v[158:161], v[120:123]
	v_mfma_f32_16x16x32_bf16 v[108:111], v[134:137], v[166:169], v[108:111]
	v_mfma_f32_16x16x32_bf16 v[104:107], v[150:153], v[166:169], v[104:107]
	v_mfma_f32_16x16x32_bf16 v[92:95], v[134:137], v[182:185], v[92:95]
	v_mfma_f32_16x16x32_bf16 v[88:91], v[150:153], v[182:185], v[88:91]
	v_mfma_f32_16x16x32_bf16 v[76:79], v[134:137], v[208:211], v[76:79]
	v_mfma_f32_16x16x32_bf16 v[72:75], v[150:153], v[208:211], v[72:75]
	v_mfma_f32_16x16x32_bf16 v[124:127], v[142:145], v[162:165], v[124:127]
	v_mfma_f32_16x16x32_bf16 v[120:123], v[154:157], v[162:165], v[120:123]
	v_mfma_f32_16x16x32_bf16 v[108:111], v[142:145], v[170:173], v[108:111]
	v_mfma_f32_16x16x32_bf16 v[104:107], v[154:157], v[170:173], v[104:107]
	v_mfma_f32_16x16x32_bf16 v[92:95], v[142:145], v[200:203], v[92:95]
	v_mfma_f32_16x16x32_bf16 v[88:91], v[154:157], v[200:203], v[88:91]
	v_mfma_f32_16x16x32_bf16 v[76:79], v[142:145], v[212:215], v[76:79]
	v_mfma_f32_16x16x32_bf16 v[72:75], v[154:157], v[212:215], v[72:75]
	s_setprio 0
	s_barrier
	s_add_i32 s12, 0, 0x1c000
	s_add_i32 s1, s1, s75
	v_add_u32_e32 v140, s12, v141
	v_lshl_add_u64 v[138:139], v[138:139], 0, s[20:21]
	s_mov_b32 m0, s1
	ds_read_b128 v[216:219], v140
	ds_read_b128 v[220:223], v140 offset:1024
	ds_read_b128 v[224:227], v140 offset:2048
	ds_read_b128 v[228:231], v140 offset:3072
	global_load_lds_dwordx4 v[138:139], off
	v_lshl_add_u64 v[138:139], v[174:175], 0, s[20:21]
	s_add_i32 m0, s1, 0x2000
	s_nop 0
	global_load_lds_dwordx4 v[138:139], off
	s_barrier
	s_waitcnt lgkmcnt(0)
	s_setprio 1
	s_waitcnt lgkmcnt(0)
	v_mfma_f32_16x16x32_bf16 v[116:119], v[216:219], v[158:161], v[116:119]
	v_mfma_f32_16x16x32_bf16 v[112:115], v[224:227], v[158:161], v[112:115]
	v_mfma_f32_16x16x32_bf16 v[100:103], v[216:219], v[166:169], v[100:103]
	v_mfma_f32_16x16x32_bf16 v[96:99], v[224:227], v[166:169], v[96:99]
	v_mfma_f32_16x16x32_bf16 v[84:87], v[216:219], v[182:185], v[84:87]
	v_mfma_f32_16x16x32_bf16 v[80:83], v[224:227], v[182:185], v[80:83]
	v_mfma_f32_16x16x32_bf16 v[68:71], v[216:219], v[208:211], v[68:71]
	v_mfma_f32_16x16x32_bf16 v[64:67], v[224:227], v[208:211], v[64:67]
	v_mfma_f32_16x16x32_bf16 v[116:119], v[220:223], v[162:165], v[116:119]
	v_mfma_f32_16x16x32_bf16 v[112:115], v[228:231], v[162:165], v[112:115]
	v_mfma_f32_16x16x32_bf16 v[100:103], v[220:223], v[170:173], v[100:103]
	v_mfma_f32_16x16x32_bf16 v[96:99], v[228:231], v[170:173], v[96:99]
	v_mfma_f32_16x16x32_bf16 v[84:87], v[220:223], v[200:203], v[84:87]
	v_mfma_f32_16x16x32_bf16 v[80:83], v[228:231], v[200:203], v[80:83]
	v_mfma_f32_16x16x32_bf16 v[68:71], v[220:223], v[212:215], v[68:71]
	v_mfma_f32_16x16x32_bf16 v[64:67], v[228:231], v[212:215], v[64:67]
	s_setprio 0
	s_mov_b32 m0, s83
	v_lshl_add_u64 v[138:139], v[186:187], 0, s[20:21]
	s_barrier
	ds_read_b128 v[158:161], v149 offset:49152
	ds_read_b128 v[162:165], v149 offset:50176
	ds_read_b128 v[166:169], v149 offset:51200
	ds_read_b128 v[170:173], v149 offset:52224
	ds_read_b128 v[182:185], v149 offset:53248
	ds_read_b128 v[200:203], v149 offset:54272
	ds_read_b128 v[208:211], v149 offset:55296
	ds_read_b128 v[212:215], v149 offset:56320
	global_load_lds_dwordx4 v[138:139], off
	v_lshl_add_u64 v[138:139], v[190:191], 0, s[20:21]
	s_mov_b32 m0, s74
	s_nop 0
	global_load_lds_dwordx4 v[138:139], off
	s_barrier
	s_waitcnt lgkmcnt(0)
	s_setprio 1
	s_waitcnt lgkmcnt(0)
	v_mfma_f32_16x16x32_bf16 v[60:63], v[134:137], v[158:161], v[60:63]
	v_mfma_f32_16x16x32_bf16 v[56:59], v[150:153], v[158:161], v[56:59]
	v_mfma_f32_16x16x32_bf16 v[44:47], v[134:137], v[166:169], v[44:47]
	v_mfma_f32_16x16x32_bf16 v[40:43], v[150:153], v[166:169], v[40:43]
	v_mfma_f32_16x16x32_bf16 v[28:31], v[134:137], v[182:185], v[28:31]
	v_mfma_f32_16x16x32_bf16 v[24:27], v[150:153], v[182:185], v[24:27]
	v_mfma_f32_16x16x32_bf16 v[12:15], v[134:137], v[208:211], v[12:15]
	v_mfma_f32_16x16x32_bf16 v[8:11], v[150:153], v[208:211], v[8:11]
	v_mfma_f32_16x16x32_bf16 v[60:63], v[142:145], v[162:165], v[60:63]
	v_mfma_f32_16x16x32_bf16 v[56:59], v[154:157], v[162:165], v[56:59]
	v_mfma_f32_16x16x32_bf16 v[44:47], v[142:145], v[170:173], v[44:47]
	v_mfma_f32_16x16x32_bf16 v[40:43], v[154:157], v[170:173], v[40:43]
	v_mfma_f32_16x16x32_bf16 v[28:31], v[142:145], v[200:203], v[28:31]
	v_mfma_f32_16x16x32_bf16 v[24:27], v[154:157], v[200:203], v[24:27]
	v_mfma_f32_16x16x32_bf16 v[12:15], v[142:145], v[212:215], v[12:15]
	v_mfma_f32_16x16x32_bf16 v[8:11], v[154:157], v[212:215], v[8:11]
	s_setprio 0
	s_barrier
	s_add_u32 s2, s70, 0x80080
	s_addc_u32 s3, s71, 0
	s_add_i32 s1, s12, s75
	v_lshl_add_u64 v[134:135], s[2:3], 0, v[176:177]
	s_mov_b32 m0, s1
	s_nop 0
	global_load_lds_dwordx4 v[134:135], off
	v_lshl_add_u64 v[134:135], s[2:3], 0, v[128:129]
	s_add_i32 m0, s1, 0x2000
	s_nop 0
	global_load_lds_dwordx4 v[134:135], off
	s_waitcnt vmcnt(6)
	s_barrier
	s_setprio 1
	v_mfma_f32_16x16x32_bf16 v[52:55], v[216:219], v[158:161], v[52:55]
	v_mfma_f32_16x16x32_bf16 v[48:51], v[224:227], v[158:161], v[48:51]
	v_mfma_f32_16x16x32_bf16 v[36:39], v[216:219], v[166:169], v[36:39]
	v_mfma_f32_16x16x32_bf16 v[32:35], v[224:227], v[166:169], v[32:35]
	v_mfma_f32_16x16x32_bf16 v[20:23], v[216:219], v[182:185], v[20:23]
	v_mfma_f32_16x16x32_bf16 v[16:19], v[224:227], v[182:185], v[16:19]
	v_mfma_f32_16x16x32_bf16 v[4:7], v[216:219], v[208:211], v[4:7]
	v_mfma_f32_16x16x32_bf16 v[0:3], v[224:227], v[208:211], v[0:3]
	v_mfma_f32_16x16x32_bf16 v[52:55], v[220:223], v[162:165], v[52:55]
	v_mfma_f32_16x16x32_bf16 v[48:51], v[228:231], v[162:165], v[48:51]
	v_mfma_f32_16x16x32_bf16 v[36:39], v[220:223], v[170:173], v[36:39]
	v_mfma_f32_16x16x32_bf16 v[32:35], v[228:231], v[170:173], v[32:35]
	v_mfma_f32_16x16x32_bf16 v[20:23], v[220:223], v[200:203], v[20:23]
	v_mfma_f32_16x16x32_bf16 v[16:19], v[228:231], v[200:203], v[16:19]
	v_mfma_f32_16x16x32_bf16 v[4:7], v[220:223], v[212:215], v[4:7]
	v_mfma_f32_16x16x32_bf16 v[0:3], v[228:231], v[212:215], v[0:3]
	s_setprio 0
	s_add_i32 s88, s88, 2
	s_add_u32 s42, s42, 0x100
	s_addc_u32 s43, s43, 0
	s_add_u32 s61, s61, 0x100
	s_addc_u32 s87, s87, 0
	s_cmp_gt_u32 s88, 29
	s_barrier
	s_cbranch_scc0 .LBB0_647
	v_and_b32_e32 v198, 15, v147
	v_ashrrev_i32_e32 v252, 4, v147
	s_lshl_b32 s1, s52, 8
	s_add_i32 s1, s1, s81
	v_or_b32_e32 v198, s1, v198
	s_lshl_b32 s1, s49, 8
	s_or_b32 s1, s1, s82
	v_lshl_add_u32 v140, v252, 2, s1
	v_lshl_add_u32 v140, v198, 11, v140
	v_lshlrev_b32_e32 v140, 1, v140
	v_lshlrev_b32_e32 v146, 5, v252
	v_lshl_add_u32 v146, v198, 7, v146
	s_mov_b32 s49, s46
	s_mov_b32 s52, s44
	s_mov_b64 s[70:71], s[68:69]
	s_movk_i32 s14, 0x3fff
	s_mov_b64 s[42:43], s[38:39]
	v_mov_b32_e32 v148, v146
	global_load_dwordx4 v[208:211], v148, s[16:17]
	global_load_dwordx4 v[212:215], v148, s[16:17] offset:16
	v_add_u32_e32 v188, 0x800, v146
	global_load_dwordx4 v[216:219], v188, s[16:17]
	global_load_dwordx4 v[220:223], v188, s[16:17] offset:16
	v_add_u32_e32 v192, 0x1000, v146
	global_load_dwordx4 v[224:227], v192, s[16:17]
	global_load_dwordx4 v[228:231], v192, s[16:17] offset:16
	v_add_u32_e32 v196, 0x1800, v146
	global_load_dwordx4 v[232:235], v196, s[16:17]
	global_load_dwordx4 v[236:239], v196, s[16:17] offset:16
	v_mov_b32_e32 v148, v140
	global_load_dwordx2 v[152:153], v148, s[58:59] offset:0
	global_load_dwordx2 v[154:155], v148, s[56:57] offset:0
	global_load_dwordx2 v[156:157], v148, s[58:59] offset:32
	global_load_dwordx2 v[158:159], v148, s[56:57] offset:32
	global_load_dwordx2 v[160:161], v148, s[58:59] offset:256
	global_load_dwordx2 v[162:163], v148, s[56:57] offset:256
	global_load_dwordx2 v[164:165], v148, s[58:59] offset:288
	global_load_dwordx2 v[166:167], v148, s[56:57] offset:288
	v_add_u32_e32 v188, 0x10000, v140
	global_load_dwordx2 v[168:169], v188, s[58:59] offset:0
	global_load_dwordx2 v[170:171], v188, s[56:57] offset:0
	global_load_dwordx2 v[172:173], v188, s[58:59] offset:32
	global_load_dwordx2 v[174:175], v188, s[56:57] offset:32
	global_load_dwordx2 v[240:241], v188, s[58:59] offset:256
	global_load_dwordx2 v[242:243], v188, s[56:57] offset:256
	global_load_dwordx2 v[244:245], v188, s[58:59] offset:288
	global_load_dwordx2 v[246:247], v188, s[56:57] offset:288
	v_add_u32_e32 v192, 0x20000, v140
	global_load_dwordx2 v[182:183], v192, s[58:59] offset:0
	global_load_dwordx2 v[184:185], v192, s[56:57] offset:0
	global_load_dwordx2 v[186:187], v192, s[58:59] offset:32
	global_load_dwordx2 v[200:201], v192, s[56:57] offset:32
	global_load_dwordx2 v[202:203], v192, s[58:59] offset:256
	global_load_dwordx2 v[204:205], v192, s[56:57] offset:256
	global_load_dwordx2 v[134:135], v192, s[58:59] offset:288
	global_load_dwordx2 v[136:137], v192, s[56:57] offset:288
	v_add_u32_e32 v196, 0x30000, v140
	global_load_dwordx2 v[138:139], v196, s[58:59] offset:0
	global_load_dwordx2 v[142:143], v196, s[56:57] offset:0
	global_load_dwordx2 v[144:145], v196, s[58:59] offset:32
	global_load_dwordx2 v[190:191], v196, s[56:57] offset:32
	global_load_dwordx2 v[194:195], v196, s[58:59] offset:256
	global_load_dwordx2 v[248:249], v196, s[56:57] offset:256
	global_load_dwordx2 v[150:151], v196, s[58:59] offset:288
	s_waitcnt vmcnt(31)
	v_add_f32_e32 v208, v208, v209
	v_add_f32_e32 v210, v210, v211
	v_add_f32_e32 v212, v212, v213
	v_add_f32_e32 v214, v214, v215
	v_add_f32_e32 v208, v208, v210
	v_add_f32_e32 v212, v212, v214
	v_add_f32_e32 v208, v208, v212
	v_add_f32_e32 v216, v216, v217
	v_add_f32_e32 v218, v218, v219
	v_add_f32_e32 v220, v220, v221
	v_add_f32_e32 v222, v222, v223
	v_add_f32_e32 v216, v216, v218
	v_add_f32_e32 v220, v220, v222
	v_add_f32_e32 v216, v216, v220
	v_add_f32_e32 v224, v224, v225
	v_add_f32_e32 v226, v226, v227
	v_add_f32_e32 v228, v228, v229
	v_add_f32_e32 v230, v230, v231
	v_add_f32_e32 v224, v224, v226
	v_add_f32_e32 v228, v228, v230
	v_add_f32_e32 v224, v224, v228
	v_add_f32_e32 v232, v232, v233
	v_add_f32_e32 v234, v234, v235
	v_add_f32_e32 v236, v236, v237
	v_add_f32_e32 v238, v238, v239
	v_add_f32_e32 v232, v232, v234
	v_add_f32_e32 v236, v236, v238
	v_add_f32_e32 v232, v232, v236
	ds_bpermute_b32 v209, v207, v208
	ds_bpermute_b32 v217, v207, v216
	ds_bpermute_b32 v225, v207, v224
	ds_bpermute_b32 v233, v207, v232
	s_waitcnt lgkmcnt(0)
	v_add_f32_e32 v208, v208, v209
	v_add_f32_e32 v216, v216, v217
	v_add_f32_e32 v224, v224, v225
	v_add_f32_e32 v232, v232, v233
	ds_bpermute_b32 v209, v206, v208
	ds_bpermute_b32 v217, v206, v216
	ds_bpermute_b32 v225, v206, v224
	ds_bpermute_b32 v233, v206, v232
	s_waitcnt lgkmcnt(0)
	v_add_f32_e32 v208, v208, v209
	v_add_f32_e32 v216, v216, v217
	v_add_f32_e32 v224, v224, v225
	v_add_f32_e32 v232, v232, v233
	v_mul_f32_e32 v208, 0x3a000000, v208
	v_add_f32_e32 v208, 0x358637bd, v208
	v_mul_f32_e32 v216, 0x3a000000, v216
	v_add_f32_e32 v216, 0x358637bd, v216
	v_mul_f32_e32 v224, 0x3a000000, v224
	v_add_f32_e32 v224, 0x358637bd, v224
	v_mul_f32_e32 v232, 0x3a000000, v232
	v_add_f32_e32 v232, 0x358637bd, v232
	v_rsq_f32_e32 v208, v208
	v_rsq_f32_e32 v216, v216
	v_rsq_f32_e32 v224, v224
	v_rsq_f32_e32 v232, v232
	s_nop 0
	v_mov_b32_e32 v209, v216
	v_mov_b32_e32 v210, v224
	v_mov_b32_e32 v211, v232
	v_add_u32_e32 v148, 0x30000, v140
	global_load_dwordx2 v[238:239], v148, s[56:57] offset:288
	s_waitcnt vmcnt(16)
	v_mov_b32_e32 v188, v140
	v_mul_f32_e32 v124, v124, v208
	v_mul_f32_e32 v125, v125, v208
	v_mul_f32_e32 v126, v126, v208
	v_mul_f32_e32 v127, v127, v208
	v_mul_f32_e32 v124, 0xbfb8aa3b, v124
	v_mul_f32_e32 v125, 0xbfb8aa3b, v125
	v_mul_f32_e32 v126, 0xbfb8aa3b, v126
	v_mul_f32_e32 v127, 0xbfb8aa3b, v127
	v_exp_f32_e32 v124, v124
	v_exp_f32_e32 v125, v125
	v_exp_f32_e32 v126, v126
	v_exp_f32_e32 v127, v127
	v_add_f32_e32 v124, 1.0, v124
	v_add_f32_e32 v125, 1.0, v125
	v_add_f32_e32 v126, 1.0, v126
	v_add_f32_e32 v127, 1.0, v127
	v_div_scale_f32 v216, s[2:3], v124, v124, 1.0
	v_div_scale_f32 v217, s[2:3], v125, v125, 1.0
	v_div_scale_f32 v218, s[2:3], v126, v126, 1.0
	v_div_scale_f32 v219, s[2:3], v127, v127, 1.0
	v_rcp_f32_e32 v220, v216
	v_rcp_f32_e32 v221, v217
	v_rcp_f32_e32 v222, v218
	v_rcp_f32_e32 v223, v219
	v_fma_f32 v224, -v216, v220, 1.0
	v_fma_f32 v225, -v217, v221, 1.0
	v_fma_f32 v226, -v218, v222, 1.0
	v_fma_f32 v227, -v219, v223, 1.0
	v_fmac_f32_e32 v220, v224, v220
	v_fmac_f32_e32 v221, v225, v221
	v_fmac_f32_e32 v222, v226, v222
	v_fmac_f32_e32 v223, v227, v223
	v_div_scale_f32 v224, vcc, 1.0, v124, 1.0
	v_mul_f32_e32 v228, v224, v220
	v_fma_f32 v229, -v216, v228, v224
	v_fmac_f32_e32 v228, v229, v220
	v_fma_f32 v216, -v216, v228, v224
	v_div_fmas_f32 v216, v216, v220, v228
	v_div_fixup_f32 v124, v216, v124, 1.0
	v_div_scale_f32 v225, vcc, 1.0, v125, 1.0
	v_mul_f32_e32 v228, v225, v221
	v_fma_f32 v229, -v217, v228, v225
	v_fmac_f32_e32 v228, v229, v221
	v_fma_f32 v217, -v217, v228, v225
	v_div_fmas_f32 v217, v217, v221, v228
	v_div_fixup_f32 v125, v217, v125, 1.0
	v_div_scale_f32 v226, vcc, 1.0, v126, 1.0
	v_mul_f32_e32 v228, v226, v222
	v_fma_f32 v229, -v218, v228, v226
	v_fmac_f32_e32 v228, v229, v222
	v_fma_f32 v218, -v218, v228, v226
	v_div_fmas_f32 v218, v218, v222, v228
	v_div_fixup_f32 v126, v218, v126, 1.0
	v_div_scale_f32 v227, vcc, 1.0, v127, 1.0
	v_mul_f32_e32 v228, v227, v223
	v_fma_f32 v229, -v219, v228, v227
	v_fmac_f32_e32 v228, v229, v223
	v_fma_f32 v219, -v219, v228, v227
	v_div_fmas_f32 v219, v219, v223, v228
	v_div_fixup_f32 v127, v219, v127, 1.0
	v_lshlrev_b32_e32 v230, 16, v152
	v_and_b32_e32 v152, 0xffff0000, v152
	v_lshlrev_b32_e32 v231, 16, v153
	v_and_b32_e32 v153, 0xffff0000, v153
	v_lshlrev_b32_e32 v232, 16, v154
	v_and_b32_e32 v154, 0xffff0000, v154
	v_lshlrev_b32_e32 v233, 16, v155
	v_and_b32_e32 v155, 0xffff0000, v155
	v_fma_f32 v124, v124, v232, v230
	v_fma_f32 v125, v125, v154, v152
	v_fma_f32 v126, v126, v233, v231
	v_fma_f32 v127, v127, v155, v153
	v_cvt_pk_bf16_f32 v152, v124, v125
	v_cvt_pk_bf16_f32 v153, v126, v127
	global_store_dwordx2 v188, v[152:153], s[62:63] offset:0
	v_mul_f32_e32 v120, v120, v208
	v_mul_f32_e32 v121, v121, v208
	v_mul_f32_e32 v122, v122, v208
	v_mul_f32_e32 v123, v123, v208
	v_mul_f32_e32 v120, 0xbfb8aa3b, v120
	v_mul_f32_e32 v121, 0xbfb8aa3b, v121
	v_mul_f32_e32 v122, 0xbfb8aa3b, v122
	v_mul_f32_e32 v123, 0xbfb8aa3b, v123
	v_exp_f32_e32 v120, v120
	v_exp_f32_e32 v121, v121
	v_exp_f32_e32 v122, v122
	v_exp_f32_e32 v123, v123
	v_add_f32_e32 v120, 1.0, v120
	v_add_f32_e32 v121, 1.0, v121
	v_add_f32_e32 v122, 1.0, v122
	v_add_f32_e32 v123, 1.0, v123
	v_div_scale_f32 v216, s[2:3], v120, v120, 1.0
	v_div_scale_f32 v217, s[2:3], v121, v121, 1.0
	v_div_scale_f32 v218, s[2:3], v122, v122, 1.0
	v_div_scale_f32 v219, s[2:3], v123, v123, 1.0
	v_rcp_f32_e32 v220, v216
	v_rcp_f32_e32 v221, v217
	v_rcp_f32_e32 v222, v218
	v_rcp_f32_e32 v223, v219
	v_fma_f32 v224, -v216, v220, 1.0
	v_fma_f32 v225, -v217, v221, 1.0
	v_fma_f32 v226, -v218, v222, 1.0
	v_fma_f32 v227, -v219, v223, 1.0
	v_fmac_f32_e32 v220, v224, v220
	v_fmac_f32_e32 v221, v225, v221
	v_fmac_f32_e32 v222, v226, v222
	v_fmac_f32_e32 v223, v227, v223
	v_div_scale_f32 v224, vcc, 1.0, v120, 1.0
	v_mul_f32_e32 v228, v224, v220
	v_fma_f32 v229, -v216, v228, v224
	v_fmac_f32_e32 v228, v229, v220
	v_fma_f32 v216, -v216, v228, v224
	v_div_fmas_f32 v216, v216, v220, v228
	v_div_fixup_f32 v120, v216, v120, 1.0
	v_div_scale_f32 v225, vcc, 1.0, v121, 1.0
	v_mul_f32_e32 v228, v225, v221
	v_fma_f32 v229, -v217, v228, v225
	v_fmac_f32_e32 v228, v229, v221
	v_fma_f32 v217, -v217, v228, v225
	v_div_fmas_f32 v217, v217, v221, v228
	v_div_fixup_f32 v121, v217, v121, 1.0
	v_div_scale_f32 v226, vcc, 1.0, v122, 1.0
	v_mul_f32_e32 v228, v226, v222
	v_fma_f32 v229, -v218, v228, v226
	v_fmac_f32_e32 v228, v229, v222
	v_fma_f32 v218, -v218, v228, v226
	v_div_fmas_f32 v218, v218, v222, v228
	v_div_fixup_f32 v122, v218, v122, 1.0
	v_div_scale_f32 v227, vcc, 1.0, v123, 1.0
	v_mul_f32_e32 v228, v227, v223
	v_fma_f32 v229, -v219, v228, v227
	v_fmac_f32_e32 v228, v229, v223
	v_fma_f32 v219, -v219, v228, v227
	v_div_fmas_f32 v219, v219, v223, v228
	v_div_fixup_f32 v123, v219, v123, 1.0
	v_lshlrev_b32_e32 v230, 16, v156
	v_and_b32_e32 v156, 0xffff0000, v156
	v_lshlrev_b32_e32 v231, 16, v157
	v_and_b32_e32 v157, 0xffff0000, v157
	v_lshlrev_b32_e32 v232, 16, v158
	v_and_b32_e32 v158, 0xffff0000, v158
	v_lshlrev_b32_e32 v233, 16, v159
	v_and_b32_e32 v159, 0xffff0000, v159
	v_fma_f32 v120, v120, v232, v230
	v_fma_f32 v121, v121, v158, v156
	v_fma_f32 v122, v122, v233, v231
	v_fma_f32 v123, v123, v159, v157
	v_cvt_pk_bf16_f32 v156, v120, v121
	v_cvt_pk_bf16_f32 v157, v122, v123
	global_store_dwordx2 v188, v[156:157], s[62:63] offset:32
	v_mul_f32_e32 v116, v116, v208
	v_mul_f32_e32 v117, v117, v208
	v_mul_f32_e32 v118, v118, v208
	v_mul_f32_e32 v119, v119, v208
	v_mul_f32_e32 v116, 0xbfb8aa3b, v116
	v_mul_f32_e32 v117, 0xbfb8aa3b, v117
	v_mul_f32_e32 v118, 0xbfb8aa3b, v118
	v_mul_f32_e32 v119, 0xbfb8aa3b, v119
	v_exp_f32_e32 v116, v116
	v_exp_f32_e32 v117, v117
	v_exp_f32_e32 v118, v118
	v_exp_f32_e32 v119, v119
	v_add_f32_e32 v116, 1.0, v116
	v_add_f32_e32 v117, 1.0, v117
	v_add_f32_e32 v118, 1.0, v118
	v_add_f32_e32 v119, 1.0, v119
	v_div_scale_f32 v216, s[2:3], v116, v116, 1.0
	v_div_scale_f32 v217, s[2:3], v117, v117, 1.0
	v_div_scale_f32 v218, s[2:3], v118, v118, 1.0
	v_div_scale_f32 v219, s[2:3], v119, v119, 1.0
	v_rcp_f32_e32 v220, v216
	v_rcp_f32_e32 v221, v217
	v_rcp_f32_e32 v222, v218
	v_rcp_f32_e32 v223, v219
	v_fma_f32 v224, -v216, v220, 1.0
	v_fma_f32 v225, -v217, v221, 1.0
	v_fma_f32 v226, -v218, v222, 1.0
	v_fma_f32 v227, -v219, v223, 1.0
	v_fmac_f32_e32 v220, v224, v220
	v_fmac_f32_e32 v221, v225, v221
	v_fmac_f32_e32 v222, v226, v222
	v_fmac_f32_e32 v223, v227, v223
	v_div_scale_f32 v224, vcc, 1.0, v116, 1.0
	v_mul_f32_e32 v228, v224, v220
	v_fma_f32 v229, -v216, v228, v224
	v_fmac_f32_e32 v228, v229, v220
	v_fma_f32 v216, -v216, v228, v224
	v_div_fmas_f32 v216, v216, v220, v228
	v_div_fixup_f32 v116, v216, v116, 1.0
	v_div_scale_f32 v225, vcc, 1.0, v117, 1.0
	v_mul_f32_e32 v228, v225, v221
	v_fma_f32 v229, -v217, v228, v225
	v_fmac_f32_e32 v228, v229, v221
	v_fma_f32 v217, -v217, v228, v225
	v_div_fmas_f32 v217, v217, v221, v228
	v_div_fixup_f32 v117, v217, v117, 1.0
	v_div_scale_f32 v226, vcc, 1.0, v118, 1.0
	v_mul_f32_e32 v228, v226, v222
	v_fma_f32 v229, -v218, v228, v226
	v_fmac_f32_e32 v228, v229, v222
	v_fma_f32 v218, -v218, v228, v226
	v_div_fmas_f32 v218, v218, v222, v228
	v_div_fixup_f32 v118, v218, v118, 1.0
	v_div_scale_f32 v227, vcc, 1.0, v119, 1.0
	v_mul_f32_e32 v228, v227, v223
	v_fma_f32 v229, -v219, v228, v227
	v_fmac_f32_e32 v228, v229, v223
	v_fma_f32 v219, -v219, v228, v227
	v_div_fmas_f32 v219, v219, v223, v228
	v_div_fixup_f32 v119, v219, v119, 1.0
	v_lshlrev_b32_e32 v230, 16, v160
	v_and_b32_e32 v160, 0xffff0000, v160
	v_lshlrev_b32_e32 v231, 16, v161
	v_and_b32_e32 v161, 0xffff0000, v161
	v_lshlrev_b32_e32 v232, 16, v162
	v_and_b32_e32 v162, 0xffff0000, v162
	v_lshlrev_b32_e32 v233, 16, v163
	v_and_b32_e32 v163, 0xffff0000, v163
	v_fma_f32 v116, v116, v232, v230
	v_fma_f32 v117, v117, v162, v160
	v_fma_f32 v118, v118, v233, v231
	v_fma_f32 v119, v119, v163, v161
	v_cvt_pk_bf16_f32 v160, v116, v117
	v_cvt_pk_bf16_f32 v161, v118, v119
	global_store_dwordx2 v188, v[160:161], s[62:63] offset:256
	v_mul_f32_e32 v112, v112, v208
	v_mul_f32_e32 v113, v113, v208
	v_mul_f32_e32 v114, v114, v208
	v_mul_f32_e32 v115, v115, v208
	v_mul_f32_e32 v112, 0xbfb8aa3b, v112
	v_mul_f32_e32 v113, 0xbfb8aa3b, v113
	v_mul_f32_e32 v114, 0xbfb8aa3b, v114
	v_mul_f32_e32 v115, 0xbfb8aa3b, v115
	v_exp_f32_e32 v112, v112
	v_exp_f32_e32 v113, v113
	v_exp_f32_e32 v114, v114
	v_exp_f32_e32 v115, v115
	v_add_f32_e32 v112, 1.0, v112
	v_add_f32_e32 v113, 1.0, v113
	v_add_f32_e32 v114, 1.0, v114
	v_add_f32_e32 v115, 1.0, v115
	v_div_scale_f32 v216, s[2:3], v112, v112, 1.0
	v_div_scale_f32 v217, s[2:3], v113, v113, 1.0
	v_div_scale_f32 v218, s[2:3], v114, v114, 1.0
	v_div_scale_f32 v219, s[2:3], v115, v115, 1.0
	v_rcp_f32_e32 v220, v216
	v_rcp_f32_e32 v221, v217
	v_rcp_f32_e32 v222, v218
	v_rcp_f32_e32 v223, v219
	v_fma_f32 v224, -v216, v220, 1.0
	v_fma_f32 v225, -v217, v221, 1.0
	v_fma_f32 v226, -v218, v222, 1.0
	v_fma_f32 v227, -v219, v223, 1.0
	v_fmac_f32_e32 v220, v224, v220
	v_fmac_f32_e32 v221, v225, v221
	v_fmac_f32_e32 v222, v226, v222
	v_fmac_f32_e32 v223, v227, v223
	v_div_scale_f32 v224, vcc, 1.0, v112, 1.0
	v_mul_f32_e32 v228, v224, v220
	v_fma_f32 v229, -v216, v228, v224
	v_fmac_f32_e32 v228, v229, v220
	v_fma_f32 v216, -v216, v228, v224
	v_div_fmas_f32 v216, v216, v220, v228
	v_div_fixup_f32 v112, v216, v112, 1.0
	v_div_scale_f32 v225, vcc, 1.0, v113, 1.0
	v_mul_f32_e32 v228, v225, v221
	v_fma_f32 v229, -v217, v228, v225
	v_fmac_f32_e32 v228, v229, v221
	v_fma_f32 v217, -v217, v228, v225
	v_div_fmas_f32 v217, v217, v221, v228
	v_div_fixup_f32 v113, v217, v113, 1.0
	v_div_scale_f32 v226, vcc, 1.0, v114, 1.0
	v_mul_f32_e32 v228, v226, v222
	v_fma_f32 v229, -v218, v228, v226
	v_fmac_f32_e32 v228, v229, v222
	v_fma_f32 v218, -v218, v228, v226
	v_div_fmas_f32 v218, v218, v222, v228
	v_div_fixup_f32 v114, v218, v114, 1.0
	v_div_scale_f32 v227, vcc, 1.0, v115, 1.0
	v_mul_f32_e32 v228, v227, v223
	v_fma_f32 v229, -v219, v228, v227
	v_fmac_f32_e32 v228, v229, v223
	v_fma_f32 v219, -v219, v228, v227
	v_div_fmas_f32 v219, v219, v223, v228
	v_div_fixup_f32 v115, v219, v115, 1.0
	v_lshlrev_b32_e32 v230, 16, v164
	v_and_b32_e32 v164, 0xffff0000, v164
	v_lshlrev_b32_e32 v231, 16, v165
	v_and_b32_e32 v165, 0xffff0000, v165
	v_lshlrev_b32_e32 v232, 16, v166
	v_and_b32_e32 v166, 0xffff0000, v166
	v_lshlrev_b32_e32 v233, 16, v167
	v_and_b32_e32 v167, 0xffff0000, v167
	v_fma_f32 v112, v112, v232, v230
	v_fma_f32 v113, v113, v166, v164
	v_fma_f32 v114, v114, v233, v231
	v_fma_f32 v115, v115, v167, v165
	v_cvt_pk_bf16_f32 v164, v112, v113
	v_cvt_pk_bf16_f32 v165, v114, v115
	global_store_dwordx2 v188, v[164:165], s[62:63] offset:288
	v_add_u32_e32 v192, 0x10000, v140
	v_mul_f32_e32 v108, v108, v209
	v_mul_f32_e32 v109, v109, v209
	v_mul_f32_e32 v110, v110, v209
	v_mul_f32_e32 v111, v111, v209
	v_mul_f32_e32 v108, 0xbfb8aa3b, v108
	v_mul_f32_e32 v109, 0xbfb8aa3b, v109
	v_mul_f32_e32 v110, 0xbfb8aa3b, v110
	v_mul_f32_e32 v111, 0xbfb8aa3b, v111
	v_exp_f32_e32 v108, v108
	v_exp_f32_e32 v109, v109
	v_exp_f32_e32 v110, v110
	v_exp_f32_e32 v111, v111
	v_add_f32_e32 v108, 1.0, v108
	v_add_f32_e32 v109, 1.0, v109
	v_add_f32_e32 v110, 1.0, v110
	v_add_f32_e32 v111, 1.0, v111
	v_div_scale_f32 v216, s[2:3], v108, v108, 1.0
	v_div_scale_f32 v217, s[2:3], v109, v109, 1.0
	v_div_scale_f32 v218, s[2:3], v110, v110, 1.0
	v_div_scale_f32 v219, s[2:3], v111, v111, 1.0
	v_rcp_f32_e32 v220, v216
	v_rcp_f32_e32 v221, v217
	v_rcp_f32_e32 v222, v218
	v_rcp_f32_e32 v223, v219
	v_fma_f32 v224, -v216, v220, 1.0
	v_fma_f32 v225, -v217, v221, 1.0
	v_fma_f32 v226, -v218, v222, 1.0
	v_fma_f32 v227, -v219, v223, 1.0
	v_fmac_f32_e32 v220, v224, v220
	v_fmac_f32_e32 v221, v225, v221
	v_fmac_f32_e32 v222, v226, v222
	v_fmac_f32_e32 v223, v227, v223
	v_div_scale_f32 v224, vcc, 1.0, v108, 1.0
	v_mul_f32_e32 v228, v224, v220
	v_fma_f32 v229, -v216, v228, v224
	v_fmac_f32_e32 v228, v229, v220
	v_fma_f32 v216, -v216, v228, v224
	v_div_fmas_f32 v216, v216, v220, v228
	v_div_fixup_f32 v108, v216, v108, 1.0
	v_div_scale_f32 v225, vcc, 1.0, v109, 1.0
	v_mul_f32_e32 v228, v225, v221
	v_fma_f32 v229, -v217, v228, v225
	v_fmac_f32_e32 v228, v229, v221
	v_fma_f32 v217, -v217, v228, v225
	v_div_fmas_f32 v217, v217, v221, v228
	v_div_fixup_f32 v109, v217, v109, 1.0
	v_div_scale_f32 v226, vcc, 1.0, v110, 1.0
	v_mul_f32_e32 v228, v226, v222
	v_fma_f32 v229, -v218, v228, v226
	v_fmac_f32_e32 v228, v229, v222
	v_fma_f32 v218, -v218, v228, v226
	v_div_fmas_f32 v218, v218, v222, v228
	v_div_fixup_f32 v110, v218, v110, 1.0
	v_div_scale_f32 v227, vcc, 1.0, v111, 1.0
	v_mul_f32_e32 v228, v227, v223
	v_fma_f32 v229, -v219, v228, v227
	v_fmac_f32_e32 v228, v229, v223
	v_fma_f32 v219, -v219, v228, v227
	v_div_fmas_f32 v219, v219, v223, v228
	v_div_fixup_f32 v111, v219, v111, 1.0
	v_lshlrev_b32_e32 v230, 16, v168
	v_and_b32_e32 v168, 0xffff0000, v168
	v_lshlrev_b32_e32 v231, 16, v169
	v_and_b32_e32 v169, 0xffff0000, v169
	v_lshlrev_b32_e32 v232, 16, v170
	v_and_b32_e32 v170, 0xffff0000, v170
	v_lshlrev_b32_e32 v233, 16, v171
	v_and_b32_e32 v171, 0xffff0000, v171
	v_fma_f32 v108, v108, v232, v230
	v_fma_f32 v109, v109, v170, v168
	v_fma_f32 v110, v110, v233, v231
	v_fma_f32 v111, v111, v171, v169
	v_cvt_pk_bf16_f32 v168, v108, v109
	v_cvt_pk_bf16_f32 v169, v110, v111
	global_store_dwordx2 v192, v[168:169], s[62:63] offset:0
	v_mul_f32_e32 v104, v104, v209
	v_mul_f32_e32 v105, v105, v209
	v_mul_f32_e32 v106, v106, v209
	v_mul_f32_e32 v107, v107, v209
	v_mul_f32_e32 v104, 0xbfb8aa3b, v104
	v_mul_f32_e32 v105, 0xbfb8aa3b, v105
	v_mul_f32_e32 v106, 0xbfb8aa3b, v106
	v_mul_f32_e32 v107, 0xbfb8aa3b, v107
	v_exp_f32_e32 v104, v104
	v_exp_f32_e32 v105, v105
	v_exp_f32_e32 v106, v106
	v_exp_f32_e32 v107, v107
	v_add_f32_e32 v104, 1.0, v104
	v_add_f32_e32 v105, 1.0, v105
	v_add_f32_e32 v106, 1.0, v106
	v_add_f32_e32 v107, 1.0, v107
	v_div_scale_f32 v216, s[2:3], v104, v104, 1.0
	v_div_scale_f32 v217, s[2:3], v105, v105, 1.0
	v_div_scale_f32 v218, s[2:3], v106, v106, 1.0
	v_div_scale_f32 v219, s[2:3], v107, v107, 1.0
	v_rcp_f32_e32 v220, v216
	v_rcp_f32_e32 v221, v217
	v_rcp_f32_e32 v222, v218
	v_rcp_f32_e32 v223, v219
	v_fma_f32 v224, -v216, v220, 1.0
	v_fma_f32 v225, -v217, v221, 1.0
	v_fma_f32 v226, -v218, v222, 1.0
	v_fma_f32 v227, -v219, v223, 1.0
	v_fmac_f32_e32 v220, v224, v220
	v_fmac_f32_e32 v221, v225, v221
	v_fmac_f32_e32 v222, v226, v222
	v_fmac_f32_e32 v223, v227, v223
	v_div_scale_f32 v224, vcc, 1.0, v104, 1.0
	v_mul_f32_e32 v228, v224, v220
	v_fma_f32 v229, -v216, v228, v224
	v_fmac_f32_e32 v228, v229, v220
	v_fma_f32 v216, -v216, v228, v224
	v_div_fmas_f32 v216, v216, v220, v228
	v_div_fixup_f32 v104, v216, v104, 1.0
	v_div_scale_f32 v225, vcc, 1.0, v105, 1.0
	v_mul_f32_e32 v228, v225, v221
	v_fma_f32 v229, -v217, v228, v225
	v_fmac_f32_e32 v228, v229, v221
	v_fma_f32 v217, -v217, v228, v225
	v_div_fmas_f32 v217, v217, v221, v228
	v_div_fixup_f32 v105, v217, v105, 1.0
	v_div_scale_f32 v226, vcc, 1.0, v106, 1.0
	v_mul_f32_e32 v228, v226, v222
	v_fma_f32 v229, -v218, v228, v226
	v_fmac_f32_e32 v228, v229, v222
	v_fma_f32 v218, -v218, v228, v226
	v_div_fmas_f32 v218, v218, v222, v228
	v_div_fixup_f32 v106, v218, v106, 1.0
	v_div_scale_f32 v227, vcc, 1.0, v107, 1.0
	v_mul_f32_e32 v228, v227, v223
	v_fma_f32 v229, -v219, v228, v227
	v_fmac_f32_e32 v228, v229, v223
	v_fma_f32 v219, -v219, v228, v227
	v_div_fmas_f32 v219, v219, v223, v228
	v_div_fixup_f32 v107, v219, v107, 1.0
	v_lshlrev_b32_e32 v230, 16, v172
	v_and_b32_e32 v172, 0xffff0000, v172
	v_lshlrev_b32_e32 v231, 16, v173
	v_and_b32_e32 v173, 0xffff0000, v173
	v_lshlrev_b32_e32 v232, 16, v174
	v_and_b32_e32 v174, 0xffff0000, v174
	v_lshlrev_b32_e32 v233, 16, v175
	v_and_b32_e32 v175, 0xffff0000, v175
	v_fma_f32 v104, v104, v232, v230
	v_fma_f32 v105, v105, v174, v172
	v_fma_f32 v106, v106, v233, v231
	v_fma_f32 v107, v107, v175, v173
	v_cvt_pk_bf16_f32 v172, v104, v105
	v_cvt_pk_bf16_f32 v173, v106, v107
	global_store_dwordx2 v192, v[172:173], s[62:63] offset:32
	v_mul_f32_e32 v100, v100, v209
	v_mul_f32_e32 v101, v101, v209
	v_mul_f32_e32 v102, v102, v209
	v_mul_f32_e32 v103, v103, v209
	v_mul_f32_e32 v100, 0xbfb8aa3b, v100
	v_mul_f32_e32 v101, 0xbfb8aa3b, v101
	v_mul_f32_e32 v102, 0xbfb8aa3b, v102
	v_mul_f32_e32 v103, 0xbfb8aa3b, v103
	v_exp_f32_e32 v100, v100
	v_exp_f32_e32 v101, v101
	v_exp_f32_e32 v102, v102
	v_exp_f32_e32 v103, v103
	v_add_f32_e32 v100, 1.0, v100
	v_add_f32_e32 v101, 1.0, v101
	v_add_f32_e32 v102, 1.0, v102
	v_add_f32_e32 v103, 1.0, v103
	v_div_scale_f32 v216, s[2:3], v100, v100, 1.0
	v_div_scale_f32 v217, s[2:3], v101, v101, 1.0
	v_div_scale_f32 v218, s[2:3], v102, v102, 1.0
	v_div_scale_f32 v219, s[2:3], v103, v103, 1.0
	v_rcp_f32_e32 v220, v216
	v_rcp_f32_e32 v221, v217
	v_rcp_f32_e32 v222, v218
	v_rcp_f32_e32 v223, v219
	v_fma_f32 v224, -v216, v220, 1.0
	v_fma_f32 v225, -v217, v221, 1.0
	v_fma_f32 v226, -v218, v222, 1.0
	v_fma_f32 v227, -v219, v223, 1.0
	v_fmac_f32_e32 v220, v224, v220
	v_fmac_f32_e32 v221, v225, v221
	v_fmac_f32_e32 v222, v226, v222
	v_fmac_f32_e32 v223, v227, v223
	v_div_scale_f32 v224, vcc, 1.0, v100, 1.0
	v_mul_f32_e32 v228, v224, v220
	v_fma_f32 v229, -v216, v228, v224
	v_fmac_f32_e32 v228, v229, v220
	v_fma_f32 v216, -v216, v228, v224
	v_div_fmas_f32 v216, v216, v220, v228
	v_div_fixup_f32 v100, v216, v100, 1.0
	v_div_scale_f32 v225, vcc, 1.0, v101, 1.0
	v_mul_f32_e32 v228, v225, v221
	v_fma_f32 v229, -v217, v228, v225
	v_fmac_f32_e32 v228, v229, v221
	v_fma_f32 v217, -v217, v228, v225
	v_div_fmas_f32 v217, v217, v221, v228
	v_div_fixup_f32 v101, v217, v101, 1.0
	v_div_scale_f32 v226, vcc, 1.0, v102, 1.0
	v_mul_f32_e32 v228, v226, v222
	v_fma_f32 v229, -v218, v228, v226
	v_fmac_f32_e32 v228, v229, v222
	v_fma_f32 v218, -v218, v228, v226
	v_div_fmas_f32 v218, v218, v222, v228
	v_div_fixup_f32 v102, v218, v102, 1.0
	v_div_scale_f32 v227, vcc, 1.0, v103, 1.0
	v_mul_f32_e32 v228, v227, v223
	v_fma_f32 v229, -v219, v228, v227
	v_fmac_f32_e32 v228, v229, v223
	v_fma_f32 v219, -v219, v228, v227
	v_div_fmas_f32 v219, v219, v223, v228
	v_div_fixup_f32 v103, v219, v103, 1.0
	v_lshlrev_b32_e32 v230, 16, v240
	v_and_b32_e32 v240, 0xffff0000, v240
	v_lshlrev_b32_e32 v231, 16, v241
	v_and_b32_e32 v241, 0xffff0000, v241
	v_lshlrev_b32_e32 v232, 16, v242
	v_and_b32_e32 v242, 0xffff0000, v242
	v_lshlrev_b32_e32 v233, 16, v243
	v_and_b32_e32 v243, 0xffff0000, v243
	v_fma_f32 v100, v100, v232, v230
	v_fma_f32 v101, v101, v242, v240
	v_fma_f32 v102, v102, v233, v231
	v_fma_f32 v103, v103, v243, v241
	v_cvt_pk_bf16_f32 v240, v100, v101
	v_cvt_pk_bf16_f32 v241, v102, v103
	global_store_dwordx2 v192, v[240:241], s[62:63] offset:256
	v_mul_f32_e32 v96, v96, v209
	v_mul_f32_e32 v97, v97, v209
	v_mul_f32_e32 v98, v98, v209
	v_mul_f32_e32 v99, v99, v209
	v_mul_f32_e32 v96, 0xbfb8aa3b, v96
	v_mul_f32_e32 v97, 0xbfb8aa3b, v97
	v_mul_f32_e32 v98, 0xbfb8aa3b, v98
	v_mul_f32_e32 v99, 0xbfb8aa3b, v99
	v_exp_f32_e32 v96, v96
	v_exp_f32_e32 v97, v97
	v_exp_f32_e32 v98, v98
	v_exp_f32_e32 v99, v99
	v_add_f32_e32 v96, 1.0, v96
	v_add_f32_e32 v97, 1.0, v97
	v_add_f32_e32 v98, 1.0, v98
	v_add_f32_e32 v99, 1.0, v99
	v_div_scale_f32 v216, s[2:3], v96, v96, 1.0
	v_div_scale_f32 v217, s[2:3], v97, v97, 1.0
	v_div_scale_f32 v218, s[2:3], v98, v98, 1.0
	v_div_scale_f32 v219, s[2:3], v99, v99, 1.0
	v_rcp_f32_e32 v220, v216
	v_rcp_f32_e32 v221, v217
	v_rcp_f32_e32 v222, v218
	v_rcp_f32_e32 v223, v219
	v_fma_f32 v224, -v216, v220, 1.0
	v_fma_f32 v225, -v217, v221, 1.0
	v_fma_f32 v226, -v218, v222, 1.0
	v_fma_f32 v227, -v219, v223, 1.0
	v_fmac_f32_e32 v220, v224, v220
	v_fmac_f32_e32 v221, v225, v221
	v_fmac_f32_e32 v222, v226, v222
	v_fmac_f32_e32 v223, v227, v223
	v_div_scale_f32 v224, vcc, 1.0, v96, 1.0
	v_mul_f32_e32 v228, v224, v220
	v_fma_f32 v229, -v216, v228, v224
	v_fmac_f32_e32 v228, v229, v220
	v_fma_f32 v216, -v216, v228, v224
	v_div_fmas_f32 v216, v216, v220, v228
	v_div_fixup_f32 v96, v216, v96, 1.0
	v_div_scale_f32 v225, vcc, 1.0, v97, 1.0
	v_mul_f32_e32 v228, v225, v221
	v_fma_f32 v229, -v217, v228, v225
	v_fmac_f32_e32 v228, v229, v221
	v_fma_f32 v217, -v217, v228, v225
	v_div_fmas_f32 v217, v217, v221, v228
	v_div_fixup_f32 v97, v217, v97, 1.0
	v_div_scale_f32 v226, vcc, 1.0, v98, 1.0
	v_mul_f32_e32 v228, v226, v222
	v_fma_f32 v229, -v218, v228, v226
	v_fmac_f32_e32 v228, v229, v222
	v_fma_f32 v218, -v218, v228, v226
	v_div_fmas_f32 v218, v218, v222, v228
	v_div_fixup_f32 v98, v218, v98, 1.0
	v_div_scale_f32 v227, vcc, 1.0, v99, 1.0
	v_mul_f32_e32 v228, v227, v223
	v_fma_f32 v229, -v219, v228, v227
	v_fmac_f32_e32 v228, v229, v223
	v_fma_f32 v219, -v219, v228, v227
	v_div_fmas_f32 v219, v219, v223, v228
	v_div_fixup_f32 v99, v219, v99, 1.0
	v_lshlrev_b32_e32 v230, 16, v244
	v_and_b32_e32 v244, 0xffff0000, v244
	v_lshlrev_b32_e32 v231, 16, v245
	v_and_b32_e32 v245, 0xffff0000, v245
	v_lshlrev_b32_e32 v232, 16, v246
	v_and_b32_e32 v246, 0xffff0000, v246
	v_lshlrev_b32_e32 v233, 16, v247
	v_and_b32_e32 v247, 0xffff0000, v247
	v_fma_f32 v96, v96, v232, v230
	v_fma_f32 v97, v97, v246, v244
	v_fma_f32 v98, v98, v233, v231
	v_fma_f32 v99, v99, v247, v245
	v_cvt_pk_bf16_f32 v244, v96, v97
	v_cvt_pk_bf16_f32 v245, v98, v99
	global_store_dwordx2 v192, v[244:245], s[62:63] offset:288
	v_add_u32_e32 v196, 0x4000, v146
	global_load_dwordx4 v[96:99], v196, s[16:17]
	global_load_dwordx4 v[100:103], v196, s[16:17] offset:16
	v_add_u32_e32 v148, 0x4800, v146
	global_load_dwordx4 v[104:107], v148, s[16:17]
	global_load_dwordx4 v[108:111], v148, s[16:17] offset:16
	v_add_u32_e32 v188, 0x5000, v146
	global_load_dwordx4 v[112:115], v188, s[16:17]
	global_load_dwordx4 v[116:119], v188, s[16:17] offset:16
	v_add_u32_e32 v192, 0x5800, v146
	global_load_dwordx4 v[120:123], v192, s[16:17]
	global_load_dwordx4 v[124:127], v192, s[16:17] offset:16
	v_add_u32_e32 v196, 0x80000, v140
	global_load_dwordx2 v[152:153], v196, s[58:59] offset:0
	global_load_dwordx2 v[154:155], v196, s[56:57] offset:0
	global_load_dwordx2 v[156:157], v196, s[58:59] offset:32
	global_load_dwordx2 v[158:159], v196, s[56:57] offset:32
	global_load_dwordx2 v[160:161], v196, s[58:59] offset:256
	global_load_dwordx2 v[162:163], v196, s[56:57] offset:256
	global_load_dwordx2 v[164:165], v196, s[58:59] offset:288
	global_load_dwordx2 v[166:167], v196, s[56:57] offset:288
	v_add_u32_e32 v148, 0x90000, v140
	global_load_dwordx2 v[168:169], v148, s[58:59] offset:0
	global_load_dwordx2 v[170:171], v148, s[56:57] offset:0
	global_load_dwordx2 v[172:173], v148, s[58:59] offset:32
	global_load_dwordx2 v[174:175], v148, s[56:57] offset:32
	global_load_dwordx2 v[240:241], v148, s[58:59] offset:256
	global_load_dwordx2 v[242:243], v148, s[56:57] offset:256
	global_load_dwordx2 v[244:245], v148, s[58:59] offset:288
	global_load_dwordx2 v[246:247], v148, s[56:57] offset:288
	s_waitcnt vmcnt(32)
	v_add_u32_e32 v188, 0x20000, v140
	v_mul_f32_e32 v92, v92, v210
	v_mul_f32_e32 v93, v93, v210
	v_mul_f32_e32 v94, v94, v210
	v_mul_f32_e32 v95, v95, v210
	v_mul_f32_e32 v92, 0xbfb8aa3b, v92
	v_mul_f32_e32 v93, 0xbfb8aa3b, v93
	v_mul_f32_e32 v94, 0xbfb8aa3b, v94
	v_mul_f32_e32 v95, 0xbfb8aa3b, v95
	v_exp_f32_e32 v92, v92
	v_exp_f32_e32 v93, v93
	v_exp_f32_e32 v94, v94
	v_exp_f32_e32 v95, v95
	v_add_f32_e32 v92, 1.0, v92
	v_add_f32_e32 v93, 1.0, v93
	v_add_f32_e32 v94, 1.0, v94
	v_add_f32_e32 v95, 1.0, v95
	v_div_scale_f32 v216, s[2:3], v92, v92, 1.0
	v_div_scale_f32 v217, s[2:3], v93, v93, 1.0
	v_div_scale_f32 v218, s[2:3], v94, v94, 1.0
	v_div_scale_f32 v219, s[2:3], v95, v95, 1.0
	v_rcp_f32_e32 v220, v216
	v_rcp_f32_e32 v221, v217
	v_rcp_f32_e32 v222, v218
	v_rcp_f32_e32 v223, v219
	v_fma_f32 v224, -v216, v220, 1.0
	v_fma_f32 v225, -v217, v221, 1.0
	v_fma_f32 v226, -v218, v222, 1.0
	v_fma_f32 v227, -v219, v223, 1.0
	v_fmac_f32_e32 v220, v224, v220
	v_fmac_f32_e32 v221, v225, v221
	v_fmac_f32_e32 v222, v226, v222
	v_fmac_f32_e32 v223, v227, v223
	v_div_scale_f32 v224, vcc, 1.0, v92, 1.0
	v_mul_f32_e32 v228, v224, v220
	v_fma_f32 v229, -v216, v228, v224
	v_fmac_f32_e32 v228, v229, v220
	v_fma_f32 v216, -v216, v228, v224
	v_div_fmas_f32 v216, v216, v220, v228
	v_div_fixup_f32 v92, v216, v92, 1.0
	v_div_scale_f32 v225, vcc, 1.0, v93, 1.0
	v_mul_f32_e32 v228, v225, v221
	v_fma_f32 v229, -v217, v228, v225
	v_fmac_f32_e32 v228, v229, v221
	v_fma_f32 v217, -v217, v228, v225
	v_div_fmas_f32 v217, v217, v221, v228
	v_div_fixup_f32 v93, v217, v93, 1.0
	v_div_scale_f32 v226, vcc, 1.0, v94, 1.0
	v_mul_f32_e32 v228, v226, v222
	v_fma_f32 v229, -v218, v228, v226
	v_fmac_f32_e32 v228, v229, v222
	v_fma_f32 v218, -v218, v228, v226
	v_div_fmas_f32 v218, v218, v222, v228
	v_div_fixup_f32 v94, v218, v94, 1.0
	v_div_scale_f32 v227, vcc, 1.0, v95, 1.0
	v_mul_f32_e32 v228, v227, v223
	v_fma_f32 v229, -v219, v228, v227
	v_fmac_f32_e32 v228, v229, v223
	v_fma_f32 v219, -v219, v228, v227
	v_div_fmas_f32 v219, v219, v223, v228
	v_div_fixup_f32 v95, v219, v95, 1.0
	v_lshlrev_b32_e32 v230, 16, v182
	v_and_b32_e32 v182, 0xffff0000, v182
	v_lshlrev_b32_e32 v231, 16, v183
	v_and_b32_e32 v183, 0xffff0000, v183
	v_lshlrev_b32_e32 v232, 16, v184
	v_and_b32_e32 v184, 0xffff0000, v184
	v_lshlrev_b32_e32 v233, 16, v185
	v_and_b32_e32 v185, 0xffff0000, v185
	v_fma_f32 v92, v92, v232, v230
	v_fma_f32 v93, v93, v184, v182
	v_fma_f32 v94, v94, v233, v231
	v_fma_f32 v95, v95, v185, v183
	v_cvt_pk_bf16_f32 v182, v92, v93
	v_cvt_pk_bf16_f32 v183, v94, v95
	global_store_dwordx2 v188, v[182:183], s[62:63] offset:0
	v_mul_f32_e32 v88, v88, v210
	v_mul_f32_e32 v89, v89, v210
	v_mul_f32_e32 v90, v90, v210
	v_mul_f32_e32 v91, v91, v210
	v_mul_f32_e32 v88, 0xbfb8aa3b, v88
	v_mul_f32_e32 v89, 0xbfb8aa3b, v89
	v_mul_f32_e32 v90, 0xbfb8aa3b, v90
	v_mul_f32_e32 v91, 0xbfb8aa3b, v91
	v_exp_f32_e32 v88, v88
	v_exp_f32_e32 v89, v89
	v_exp_f32_e32 v90, v90
	v_exp_f32_e32 v91, v91
	v_add_f32_e32 v88, 1.0, v88
	v_add_f32_e32 v89, 1.0, v89
	v_add_f32_e32 v90, 1.0, v90
	v_add_f32_e32 v91, 1.0, v91
	v_div_scale_f32 v216, s[2:3], v88, v88, 1.0
	v_div_scale_f32 v217, s[2:3], v89, v89, 1.0
	v_div_scale_f32 v218, s[2:3], v90, v90, 1.0
	v_div_scale_f32 v219, s[2:3], v91, v91, 1.0
	v_rcp_f32_e32 v220, v216
	v_rcp_f32_e32 v221, v217
	v_rcp_f32_e32 v222, v218
	v_rcp_f32_e32 v223, v219
	v_fma_f32 v224, -v216, v220, 1.0
	v_fma_f32 v225, -v217, v221, 1.0
	v_fma_f32 v226, -v218, v222, 1.0
	v_fma_f32 v227, -v219, v223, 1.0
	v_fmac_f32_e32 v220, v224, v220
	v_fmac_f32_e32 v221, v225, v221
	v_fmac_f32_e32 v222, v226, v222
	v_fmac_f32_e32 v223, v227, v223
	v_div_scale_f32 v224, vcc, 1.0, v88, 1.0
	v_mul_f32_e32 v228, v224, v220
	v_fma_f32 v229, -v216, v228, v224
	v_fmac_f32_e32 v228, v229, v220
	v_fma_f32 v216, -v216, v228, v224
	v_div_fmas_f32 v216, v216, v220, v228
	v_div_fixup_f32 v88, v216, v88, 1.0
	v_div_scale_f32 v225, vcc, 1.0, v89, 1.0
	v_mul_f32_e32 v228, v225, v221
	v_fma_f32 v229, -v217, v228, v225
	v_fmac_f32_e32 v228, v229, v221
	v_fma_f32 v217, -v217, v228, v225
	v_div_fmas_f32 v217, v217, v221, v228
	v_div_fixup_f32 v89, v217, v89, 1.0
	v_div_scale_f32 v226, vcc, 1.0, v90, 1.0
	v_mul_f32_e32 v228, v226, v222
	v_fma_f32 v229, -v218, v228, v226
	v_fmac_f32_e32 v228, v229, v222
	v_fma_f32 v218, -v218, v228, v226
	v_div_fmas_f32 v218, v218, v222, v228
	v_div_fixup_f32 v90, v218, v90, 1.0
	v_div_scale_f32 v227, vcc, 1.0, v91, 1.0
	v_mul_f32_e32 v228, v227, v223
	v_fma_f32 v229, -v219, v228, v227
	v_fmac_f32_e32 v228, v229, v223
	v_fma_f32 v219, -v219, v228, v227
	v_div_fmas_f32 v219, v219, v223, v228
	v_div_fixup_f32 v91, v219, v91, 1.0
	v_lshlrev_b32_e32 v230, 16, v186
	v_and_b32_e32 v186, 0xffff0000, v186
	v_lshlrev_b32_e32 v231, 16, v187
	v_and_b32_e32 v187, 0xffff0000, v187
	v_lshlrev_b32_e32 v232, 16, v200
	v_and_b32_e32 v200, 0xffff0000, v200
	v_lshlrev_b32_e32 v233, 16, v201
	v_and_b32_e32 v201, 0xffff0000, v201
	v_fma_f32 v88, v88, v232, v230
	v_fma_f32 v89, v89, v200, v186
	v_fma_f32 v90, v90, v233, v231
	v_fma_f32 v91, v91, v201, v187
	v_cvt_pk_bf16_f32 v186, v88, v89
	v_cvt_pk_bf16_f32 v187, v90, v91
	global_store_dwordx2 v188, v[186:187], s[62:63] offset:32
	v_mul_f32_e32 v84, v84, v210
	v_mul_f32_e32 v85, v85, v210
	v_mul_f32_e32 v86, v86, v210
	v_mul_f32_e32 v87, v87, v210
	v_mul_f32_e32 v84, 0xbfb8aa3b, v84
	v_mul_f32_e32 v85, 0xbfb8aa3b, v85
	v_mul_f32_e32 v86, 0xbfb8aa3b, v86
	v_mul_f32_e32 v87, 0xbfb8aa3b, v87
	v_exp_f32_e32 v84, v84
	v_exp_f32_e32 v85, v85
	v_exp_f32_e32 v86, v86
	v_exp_f32_e32 v87, v87
	v_add_f32_e32 v84, 1.0, v84
	v_add_f32_e32 v85, 1.0, v85
	v_add_f32_e32 v86, 1.0, v86
	v_add_f32_e32 v87, 1.0, v87
	v_div_scale_f32 v216, s[2:3], v84, v84, 1.0
	v_div_scale_f32 v217, s[2:3], v85, v85, 1.0
	v_div_scale_f32 v218, s[2:3], v86, v86, 1.0
	v_div_scale_f32 v219, s[2:3], v87, v87, 1.0
	v_rcp_f32_e32 v220, v216
	v_rcp_f32_e32 v221, v217
	v_rcp_f32_e32 v222, v218
	v_rcp_f32_e32 v223, v219
	v_fma_f32 v224, -v216, v220, 1.0
	v_fma_f32 v225, -v217, v221, 1.0
	v_fma_f32 v226, -v218, v222, 1.0
	v_fma_f32 v227, -v219, v223, 1.0
	v_fmac_f32_e32 v220, v224, v220
	v_fmac_f32_e32 v221, v225, v221
	v_fmac_f32_e32 v222, v226, v222
	v_fmac_f32_e32 v223, v227, v223
	v_div_scale_f32 v224, vcc, 1.0, v84, 1.0
	v_mul_f32_e32 v228, v224, v220
	v_fma_f32 v229, -v216, v228, v224
	v_fmac_f32_e32 v228, v229, v220
	v_fma_f32 v216, -v216, v228, v224
	v_div_fmas_f32 v216, v216, v220, v228
	v_div_fixup_f32 v84, v216, v84, 1.0
	v_div_scale_f32 v225, vcc, 1.0, v85, 1.0
	v_mul_f32_e32 v228, v225, v221
	v_fma_f32 v229, -v217, v228, v225
	v_fmac_f32_e32 v228, v229, v221
	v_fma_f32 v217, -v217, v228, v225
	v_div_fmas_f32 v217, v217, v221, v228
	v_div_fixup_f32 v85, v217, v85, 1.0
	v_div_scale_f32 v226, vcc, 1.0, v86, 1.0
	v_mul_f32_e32 v228, v226, v222
	v_fma_f32 v229, -v218, v228, v226
	v_fmac_f32_e32 v228, v229, v222
	v_fma_f32 v218, -v218, v228, v226
	v_div_fmas_f32 v218, v218, v222, v228
	v_div_fixup_f32 v86, v218, v86, 1.0
	v_div_scale_f32 v227, vcc, 1.0, v87, 1.0
	v_mul_f32_e32 v228, v227, v223
	v_fma_f32 v229, -v219, v228, v227
	v_fmac_f32_e32 v228, v229, v223
	v_fma_f32 v219, -v219, v228, v227
	v_div_fmas_f32 v219, v219, v223, v228
	v_div_fixup_f32 v87, v219, v87, 1.0
	v_lshlrev_b32_e32 v230, 16, v202
	v_and_b32_e32 v202, 0xffff0000, v202
	v_lshlrev_b32_e32 v231, 16, v203
	v_and_b32_e32 v203, 0xffff0000, v203
	v_lshlrev_b32_e32 v232, 16, v204
	v_and_b32_e32 v204, 0xffff0000, v204
	v_lshlrev_b32_e32 v233, 16, v205
	v_and_b32_e32 v205, 0xffff0000, v205
	v_fma_f32 v84, v84, v232, v230
	v_fma_f32 v85, v85, v204, v202
	v_fma_f32 v86, v86, v233, v231
	v_fma_f32 v87, v87, v205, v203
	v_cvt_pk_bf16_f32 v202, v84, v85
	v_cvt_pk_bf16_f32 v203, v86, v87
	global_store_dwordx2 v188, v[202:203], s[62:63] offset:256
	v_mul_f32_e32 v80, v80, v210
	v_mul_f32_e32 v81, v81, v210
	v_mul_f32_e32 v82, v82, v210
	v_mul_f32_e32 v83, v83, v210
	v_mul_f32_e32 v80, 0xbfb8aa3b, v80
	v_mul_f32_e32 v81, 0xbfb8aa3b, v81
	v_mul_f32_e32 v82, 0xbfb8aa3b, v82
	v_mul_f32_e32 v83, 0xbfb8aa3b, v83
	v_exp_f32_e32 v80, v80
	v_exp_f32_e32 v81, v81
	v_exp_f32_e32 v82, v82
	v_exp_f32_e32 v83, v83
	v_add_f32_e32 v80, 1.0, v80
	v_add_f32_e32 v81, 1.0, v81
	v_add_f32_e32 v82, 1.0, v82
	v_add_f32_e32 v83, 1.0, v83
	v_div_scale_f32 v216, s[2:3], v80, v80, 1.0
	v_div_scale_f32 v217, s[2:3], v81, v81, 1.0
	v_div_scale_f32 v218, s[2:3], v82, v82, 1.0
	v_div_scale_f32 v219, s[2:3], v83, v83, 1.0
	v_rcp_f32_e32 v220, v216
	v_rcp_f32_e32 v221, v217
	v_rcp_f32_e32 v222, v218
	v_rcp_f32_e32 v223, v219
	v_fma_f32 v224, -v216, v220, 1.0
	v_fma_f32 v225, -v217, v221, 1.0
	v_fma_f32 v226, -v218, v222, 1.0
	v_fma_f32 v227, -v219, v223, 1.0
	v_fmac_f32_e32 v220, v224, v220
	v_fmac_f32_e32 v221, v225, v221
	v_fmac_f32_e32 v222, v226, v222
	v_fmac_f32_e32 v223, v227, v223
	v_div_scale_f32 v224, vcc, 1.0, v80, 1.0
	v_mul_f32_e32 v228, v224, v220
	v_fma_f32 v229, -v216, v228, v224
	v_fmac_f32_e32 v228, v229, v220
	v_fma_f32 v216, -v216, v228, v224
	v_div_fmas_f32 v216, v216, v220, v228
	v_div_fixup_f32 v80, v216, v80, 1.0
	v_div_scale_f32 v225, vcc, 1.0, v81, 1.0
	v_mul_f32_e32 v228, v225, v221
	v_fma_f32 v229, -v217, v228, v225
	v_fmac_f32_e32 v228, v229, v221
	v_fma_f32 v217, -v217, v228, v225
	v_div_fmas_f32 v217, v217, v221, v228
	v_div_fixup_f32 v81, v217, v81, 1.0
	v_div_scale_f32 v226, vcc, 1.0, v82, 1.0
	v_mul_f32_e32 v228, v226, v222
	v_fma_f32 v229, -v218, v228, v226
	v_fmac_f32_e32 v228, v229, v222
	v_fma_f32 v218, -v218, v228, v226
	v_div_fmas_f32 v218, v218, v222, v228
	v_div_fixup_f32 v82, v218, v82, 1.0
	v_div_scale_f32 v227, vcc, 1.0, v83, 1.0
	v_mul_f32_e32 v228, v227, v223
	v_fma_f32 v229, -v219, v228, v227
	v_fmac_f32_e32 v228, v229, v223
	v_fma_f32 v219, -v219, v228, v227
	v_div_fmas_f32 v219, v219, v223, v228
	v_div_fixup_f32 v83, v219, v83, 1.0
	v_lshlrev_b32_e32 v230, 16, v134
	v_and_b32_e32 v134, 0xffff0000, v134
	v_lshlrev_b32_e32 v231, 16, v135
	v_and_b32_e32 v135, 0xffff0000, v135
	v_lshlrev_b32_e32 v232, 16, v136
	v_and_b32_e32 v136, 0xffff0000, v136
	v_lshlrev_b32_e32 v233, 16, v137
	v_and_b32_e32 v137, 0xffff0000, v137
	v_fma_f32 v80, v80, v232, v230
	v_fma_f32 v81, v81, v136, v134
	v_fma_f32 v82, v82, v233, v231
	v_fma_f32 v83, v83, v137, v135
	v_cvt_pk_bf16_f32 v134, v80, v81
	v_cvt_pk_bf16_f32 v135, v82, v83
	global_store_dwordx2 v188, v[134:135], s[62:63] offset:288
	v_add_u32_e32 v192, 0x30000, v140
	v_mul_f32_e32 v76, v76, v211
	v_mul_f32_e32 v77, v77, v211
	v_mul_f32_e32 v78, v78, v211
	v_mul_f32_e32 v79, v79, v211
	v_mul_f32_e32 v76, 0xbfb8aa3b, v76
	v_mul_f32_e32 v77, 0xbfb8aa3b, v77
	v_mul_f32_e32 v78, 0xbfb8aa3b, v78
	v_mul_f32_e32 v79, 0xbfb8aa3b, v79
	v_exp_f32_e32 v76, v76
	v_exp_f32_e32 v77, v77
	v_exp_f32_e32 v78, v78
	v_exp_f32_e32 v79, v79
	v_add_f32_e32 v76, 1.0, v76
	v_add_f32_e32 v77, 1.0, v77
	v_add_f32_e32 v78, 1.0, v78
	v_add_f32_e32 v79, 1.0, v79
	v_div_scale_f32 v216, s[2:3], v76, v76, 1.0
	v_div_scale_f32 v217, s[2:3], v77, v77, 1.0
	v_div_scale_f32 v218, s[2:3], v78, v78, 1.0
	v_div_scale_f32 v219, s[2:3], v79, v79, 1.0
	v_rcp_f32_e32 v220, v216
	v_rcp_f32_e32 v221, v217
	v_rcp_f32_e32 v222, v218
	v_rcp_f32_e32 v223, v219
	v_fma_f32 v224, -v216, v220, 1.0
	v_fma_f32 v225, -v217, v221, 1.0
	v_fma_f32 v226, -v218, v222, 1.0
	v_fma_f32 v227, -v219, v223, 1.0
	v_fmac_f32_e32 v220, v224, v220
	v_fmac_f32_e32 v221, v225, v221
	v_fmac_f32_e32 v222, v226, v222
	v_fmac_f32_e32 v223, v227, v223
	v_div_scale_f32 v224, vcc, 1.0, v76, 1.0
	v_mul_f32_e32 v228, v224, v220
	v_fma_f32 v229, -v216, v228, v224
	v_fmac_f32_e32 v228, v229, v220
	v_fma_f32 v216, -v216, v228, v224
	v_div_fmas_f32 v216, v216, v220, v228
	v_div_fixup_f32 v76, v216, v76, 1.0
	v_div_scale_f32 v225, vcc, 1.0, v77, 1.0
	v_mul_f32_e32 v228, v225, v221
	v_fma_f32 v229, -v217, v228, v225
	v_fmac_f32_e32 v228, v229, v221
	v_fma_f32 v217, -v217, v228, v225
	v_div_fmas_f32 v217, v217, v221, v228
	v_div_fixup_f32 v77, v217, v77, 1.0
	v_div_scale_f32 v226, vcc, 1.0, v78, 1.0
	v_mul_f32_e32 v228, v226, v222
	v_fma_f32 v229, -v218, v228, v226
	v_fmac_f32_e32 v228, v229, v222
	v_fma_f32 v218, -v218, v228, v226
	v_div_fmas_f32 v218, v218, v222, v228
	v_div_fixup_f32 v78, v218, v78, 1.0
	v_div_scale_f32 v227, vcc, 1.0, v79, 1.0
	v_mul_f32_e32 v228, v227, v223
	v_fma_f32 v229, -v219, v228, v227
	v_fmac_f32_e32 v228, v229, v223
	v_fma_f32 v219, -v219, v228, v227
	v_div_fmas_f32 v219, v219, v223, v228
	v_div_fixup_f32 v79, v219, v79, 1.0
	v_lshlrev_b32_e32 v230, 16, v138
	v_and_b32_e32 v138, 0xffff0000, v138
	v_lshlrev_b32_e32 v231, 16, v139
	v_and_b32_e32 v139, 0xffff0000, v139
	v_lshlrev_b32_e32 v232, 16, v142
	v_and_b32_e32 v142, 0xffff0000, v142
	v_lshlrev_b32_e32 v233, 16, v143
	v_and_b32_e32 v143, 0xffff0000, v143
	v_fma_f32 v76, v76, v232, v230
	v_fma_f32 v77, v77, v142, v138
	v_fma_f32 v78, v78, v233, v231
	v_fma_f32 v79, v79, v143, v139
	v_cvt_pk_bf16_f32 v138, v76, v77
	v_cvt_pk_bf16_f32 v139, v78, v79
	global_store_dwordx2 v192, v[138:139], s[62:63] offset:0
	v_mul_f32_e32 v72, v72, v211
	v_mul_f32_e32 v73, v73, v211
	v_mul_f32_e32 v74, v74, v211
	v_mul_f32_e32 v75, v75, v211
	v_mul_f32_e32 v72, 0xbfb8aa3b, v72
	v_mul_f32_e32 v73, 0xbfb8aa3b, v73
	v_mul_f32_e32 v74, 0xbfb8aa3b, v74
	v_mul_f32_e32 v75, 0xbfb8aa3b, v75
	v_exp_f32_e32 v72, v72
	v_exp_f32_e32 v73, v73
	v_exp_f32_e32 v74, v74
	v_exp_f32_e32 v75, v75
	v_add_f32_e32 v72, 1.0, v72
	v_add_f32_e32 v73, 1.0, v73
	v_add_f32_e32 v74, 1.0, v74
	v_add_f32_e32 v75, 1.0, v75
	v_div_scale_f32 v216, s[2:3], v72, v72, 1.0
	v_div_scale_f32 v217, s[2:3], v73, v73, 1.0
	v_div_scale_f32 v218, s[2:3], v74, v74, 1.0
	v_div_scale_f32 v219, s[2:3], v75, v75, 1.0
	v_rcp_f32_e32 v220, v216
	v_rcp_f32_e32 v221, v217
	v_rcp_f32_e32 v222, v218
	v_rcp_f32_e32 v223, v219
	v_fma_f32 v224, -v216, v220, 1.0
	v_fma_f32 v225, -v217, v221, 1.0
	v_fma_f32 v226, -v218, v222, 1.0
	v_fma_f32 v227, -v219, v223, 1.0
	v_fmac_f32_e32 v220, v224, v220
	v_fmac_f32_e32 v221, v225, v221
	v_fmac_f32_e32 v222, v226, v222
	v_fmac_f32_e32 v223, v227, v223
	v_div_scale_f32 v224, vcc, 1.0, v72, 1.0
	v_mul_f32_e32 v228, v224, v220
	v_fma_f32 v229, -v216, v228, v224
	v_fmac_f32_e32 v228, v229, v220
	v_fma_f32 v216, -v216, v228, v224
	v_div_fmas_f32 v216, v216, v220, v228
	v_div_fixup_f32 v72, v216, v72, 1.0
	v_div_scale_f32 v225, vcc, 1.0, v73, 1.0
	v_mul_f32_e32 v228, v225, v221
	v_fma_f32 v229, -v217, v228, v225
	v_fmac_f32_e32 v228, v229, v221
	v_fma_f32 v217, -v217, v228, v225
	v_div_fmas_f32 v217, v217, v221, v228
	v_div_fixup_f32 v73, v217, v73, 1.0
	v_div_scale_f32 v226, vcc, 1.0, v74, 1.0
	v_mul_f32_e32 v228, v226, v222
	v_fma_f32 v229, -v218, v228, v226
	v_fmac_f32_e32 v228, v229, v222
	v_fma_f32 v218, -v218, v228, v226
	v_div_fmas_f32 v218, v218, v222, v228
	v_div_fixup_f32 v74, v218, v74, 1.0
	v_div_scale_f32 v227, vcc, 1.0, v75, 1.0
	v_mul_f32_e32 v228, v227, v223
	v_fma_f32 v229, -v219, v228, v227
	v_fmac_f32_e32 v228, v229, v223
	v_fma_f32 v219, -v219, v228, v227
	v_div_fmas_f32 v219, v219, v223, v228
	v_div_fixup_f32 v75, v219, v75, 1.0
	v_lshlrev_b32_e32 v230, 16, v144
	v_and_b32_e32 v144, 0xffff0000, v144
	v_lshlrev_b32_e32 v231, 16, v145
	v_and_b32_e32 v145, 0xffff0000, v145
	v_lshlrev_b32_e32 v232, 16, v190
	v_and_b32_e32 v190, 0xffff0000, v190
	v_lshlrev_b32_e32 v233, 16, v191
	v_and_b32_e32 v191, 0xffff0000, v191
	v_fma_f32 v72, v72, v232, v230
	v_fma_f32 v73, v73, v190, v144
	v_fma_f32 v74, v74, v233, v231
	v_fma_f32 v75, v75, v191, v145
	v_cvt_pk_bf16_f32 v144, v72, v73
	v_cvt_pk_bf16_f32 v145, v74, v75
	global_store_dwordx2 v192, v[144:145], s[62:63] offset:32
	v_mul_f32_e32 v68, v68, v211
	v_mul_f32_e32 v69, v69, v211
	v_mul_f32_e32 v70, v70, v211
	v_mul_f32_e32 v71, v71, v211
	v_mul_f32_e32 v68, 0xbfb8aa3b, v68
	v_mul_f32_e32 v69, 0xbfb8aa3b, v69
	v_mul_f32_e32 v70, 0xbfb8aa3b, v70
	v_mul_f32_e32 v71, 0xbfb8aa3b, v71
	v_exp_f32_e32 v68, v68
	v_exp_f32_e32 v69, v69
	v_exp_f32_e32 v70, v70
	v_exp_f32_e32 v71, v71
	v_add_f32_e32 v68, 1.0, v68
	v_add_f32_e32 v69, 1.0, v69
	v_add_f32_e32 v70, 1.0, v70
	v_add_f32_e32 v71, 1.0, v71
	v_div_scale_f32 v216, s[2:3], v68, v68, 1.0
	v_div_scale_f32 v217, s[2:3], v69, v69, 1.0
	v_div_scale_f32 v218, s[2:3], v70, v70, 1.0
	v_div_scale_f32 v219, s[2:3], v71, v71, 1.0
	v_rcp_f32_e32 v220, v216
	v_rcp_f32_e32 v221, v217
	v_rcp_f32_e32 v222, v218
	v_rcp_f32_e32 v223, v219
	v_fma_f32 v224, -v216, v220, 1.0
	v_fma_f32 v225, -v217, v221, 1.0
	v_fma_f32 v226, -v218, v222, 1.0
	v_fma_f32 v227, -v219, v223, 1.0
	v_fmac_f32_e32 v220, v224, v220
	v_fmac_f32_e32 v221, v225, v221
	v_fmac_f32_e32 v222, v226, v222
	v_fmac_f32_e32 v223, v227, v223
	v_div_scale_f32 v224, vcc, 1.0, v68, 1.0
	v_mul_f32_e32 v228, v224, v220
	v_fma_f32 v229, -v216, v228, v224
	v_fmac_f32_e32 v228, v229, v220
	v_fma_f32 v216, -v216, v228, v224
	v_div_fmas_f32 v216, v216, v220, v228
	v_div_fixup_f32 v68, v216, v68, 1.0
	v_div_scale_f32 v225, vcc, 1.0, v69, 1.0
	v_mul_f32_e32 v228, v225, v221
	v_fma_f32 v229, -v217, v228, v225
	v_fmac_f32_e32 v228, v229, v221
	v_fma_f32 v217, -v217, v228, v225
	v_div_fmas_f32 v217, v217, v221, v228
	v_div_fixup_f32 v69, v217, v69, 1.0
	v_div_scale_f32 v226, vcc, 1.0, v70, 1.0
	v_mul_f32_e32 v228, v226, v222
	v_fma_f32 v229, -v218, v228, v226
	v_fmac_f32_e32 v228, v229, v222
	v_fma_f32 v218, -v218, v228, v226
	v_div_fmas_f32 v218, v218, v222, v228
	v_div_fixup_f32 v70, v218, v70, 1.0
	v_div_scale_f32 v227, vcc, 1.0, v71, 1.0
	v_mul_f32_e32 v228, v227, v223
	v_fma_f32 v229, -v219, v228, v227
	v_fmac_f32_e32 v228, v229, v223
	v_fma_f32 v219, -v219, v228, v227
	v_div_fmas_f32 v219, v219, v223, v228
	v_div_fixup_f32 v71, v219, v71, 1.0
	v_lshlrev_b32_e32 v230, 16, v194
	v_and_b32_e32 v194, 0xffff0000, v194
	v_lshlrev_b32_e32 v231, 16, v195
	v_and_b32_e32 v195, 0xffff0000, v195
	v_lshlrev_b32_e32 v232, 16, v248
	v_and_b32_e32 v248, 0xffff0000, v248
	v_lshlrev_b32_e32 v233, 16, v249
	v_and_b32_e32 v249, 0xffff0000, v249
	v_fma_f32 v68, v68, v232, v230
	v_fma_f32 v69, v69, v248, v194
	v_fma_f32 v70, v70, v233, v231
	v_fma_f32 v71, v71, v249, v195
	v_cvt_pk_bf16_f32 v194, v68, v69
	v_cvt_pk_bf16_f32 v195, v70, v71
	global_store_dwordx2 v192, v[194:195], s[62:63] offset:256
	v_mul_f32_e32 v64, v64, v211
	v_mul_f32_e32 v65, v65, v211
	v_mul_f32_e32 v66, v66, v211
	v_mul_f32_e32 v67, v67, v211
	v_mul_f32_e32 v64, 0xbfb8aa3b, v64
	v_mul_f32_e32 v65, 0xbfb8aa3b, v65
	v_mul_f32_e32 v66, 0xbfb8aa3b, v66
	v_mul_f32_e32 v67, 0xbfb8aa3b, v67
	v_exp_f32_e32 v64, v64
	v_exp_f32_e32 v65, v65
	v_exp_f32_e32 v66, v66
	v_exp_f32_e32 v67, v67
	v_add_f32_e32 v64, 1.0, v64
	v_add_f32_e32 v65, 1.0, v65
	v_add_f32_e32 v66, 1.0, v66
	v_add_f32_e32 v67, 1.0, v67
	v_div_scale_f32 v216, s[2:3], v64, v64, 1.0
	v_div_scale_f32 v217, s[2:3], v65, v65, 1.0
	v_div_scale_f32 v218, s[2:3], v66, v66, 1.0
	v_div_scale_f32 v219, s[2:3], v67, v67, 1.0
	v_rcp_f32_e32 v220, v216
	v_rcp_f32_e32 v221, v217
	v_rcp_f32_e32 v222, v218
	v_rcp_f32_e32 v223, v219
	v_fma_f32 v224, -v216, v220, 1.0
	v_fma_f32 v225, -v217, v221, 1.0
	v_fma_f32 v226, -v218, v222, 1.0
	v_fma_f32 v227, -v219, v223, 1.0
	v_fmac_f32_e32 v220, v224, v220
	v_fmac_f32_e32 v221, v225, v221
	v_fmac_f32_e32 v222, v226, v222
	v_fmac_f32_e32 v223, v227, v223
	v_div_scale_f32 v224, vcc, 1.0, v64, 1.0
	v_mul_f32_e32 v228, v224, v220
	v_fma_f32 v229, -v216, v228, v224
	v_fmac_f32_e32 v228, v229, v220
	v_fma_f32 v216, -v216, v228, v224
	v_div_fmas_f32 v216, v216, v220, v228
	v_div_fixup_f32 v64, v216, v64, 1.0
	v_div_scale_f32 v225, vcc, 1.0, v65, 1.0
	v_mul_f32_e32 v228, v225, v221
	v_fma_f32 v229, -v217, v228, v225
	v_fmac_f32_e32 v228, v229, v221
	v_fma_f32 v217, -v217, v228, v225
	v_div_fmas_f32 v217, v217, v221, v228
	v_div_fixup_f32 v65, v217, v65, 1.0
	v_div_scale_f32 v226, vcc, 1.0, v66, 1.0
	v_mul_f32_e32 v228, v226, v222
	v_fma_f32 v229, -v218, v228, v226
	v_fmac_f32_e32 v228, v229, v222
	v_fma_f32 v218, -v218, v228, v226
	v_div_fmas_f32 v218, v218, v222, v228
	v_div_fixup_f32 v66, v218, v66, 1.0
	v_div_scale_f32 v227, vcc, 1.0, v67, 1.0
	v_mul_f32_e32 v228, v227, v223
	v_fma_f32 v229, -v219, v228, v227
	v_fmac_f32_e32 v228, v229, v223
	v_fma_f32 v219, -v219, v228, v227
	v_div_fmas_f32 v219, v219, v223, v228
	v_div_fixup_f32 v67, v219, v67, 1.0
	v_lshlrev_b32_e32 v230, 16, v150
	v_and_b32_e32 v150, 0xffff0000, v150
	v_lshlrev_b32_e32 v231, 16, v151
	v_and_b32_e32 v151, 0xffff0000, v151
	v_lshlrev_b32_e32 v232, 16, v238
	v_and_b32_e32 v238, 0xffff0000, v238
	v_lshlrev_b32_e32 v233, 16, v239
	v_and_b32_e32 v239, 0xffff0000, v239
	v_fma_f32 v64, v64, v232, v230
	v_fma_f32 v65, v65, v238, v150
	v_fma_f32 v66, v66, v233, v231
	v_fma_f32 v67, v67, v239, v151
	v_cvt_pk_bf16_f32 v150, v64, v65
	v_cvt_pk_bf16_f32 v151, v66, v67
	global_store_dwordx2 v192, v[150:151], s[62:63] offset:288
	v_add_u32_e32 v196, 0xa0000, v140
	global_load_dwordx2 v[182:183], v196, s[58:59] offset:0
	global_load_dwordx2 v[184:185], v196, s[56:57] offset:0
	global_load_dwordx2 v[186:187], v196, s[58:59] offset:32
	global_load_dwordx2 v[200:201], v196, s[56:57] offset:32
	global_load_dwordx2 v[202:203], v196, s[58:59] offset:256
	global_load_dwordx2 v[204:205], v196, s[56:57] offset:256
	global_load_dwordx2 v[134:135], v196, s[58:59] offset:288
	global_load_dwordx2 v[136:137], v196, s[56:57] offset:288
	v_add_u32_e32 v148, 0xb0000, v140
	global_load_dwordx2 v[138:139], v148, s[58:59] offset:0
	global_load_dwordx2 v[142:143], v148, s[56:57] offset:0
	global_load_dwordx2 v[144:145], v148, s[58:59] offset:32
	global_load_dwordx2 v[190:191], v148, s[56:57] offset:32
	global_load_dwordx2 v[194:195], v148, s[58:59] offset:256
	global_load_dwordx2 v[248:249], v148, s[56:57] offset:256
	global_load_dwordx2 v[150:151], v148, s[58:59] offset:288
	v_add_u32_e32 v188, 0xb0000, v140
	global_load_dwordx2 v[234:235], v188, s[56:57] offset:288
	s_waitcnt vmcnt(40)
	v_add_f32_e32 v96, v96, v97
	v_add_f32_e32 v98, v98, v99
	v_add_f32_e32 v100, v100, v101
	v_add_f32_e32 v102, v102, v103
	v_add_f32_e32 v96, v96, v98
	v_add_f32_e32 v100, v100, v102
	v_add_f32_e32 v96, v96, v100
	v_add_f32_e32 v104, v104, v105
	v_add_f32_e32 v106, v106, v107
	v_add_f32_e32 v108, v108, v109
	v_add_f32_e32 v110, v110, v111
	v_add_f32_e32 v104, v104, v106
	v_add_f32_e32 v108, v108, v110
	v_add_f32_e32 v104, v104, v108
	v_add_f32_e32 v112, v112, v113
	v_add_f32_e32 v114, v114, v115
	v_add_f32_e32 v116, v116, v117
	v_add_f32_e32 v118, v118, v119
	v_add_f32_e32 v112, v112, v114
	v_add_f32_e32 v116, v116, v118
	v_add_f32_e32 v112, v112, v116
	v_add_f32_e32 v120, v120, v121
	v_add_f32_e32 v122, v122, v123
	v_add_f32_e32 v124, v124, v125
	v_add_f32_e32 v126, v126, v127
	v_add_f32_e32 v120, v120, v122
	v_add_f32_e32 v124, v124, v126
	v_add_f32_e32 v120, v120, v124
	ds_bpermute_b32 v97, v207, v96
	ds_bpermute_b32 v105, v207, v104
	ds_bpermute_b32 v113, v207, v112
	ds_bpermute_b32 v121, v207, v120
	s_waitcnt lgkmcnt(0)
	v_add_f32_e32 v96, v96, v97
	v_add_f32_e32 v104, v104, v105
	v_add_f32_e32 v112, v112, v113
	v_add_f32_e32 v120, v120, v121
	ds_bpermute_b32 v97, v206, v96
	ds_bpermute_b32 v105, v206, v104
	ds_bpermute_b32 v113, v206, v112
	ds_bpermute_b32 v121, v206, v120
	s_waitcnt lgkmcnt(0)
	v_add_f32_e32 v96, v96, v97
	v_add_f32_e32 v104, v104, v105
	v_add_f32_e32 v112, v112, v113
	v_add_f32_e32 v120, v120, v121
	v_mul_f32_e32 v96, 0x3a000000, v96
	v_add_f32_e32 v96, 0x358637bd, v96
	v_mul_f32_e32 v104, 0x3a000000, v104
	v_add_f32_e32 v104, 0x358637bd, v104
	v_mul_f32_e32 v112, 0x3a000000, v112
	v_add_f32_e32 v112, 0x358637bd, v112
	v_mul_f32_e32 v120, 0x3a000000, v120
	v_add_f32_e32 v120, 0x358637bd, v120
	v_rsq_f32_e32 v96, v96
	v_rsq_f32_e32 v104, v104
	v_rsq_f32_e32 v112, v112
	v_rsq_f32_e32 v120, v120
	s_nop 0
	v_mov_b32_e32 v212, v96
	v_mov_b32_e32 v213, v104
	v_mov_b32_e32 v214, v112
	v_mov_b32_e32 v215, v120
	s_waitcnt vmcnt(24)
	v_add_u32_e32 v192, 0x80000, v140
	v_mul_f32_e32 v60, v60, v212
	v_mul_f32_e32 v61, v61, v212
	v_mul_f32_e32 v62, v62, v212
	v_mul_f32_e32 v63, v63, v212
	v_mul_f32_e32 v60, 0xbfb8aa3b, v60
	v_mul_f32_e32 v61, 0xbfb8aa3b, v61
	v_mul_f32_e32 v62, 0xbfb8aa3b, v62
	v_mul_f32_e32 v63, 0xbfb8aa3b, v63
	v_exp_f32_e32 v60, v60
	v_exp_f32_e32 v61, v61
	v_exp_f32_e32 v62, v62
	v_exp_f32_e32 v63, v63
	v_add_f32_e32 v60, 1.0, v60
	v_add_f32_e32 v61, 1.0, v61
	v_add_f32_e32 v62, 1.0, v62
	v_add_f32_e32 v63, 1.0, v63
	v_div_scale_f32 v216, s[2:3], v60, v60, 1.0
	v_div_scale_f32 v217, s[2:3], v61, v61, 1.0
	v_div_scale_f32 v218, s[2:3], v62, v62, 1.0
	v_div_scale_f32 v219, s[2:3], v63, v63, 1.0
	v_rcp_f32_e32 v220, v216
	v_rcp_f32_e32 v221, v217
	v_rcp_f32_e32 v222, v218
	v_rcp_f32_e32 v223, v219
	v_fma_f32 v224, -v216, v220, 1.0
	v_fma_f32 v225, -v217, v221, 1.0
	v_fma_f32 v226, -v218, v222, 1.0
	v_fma_f32 v227, -v219, v223, 1.0
	v_fmac_f32_e32 v220, v224, v220
	v_fmac_f32_e32 v221, v225, v221
	v_fmac_f32_e32 v222, v226, v222
	v_fmac_f32_e32 v223, v227, v223
	v_div_scale_f32 v224, vcc, 1.0, v60, 1.0
	v_mul_f32_e32 v228, v224, v220
	v_fma_f32 v229, -v216, v228, v224
	v_fmac_f32_e32 v228, v229, v220
	v_fma_f32 v216, -v216, v228, v224
	v_div_fmas_f32 v216, v216, v220, v228
	v_div_fixup_f32 v60, v216, v60, 1.0
	v_div_scale_f32 v225, vcc, 1.0, v61, 1.0
	v_mul_f32_e32 v228, v225, v221
	v_fma_f32 v229, -v217, v228, v225
	v_fmac_f32_e32 v228, v229, v221
	v_fma_f32 v217, -v217, v228, v225
	v_div_fmas_f32 v217, v217, v221, v228
	v_div_fixup_f32 v61, v217, v61, 1.0
	v_div_scale_f32 v226, vcc, 1.0, v62, 1.0
	v_mul_f32_e32 v228, v226, v222
	v_fma_f32 v229, -v218, v228, v226
	v_fmac_f32_e32 v228, v229, v222
	v_fma_f32 v218, -v218, v228, v226
	v_div_fmas_f32 v218, v218, v222, v228
	v_div_fixup_f32 v62, v218, v62, 1.0
	v_div_scale_f32 v227, vcc, 1.0, v63, 1.0
	v_mul_f32_e32 v228, v227, v223
	v_fma_f32 v229, -v219, v228, v227
	v_fmac_f32_e32 v228, v229, v223
	v_fma_f32 v219, -v219, v228, v227
	v_div_fmas_f32 v219, v219, v223, v228
	v_div_fixup_f32 v63, v219, v63, 1.0
	v_lshlrev_b32_e32 v230, 16, v152
	v_and_b32_e32 v152, 0xffff0000, v152
	v_lshlrev_b32_e32 v231, 16, v153
	v_and_b32_e32 v153, 0xffff0000, v153
	v_lshlrev_b32_e32 v232, 16, v154
	v_and_b32_e32 v154, 0xffff0000, v154
	v_lshlrev_b32_e32 v233, 16, v155
	v_and_b32_e32 v155, 0xffff0000, v155
	v_fma_f32 v60, v60, v232, v230
	v_fma_f32 v61, v61, v154, v152
	v_fma_f32 v62, v62, v233, v231
	v_fma_f32 v63, v63, v155, v153
	v_cvt_pk_bf16_f32 v152, v60, v61
	v_cvt_pk_bf16_f32 v153, v62, v63
	global_store_dwordx2 v192, v[152:153], s[62:63] offset:0
	v_mul_f32_e32 v56, v56, v212
	v_mul_f32_e32 v57, v57, v212
	v_mul_f32_e32 v58, v58, v212
	v_mul_f32_e32 v59, v59, v212
	v_mul_f32_e32 v56, 0xbfb8aa3b, v56
	v_mul_f32_e32 v57, 0xbfb8aa3b, v57
	v_mul_f32_e32 v58, 0xbfb8aa3b, v58
	v_mul_f32_e32 v59, 0xbfb8aa3b, v59
	v_exp_f32_e32 v56, v56
	v_exp_f32_e32 v57, v57
	v_exp_f32_e32 v58, v58
	v_exp_f32_e32 v59, v59
	v_add_f32_e32 v56, 1.0, v56
	v_add_f32_e32 v57, 1.0, v57
	v_add_f32_e32 v58, 1.0, v58
	v_add_f32_e32 v59, 1.0, v59
	v_div_scale_f32 v216, s[2:3], v56, v56, 1.0
	v_div_scale_f32 v217, s[2:3], v57, v57, 1.0
	v_div_scale_f32 v218, s[2:3], v58, v58, 1.0
	v_div_scale_f32 v219, s[2:3], v59, v59, 1.0
	v_rcp_f32_e32 v220, v216
	v_rcp_f32_e32 v221, v217
	v_rcp_f32_e32 v222, v218
	v_rcp_f32_e32 v223, v219
	v_fma_f32 v224, -v216, v220, 1.0
	v_fma_f32 v225, -v217, v221, 1.0
	v_fma_f32 v226, -v218, v222, 1.0
	v_fma_f32 v227, -v219, v223, 1.0
	v_fmac_f32_e32 v220, v224, v220
	v_fmac_f32_e32 v221, v225, v221
	v_fmac_f32_e32 v222, v226, v222
	v_fmac_f32_e32 v223, v227, v223
	v_div_scale_f32 v224, vcc, 1.0, v56, 1.0
	v_mul_f32_e32 v228, v224, v220
	v_fma_f32 v229, -v216, v228, v224
	v_fmac_f32_e32 v228, v229, v220
	v_fma_f32 v216, -v216, v228, v224
	v_div_fmas_f32 v216, v216, v220, v228
	v_div_fixup_f32 v56, v216, v56, 1.0
	v_div_scale_f32 v225, vcc, 1.0, v57, 1.0
	v_mul_f32_e32 v228, v225, v221
	v_fma_f32 v229, -v217, v228, v225
	v_fmac_f32_e32 v228, v229, v221
	v_fma_f32 v217, -v217, v228, v225
	v_div_fmas_f32 v217, v217, v221, v228
	v_div_fixup_f32 v57, v217, v57, 1.0
	v_div_scale_f32 v226, vcc, 1.0, v58, 1.0
	v_mul_f32_e32 v228, v226, v222
	v_fma_f32 v229, -v218, v228, v226
	v_fmac_f32_e32 v228, v229, v222
	v_fma_f32 v218, -v218, v228, v226
	v_div_fmas_f32 v218, v218, v222, v228
	v_div_fixup_f32 v58, v218, v58, 1.0
	v_div_scale_f32 v227, vcc, 1.0, v59, 1.0
	v_mul_f32_e32 v228, v227, v223
	v_fma_f32 v229, -v219, v228, v227
	v_fmac_f32_e32 v228, v229, v223
	v_fma_f32 v219, -v219, v228, v227
	v_div_fmas_f32 v219, v219, v223, v228
	v_div_fixup_f32 v59, v219, v59, 1.0
	v_lshlrev_b32_e32 v230, 16, v156
	v_and_b32_e32 v156, 0xffff0000, v156
	v_lshlrev_b32_e32 v231, 16, v157
	v_and_b32_e32 v157, 0xffff0000, v157
	v_lshlrev_b32_e32 v232, 16, v158
	v_and_b32_e32 v158, 0xffff0000, v158
	v_lshlrev_b32_e32 v233, 16, v159
	v_and_b32_e32 v159, 0xffff0000, v159
	v_fma_f32 v56, v56, v232, v230
	v_fma_f32 v57, v57, v158, v156
	v_fma_f32 v58, v58, v233, v231
	v_fma_f32 v59, v59, v159, v157
	v_cvt_pk_bf16_f32 v156, v56, v57
	v_cvt_pk_bf16_f32 v157, v58, v59
	global_store_dwordx2 v192, v[156:157], s[62:63] offset:32
	v_mul_f32_e32 v52, v52, v212
	v_mul_f32_e32 v53, v53, v212
	v_mul_f32_e32 v54, v54, v212
	v_mul_f32_e32 v55, v55, v212
	v_mul_f32_e32 v52, 0xbfb8aa3b, v52
	v_mul_f32_e32 v53, 0xbfb8aa3b, v53
	v_mul_f32_e32 v54, 0xbfb8aa3b, v54
	v_mul_f32_e32 v55, 0xbfb8aa3b, v55
	v_exp_f32_e32 v52, v52
	v_exp_f32_e32 v53, v53
	v_exp_f32_e32 v54, v54
	v_exp_f32_e32 v55, v55
	v_add_f32_e32 v52, 1.0, v52
	v_add_f32_e32 v53, 1.0, v53
	v_add_f32_e32 v54, 1.0, v54
	v_add_f32_e32 v55, 1.0, v55
	v_div_scale_f32 v216, s[2:3], v52, v52, 1.0
	v_div_scale_f32 v217, s[2:3], v53, v53, 1.0
	v_div_scale_f32 v218, s[2:3], v54, v54, 1.0
	v_div_scale_f32 v219, s[2:3], v55, v55, 1.0
	v_rcp_f32_e32 v220, v216
	v_rcp_f32_e32 v221, v217
	v_rcp_f32_e32 v222, v218
	v_rcp_f32_e32 v223, v219
	v_fma_f32 v224, -v216, v220, 1.0
	v_fma_f32 v225, -v217, v221, 1.0
	v_fma_f32 v226, -v218, v222, 1.0
	v_fma_f32 v227, -v219, v223, 1.0
	v_fmac_f32_e32 v220, v224, v220
	v_fmac_f32_e32 v221, v225, v221
	v_fmac_f32_e32 v222, v226, v222
	v_fmac_f32_e32 v223, v227, v223
	v_div_scale_f32 v224, vcc, 1.0, v52, 1.0
	v_mul_f32_e32 v228, v224, v220
	v_fma_f32 v229, -v216, v228, v224
	v_fmac_f32_e32 v228, v229, v220
	v_fma_f32 v216, -v216, v228, v224
	v_div_fmas_f32 v216, v216, v220, v228
	v_div_fixup_f32 v52, v216, v52, 1.0
	v_div_scale_f32 v225, vcc, 1.0, v53, 1.0
	v_mul_f32_e32 v228, v225, v221
	v_fma_f32 v229, -v217, v228, v225
	v_fmac_f32_e32 v228, v229, v221
	v_fma_f32 v217, -v217, v228, v225
	v_div_fmas_f32 v217, v217, v221, v228
	v_div_fixup_f32 v53, v217, v53, 1.0
	v_div_scale_f32 v226, vcc, 1.0, v54, 1.0
	v_mul_f32_e32 v228, v226, v222
	v_fma_f32 v229, -v218, v228, v226
	v_fmac_f32_e32 v228, v229, v222
	v_fma_f32 v218, -v218, v228, v226
	v_div_fmas_f32 v218, v218, v222, v228
	v_div_fixup_f32 v54, v218, v54, 1.0
	v_div_scale_f32 v227, vcc, 1.0, v55, 1.0
	v_mul_f32_e32 v228, v227, v223
	v_fma_f32 v229, -v219, v228, v227
	v_fmac_f32_e32 v228, v229, v223
	v_fma_f32 v219, -v219, v228, v227
	v_div_fmas_f32 v219, v219, v223, v228
	v_div_fixup_f32 v55, v219, v55, 1.0
	v_lshlrev_b32_e32 v230, 16, v160
	v_and_b32_e32 v160, 0xffff0000, v160
	v_lshlrev_b32_e32 v231, 16, v161
	v_and_b32_e32 v161, 0xffff0000, v161
	v_lshlrev_b32_e32 v232, 16, v162
	v_and_b32_e32 v162, 0xffff0000, v162
	v_lshlrev_b32_e32 v233, 16, v163
	v_and_b32_e32 v163, 0xffff0000, v163
	v_fma_f32 v52, v52, v232, v230
	v_fma_f32 v53, v53, v162, v160
	v_fma_f32 v54, v54, v233, v231
	v_fma_f32 v55, v55, v163, v161
	v_cvt_pk_bf16_f32 v160, v52, v53
	v_cvt_pk_bf16_f32 v161, v54, v55
	global_store_dwordx2 v192, v[160:161], s[62:63] offset:256
	v_mul_f32_e32 v48, v48, v212
	v_mul_f32_e32 v49, v49, v212
	v_mul_f32_e32 v50, v50, v212
	v_mul_f32_e32 v51, v51, v212
	v_mul_f32_e32 v48, 0xbfb8aa3b, v48
	v_mul_f32_e32 v49, 0xbfb8aa3b, v49
	v_mul_f32_e32 v50, 0xbfb8aa3b, v50
	v_mul_f32_e32 v51, 0xbfb8aa3b, v51
	v_exp_f32_e32 v48, v48
	v_exp_f32_e32 v49, v49
	v_exp_f32_e32 v50, v50
	v_exp_f32_e32 v51, v51
	v_add_f32_e32 v48, 1.0, v48
	v_add_f32_e32 v49, 1.0, v49
	v_add_f32_e32 v50, 1.0, v50
	v_add_f32_e32 v51, 1.0, v51
	v_div_scale_f32 v216, s[2:3], v48, v48, 1.0
	v_div_scale_f32 v217, s[2:3], v49, v49, 1.0
	v_div_scale_f32 v218, s[2:3], v50, v50, 1.0
	v_div_scale_f32 v219, s[2:3], v51, v51, 1.0
	v_rcp_f32_e32 v220, v216
	v_rcp_f32_e32 v221, v217
	v_rcp_f32_e32 v222, v218
	v_rcp_f32_e32 v223, v219
	v_fma_f32 v224, -v216, v220, 1.0
	v_fma_f32 v225, -v217, v221, 1.0
	v_fma_f32 v226, -v218, v222, 1.0
	v_fma_f32 v227, -v219, v223, 1.0
	v_fmac_f32_e32 v220, v224, v220
	v_fmac_f32_e32 v221, v225, v221
	v_fmac_f32_e32 v222, v226, v222
	v_fmac_f32_e32 v223, v227, v223
	v_div_scale_f32 v224, vcc, 1.0, v48, 1.0
	v_mul_f32_e32 v228, v224, v220
	v_fma_f32 v229, -v216, v228, v224
	v_fmac_f32_e32 v228, v229, v220
	v_fma_f32 v216, -v216, v228, v224
	v_div_fmas_f32 v216, v216, v220, v228
	v_div_fixup_f32 v48, v216, v48, 1.0
	v_div_scale_f32 v225, vcc, 1.0, v49, 1.0
	v_mul_f32_e32 v228, v225, v221
	v_fma_f32 v229, -v217, v228, v225
	v_fmac_f32_e32 v228, v229, v221
	v_fma_f32 v217, -v217, v228, v225
	v_div_fmas_f32 v217, v217, v221, v228
	v_div_fixup_f32 v49, v217, v49, 1.0
	v_div_scale_f32 v226, vcc, 1.0, v50, 1.0
	v_mul_f32_e32 v228, v226, v222
	v_fma_f32 v229, -v218, v228, v226
	v_fmac_f32_e32 v228, v229, v222
	v_fma_f32 v218, -v218, v228, v226
	v_div_fmas_f32 v218, v218, v222, v228
	v_div_fixup_f32 v50, v218, v50, 1.0
	v_div_scale_f32 v227, vcc, 1.0, v51, 1.0
	v_mul_f32_e32 v228, v227, v223
	v_fma_f32 v229, -v219, v228, v227
	v_fmac_f32_e32 v228, v229, v223
	v_fma_f32 v219, -v219, v228, v227
	v_div_fmas_f32 v219, v219, v223, v228
	v_div_fixup_f32 v51, v219, v51, 1.0
	v_lshlrev_b32_e32 v230, 16, v164
	v_and_b32_e32 v164, 0xffff0000, v164
	v_lshlrev_b32_e32 v231, 16, v165
	v_and_b32_e32 v165, 0xffff0000, v165
	v_lshlrev_b32_e32 v232, 16, v166
	v_and_b32_e32 v166, 0xffff0000, v166
	v_lshlrev_b32_e32 v233, 16, v167
	v_and_b32_e32 v167, 0xffff0000, v167
	v_fma_f32 v48, v48, v232, v230
	v_fma_f32 v49, v49, v166, v164
	v_fma_f32 v50, v50, v233, v231
	v_fma_f32 v51, v51, v167, v165
	v_cvt_pk_bf16_f32 v164, v48, v49
	v_cvt_pk_bf16_f32 v165, v50, v51
	global_store_dwordx2 v192, v[164:165], s[62:63] offset:288
	v_add_u32_e32 v196, 0x90000, v140
	v_mul_f32_e32 v44, v44, v213
	v_mul_f32_e32 v45, v45, v213
	v_mul_f32_e32 v46, v46, v213
	v_mul_f32_e32 v47, v47, v213
	v_mul_f32_e32 v44, 0xbfb8aa3b, v44
	v_mul_f32_e32 v45, 0xbfb8aa3b, v45
	v_mul_f32_e32 v46, 0xbfb8aa3b, v46
	v_mul_f32_e32 v47, 0xbfb8aa3b, v47
	v_exp_f32_e32 v44, v44
	v_exp_f32_e32 v45, v45
	v_exp_f32_e32 v46, v46
	v_exp_f32_e32 v47, v47
	v_add_f32_e32 v44, 1.0, v44
	v_add_f32_e32 v45, 1.0, v45
	v_add_f32_e32 v46, 1.0, v46
	v_add_f32_e32 v47, 1.0, v47
	v_div_scale_f32 v216, s[2:3], v44, v44, 1.0
	v_div_scale_f32 v217, s[2:3], v45, v45, 1.0
	v_div_scale_f32 v218, s[2:3], v46, v46, 1.0
	v_div_scale_f32 v219, s[2:3], v47, v47, 1.0
	v_rcp_f32_e32 v220, v216
	v_rcp_f32_e32 v221, v217
	v_rcp_f32_e32 v222, v218
	v_rcp_f32_e32 v223, v219
	v_fma_f32 v224, -v216, v220, 1.0
	v_fma_f32 v225, -v217, v221, 1.0
	v_fma_f32 v226, -v218, v222, 1.0
	v_fma_f32 v227, -v219, v223, 1.0
	v_fmac_f32_e32 v220, v224, v220
	v_fmac_f32_e32 v221, v225, v221
	v_fmac_f32_e32 v222, v226, v222
	v_fmac_f32_e32 v223, v227, v223
	v_div_scale_f32 v224, vcc, 1.0, v44, 1.0
	v_mul_f32_e32 v228, v224, v220
	v_fma_f32 v229, -v216, v228, v224
	v_fmac_f32_e32 v228, v229, v220
	v_fma_f32 v216, -v216, v228, v224
	v_div_fmas_f32 v216, v216, v220, v228
	v_div_fixup_f32 v44, v216, v44, 1.0
	v_div_scale_f32 v225, vcc, 1.0, v45, 1.0
	v_mul_f32_e32 v228, v225, v221
	v_fma_f32 v229, -v217, v228, v225
	v_fmac_f32_e32 v228, v229, v221
	v_fma_f32 v217, -v217, v228, v225
	v_div_fmas_f32 v217, v217, v221, v228
	v_div_fixup_f32 v45, v217, v45, 1.0
	v_div_scale_f32 v226, vcc, 1.0, v46, 1.0
	v_mul_f32_e32 v228, v226, v222
	v_fma_f32 v229, -v218, v228, v226
	v_fmac_f32_e32 v228, v229, v222
	v_fma_f32 v218, -v218, v228, v226
	v_div_fmas_f32 v218, v218, v222, v228
	v_div_fixup_f32 v46, v218, v46, 1.0
	v_div_scale_f32 v227, vcc, 1.0, v47, 1.0
	v_mul_f32_e32 v228, v227, v223
	v_fma_f32 v229, -v219, v228, v227
	v_fmac_f32_e32 v228, v229, v223
	v_fma_f32 v219, -v219, v228, v227
	v_div_fmas_f32 v219, v219, v223, v228
	v_div_fixup_f32 v47, v219, v47, 1.0
	v_lshlrev_b32_e32 v230, 16, v168
	v_and_b32_e32 v168, 0xffff0000, v168
	v_lshlrev_b32_e32 v231, 16, v169
	v_and_b32_e32 v169, 0xffff0000, v169
	v_lshlrev_b32_e32 v232, 16, v170
	v_and_b32_e32 v170, 0xffff0000, v170
	v_lshlrev_b32_e32 v233, 16, v171
	v_and_b32_e32 v171, 0xffff0000, v171
	v_fma_f32 v44, v44, v232, v230
	v_fma_f32 v45, v45, v170, v168
	v_fma_f32 v46, v46, v233, v231
	v_fma_f32 v47, v47, v171, v169
	v_cvt_pk_bf16_f32 v168, v44, v45
	v_cvt_pk_bf16_f32 v169, v46, v47
	global_store_dwordx2 v196, v[168:169], s[62:63] offset:0
	v_mul_f32_e32 v40, v40, v213
	v_mul_f32_e32 v41, v41, v213
	v_mul_f32_e32 v42, v42, v213
	v_mul_f32_e32 v43, v43, v213
	v_mul_f32_e32 v40, 0xbfb8aa3b, v40
	v_mul_f32_e32 v41, 0xbfb8aa3b, v41
	v_mul_f32_e32 v42, 0xbfb8aa3b, v42
	v_mul_f32_e32 v43, 0xbfb8aa3b, v43
	v_exp_f32_e32 v40, v40
	v_exp_f32_e32 v41, v41
	v_exp_f32_e32 v42, v42
	v_exp_f32_e32 v43, v43
	v_add_f32_e32 v40, 1.0, v40
	v_add_f32_e32 v41, 1.0, v41
	v_add_f32_e32 v42, 1.0, v42
	v_add_f32_e32 v43, 1.0, v43
	v_div_scale_f32 v216, s[2:3], v40, v40, 1.0
	v_div_scale_f32 v217, s[2:3], v41, v41, 1.0
	v_div_scale_f32 v218, s[2:3], v42, v42, 1.0
	v_div_scale_f32 v219, s[2:3], v43, v43, 1.0
	v_rcp_f32_e32 v220, v216
	v_rcp_f32_e32 v221, v217
	v_rcp_f32_e32 v222, v218
	v_rcp_f32_e32 v223, v219
	v_fma_f32 v224, -v216, v220, 1.0
	v_fma_f32 v225, -v217, v221, 1.0
	v_fma_f32 v226, -v218, v222, 1.0
	v_fma_f32 v227, -v219, v223, 1.0
	v_fmac_f32_e32 v220, v224, v220
	v_fmac_f32_e32 v221, v225, v221
	v_fmac_f32_e32 v222, v226, v222
	v_fmac_f32_e32 v223, v227, v223
	v_div_scale_f32 v224, vcc, 1.0, v40, 1.0
	v_mul_f32_e32 v228, v224, v220
	v_fma_f32 v229, -v216, v228, v224
	v_fmac_f32_e32 v228, v229, v220
	v_fma_f32 v216, -v216, v228, v224
	v_div_fmas_f32 v216, v216, v220, v228
	v_div_fixup_f32 v40, v216, v40, 1.0
	v_div_scale_f32 v225, vcc, 1.0, v41, 1.0
	v_mul_f32_e32 v228, v225, v221
	v_fma_f32 v229, -v217, v228, v225
	v_fmac_f32_e32 v228, v229, v221
	v_fma_f32 v217, -v217, v228, v225
	v_div_fmas_f32 v217, v217, v221, v228
	v_div_fixup_f32 v41, v217, v41, 1.0
	v_div_scale_f32 v226, vcc, 1.0, v42, 1.0
	v_mul_f32_e32 v228, v226, v222
	v_fma_f32 v229, -v218, v228, v226
	v_fmac_f32_e32 v228, v229, v222
	v_fma_f32 v218, -v218, v228, v226
	v_div_fmas_f32 v218, v218, v222, v228
	v_div_fixup_f32 v42, v218, v42, 1.0
	v_div_scale_f32 v227, vcc, 1.0, v43, 1.0
	v_mul_f32_e32 v228, v227, v223
	v_fma_f32 v229, -v219, v228, v227
	v_fmac_f32_e32 v228, v229, v223
	v_fma_f32 v219, -v219, v228, v227
	v_div_fmas_f32 v219, v219, v223, v228
	v_div_fixup_f32 v43, v219, v43, 1.0
	v_lshlrev_b32_e32 v230, 16, v172
	v_and_b32_e32 v172, 0xffff0000, v172
	v_lshlrev_b32_e32 v231, 16, v173
	v_and_b32_e32 v173, 0xffff0000, v173
	v_lshlrev_b32_e32 v232, 16, v174
	v_and_b32_e32 v174, 0xffff0000, v174
	v_lshlrev_b32_e32 v233, 16, v175
	v_and_b32_e32 v175, 0xffff0000, v175
	v_fma_f32 v40, v40, v232, v230
	v_fma_f32 v41, v41, v174, v172
	v_fma_f32 v42, v42, v233, v231
	v_fma_f32 v43, v43, v175, v173
	v_cvt_pk_bf16_f32 v172, v40, v41
	v_cvt_pk_bf16_f32 v173, v42, v43
	global_store_dwordx2 v196, v[172:173], s[62:63] offset:32
	v_mul_f32_e32 v36, v36, v213
	v_mul_f32_e32 v37, v37, v213
	v_mul_f32_e32 v38, v38, v213
	v_mul_f32_e32 v39, v39, v213
	v_mul_f32_e32 v36, 0xbfb8aa3b, v36
	v_mul_f32_e32 v37, 0xbfb8aa3b, v37
	v_mul_f32_e32 v38, 0xbfb8aa3b, v38
	v_mul_f32_e32 v39, 0xbfb8aa3b, v39
	v_exp_f32_e32 v36, v36
	v_exp_f32_e32 v37, v37
	v_exp_f32_e32 v38, v38
	v_exp_f32_e32 v39, v39
	v_add_f32_e32 v36, 1.0, v36
	v_add_f32_e32 v37, 1.0, v37
	v_add_f32_e32 v38, 1.0, v38
	v_add_f32_e32 v39, 1.0, v39
	v_div_scale_f32 v216, s[2:3], v36, v36, 1.0
	v_div_scale_f32 v217, s[2:3], v37, v37, 1.0
	v_div_scale_f32 v218, s[2:3], v38, v38, 1.0
	v_div_scale_f32 v219, s[2:3], v39, v39, 1.0
	v_rcp_f32_e32 v220, v216
	v_rcp_f32_e32 v221, v217
	v_rcp_f32_e32 v222, v218
	v_rcp_f32_e32 v223, v219
	v_fma_f32 v224, -v216, v220, 1.0
	v_fma_f32 v225, -v217, v221, 1.0
	v_fma_f32 v226, -v218, v222, 1.0
	v_fma_f32 v227, -v219, v223, 1.0
	v_fmac_f32_e32 v220, v224, v220
	v_fmac_f32_e32 v221, v225, v221
	v_fmac_f32_e32 v222, v226, v222
	v_fmac_f32_e32 v223, v227, v223
	v_div_scale_f32 v224, vcc, 1.0, v36, 1.0
	v_mul_f32_e32 v228, v224, v220
	v_fma_f32 v229, -v216, v228, v224
	v_fmac_f32_e32 v228, v229, v220
	v_fma_f32 v216, -v216, v228, v224
	v_div_fmas_f32 v216, v216, v220, v228
	v_div_fixup_f32 v36, v216, v36, 1.0
	v_div_scale_f32 v225, vcc, 1.0, v37, 1.0
	v_mul_f32_e32 v228, v225, v221
	v_fma_f32 v229, -v217, v228, v225
	v_fmac_f32_e32 v228, v229, v221
	v_fma_f32 v217, -v217, v228, v225
	v_div_fmas_f32 v217, v217, v221, v228
	v_div_fixup_f32 v37, v217, v37, 1.0
	v_div_scale_f32 v226, vcc, 1.0, v38, 1.0
	v_mul_f32_e32 v228, v226, v222
	v_fma_f32 v229, -v218, v228, v226
	v_fmac_f32_e32 v228, v229, v222
	v_fma_f32 v218, -v218, v228, v226
	v_div_fmas_f32 v218, v218, v222, v228
	v_div_fixup_f32 v38, v218, v38, 1.0
	v_div_scale_f32 v227, vcc, 1.0, v39, 1.0
	v_mul_f32_e32 v228, v227, v223
	v_fma_f32 v229, -v219, v228, v227
	v_fmac_f32_e32 v228, v229, v223
	v_fma_f32 v219, -v219, v228, v227
	v_div_fmas_f32 v219, v219, v223, v228
	v_div_fixup_f32 v39, v219, v39, 1.0
	v_lshlrev_b32_e32 v230, 16, v240
	v_and_b32_e32 v240, 0xffff0000, v240
	v_lshlrev_b32_e32 v231, 16, v241
	v_and_b32_e32 v241, 0xffff0000, v241
	v_lshlrev_b32_e32 v232, 16, v242
	v_and_b32_e32 v242, 0xffff0000, v242
	v_lshlrev_b32_e32 v233, 16, v243
	v_and_b32_e32 v243, 0xffff0000, v243
	v_fma_f32 v36, v36, v232, v230
	v_fma_f32 v37, v37, v242, v240
	v_fma_f32 v38, v38, v233, v231
	v_fma_f32 v39, v39, v243, v241
	v_cvt_pk_bf16_f32 v240, v36, v37
	v_cvt_pk_bf16_f32 v241, v38, v39
	global_store_dwordx2 v196, v[240:241], s[62:63] offset:256
	v_mul_f32_e32 v32, v32, v213
	v_mul_f32_e32 v33, v33, v213
	v_mul_f32_e32 v34, v34, v213
	v_mul_f32_e32 v35, v35, v213
	v_mul_f32_e32 v32, 0xbfb8aa3b, v32
	v_mul_f32_e32 v33, 0xbfb8aa3b, v33
	v_mul_f32_e32 v34, 0xbfb8aa3b, v34
	v_mul_f32_e32 v35, 0xbfb8aa3b, v35
	v_exp_f32_e32 v32, v32
	v_exp_f32_e32 v33, v33
	v_exp_f32_e32 v34, v34
	v_exp_f32_e32 v35, v35
	v_add_f32_e32 v32, 1.0, v32
	v_add_f32_e32 v33, 1.0, v33
	v_add_f32_e32 v34, 1.0, v34
	v_add_f32_e32 v35, 1.0, v35
	v_div_scale_f32 v216, s[2:3], v32, v32, 1.0
	v_div_scale_f32 v217, s[2:3], v33, v33, 1.0
	v_div_scale_f32 v218, s[2:3], v34, v34, 1.0
	v_div_scale_f32 v219, s[2:3], v35, v35, 1.0
	v_rcp_f32_e32 v220, v216
	v_rcp_f32_e32 v221, v217
	v_rcp_f32_e32 v222, v218
	v_rcp_f32_e32 v223, v219
	v_fma_f32 v224, -v216, v220, 1.0
	v_fma_f32 v225, -v217, v221, 1.0
	v_fma_f32 v226, -v218, v222, 1.0
	v_fma_f32 v227, -v219, v223, 1.0
	v_fmac_f32_e32 v220, v224, v220
	v_fmac_f32_e32 v221, v225, v221
	v_fmac_f32_e32 v222, v226, v222
	v_fmac_f32_e32 v223, v227, v223
	v_div_scale_f32 v224, vcc, 1.0, v32, 1.0
	v_mul_f32_e32 v228, v224, v220
	v_fma_f32 v229, -v216, v228, v224
	v_fmac_f32_e32 v228, v229, v220
	v_fma_f32 v216, -v216, v228, v224
	v_div_fmas_f32 v216, v216, v220, v228
	v_div_fixup_f32 v32, v216, v32, 1.0
	v_div_scale_f32 v225, vcc, 1.0, v33, 1.0
	v_mul_f32_e32 v228, v225, v221
	v_fma_f32 v229, -v217, v228, v225
	v_fmac_f32_e32 v228, v229, v221
	v_fma_f32 v217, -v217, v228, v225
	v_div_fmas_f32 v217, v217, v221, v228
	v_div_fixup_f32 v33, v217, v33, 1.0
	v_div_scale_f32 v226, vcc, 1.0, v34, 1.0
	v_mul_f32_e32 v228, v226, v222
	v_fma_f32 v229, -v218, v228, v226
	v_fmac_f32_e32 v228, v229, v222
	v_fma_f32 v218, -v218, v228, v226
	v_div_fmas_f32 v218, v218, v222, v228
	v_div_fixup_f32 v34, v218, v34, 1.0
	v_div_scale_f32 v227, vcc, 1.0, v35, 1.0
	v_mul_f32_e32 v228, v227, v223
	v_fma_f32 v229, -v219, v228, v227
	v_fmac_f32_e32 v228, v229, v223
	v_fma_f32 v219, -v219, v228, v227
	v_div_fmas_f32 v219, v219, v223, v228
	v_div_fixup_f32 v35, v219, v35, 1.0
	v_lshlrev_b32_e32 v230, 16, v244
	v_and_b32_e32 v244, 0xffff0000, v244
	v_lshlrev_b32_e32 v231, 16, v245
	v_and_b32_e32 v245, 0xffff0000, v245
	v_lshlrev_b32_e32 v232, 16, v246
	v_and_b32_e32 v246, 0xffff0000, v246
	v_lshlrev_b32_e32 v233, 16, v247
	v_and_b32_e32 v247, 0xffff0000, v247
	v_fma_f32 v32, v32, v232, v230
	v_fma_f32 v33, v33, v246, v244
	v_fma_f32 v34, v34, v233, v231
	v_fma_f32 v35, v35, v247, v245
	v_cvt_pk_bf16_f32 v244, v32, v33
	v_cvt_pk_bf16_f32 v245, v34, v35
	global_store_dwordx2 v196, v[244:245], s[62:63] offset:288
	s_waitcnt vmcnt(8)
	v_add_u32_e32 v148, 0xa0000, v140
	v_mul_f32_e32 v28, v28, v214
	v_mul_f32_e32 v29, v29, v214
	v_mul_f32_e32 v30, v30, v214
	v_mul_f32_e32 v31, v31, v214
	v_mul_f32_e32 v28, 0xbfb8aa3b, v28
	v_mul_f32_e32 v29, 0xbfb8aa3b, v29
	v_mul_f32_e32 v30, 0xbfb8aa3b, v30
	v_mul_f32_e32 v31, 0xbfb8aa3b, v31
	v_exp_f32_e32 v28, v28
	v_exp_f32_e32 v29, v29
	v_exp_f32_e32 v30, v30
	v_exp_f32_e32 v31, v31
	v_add_f32_e32 v28, 1.0, v28
	v_add_f32_e32 v29, 1.0, v29
	v_add_f32_e32 v30, 1.0, v30
	v_add_f32_e32 v31, 1.0, v31
	v_div_scale_f32 v216, s[2:3], v28, v28, 1.0
	v_div_scale_f32 v217, s[2:3], v29, v29, 1.0
	v_div_scale_f32 v218, s[2:3], v30, v30, 1.0
	v_div_scale_f32 v219, s[2:3], v31, v31, 1.0
	v_rcp_f32_e32 v220, v216
	v_rcp_f32_e32 v221, v217
	v_rcp_f32_e32 v222, v218
	v_rcp_f32_e32 v223, v219
	v_fma_f32 v224, -v216, v220, 1.0
	v_fma_f32 v225, -v217, v221, 1.0
	v_fma_f32 v226, -v218, v222, 1.0
	v_fma_f32 v227, -v219, v223, 1.0
	v_fmac_f32_e32 v220, v224, v220
	v_fmac_f32_e32 v221, v225, v221
	v_fmac_f32_e32 v222, v226, v222
	v_fmac_f32_e32 v223, v227, v223
	v_div_scale_f32 v224, vcc, 1.0, v28, 1.0
	v_mul_f32_e32 v228, v224, v220
	v_fma_f32 v229, -v216, v228, v224
	v_fmac_f32_e32 v228, v229, v220
	v_fma_f32 v216, -v216, v228, v224
	v_div_fmas_f32 v216, v216, v220, v228
	v_div_fixup_f32 v28, v216, v28, 1.0
	v_div_scale_f32 v225, vcc, 1.0, v29, 1.0
	v_mul_f32_e32 v228, v225, v221
	v_fma_f32 v229, -v217, v228, v225
	v_fmac_f32_e32 v228, v229, v221
	v_fma_f32 v217, -v217, v228, v225
	v_div_fmas_f32 v217, v217, v221, v228
	v_div_fixup_f32 v29, v217, v29, 1.0
	v_div_scale_f32 v226, vcc, 1.0, v30, 1.0
	v_mul_f32_e32 v228, v226, v222
	v_fma_f32 v229, -v218, v228, v226
	v_fmac_f32_e32 v228, v229, v222
	v_fma_f32 v218, -v218, v228, v226
	v_div_fmas_f32 v218, v218, v222, v228
	v_div_fixup_f32 v30, v218, v30, 1.0
	v_div_scale_f32 v227, vcc, 1.0, v31, 1.0
	v_mul_f32_e32 v228, v227, v223
	v_fma_f32 v229, -v219, v228, v227
	v_fmac_f32_e32 v228, v229, v223
	v_fma_f32 v219, -v219, v228, v227
	v_div_fmas_f32 v219, v219, v223, v228
	v_div_fixup_f32 v31, v219, v31, 1.0
	v_lshlrev_b32_e32 v230, 16, v182
	v_and_b32_e32 v182, 0xffff0000, v182
	v_lshlrev_b32_e32 v231, 16, v183
	v_and_b32_e32 v183, 0xffff0000, v183
	v_lshlrev_b32_e32 v232, 16, v184
	v_and_b32_e32 v184, 0xffff0000, v184
	v_lshlrev_b32_e32 v233, 16, v185
	v_and_b32_e32 v185, 0xffff0000, v185
	v_fma_f32 v28, v28, v232, v230
	v_fma_f32 v29, v29, v184, v182
	v_fma_f32 v30, v30, v233, v231
	v_fma_f32 v31, v31, v185, v183
	v_cvt_pk_bf16_f32 v182, v28, v29
	v_cvt_pk_bf16_f32 v183, v30, v31
	global_store_dwordx2 v148, v[182:183], s[62:63] offset:0
	v_mul_f32_e32 v24, v24, v214
	v_mul_f32_e32 v25, v25, v214
	v_mul_f32_e32 v26, v26, v214
	v_mul_f32_e32 v27, v27, v214
	v_mul_f32_e32 v24, 0xbfb8aa3b, v24
	v_mul_f32_e32 v25, 0xbfb8aa3b, v25
	v_mul_f32_e32 v26, 0xbfb8aa3b, v26
	v_mul_f32_e32 v27, 0xbfb8aa3b, v27
	v_exp_f32_e32 v24, v24
	v_exp_f32_e32 v25, v25
	v_exp_f32_e32 v26, v26
	v_exp_f32_e32 v27, v27
	v_add_f32_e32 v24, 1.0, v24
	v_add_f32_e32 v25, 1.0, v25
	v_add_f32_e32 v26, 1.0, v26
	v_add_f32_e32 v27, 1.0, v27
	v_div_scale_f32 v216, s[2:3], v24, v24, 1.0
	v_div_scale_f32 v217, s[2:3], v25, v25, 1.0
	v_div_scale_f32 v218, s[2:3], v26, v26, 1.0
	v_div_scale_f32 v219, s[2:3], v27, v27, 1.0
	v_rcp_f32_e32 v220, v216
	v_rcp_f32_e32 v221, v217
	v_rcp_f32_e32 v222, v218
	v_rcp_f32_e32 v223, v219
	v_fma_f32 v224, -v216, v220, 1.0
	v_fma_f32 v225, -v217, v221, 1.0
	v_fma_f32 v226, -v218, v222, 1.0
	v_fma_f32 v227, -v219, v223, 1.0
	v_fmac_f32_e32 v220, v224, v220
	v_fmac_f32_e32 v221, v225, v221
	v_fmac_f32_e32 v222, v226, v222
	v_fmac_f32_e32 v223, v227, v223
	v_div_scale_f32 v224, vcc, 1.0, v24, 1.0
	v_mul_f32_e32 v228, v224, v220
	v_fma_f32 v229, -v216, v228, v224
	v_fmac_f32_e32 v228, v229, v220
	v_fma_f32 v216, -v216, v228, v224
	v_div_fmas_f32 v216, v216, v220, v228
	v_div_fixup_f32 v24, v216, v24, 1.0
	v_div_scale_f32 v225, vcc, 1.0, v25, 1.0
	v_mul_f32_e32 v228, v225, v221
	v_fma_f32 v229, -v217, v228, v225
	v_fmac_f32_e32 v228, v229, v221
	v_fma_f32 v217, -v217, v228, v225
	v_div_fmas_f32 v217, v217, v221, v228
	v_div_fixup_f32 v25, v217, v25, 1.0
	v_div_scale_f32 v226, vcc, 1.0, v26, 1.0
	v_mul_f32_e32 v228, v226, v222
	v_fma_f32 v229, -v218, v228, v226
	v_fmac_f32_e32 v228, v229, v222
	v_fma_f32 v218, -v218, v228, v226
	v_div_fmas_f32 v218, v218, v222, v228
	v_div_fixup_f32 v26, v218, v26, 1.0
	v_div_scale_f32 v227, vcc, 1.0, v27, 1.0
	v_mul_f32_e32 v228, v227, v223
	v_fma_f32 v229, -v219, v228, v227
	v_fmac_f32_e32 v228, v229, v223
	v_fma_f32 v219, -v219, v228, v227
	v_div_fmas_f32 v219, v219, v223, v228
	v_div_fixup_f32 v27, v219, v27, 1.0
	v_lshlrev_b32_e32 v230, 16, v186
	v_and_b32_e32 v186, 0xffff0000, v186
	v_lshlrev_b32_e32 v231, 16, v187
	v_and_b32_e32 v187, 0xffff0000, v187
	v_lshlrev_b32_e32 v232, 16, v200
	v_and_b32_e32 v200, 0xffff0000, v200
	v_lshlrev_b32_e32 v233, 16, v201
	v_and_b32_e32 v201, 0xffff0000, v201
	v_fma_f32 v24, v24, v232, v230
	v_fma_f32 v25, v25, v200, v186
	v_fma_f32 v26, v26, v233, v231
	v_fma_f32 v27, v27, v201, v187
	v_cvt_pk_bf16_f32 v186, v24, v25
	v_cvt_pk_bf16_f32 v187, v26, v27
	global_store_dwordx2 v148, v[186:187], s[62:63] offset:32
	v_mul_f32_e32 v20, v20, v214
	v_mul_f32_e32 v21, v21, v214
	v_mul_f32_e32 v22, v22, v214
	v_mul_f32_e32 v23, v23, v214
	v_mul_f32_e32 v20, 0xbfb8aa3b, v20
	v_mul_f32_e32 v21, 0xbfb8aa3b, v21
	v_mul_f32_e32 v22, 0xbfb8aa3b, v22
	v_mul_f32_e32 v23, 0xbfb8aa3b, v23
	v_exp_f32_e32 v20, v20
	v_exp_f32_e32 v21, v21
	v_exp_f32_e32 v22, v22
	v_exp_f32_e32 v23, v23
	v_add_f32_e32 v20, 1.0, v20
	v_add_f32_e32 v21, 1.0, v21
	v_add_f32_e32 v22, 1.0, v22
	v_add_f32_e32 v23, 1.0, v23
	v_div_scale_f32 v216, s[2:3], v20, v20, 1.0
	v_div_scale_f32 v217, s[2:3], v21, v21, 1.0
	v_div_scale_f32 v218, s[2:3], v22, v22, 1.0
	v_div_scale_f32 v219, s[2:3], v23, v23, 1.0
	v_rcp_f32_e32 v220, v216
	v_rcp_f32_e32 v221, v217
	v_rcp_f32_e32 v222, v218
	v_rcp_f32_e32 v223, v219
	v_fma_f32 v224, -v216, v220, 1.0
	v_fma_f32 v225, -v217, v221, 1.0
	v_fma_f32 v226, -v218, v222, 1.0
	v_fma_f32 v227, -v219, v223, 1.0
	v_fmac_f32_e32 v220, v224, v220
	v_fmac_f32_e32 v221, v225, v221
	v_fmac_f32_e32 v222, v226, v222
	v_fmac_f32_e32 v223, v227, v223
	v_div_scale_f32 v224, vcc, 1.0, v20, 1.0
	v_mul_f32_e32 v228, v224, v220
	v_fma_f32 v229, -v216, v228, v224
	v_fmac_f32_e32 v228, v229, v220
	v_fma_f32 v216, -v216, v228, v224
	v_div_fmas_f32 v216, v216, v220, v228
	v_div_fixup_f32 v20, v216, v20, 1.0
	v_div_scale_f32 v225, vcc, 1.0, v21, 1.0
	v_mul_f32_e32 v228, v225, v221
	v_fma_f32 v229, -v217, v228, v225
	v_fmac_f32_e32 v228, v229, v221
	v_fma_f32 v217, -v217, v228, v225
	v_div_fmas_f32 v217, v217, v221, v228
	v_div_fixup_f32 v21, v217, v21, 1.0
	v_div_scale_f32 v226, vcc, 1.0, v22, 1.0
	v_mul_f32_e32 v228, v226, v222
	v_fma_f32 v229, -v218, v228, v226
	v_fmac_f32_e32 v228, v229, v222
	v_fma_f32 v218, -v218, v228, v226
	v_div_fmas_f32 v218, v218, v222, v228
	v_div_fixup_f32 v22, v218, v22, 1.0
	v_div_scale_f32 v227, vcc, 1.0, v23, 1.0
	v_mul_f32_e32 v228, v227, v223
	v_fma_f32 v229, -v219, v228, v227
	v_fmac_f32_e32 v228, v229, v223
	v_fma_f32 v219, -v219, v228, v227
	v_div_fmas_f32 v219, v219, v223, v228
	v_div_fixup_f32 v23, v219, v23, 1.0
	v_lshlrev_b32_e32 v230, 16, v202
	v_and_b32_e32 v202, 0xffff0000, v202
	v_lshlrev_b32_e32 v231, 16, v203
	v_and_b32_e32 v203, 0xffff0000, v203
	v_lshlrev_b32_e32 v232, 16, v204
	v_and_b32_e32 v204, 0xffff0000, v204
	v_lshlrev_b32_e32 v233, 16, v205
	v_and_b32_e32 v205, 0xffff0000, v205
	v_fma_f32 v20, v20, v232, v230
	v_fma_f32 v21, v21, v204, v202
	v_fma_f32 v22, v22, v233, v231
	v_fma_f32 v23, v23, v205, v203
	v_cvt_pk_bf16_f32 v202, v20, v21
	v_cvt_pk_bf16_f32 v203, v22, v23
	global_store_dwordx2 v148, v[202:203], s[62:63] offset:256
	v_mul_f32_e32 v16, v16, v214
	v_mul_f32_e32 v17, v17, v214
	v_mul_f32_e32 v18, v18, v214
	v_mul_f32_e32 v19, v19, v214
	v_mul_f32_e32 v16, 0xbfb8aa3b, v16
	v_mul_f32_e32 v17, 0xbfb8aa3b, v17
	v_mul_f32_e32 v18, 0xbfb8aa3b, v18
	v_mul_f32_e32 v19, 0xbfb8aa3b, v19
	v_exp_f32_e32 v16, v16
	v_exp_f32_e32 v17, v17
	v_exp_f32_e32 v18, v18
	v_exp_f32_e32 v19, v19
	v_add_f32_e32 v16, 1.0, v16
	v_add_f32_e32 v17, 1.0, v17
	v_add_f32_e32 v18, 1.0, v18
	v_add_f32_e32 v19, 1.0, v19
	v_div_scale_f32 v216, s[2:3], v16, v16, 1.0
	v_div_scale_f32 v217, s[2:3], v17, v17, 1.0
	v_div_scale_f32 v218, s[2:3], v18, v18, 1.0
	v_div_scale_f32 v219, s[2:3], v19, v19, 1.0
	v_rcp_f32_e32 v220, v216
	v_rcp_f32_e32 v221, v217
	v_rcp_f32_e32 v222, v218
	v_rcp_f32_e32 v223, v219
	v_fma_f32 v224, -v216, v220, 1.0
	v_fma_f32 v225, -v217, v221, 1.0
	v_fma_f32 v226, -v218, v222, 1.0
	v_fma_f32 v227, -v219, v223, 1.0
	v_fmac_f32_e32 v220, v224, v220
	v_fmac_f32_e32 v221, v225, v221
	v_fmac_f32_e32 v222, v226, v222
	v_fmac_f32_e32 v223, v227, v223
	v_div_scale_f32 v224, vcc, 1.0, v16, 1.0
	v_mul_f32_e32 v228, v224, v220
	v_fma_f32 v229, -v216, v228, v224
	v_fmac_f32_e32 v228, v229, v220
	v_fma_f32 v216, -v216, v228, v224
	v_div_fmas_f32 v216, v216, v220, v228
	v_div_fixup_f32 v16, v216, v16, 1.0
	v_div_scale_f32 v225, vcc, 1.0, v17, 1.0
	v_mul_f32_e32 v228, v225, v221
	v_fma_f32 v229, -v217, v228, v225
	v_fmac_f32_e32 v228, v229, v221
	v_fma_f32 v217, -v217, v228, v225
	v_div_fmas_f32 v217, v217, v221, v228
	v_div_fixup_f32 v17, v217, v17, 1.0
	v_div_scale_f32 v226, vcc, 1.0, v18, 1.0
	v_mul_f32_e32 v228, v226, v222
	v_fma_f32 v229, -v218, v228, v226
	v_fmac_f32_e32 v228, v229, v222
	v_fma_f32 v218, -v218, v228, v226
	v_div_fmas_f32 v218, v218, v222, v228
	v_div_fixup_f32 v18, v218, v18, 1.0
	v_div_scale_f32 v227, vcc, 1.0, v19, 1.0
	v_mul_f32_e32 v228, v227, v223
	v_fma_f32 v229, -v219, v228, v227
	v_fmac_f32_e32 v228, v229, v223
	v_fma_f32 v219, -v219, v228, v227
	v_div_fmas_f32 v219, v219, v223, v228
	v_div_fixup_f32 v19, v219, v19, 1.0
	v_lshlrev_b32_e32 v230, 16, v134
	v_and_b32_e32 v134, 0xffff0000, v134
	v_lshlrev_b32_e32 v231, 16, v135
	v_and_b32_e32 v135, 0xffff0000, v135
	v_lshlrev_b32_e32 v232, 16, v136
	v_and_b32_e32 v136, 0xffff0000, v136
	v_lshlrev_b32_e32 v233, 16, v137
	v_and_b32_e32 v137, 0xffff0000, v137
	v_fma_f32 v16, v16, v232, v230
	v_fma_f32 v17, v17, v136, v134
	v_fma_f32 v18, v18, v233, v231
	v_fma_f32 v19, v19, v137, v135
	v_cvt_pk_bf16_f32 v134, v16, v17
	v_cvt_pk_bf16_f32 v135, v18, v19
	global_store_dwordx2 v148, v[134:135], s[62:63] offset:288
	v_add_u32_e32 v188, 0xb0000, v140
	v_mul_f32_e32 v12, v12, v215
	v_mul_f32_e32 v13, v13, v215
	v_mul_f32_e32 v14, v14, v215
	v_mul_f32_e32 v15, v15, v215
	v_mul_f32_e32 v12, 0xbfb8aa3b, v12
	v_mul_f32_e32 v13, 0xbfb8aa3b, v13
	v_mul_f32_e32 v14, 0xbfb8aa3b, v14
	v_mul_f32_e32 v15, 0xbfb8aa3b, v15
	v_exp_f32_e32 v12, v12
	v_exp_f32_e32 v13, v13
	v_exp_f32_e32 v14, v14
	v_exp_f32_e32 v15, v15
	v_add_f32_e32 v12, 1.0, v12
	v_add_f32_e32 v13, 1.0, v13
	v_add_f32_e32 v14, 1.0, v14
	v_add_f32_e32 v15, 1.0, v15
	v_div_scale_f32 v216, s[2:3], v12, v12, 1.0
	v_div_scale_f32 v217, s[2:3], v13, v13, 1.0
	v_div_scale_f32 v218, s[2:3], v14, v14, 1.0
	v_div_scale_f32 v219, s[2:3], v15, v15, 1.0
	v_rcp_f32_e32 v220, v216
	v_rcp_f32_e32 v221, v217
	v_rcp_f32_e32 v222, v218
	v_rcp_f32_e32 v223, v219
	v_fma_f32 v224, -v216, v220, 1.0
	v_fma_f32 v225, -v217, v221, 1.0
	v_fma_f32 v226, -v218, v222, 1.0
	v_fma_f32 v227, -v219, v223, 1.0
	v_fmac_f32_e32 v220, v224, v220
	v_fmac_f32_e32 v221, v225, v221
	v_fmac_f32_e32 v222, v226, v222
	v_fmac_f32_e32 v223, v227, v223
	v_div_scale_f32 v224, vcc, 1.0, v12, 1.0
	v_mul_f32_e32 v228, v224, v220
	v_fma_f32 v229, -v216, v228, v224
	v_fmac_f32_e32 v228, v229, v220
	v_fma_f32 v216, -v216, v228, v224
	v_div_fmas_f32 v216, v216, v220, v228
	v_div_fixup_f32 v12, v216, v12, 1.0
	v_div_scale_f32 v225, vcc, 1.0, v13, 1.0
	v_mul_f32_e32 v228, v225, v221
	v_fma_f32 v229, -v217, v228, v225
	v_fmac_f32_e32 v228, v229, v221
	v_fma_f32 v217, -v217, v228, v225
	v_div_fmas_f32 v217, v217, v221, v228
	v_div_fixup_f32 v13, v217, v13, 1.0
	v_div_scale_f32 v226, vcc, 1.0, v14, 1.0
	v_mul_f32_e32 v228, v226, v222
	v_fma_f32 v229, -v218, v228, v226
	v_fmac_f32_e32 v228, v229, v222
	v_fma_f32 v218, -v218, v228, v226
	v_div_fmas_f32 v218, v218, v222, v228
	v_div_fixup_f32 v14, v218, v14, 1.0
	v_div_scale_f32 v227, vcc, 1.0, v15, 1.0
	v_mul_f32_e32 v228, v227, v223
	v_fma_f32 v229, -v219, v228, v227
	v_fmac_f32_e32 v228, v229, v223
	v_fma_f32 v219, -v219, v228, v227
	v_div_fmas_f32 v219, v219, v223, v228
	v_div_fixup_f32 v15, v219, v15, 1.0
	v_lshlrev_b32_e32 v230, 16, v138
	v_and_b32_e32 v138, 0xffff0000, v138
	v_lshlrev_b32_e32 v231, 16, v139
	v_and_b32_e32 v139, 0xffff0000, v139
	v_lshlrev_b32_e32 v232, 16, v142
	v_and_b32_e32 v142, 0xffff0000, v142
	v_lshlrev_b32_e32 v233, 16, v143
	v_and_b32_e32 v143, 0xffff0000, v143
	v_fma_f32 v12, v12, v232, v230
	v_fma_f32 v13, v13, v142, v138
	v_fma_f32 v14, v14, v233, v231
	v_fma_f32 v15, v15, v143, v139
	v_cvt_pk_bf16_f32 v138, v12, v13
	v_cvt_pk_bf16_f32 v139, v14, v15
	global_store_dwordx2 v188, v[138:139], s[62:63] offset:0
	v_mul_f32_e32 v8, v8, v215
	v_mul_f32_e32 v9, v9, v215
	v_mul_f32_e32 v10, v10, v215
	v_mul_f32_e32 v11, v11, v215
	v_mul_f32_e32 v8, 0xbfb8aa3b, v8
	v_mul_f32_e32 v9, 0xbfb8aa3b, v9
	v_mul_f32_e32 v10, 0xbfb8aa3b, v10
	v_mul_f32_e32 v11, 0xbfb8aa3b, v11
	v_exp_f32_e32 v8, v8
	v_exp_f32_e32 v9, v9
	v_exp_f32_e32 v10, v10
	v_exp_f32_e32 v11, v11
	v_add_f32_e32 v8, 1.0, v8
	v_add_f32_e32 v9, 1.0, v9
	v_add_f32_e32 v10, 1.0, v10
	v_add_f32_e32 v11, 1.0, v11
	v_div_scale_f32 v216, s[2:3], v8, v8, 1.0
	v_div_scale_f32 v217, s[2:3], v9, v9, 1.0
	v_div_scale_f32 v218, s[2:3], v10, v10, 1.0
	v_div_scale_f32 v219, s[2:3], v11, v11, 1.0
	v_rcp_f32_e32 v220, v216
	v_rcp_f32_e32 v221, v217
	v_rcp_f32_e32 v222, v218
	v_rcp_f32_e32 v223, v219
	v_fma_f32 v224, -v216, v220, 1.0
	v_fma_f32 v225, -v217, v221, 1.0
	v_fma_f32 v226, -v218, v222, 1.0
	v_fma_f32 v227, -v219, v223, 1.0
	v_fmac_f32_e32 v220, v224, v220
	v_fmac_f32_e32 v221, v225, v221
	v_fmac_f32_e32 v222, v226, v222
	v_fmac_f32_e32 v223, v227, v223
	v_div_scale_f32 v224, vcc, 1.0, v8, 1.0
	v_mul_f32_e32 v228, v224, v220
	v_fma_f32 v229, -v216, v228, v224
	v_fmac_f32_e32 v228, v229, v220
	v_fma_f32 v216, -v216, v228, v224
	v_div_fmas_f32 v216, v216, v220, v228
	v_div_fixup_f32 v8, v216, v8, 1.0
	v_div_scale_f32 v225, vcc, 1.0, v9, 1.0
	v_mul_f32_e32 v228, v225, v221
	v_fma_f32 v229, -v217, v228, v225
	v_fmac_f32_e32 v228, v229, v221
	v_fma_f32 v217, -v217, v228, v225
	v_div_fmas_f32 v217, v217, v221, v228
	v_div_fixup_f32 v9, v217, v9, 1.0
	v_div_scale_f32 v226, vcc, 1.0, v10, 1.0
	v_mul_f32_e32 v228, v226, v222
	v_fma_f32 v229, -v218, v228, v226
	v_fmac_f32_e32 v228, v229, v222
	v_fma_f32 v218, -v218, v228, v226
	v_div_fmas_f32 v218, v218, v222, v228
	v_div_fixup_f32 v10, v218, v10, 1.0
	v_div_scale_f32 v227, vcc, 1.0, v11, 1.0
	v_mul_f32_e32 v228, v227, v223
	v_fma_f32 v229, -v219, v228, v227
	v_fmac_f32_e32 v228, v229, v223
	v_fma_f32 v219, -v219, v228, v227
	v_div_fmas_f32 v219, v219, v223, v228
	v_div_fixup_f32 v11, v219, v11, 1.0
	v_lshlrev_b32_e32 v230, 16, v144
	v_and_b32_e32 v144, 0xffff0000, v144
	v_lshlrev_b32_e32 v231, 16, v145
	v_and_b32_e32 v145, 0xffff0000, v145
	v_lshlrev_b32_e32 v232, 16, v190
	v_and_b32_e32 v190, 0xffff0000, v190
	v_lshlrev_b32_e32 v233, 16, v191
	v_and_b32_e32 v191, 0xffff0000, v191
	v_fma_f32 v8, v8, v232, v230
	v_fma_f32 v9, v9, v190, v144
	v_fma_f32 v10, v10, v233, v231
	v_fma_f32 v11, v11, v191, v145
	v_cvt_pk_bf16_f32 v144, v8, v9
	v_cvt_pk_bf16_f32 v145, v10, v11
	global_store_dwordx2 v188, v[144:145], s[62:63] offset:32
	v_mul_f32_e32 v4, v4, v215
	v_mul_f32_e32 v5, v5, v215
	v_mul_f32_e32 v6, v6, v215
	v_mul_f32_e32 v7, v7, v215
	v_mul_f32_e32 v4, 0xbfb8aa3b, v4
	v_mul_f32_e32 v5, 0xbfb8aa3b, v5
	v_mul_f32_e32 v6, 0xbfb8aa3b, v6
	v_mul_f32_e32 v7, 0xbfb8aa3b, v7
	v_exp_f32_e32 v4, v4
	v_exp_f32_e32 v5, v5
	v_exp_f32_e32 v6, v6
	v_exp_f32_e32 v7, v7
	v_add_f32_e32 v4, 1.0, v4
	v_add_f32_e32 v5, 1.0, v5
	v_add_f32_e32 v6, 1.0, v6
	v_add_f32_e32 v7, 1.0, v7
	v_div_scale_f32 v216, s[2:3], v4, v4, 1.0
	v_div_scale_f32 v217, s[2:3], v5, v5, 1.0
	v_div_scale_f32 v218, s[2:3], v6, v6, 1.0
	v_div_scale_f32 v219, s[2:3], v7, v7, 1.0
	v_rcp_f32_e32 v220, v216
	v_rcp_f32_e32 v221, v217
	v_rcp_f32_e32 v222, v218
	v_rcp_f32_e32 v223, v219
	v_fma_f32 v224, -v216, v220, 1.0
	v_fma_f32 v225, -v217, v221, 1.0
	v_fma_f32 v226, -v218, v222, 1.0
	v_fma_f32 v227, -v219, v223, 1.0
	v_fmac_f32_e32 v220, v224, v220
	v_fmac_f32_e32 v221, v225, v221
	v_fmac_f32_e32 v222, v226, v222
	v_fmac_f32_e32 v223, v227, v223
	v_div_scale_f32 v224, vcc, 1.0, v4, 1.0
	v_mul_f32_e32 v228, v224, v220
	v_fma_f32 v229, -v216, v228, v224
	v_fmac_f32_e32 v228, v229, v220
	v_fma_f32 v216, -v216, v228, v224
	v_div_fmas_f32 v216, v216, v220, v228
	v_div_fixup_f32 v4, v216, v4, 1.0
	v_div_scale_f32 v225, vcc, 1.0, v5, 1.0
	v_mul_f32_e32 v228, v225, v221
	v_fma_f32 v229, -v217, v228, v225
	v_fmac_f32_e32 v228, v229, v221
	v_fma_f32 v217, -v217, v228, v225
	v_div_fmas_f32 v217, v217, v221, v228
	v_div_fixup_f32 v5, v217, v5, 1.0
	v_div_scale_f32 v226, vcc, 1.0, v6, 1.0
	v_mul_f32_e32 v228, v226, v222
	v_fma_f32 v229, -v218, v228, v226
	v_fmac_f32_e32 v228, v229, v222
	v_fma_f32 v218, -v218, v228, v226
	v_div_fmas_f32 v218, v218, v222, v228
	v_div_fixup_f32 v6, v218, v6, 1.0
	v_div_scale_f32 v227, vcc, 1.0, v7, 1.0
	v_mul_f32_e32 v228, v227, v223
	v_fma_f32 v229, -v219, v228, v227
	v_fmac_f32_e32 v228, v229, v223
	v_fma_f32 v219, -v219, v228, v227
	v_div_fmas_f32 v219, v219, v223, v228
	v_div_fixup_f32 v7, v219, v7, 1.0
	v_lshlrev_b32_e32 v230, 16, v194
	v_and_b32_e32 v194, 0xffff0000, v194
	v_lshlrev_b32_e32 v231, 16, v195
	v_and_b32_e32 v195, 0xffff0000, v195
	v_lshlrev_b32_e32 v232, 16, v248
	v_and_b32_e32 v248, 0xffff0000, v248
	v_lshlrev_b32_e32 v233, 16, v249
	v_and_b32_e32 v249, 0xffff0000, v249
	v_fma_f32 v4, v4, v232, v230
	v_fma_f32 v5, v5, v248, v194
	v_fma_f32 v6, v6, v233, v231
	v_fma_f32 v7, v7, v249, v195
	v_cvt_pk_bf16_f32 v194, v4, v5
	v_cvt_pk_bf16_f32 v195, v6, v7
	global_store_dwordx2 v188, v[194:195], s[62:63] offset:256
	v_mul_f32_e32 v0, v0, v215
	v_mul_f32_e32 v1, v1, v215
	v_mul_f32_e32 v2, v2, v215
	v_mul_f32_e32 v3, v3, v215
	v_mul_f32_e32 v0, 0xbfb8aa3b, v0
	v_mul_f32_e32 v1, 0xbfb8aa3b, v1
	v_mul_f32_e32 v2, 0xbfb8aa3b, v2
	v_mul_f32_e32 v3, 0xbfb8aa3b, v3
	v_exp_f32_e32 v0, v0
	v_exp_f32_e32 v1, v1
	v_exp_f32_e32 v2, v2
	v_exp_f32_e32 v3, v3
	v_add_f32_e32 v0, 1.0, v0
	v_add_f32_e32 v1, 1.0, v1
	v_add_f32_e32 v2, 1.0, v2
	v_add_f32_e32 v3, 1.0, v3
	v_div_scale_f32 v216, s[2:3], v0, v0, 1.0
	v_div_scale_f32 v217, s[2:3], v1, v1, 1.0
	v_div_scale_f32 v218, s[2:3], v2, v2, 1.0
	v_div_scale_f32 v219, s[2:3], v3, v3, 1.0
	v_rcp_f32_e32 v220, v216
	v_rcp_f32_e32 v221, v217
	v_rcp_f32_e32 v222, v218
	v_rcp_f32_e32 v223, v219
	v_fma_f32 v224, -v216, v220, 1.0
	v_fma_f32 v225, -v217, v221, 1.0
	v_fma_f32 v226, -v218, v222, 1.0
	v_fma_f32 v227, -v219, v223, 1.0
	v_fmac_f32_e32 v220, v224, v220
	v_fmac_f32_e32 v221, v225, v221
	v_fmac_f32_e32 v222, v226, v222
	v_fmac_f32_e32 v223, v227, v223
	v_div_scale_f32 v224, vcc, 1.0, v0, 1.0
	v_mul_f32_e32 v228, v224, v220
	v_fma_f32 v229, -v216, v228, v224
	v_fmac_f32_e32 v228, v229, v220
	v_fma_f32 v216, -v216, v228, v224
	v_div_fmas_f32 v216, v216, v220, v228
	v_div_fixup_f32 v0, v216, v0, 1.0
	v_div_scale_f32 v225, vcc, 1.0, v1, 1.0
	v_mul_f32_e32 v228, v225, v221
	v_fma_f32 v229, -v217, v228, v225
	v_fmac_f32_e32 v228, v229, v221
	v_fma_f32 v217, -v217, v228, v225
	v_div_fmas_f32 v217, v217, v221, v228
	v_div_fixup_f32 v1, v217, v1, 1.0
	v_div_scale_f32 v226, vcc, 1.0, v2, 1.0
	v_mul_f32_e32 v228, v226, v222
	v_fma_f32 v229, -v218, v228, v226
	v_fmac_f32_e32 v228, v229, v222
	v_fma_f32 v218, -v218, v228, v226
	v_div_fmas_f32 v218, v218, v222, v228
	v_div_fixup_f32 v2, v218, v2, 1.0
	v_div_scale_f32 v227, vcc, 1.0, v3, 1.0
	v_mul_f32_e32 v228, v227, v223
	v_fma_f32 v229, -v219, v228, v227
	v_fmac_f32_e32 v228, v229, v223
	v_fma_f32 v219, -v219, v228, v227
	v_div_fmas_f32 v219, v219, v223, v228
	v_div_fixup_f32 v3, v219, v3, 1.0
	v_lshlrev_b32_e32 v230, 16, v150
	v_and_b32_e32 v150, 0xffff0000, v150
	v_lshlrev_b32_e32 v231, 16, v151
	v_and_b32_e32 v151, 0xffff0000, v151
	v_lshlrev_b32_e32 v232, 16, v234
	v_and_b32_e32 v234, 0xffff0000, v234
	v_lshlrev_b32_e32 v233, 16, v235
	v_and_b32_e32 v235, 0xffff0000, v235
	v_fma_f32 v0, v0, v232, v230
	v_fma_f32 v1, v1, v234, v150
	v_fma_f32 v2, v2, v233, v231
	v_fma_f32 v3, v3, v235, v151
	v_cvt_pk_bf16_f32 v150, v0, v1
	v_cvt_pk_bf16_f32 v151, v2, v3
	global_store_dwordx2 v188, v[150:151], s[62:63] offset:288
	s_and_b64 vcc, exec, s[40:41]
	s_cbranch_vccz .LBB0_640
	s_waitcnt vmcnt(0)
	s_cmpk_gt_u32 s89, 0xff
	s_cbranch_scc1 .LBB0_651
	s_barrier

	.amdhsa_kernel _Z14fwd_megakernel6Params
		.amdhsa_group_segment_fixed_size 24576
		.amdhsa_private_segment_fixed_size 0
		.amdhsa_kernarg_size 440
		.amdhsa_user_sgpr_count 2
		.amdhsa_user_sgpr_dispatch_ptr 0
		.amdhsa_user_sgpr_queue_ptr 0
		.amdhsa_user_sgpr_kernarg_segment_ptr 1
		.amdhsa_user_sgpr_dispatch_id 0
		.amdhsa_user_sgpr_kernarg_preload_length 0
		.amdhsa_user_sgpr_kernarg_preload_offset 0
		.amdhsa_user_sgpr_private_segment_size 0
		.amdhsa_uses_dynamic_stack 0
		.amdhsa_enable_private_segment 0
		.amdhsa_system_sgpr_workgroup_id_x 1
		.amdhsa_system_sgpr_workgroup_id_y 0
		.amdhsa_system_sgpr_workgroup_id_z 0
		.amdhsa_system_sgpr_workgroup_info 0
		.amdhsa_system_vgpr_workitem_id 2
		.amdhsa_next_free_vgpr 256
		.amdhsa_next_free_sgpr 100
		.amdhsa_accum_offset 256
		.amdhsa_reserve_vcc 1
		.amdhsa_float_round_mode_32 0
		.amdhsa_float_round_mode_16_64 0
		.amdhsa_float_denorm_mode_32 3
		.amdhsa_float_denorm_mode_16_64 3
		.amdhsa_dx10_clamp 1
		.amdhsa_ieee_mode 1
		.amdhsa_fp16_overflow 0
		.amdhsa_tg_split 0
		.amdhsa_exception_fp_ieee_invalid_op 0
		.amdhsa_exception_fp_denorm_src 0
		.amdhsa_exception_fp_ieee_div_zero 0
		.amdhsa_exception_fp_ieee_overflow 0
		.amdhsa_exception_fp_ieee_underflow 0
		.amdhsa_exception_fp_ieee_inexact 0
		.amdhsa_exception_int_div_zero 0
	.end_amdhsa_kernel

amdhsa.kernels:
  - .agpr_count:     0
    .args:
      - .offset:         0
        .size:           184
        .value_kind:     by_value
      - .offset:         184
        .size:           4
        .value_kind:     hidden_block_count_x
      - .offset:         188
        .size:           4
        .value_kind:     hidden_block_count_y
      - .offset:         192
        .size:           4
        .value_kind:     hidden_block_count_z
      - .offset:         196
        .size:           2
        .value_kind:     hidden_group_size_x
      - .offset:         198
        .size:           2
        .value_kind:     hidden_group_size_y
      - .offset:         200
        .size:           2
        .value_kind:     hidden_group_size_z
      - .offset:         202
        .size:           2
        .value_kind:     hidden_remainder_x
      - .offset:         204
        .size:           2
        .value_kind:     hidden_remainder_y
      - .offset:         206
        .size:           2
        .value_kind:     hidden_remainder_z
      - .offset:         224
        .size:           8
        .value_kind:     hidden_global_offset_x
      - .offset:         232
        .size:           8
        .value_kind:     hidden_global_offset_y
      - .offset:         240
        .size:           8
        .value_kind:     hidden_global_offset_z
      - .offset:         248
        .size:           2
        .value_kind:     hidden_grid_dims
      - .offset:         272
        .size:           8
        .value_kind:     hidden_multigrid_sync_arg
      - .offset:         304
        .size:           4
        .value_kind:     hidden_dynamic_lds_size
    .group_segment_fixed_size: 24576
    .kernarg_segment_align: 8
    .kernarg_segment_size: 440
    .language:       OpenCL C
    .language_version:
      - 2
      - 0
    .max_flat_workgroup_size: 512
    .name:           _Z14fwd_megakernel6Params
    .private_segment_fixed_size: 0
    .sgpr_count:     106
    .sgpr_spill_count: 173
    .symbol:         _Z14fwd_megakernel6Params.kd
    .uniform_work_group_size: 1
    .uses_dynamic_stack: false
    .vgpr_count:     256
    .vgpr_spill_count: 0
    .wavefront_size: 64
